# pool mixer phase rewritten: all 32 rows of a thread strip loaded up front, lag rows from registers (no lag loads)
# speedup vs baseline: 1.0145x; 1.0111x over previous
; __device__ __forceinline__ int fresh_tid() { int t = threadIdx.x; asm volatile("" : "+v"(t)); return t; }
; __device__ __forceinline__ float bf_lo(unsigned w) { return __uint_as_float(w << 16); }
; __device__ __forceinline__ float bf_hi(unsigned w) { return __uint_as_float(w & 0xffff0000u); }
; __device__ void phase_pool() {
;     ...
;     for (int idx = blockIdx.x * NTHREADS + fresh_tid(); idx < (M_TOK / RB) * (DE / 8); idx += gridDim.x * NTHREADS) {
;         const int c8 = idx % (DE / 8), rb = idx / (DE / 8), col = c8 * 8, g = col >> 10, w = 2 << g, row0 = rb * RB, tl0 = row0 & (SEQ - 1);
;         float s[8];
; #pragma unroll
;         for (int i = 0; i < 8; ++i) s[i] = 0.f;
;         const int nh = (tl0 < w) ? tl0 : w;
;         { u32x4 hv[16];
; #pragma unroll
;           for (int k = 1; k <= 16; ++k) hv[k - 1] = (k <= nh) ? *(const u32x4*)(uz + (size_t)(row0 - k) * DE2 + col) : (u32x4){0u, 0u, 0u, 0u};
; #pragma unroll
;           for (int k = 0; k < 16; ++k) { const u32x4 v = hv[k];
;             s[0] += bf_lo(v.x); s[1] += bf_hi(v.x); s[2] += bf_lo(v.y); s[3] += bf_hi(v.y); s[4] += bf_lo(v.z); s[5] += bf_hi(v.z); s[6] += bf_lo(v.w); s[7] += bf_hi(v.w); } }
.LBB0_287:
	s_cmp_le_i32 s72, s26
	s_cselect_b64 s[98:99], -1, 0
	s_and_b64 s[0:1], s[98:99], s[10:11]
	v_cndmask_b32_e64 v0, 0, 1, s[0:1]
	s_andn2_b64 vcc, exec, s[8:9]
	v_cmp_ne_u32_e64 s[62:63], 1, v0
	s_cbranch_vccnz .LBB0_342
	s_and_b64 vcc, exec, s[62:63]
	s_cbranch_vccnz .LBB0_441
	s_cmp_lg_u32 s92, 0x20000
	s_cbranch_scc1 .Lpool_generic
	s_mov_b64 s[4:5], s[70:71]
	s_load_dwordx2 s[8:9], s[4:5], 0xa0
	v_readlane_b32 s0, v253, 42
	v_readfirstlane_b32 s1, v232
	v_lshlrev_b32_e32 v2, 4, v232
	v_lshlrev_b32_e32 v3, 4, v232
	s_lshr_b32 s14, s1, 7
	s_lshr_b32 s0, s0, 9
	s_lshl_b32 s15, s0, 5
	s_and_b32 s16, s15, 0xfff
	s_waitcnt lgkmcnt(0)
	s_add_u32 s4, s8, 0x2200000
	s_addc_u32 s5, s9, 0
	s_add_u32 s10, s8, 0xa200000
	s_addc_u32 s11, s9, 0
	s_lshl_b32 s0, s15, 13
	s_add_u32 s10, s10, s0
	s_addc_u32 s11, s11, 0
	s_cmp_eq_u32 s14, 0
	s_cbranch_scc1 .Lpool_w2
	s_cmp_eq_u32 s14, 1
	s_cbranch_scc1 .Lpool_w4
	s_cmp_eq_u32 s14, 2
	s_cbranch_scc1 .Lpool_w8
	s_branch .Lpool_w16
.Lpool_w2:
	s_cmp_eq_u32 s16, 0
	s_cbranch_scc1 .Lpool_w2_nohist
	s_sub_u32 s0, s15, 2
	s_lshl_b32 s0, s0, 14
	s_add_u32 s8, s4, s0
	s_addc_u32 s9, s5, 0
	global_load_dwordx4 v[4:7], v2, s[8:9]
	v_add_u32_e32 v2, 0x4000, v2
	global_load_dwordx4 v[8:11], v2, s[8:9]
	v_add_u32_e32 v2, 0x4000, v2
	s_branch .Lpool_w2_main
.Lpool_w2_nohist:
	v_mov_b32_e32 v4, 0
	v_mov_b32_e32 v5, 0
	v_mov_b32_e32 v6, 0
	v_mov_b32_e32 v7, 0
	v_mov_b32_e32 v8, 0
	v_mov_b32_e32 v9, 0
	v_mov_b32_e32 v10, 0
	v_mov_b32_e32 v11, 0
	s_lshl_b32 s0, s15, 14
	s_add_u32 s8, s4, s0
	s_addc_u32 s9, s5, 0
.Lpool_w2_main:
	global_load_dwordx4 v[12:15], v2, s[8:9]
	v_add_u32_e32 v2, 0x4000, v2
	global_load_dwordx4 v[16:19], v2, s[8:9]
	v_add_u32_e32 v2, 0x4000, v2
	global_load_dwordx4 v[20:23], v2, s[8:9]
	v_add_u32_e32 v2, 0x4000, v2
	global_load_dwordx4 v[24:27], v2, s[8:9]
	v_add_u32_e32 v2, 0x4000, v2
	global_load_dwordx4 v[28:31], v2, s[8:9]
	v_add_u32_e32 v2, 0x4000, v2
	global_load_dwordx4 v[32:35], v2, s[8:9]
	v_add_u32_e32 v2, 0x4000, v2
	global_load_dwordx4 v[36:39], v2, s[8:9]
	v_add_u32_e32 v2, 0x4000, v2
	global_load_dwordx4 v[40:43], v2, s[8:9]
	v_add_u32_e32 v2, 0x4000, v2
	global_load_dwordx4 v[44:47], v2, s[8:9]
	v_add_u32_e32 v2, 0x4000, v2
	global_load_dwordx4 v[48:51], v2, s[8:9]
	v_add_u32_e32 v2, 0x4000, v2
	global_load_dwordx4 v[52:55], v2, s[8:9]
	v_add_u32_e32 v2, 0x4000, v2
	global_load_dwordx4 v[56:59], v2, s[8:9]
	v_add_u32_e32 v2, 0x4000, v2
	global_load_dwordx4 v[60:63], v2, s[8:9]
	v_add_u32_e32 v2, 0x4000, v2
	global_load_dwordx4 v[64:67], v2, s[8:9]
	v_add_u32_e32 v2, 0x4000, v2
	global_load_dwordx4 v[68:71], v2, s[8:9]
	v_add_u32_e32 v2, 0x4000, v2
	global_load_dwordx4 v[72:75], v2, s[8:9]
	v_add_u32_e32 v2, 0x4000, v2
	global_load_dwordx4 v[76:79], v2, s[8:9]
	v_add_u32_e32 v2, 0x4000, v2
	global_load_dwordx4 v[80:83], v2, s[8:9]
	v_add_u32_e32 v2, 0x4000, v2
	global_load_dwordx4 v[84:87], v2, s[8:9]
	v_add_u32_e32 v2, 0x4000, v2
	global_load_dwordx4 v[88:91], v2, s[8:9]
	v_add_u32_e32 v2, 0x4000, v2
	global_load_dwordx4 v[92:95], v2, s[8:9]
	v_add_u32_e32 v2, 0x4000, v2
	global_load_dwordx4 v[96:99], v2, s[8:9]
	v_add_u32_e32 v2, 0x4000, v2
	global_load_dwordx4 v[100:103], v2, s[8:9]
	v_add_u32_e32 v2, 0x4000, v2
	global_load_dwordx4 v[104:107], v2, s[8:9]
	v_add_u32_e32 v2, 0x4000, v2
	global_load_dwordx4 v[108:111], v2, s[8:9]
	v_add_u32_e32 v2, 0x4000, v2
	global_load_dwordx4 v[112:115], v2, s[8:9]
	v_add_u32_e32 v2, 0x4000, v2
	global_load_dwordx4 v[116:119], v2, s[8:9]
	v_add_u32_e32 v2, 0x4000, v2
	global_load_dwordx4 v[120:123], v2, s[8:9]
	v_add_u32_e32 v2, 0x4000, v2
	global_load_dwordx4 v[124:127], v2, s[8:9]
	v_add_u32_e32 v2, 0x4000, v2
	global_load_dwordx4 v[128:131], v2, s[8:9]
	v_add_u32_e32 v2, 0x4000, v2
	global_load_dwordx4 v[132:135], v2, s[8:9]
	v_add_u32_e32 v2, 0x4000, v2
	global_load_dwordx4 v[136:139], v2, s[8:9]
	v_mov_b32_e32 v140, 0
	v_mov_b32_e32 v141, 0
	v_mov_b32_e32 v142, 0
	v_mov_b32_e32 v143, 0
	v_mov_b32_e32 v144, 0
	v_mov_b32_e32 v145, 0
	v_mov_b32_e32 v146, 0
	v_mov_b32_e32 v147, 0
	s_mov_b32 s43, 0x3f000000
	s_cmp_eq_u32 s16, 0
	s_waitcnt vmcnt(32)
	v_lshlrev_b32_e32 v152, 16, v8
	v_and_b32_e32 v153, 0xffff0000, v8
	v_lshlrev_b32_e32 v156, 16, v9
	v_and_b32_e32 v157, 0xffff0000, v9
	v_lshlrev_b32_e32 v160, 16, v10
	v_and_b32_e32 v161, 0xffff0000, v10
	v_lshlrev_b32_e32 v164, 16, v11
	v_and_b32_e32 v165, 0xffff0000, v11
	v_pk_add_f32 v[140:141], v[140:141], v[152:153]
	v_pk_add_f32 v[142:143], v[142:143], v[156:157]
	v_pk_add_f32 v[144:145], v[144:145], v[160:161]
	v_pk_add_f32 v[146:147], v[146:147], v[164:165]
	v_lshlrev_b32_e32 v152, 16, v4
	v_and_b32_e32 v153, 0xffff0000, v4
	v_lshlrev_b32_e32 v156, 16, v5
	v_and_b32_e32 v157, 0xffff0000, v5
	v_lshlrev_b32_e32 v160, 16, v6
	v_and_b32_e32 v161, 0xffff0000, v6
	v_lshlrev_b32_e32 v164, 16, v7
	v_and_b32_e32 v165, 0xffff0000, v7
	v_pk_add_f32 v[140:141], v[140:141], v[152:153]
	v_pk_add_f32 v[142:143], v[142:143], v[156:157]
	v_pk_add_f32 v[144:145], v[144:145], v[160:161]
	v_pk_add_f32 v[146:147], v[146:147], v[164:165]
	s_waitcnt vmcnt(31)
; __device__ __forceinline__ unsigned cvt_pk_bf16(float lo, float hi) { unsigned r; asm volatile("v_cvt_pk_bf16_f32 %0, %1, %2" : "=v"(r) : "v"(lo), "v"(hi)); return r; }
; __device__ __forceinline__ float bf_lo(unsigned w) { return __uint_as_float(w << 16); }
; __device__ __forceinline__ float bf_hi(unsigned w) { return __uint_as_float(w & 0xffff0000u); }
; __device__ void phase_pool() {
;     ...
;         for (int r0 = 0; r0 < RB; r0 += 8) {
;             u32x4 vv[8], ov[8];
; #pragma unroll
;             for (int k = 0; k < 8; ++k) { const int row = row0 + r0 + k, tl = tl0 + r0 + k;
;                 vv[k] = *(const u32x4*)(uz + (size_t)row * DE2 + col);
;                 ov[k] = (tl >= w) ? *(const u32x4*)(uz + (size_t)(row - w) * DE2 + col) : (u32x4){0u, 0u, 0u, 0u}; }
; #pragma unroll
;             for (int k = 0; k < 8; ++k) { const int row = row0 + r0 + k, tl = tl0 + r0 + k; const u32x4 v = vv[k], o2 = ov[k];
;                 s[0] += bf_lo(v.x) - bf_lo(o2.x); s[1] += bf_hi(v.x) - bf_hi(o2.x); s[2] += bf_lo(v.y) - bf_lo(o2.y); s[3] += bf_hi(v.y) - bf_hi(o2.y);
;                 s[4] += bf_lo(v.z) - bf_lo(o2.z); s[5] += bf_hi(v.z) - bf_hi(o2.z); s[6] += bf_lo(v.w) - bf_lo(o2.w); s[7] += bf_hi(v.w) - bf_hi(o2.w);
;                 const float ic = 1.0f / (float)((tl + 1 < w) ? tl + 1 : w);
;                 u32x4 o;
;                 o.x = cvt_pk_bf16(s[0] * ic - bf_lo(v.x), s[1] * ic - bf_hi(v.x)); o.y = cvt_pk_bf16(s[2] * ic - bf_lo(v.y), s[3] * ic - bf_hi(v.y));
;                 o.z = cvt_pk_bf16(s[4] * ic - bf_lo(v.z), s[5] * ic - bf_hi(v.z)); o.w = cvt_pk_bf16(s[6] * ic - bf_lo(v.w), s[7] * ic - bf_hi(v.w));
;                 *(u32x4*)(pg + (size_t)row * DE + col) = o; }
	s_cselect_b32 s42, 0x3f800000, s43
	v_lshlrev_b32_e32 v152, 16, v12
	v_and_b32_e32 v153, 0xffff0000, v12
	v_lshlrev_b32_e32 v154, 16, v4
	v_and_b32_e32 v155, 0xffff0000, v4
	v_lshlrev_b32_e32 v156, 16, v13
	v_and_b32_e32 v157, 0xffff0000, v13
	v_lshlrev_b32_e32 v158, 16, v5
	v_and_b32_e32 v159, 0xffff0000, v5
	v_lshlrev_b32_e32 v160, 16, v14
	v_and_b32_e32 v161, 0xffff0000, v14
	v_lshlrev_b32_e32 v162, 16, v6
	v_and_b32_e32 v163, 0xffff0000, v6
	v_lshlrev_b32_e32 v164, 16, v15
	v_and_b32_e32 v165, 0xffff0000, v15
	v_lshlrev_b32_e32 v166, 16, v7
	v_and_b32_e32 v167, 0xffff0000, v7
	v_pk_add_f32 v[154:155], v[152:153], v[154:155] neg_lo:[0,1] neg_hi:[0,1]
	v_pk_add_f32 v[158:159], v[156:157], v[158:159] neg_lo:[0,1] neg_hi:[0,1]
	v_pk_add_f32 v[162:163], v[160:161], v[162:163] neg_lo:[0,1] neg_hi:[0,1]
	v_pk_add_f32 v[166:167], v[164:165], v[166:167] neg_lo:[0,1] neg_hi:[0,1]
	v_pk_add_f32 v[140:141], v[140:141], v[154:155]
	v_pk_add_f32 v[142:143], v[142:143], v[158:159]
	v_pk_add_f32 v[144:145], v[144:145], v[162:163]
	v_pk_add_f32 v[146:147], v[146:147], v[166:167]
	v_fma_f32 v154, s42, v140, -v152
	v_fma_f32 v155, s42, v141, -v153
	v_fma_f32 v158, s42, v142, -v156
	v_fma_f32 v159, s42, v143, -v157
	v_fma_f32 v162, s42, v144, -v160
	v_fma_f32 v163, s42, v145, -v161
	v_fma_f32 v166, s42, v146, -v164
	v_fma_f32 v167, s42, v147, -v165
	v_cvt_pk_bf16_f32 v148, v154, v155
	v_cvt_pk_bf16_f32 v149, v158, v159
	v_cvt_pk_bf16_f32 v150, v162, v163
	v_cvt_pk_bf16_f32 v151, v166, v167
	global_store_dwordx4 v3, v[148:151], s[10:11]
	v_add_u32_e32 v3, 0x2000, v3
	s_waitcnt vmcnt(31)
	v_lshlrev_b32_e32 v152, 16, v16
	v_and_b32_e32 v153, 0xffff0000, v16
	v_lshlrev_b32_e32 v154, 16, v8
	v_and_b32_e32 v155, 0xffff0000, v8
	v_lshlrev_b32_e32 v156, 16, v17
	v_and_b32_e32 v157, 0xffff0000, v17
	v_lshlrev_b32_e32 v158, 16, v9
	v_and_b32_e32 v159, 0xffff0000, v9
	v_lshlrev_b32_e32 v160, 16, v18
	v_and_b32_e32 v161, 0xffff0000, v18
	v_lshlrev_b32_e32 v162, 16, v10
	v_and_b32_e32 v163, 0xffff0000, v10
	v_lshlrev_b32_e32 v164, 16, v19
	v_and_b32_e32 v165, 0xffff0000, v19
	v_lshlrev_b32_e32 v166, 16, v11
	v_and_b32_e32 v167, 0xffff0000, v11
	v_pk_add_f32 v[154:155], v[152:153], v[154:155] neg_lo:[0,1] neg_hi:[0,1]
	v_pk_add_f32 v[158:159], v[156:157], v[158:159] neg_lo:[0,1] neg_hi:[0,1]
	v_pk_add_f32 v[162:163], v[160:161], v[162:163] neg_lo:[0,1] neg_hi:[0,1]
	v_pk_add_f32 v[166:167], v[164:165], v[166:167] neg_lo:[0,1] neg_hi:[0,1]
	v_pk_add_f32 v[140:141], v[140:141], v[154:155]
	v_pk_add_f32 v[142:143], v[142:143], v[158:159]
	v_pk_add_f32 v[144:145], v[144:145], v[162:163]
	v_pk_add_f32 v[146:147], v[146:147], v[166:167]
	v_fma_f32 v154, s43, v140, -v152
	v_fma_f32 v155, s43, v141, -v153
	v_fma_f32 v158, s43, v142, -v156
	v_fma_f32 v159, s43, v143, -v157
	v_fma_f32 v162, s43, v144, -v160
	v_fma_f32 v163, s43, v145, -v161
	v_fma_f32 v166, s43, v146, -v164
	v_fma_f32 v167, s43, v147, -v165
	v_cvt_pk_bf16_f32 v148, v154, v155
	v_cvt_pk_bf16_f32 v149, v158, v159
	v_cvt_pk_bf16_f32 v150, v162, v163
	v_cvt_pk_bf16_f32 v151, v166, v167
	global_store_dwordx4 v3, v[148:151], s[10:11]
	v_add_u32_e32 v3, 0x2000, v3
	s_waitcnt vmcnt(31)
	v_lshlrev_b32_e32 v152, 16, v20
	v_and_b32_e32 v153, 0xffff0000, v20
	v_lshlrev_b32_e32 v154, 16, v12
	v_and_b32_e32 v155, 0xffff0000, v12
	v_lshlrev_b32_e32 v156, 16, v21
	v_and_b32_e32 v157, 0xffff0000, v21
	v_lshlrev_b32_e32 v158, 16, v13
	v_and_b32_e32 v159, 0xffff0000, v13
	v_lshlrev_b32_e32 v160, 16, v22
	v_and_b32_e32 v161, 0xffff0000, v22
	v_lshlrev_b32_e32 v162, 16, v14
	v_and_b32_e32 v163, 0xffff0000, v14
	v_lshlrev_b32_e32 v164, 16, v23
	v_and_b32_e32 v165, 0xffff0000, v23
	v_lshlrev_b32_e32 v166, 16, v15
	v_and_b32_e32 v167, 0xffff0000, v15
	v_pk_add_f32 v[154:155], v[152:153], v[154:155] neg_lo:[0,1] neg_hi:[0,1]
	v_pk_add_f32 v[158:159], v[156:157], v[158:159] neg_lo:[0,1] neg_hi:[0,1]
	v_pk_add_f32 v[162:163], v[160:161], v[162:163] neg_lo:[0,1] neg_hi:[0,1]
	v_pk_add_f32 v[166:167], v[164:165], v[166:167] neg_lo:[0,1] neg_hi:[0,1]
	v_pk_add_f32 v[140:141], v[140:141], v[154:155]
	v_pk_add_f32 v[142:143], v[142:143], v[158:159]
	v_pk_add_f32 v[144:145], v[144:145], v[162:163]
	v_pk_add_f32 v[146:147], v[146:147], v[166:167]
	v_fma_f32 v154, s43, v140, -v152
	v_fma_f32 v155, s43, v141, -v153
	v_fma_f32 v158, s43, v142, -v156
	v_fma_f32 v159, s43, v143, -v157
	v_fma_f32 v162, s43, v144, -v160
	v_fma_f32 v163, s43, v145, -v161
	v_fma_f32 v166, s43, v146, -v164
	v_fma_f32 v167, s43, v147, -v165
	v_cvt_pk_bf16_f32 v148, v154, v155
	v_cvt_pk_bf16_f32 v149, v158, v159
	v_cvt_pk_bf16_f32 v150, v162, v163
	v_cvt_pk_bf16_f32 v151, v166, v167
	global_store_dwordx4 v3, v[148:151], s[10:11]
	v_add_u32_e32 v3, 0x2000, v3
	s_waitcnt vmcnt(31)
	v_lshlrev_b32_e32 v152, 16, v24
	v_and_b32_e32 v153, 0xffff0000, v24
	v_lshlrev_b32_e32 v154, 16, v16
	v_and_b32_e32 v155, 0xffff0000, v16
	v_lshlrev_b32_e32 v156, 16, v25
	v_and_b32_e32 v157, 0xffff0000, v25
	v_lshlrev_b32_e32 v158, 16, v17
	v_and_b32_e32 v159, 0xffff0000, v17
	v_lshlrev_b32_e32 v160, 16, v26
	v_and_b32_e32 v161, 0xffff0000, v26
	v_lshlrev_b32_e32 v162, 16, v18
	v_and_b32_e32 v163, 0xffff0000, v18
	v_lshlrev_b32_e32 v164, 16, v27
	v_and_b32_e32 v165, 0xffff0000, v27
	v_lshlrev_b32_e32 v166, 16, v19
	v_and_b32_e32 v167, 0xffff0000, v19
	v_pk_add_f32 v[154:155], v[152:153], v[154:155] neg_lo:[0,1] neg_hi:[0,1]
	v_pk_add_f32 v[158:159], v[156:157], v[158:159] neg_lo:[0,1] neg_hi:[0,1]
	v_pk_add_f32 v[162:163], v[160:161], v[162:163] neg_lo:[0,1] neg_hi:[0,1]
	v_pk_add_f32 v[166:167], v[164:165], v[166:167] neg_lo:[0,1] neg_hi:[0,1]
	v_pk_add_f32 v[140:141], v[140:141], v[154:155]
	v_pk_add_f32 v[142:143], v[142:143], v[158:159]
	v_pk_add_f32 v[144:145], v[144:145], v[162:163]
	v_pk_add_f32 v[146:147], v[146:147], v[166:167]
	v_fma_f32 v154, s43, v140, -v152
	v_fma_f32 v155, s43, v141, -v153
	v_fma_f32 v158, s43, v142, -v156
	v_fma_f32 v159, s43, v143, -v157
	v_fma_f32 v162, s43, v144, -v160
	v_fma_f32 v163, s43, v145, -v161
	v_fma_f32 v166, s43, v146, -v164
	v_fma_f32 v167, s43, v147, -v165
	v_cvt_pk_bf16_f32 v148, v154, v155
	v_cvt_pk_bf16_f32 v149, v158, v159
	v_cvt_pk_bf16_f32 v150, v162, v163
	v_cvt_pk_bf16_f32 v151, v166, v167
	global_store_dwordx4 v3, v[148:151], s[10:11]
	v_add_u32_e32 v3, 0x2000, v3
	s_waitcnt vmcnt(31)
; __device__ __forceinline__ unsigned cvt_pk_bf16(float lo, float hi) { unsigned r; asm volatile("v_cvt_pk_bf16_f32 %0, %1, %2" : "=v"(r) : "v"(lo), "v"(hi)); return r; }
; __device__ __forceinline__ float bf_lo(unsigned w) { return __uint_as_float(w << 16); }
; __device__ __forceinline__ float bf_hi(unsigned w) { return __uint_as_float(w & 0xffff0000u); }
; __device__ void phase_pool() {
;     ...
;         for (int r0 = 0; r0 < RB; r0 += 8) {
;             u32x4 vv[8], ov[8];
; #pragma unroll
;             for (int k = 0; k < 8; ++k) { const int row = row0 + r0 + k, tl = tl0 + r0 + k;
;                 vv[k] = *(const u32x4*)(uz + (size_t)row * DE2 + col);
;                 ov[k] = (tl >= w) ? *(const u32x4*)(uz + (size_t)(row - w) * DE2 + col) : (u32x4){0u, 0u, 0u, 0u}; }
; #pragma unroll
;             for (int k = 0; k < 8; ++k) { const int row = row0 + r0 + k, tl = tl0 + r0 + k; const u32x4 v = vv[k], o2 = ov[k];
;                 s[0] += bf_lo(v.x) - bf_lo(o2.x); s[1] += bf_hi(v.x) - bf_hi(o2.x); s[2] += bf_lo(v.y) - bf_lo(o2.y); s[3] += bf_hi(v.y) - bf_hi(o2.y);
;                 s[4] += bf_lo(v.z) - bf_lo(o2.z); s[5] += bf_hi(v.z) - bf_hi(o2.z); s[6] += bf_lo(v.w) - bf_lo(o2.w); s[7] += bf_hi(v.w) - bf_hi(o2.w);
;                 const float ic = 1.0f / (float)((tl + 1 < w) ? tl + 1 : w);
;                 u32x4 o;
;                 o.x = cvt_pk_bf16(s[0] * ic - bf_lo(v.x), s[1] * ic - bf_hi(v.x)); o.y = cvt_pk_bf16(s[2] * ic - bf_lo(v.y), s[3] * ic - bf_hi(v.y));
;                 o.z = cvt_pk_bf16(s[4] * ic - bf_lo(v.z), s[5] * ic - bf_hi(v.z)); o.w = cvt_pk_bf16(s[6] * ic - bf_lo(v.w), s[7] * ic - bf_hi(v.w));
;                 *(u32x4*)(pg + (size_t)row * DE + col) = o; }
	v_lshlrev_b32_e32 v152, 16, v28
	v_and_b32_e32 v153, 0xffff0000, v28
	v_lshlrev_b32_e32 v154, 16, v20
	v_and_b32_e32 v155, 0xffff0000, v20
	v_lshlrev_b32_e32 v156, 16, v29
	v_and_b32_e32 v157, 0xffff0000, v29
	v_lshlrev_b32_e32 v158, 16, v21
	v_and_b32_e32 v159, 0xffff0000, v21
	v_lshlrev_b32_e32 v160, 16, v30
	v_and_b32_e32 v161, 0xffff0000, v30
	v_lshlrev_b32_e32 v162, 16, v22
	v_and_b32_e32 v163, 0xffff0000, v22
	v_lshlrev_b32_e32 v164, 16, v31
	v_and_b32_e32 v165, 0xffff0000, v31
	v_lshlrev_b32_e32 v166, 16, v23
	v_and_b32_e32 v167, 0xffff0000, v23
	v_pk_add_f32 v[154:155], v[152:153], v[154:155] neg_lo:[0,1] neg_hi:[0,1]
	v_pk_add_f32 v[158:159], v[156:157], v[158:159] neg_lo:[0,1] neg_hi:[0,1]
	v_pk_add_f32 v[162:163], v[160:161], v[162:163] neg_lo:[0,1] neg_hi:[0,1]
	v_pk_add_f32 v[166:167], v[164:165], v[166:167] neg_lo:[0,1] neg_hi:[0,1]
	v_pk_add_f32 v[140:141], v[140:141], v[154:155]
	v_pk_add_f32 v[142:143], v[142:143], v[158:159]
	v_pk_add_f32 v[144:145], v[144:145], v[162:163]
	v_pk_add_f32 v[146:147], v[146:147], v[166:167]
	v_fma_f32 v154, s43, v140, -v152
	v_fma_f32 v155, s43, v141, -v153
	v_fma_f32 v158, s43, v142, -v156
	v_fma_f32 v159, s43, v143, -v157
	v_fma_f32 v162, s43, v144, -v160
	v_fma_f32 v163, s43, v145, -v161
	v_fma_f32 v166, s43, v146, -v164
	v_fma_f32 v167, s43, v147, -v165
	v_cvt_pk_bf16_f32 v148, v154, v155
	v_cvt_pk_bf16_f32 v149, v158, v159
	v_cvt_pk_bf16_f32 v150, v162, v163
	v_cvt_pk_bf16_f32 v151, v166, v167
	global_store_dwordx4 v3, v[148:151], s[10:11]
	v_add_u32_e32 v3, 0x2000, v3
	s_waitcnt vmcnt(31)
	v_lshlrev_b32_e32 v152, 16, v32
	v_and_b32_e32 v153, 0xffff0000, v32
	v_lshlrev_b32_e32 v154, 16, v24
	v_and_b32_e32 v155, 0xffff0000, v24
	v_lshlrev_b32_e32 v156, 16, v33
	v_and_b32_e32 v157, 0xffff0000, v33
	v_lshlrev_b32_e32 v158, 16, v25
	v_and_b32_e32 v159, 0xffff0000, v25
	v_lshlrev_b32_e32 v160, 16, v34
	v_and_b32_e32 v161, 0xffff0000, v34
	v_lshlrev_b32_e32 v162, 16, v26
	v_and_b32_e32 v163, 0xffff0000, v26
	v_lshlrev_b32_e32 v164, 16, v35
	v_and_b32_e32 v165, 0xffff0000, v35
	v_lshlrev_b32_e32 v166, 16, v27
	v_and_b32_e32 v167, 0xffff0000, v27
	v_pk_add_f32 v[154:155], v[152:153], v[154:155] neg_lo:[0,1] neg_hi:[0,1]
	v_pk_add_f32 v[158:159], v[156:157], v[158:159] neg_lo:[0,1] neg_hi:[0,1]
	v_pk_add_f32 v[162:163], v[160:161], v[162:163] neg_lo:[0,1] neg_hi:[0,1]
	v_pk_add_f32 v[166:167], v[164:165], v[166:167] neg_lo:[0,1] neg_hi:[0,1]
	v_pk_add_f32 v[140:141], v[140:141], v[154:155]
	v_pk_add_f32 v[142:143], v[142:143], v[158:159]
	v_pk_add_f32 v[144:145], v[144:145], v[162:163]
	v_pk_add_f32 v[146:147], v[146:147], v[166:167]
	v_fma_f32 v154, s43, v140, -v152
	v_fma_f32 v155, s43, v141, -v153
	v_fma_f32 v158, s43, v142, -v156
	v_fma_f32 v159, s43, v143, -v157
	v_fma_f32 v162, s43, v144, -v160
	v_fma_f32 v163, s43, v145, -v161
	v_fma_f32 v166, s43, v146, -v164
	v_fma_f32 v167, s43, v147, -v165
	v_cvt_pk_bf16_f32 v148, v154, v155
	v_cvt_pk_bf16_f32 v149, v158, v159
	v_cvt_pk_bf16_f32 v150, v162, v163
	v_cvt_pk_bf16_f32 v151, v166, v167
	global_store_dwordx4 v3, v[148:151], s[10:11]
	v_add_u32_e32 v3, 0x2000, v3
	s_waitcnt vmcnt(31)
	v_lshlrev_b32_e32 v152, 16, v36
	v_and_b32_e32 v153, 0xffff0000, v36
	v_lshlrev_b32_e32 v154, 16, v28
	v_and_b32_e32 v155, 0xffff0000, v28
	v_lshlrev_b32_e32 v156, 16, v37
	v_and_b32_e32 v157, 0xffff0000, v37
	v_lshlrev_b32_e32 v158, 16, v29
	v_and_b32_e32 v159, 0xffff0000, v29
	v_lshlrev_b32_e32 v160, 16, v38
	v_and_b32_e32 v161, 0xffff0000, v38
	v_lshlrev_b32_e32 v162, 16, v30
	v_and_b32_e32 v163, 0xffff0000, v30
	v_lshlrev_b32_e32 v164, 16, v39
	v_and_b32_e32 v165, 0xffff0000, v39
	v_lshlrev_b32_e32 v166, 16, v31
	v_and_b32_e32 v167, 0xffff0000, v31
	v_pk_add_f32 v[154:155], v[152:153], v[154:155] neg_lo:[0,1] neg_hi:[0,1]
	v_pk_add_f32 v[158:159], v[156:157], v[158:159] neg_lo:[0,1] neg_hi:[0,1]
	v_pk_add_f32 v[162:163], v[160:161], v[162:163] neg_lo:[0,1] neg_hi:[0,1]
	v_pk_add_f32 v[166:167], v[164:165], v[166:167] neg_lo:[0,1] neg_hi:[0,1]
	v_pk_add_f32 v[140:141], v[140:141], v[154:155]
	v_pk_add_f32 v[142:143], v[142:143], v[158:159]
	v_pk_add_f32 v[144:145], v[144:145], v[162:163]
	v_pk_add_f32 v[146:147], v[146:147], v[166:167]
	v_fma_f32 v154, s43, v140, -v152
	v_fma_f32 v155, s43, v141, -v153
	v_fma_f32 v158, s43, v142, -v156
	v_fma_f32 v159, s43, v143, -v157
	v_fma_f32 v162, s43, v144, -v160
	v_fma_f32 v163, s43, v145, -v161
	v_fma_f32 v166, s43, v146, -v164
	v_fma_f32 v167, s43, v147, -v165
	v_cvt_pk_bf16_f32 v148, v154, v155
	v_cvt_pk_bf16_f32 v149, v158, v159
	v_cvt_pk_bf16_f32 v150, v162, v163
	v_cvt_pk_bf16_f32 v151, v166, v167
	global_store_dwordx4 v3, v[148:151], s[10:11]
	v_add_u32_e32 v3, 0x2000, v3
	s_waitcnt vmcnt(31)
	v_lshlrev_b32_e32 v152, 16, v40
	v_and_b32_e32 v153, 0xffff0000, v40
	v_lshlrev_b32_e32 v154, 16, v32
	v_and_b32_e32 v155, 0xffff0000, v32
	v_lshlrev_b32_e32 v156, 16, v41
	v_and_b32_e32 v157, 0xffff0000, v41
	v_lshlrev_b32_e32 v158, 16, v33
	v_and_b32_e32 v159, 0xffff0000, v33
	v_lshlrev_b32_e32 v160, 16, v42
	v_and_b32_e32 v161, 0xffff0000, v42
	v_lshlrev_b32_e32 v162, 16, v34
	v_and_b32_e32 v163, 0xffff0000, v34
	v_lshlrev_b32_e32 v164, 16, v43
	v_and_b32_e32 v165, 0xffff0000, v43
	v_lshlrev_b32_e32 v166, 16, v35
	v_and_b32_e32 v167, 0xffff0000, v35
	v_pk_add_f32 v[154:155], v[152:153], v[154:155] neg_lo:[0,1] neg_hi:[0,1]
	v_pk_add_f32 v[158:159], v[156:157], v[158:159] neg_lo:[0,1] neg_hi:[0,1]
	v_pk_add_f32 v[162:163], v[160:161], v[162:163] neg_lo:[0,1] neg_hi:[0,1]
	v_pk_add_f32 v[166:167], v[164:165], v[166:167] neg_lo:[0,1] neg_hi:[0,1]
	v_pk_add_f32 v[140:141], v[140:141], v[154:155]
	v_pk_add_f32 v[142:143], v[142:143], v[158:159]
	v_pk_add_f32 v[144:145], v[144:145], v[162:163]
	v_pk_add_f32 v[146:147], v[146:147], v[166:167]
	v_fma_f32 v154, s43, v140, -v152
	v_fma_f32 v155, s43, v141, -v153
	v_fma_f32 v158, s43, v142, -v156
	v_fma_f32 v159, s43, v143, -v157
	v_fma_f32 v162, s43, v144, -v160
	v_fma_f32 v163, s43, v145, -v161
	v_fma_f32 v166, s43, v146, -v164
	v_fma_f32 v167, s43, v147, -v165
	v_cvt_pk_bf16_f32 v148, v154, v155
	v_cvt_pk_bf16_f32 v149, v158, v159
	v_cvt_pk_bf16_f32 v150, v162, v163
	v_cvt_pk_bf16_f32 v151, v166, v167
	global_store_dwordx4 v3, v[148:151], s[10:11]
	v_add_u32_e32 v3, 0x2000, v3
	s_waitcnt vmcnt(31)
; __device__ __forceinline__ unsigned cvt_pk_bf16(float lo, float hi) { unsigned r; asm volatile("v_cvt_pk_bf16_f32 %0, %1, %2" : "=v"(r) : "v"(lo), "v"(hi)); return r; }
; __device__ __forceinline__ float bf_lo(unsigned w) { return __uint_as_float(w << 16); }
; __device__ __forceinline__ float bf_hi(unsigned w) { return __uint_as_float(w & 0xffff0000u); }
; __device__ void phase_pool() {
;     ...
;         for (int r0 = 0; r0 < RB; r0 += 8) {
;             u32x4 vv[8], ov[8];
; #pragma unroll
;             for (int k = 0; k < 8; ++k) { const int row = row0 + r0 + k, tl = tl0 + r0 + k;
;                 vv[k] = *(const u32x4*)(uz + (size_t)row * DE2 + col);
;                 ov[k] = (tl >= w) ? *(const u32x4*)(uz + (size_t)(row - w) * DE2 + col) : (u32x4){0u, 0u, 0u, 0u}; }
; #pragma unroll
;             for (int k = 0; k < 8; ++k) { const int row = row0 + r0 + k, tl = tl0 + r0 + k; const u32x4 v = vv[k], o2 = ov[k];
;                 s[0] += bf_lo(v.x) - bf_lo(o2.x); s[1] += bf_hi(v.x) - bf_hi(o2.x); s[2] += bf_lo(v.y) - bf_lo(o2.y); s[3] += bf_hi(v.y) - bf_hi(o2.y);
;                 s[4] += bf_lo(v.z) - bf_lo(o2.z); s[5] += bf_hi(v.z) - bf_hi(o2.z); s[6] += bf_lo(v.w) - bf_lo(o2.w); s[7] += bf_hi(v.w) - bf_hi(o2.w);
;                 const float ic = 1.0f / (float)((tl + 1 < w) ? tl + 1 : w);
;                 u32x4 o;
;                 o.x = cvt_pk_bf16(s[0] * ic - bf_lo(v.x), s[1] * ic - bf_hi(v.x)); o.y = cvt_pk_bf16(s[2] * ic - bf_lo(v.y), s[3] * ic - bf_hi(v.y));
;                 o.z = cvt_pk_bf16(s[4] * ic - bf_lo(v.z), s[5] * ic - bf_hi(v.z)); o.w = cvt_pk_bf16(s[6] * ic - bf_lo(v.w), s[7] * ic - bf_hi(v.w));
;                 *(u32x4*)(pg + (size_t)row * DE + col) = o; }
	v_lshlrev_b32_e32 v152, 16, v44
	v_and_b32_e32 v153, 0xffff0000, v44
	v_lshlrev_b32_e32 v154, 16, v36
	v_and_b32_e32 v155, 0xffff0000, v36
	v_lshlrev_b32_e32 v156, 16, v45
	v_and_b32_e32 v157, 0xffff0000, v45
	v_lshlrev_b32_e32 v158, 16, v37
	v_and_b32_e32 v159, 0xffff0000, v37
	v_lshlrev_b32_e32 v160, 16, v46
	v_and_b32_e32 v161, 0xffff0000, v46
	v_lshlrev_b32_e32 v162, 16, v38
	v_and_b32_e32 v163, 0xffff0000, v38
	v_lshlrev_b32_e32 v164, 16, v47
	v_and_b32_e32 v165, 0xffff0000, v47
	v_lshlrev_b32_e32 v166, 16, v39
	v_and_b32_e32 v167, 0xffff0000, v39
	v_pk_add_f32 v[154:155], v[152:153], v[154:155] neg_lo:[0,1] neg_hi:[0,1]
	v_pk_add_f32 v[158:159], v[156:157], v[158:159] neg_lo:[0,1] neg_hi:[0,1]
	v_pk_add_f32 v[162:163], v[160:161], v[162:163] neg_lo:[0,1] neg_hi:[0,1]
	v_pk_add_f32 v[166:167], v[164:165], v[166:167] neg_lo:[0,1] neg_hi:[0,1]
	v_pk_add_f32 v[140:141], v[140:141], v[154:155]
	v_pk_add_f32 v[142:143], v[142:143], v[158:159]
	v_pk_add_f32 v[144:145], v[144:145], v[162:163]
	v_pk_add_f32 v[146:147], v[146:147], v[166:167]
	v_fma_f32 v154, s43, v140, -v152
	v_fma_f32 v155, s43, v141, -v153
	v_fma_f32 v158, s43, v142, -v156
	v_fma_f32 v159, s43, v143, -v157
	v_fma_f32 v162, s43, v144, -v160
	v_fma_f32 v163, s43, v145, -v161
	v_fma_f32 v166, s43, v146, -v164
	v_fma_f32 v167, s43, v147, -v165
	v_cvt_pk_bf16_f32 v148, v154, v155
	v_cvt_pk_bf16_f32 v149, v158, v159
	v_cvt_pk_bf16_f32 v150, v162, v163
	v_cvt_pk_bf16_f32 v151, v166, v167
	global_store_dwordx4 v3, v[148:151], s[10:11]
	v_add_u32_e32 v3, 0x2000, v3
	s_waitcnt vmcnt(31)
	v_lshlrev_b32_e32 v152, 16, v48
	v_and_b32_e32 v153, 0xffff0000, v48
	v_lshlrev_b32_e32 v154, 16, v40
	v_and_b32_e32 v155, 0xffff0000, v40
	v_lshlrev_b32_e32 v156, 16, v49
	v_and_b32_e32 v157, 0xffff0000, v49
	v_lshlrev_b32_e32 v158, 16, v41
	v_and_b32_e32 v159, 0xffff0000, v41
	v_lshlrev_b32_e32 v160, 16, v50
	v_and_b32_e32 v161, 0xffff0000, v50
	v_lshlrev_b32_e32 v162, 16, v42
	v_and_b32_e32 v163, 0xffff0000, v42
	v_lshlrev_b32_e32 v164, 16, v51
	v_and_b32_e32 v165, 0xffff0000, v51
	v_lshlrev_b32_e32 v166, 16, v43
	v_and_b32_e32 v167, 0xffff0000, v43
	v_pk_add_f32 v[154:155], v[152:153], v[154:155] neg_lo:[0,1] neg_hi:[0,1]
	v_pk_add_f32 v[158:159], v[156:157], v[158:159] neg_lo:[0,1] neg_hi:[0,1]
	v_pk_add_f32 v[162:163], v[160:161], v[162:163] neg_lo:[0,1] neg_hi:[0,1]
	v_pk_add_f32 v[166:167], v[164:165], v[166:167] neg_lo:[0,1] neg_hi:[0,1]
	v_pk_add_f32 v[140:141], v[140:141], v[154:155]
	v_pk_add_f32 v[142:143], v[142:143], v[158:159]
	v_pk_add_f32 v[144:145], v[144:145], v[162:163]
	v_pk_add_f32 v[146:147], v[146:147], v[166:167]
	v_fma_f32 v154, s43, v140, -v152
	v_fma_f32 v155, s43, v141, -v153
	v_fma_f32 v158, s43, v142, -v156
	v_fma_f32 v159, s43, v143, -v157
	v_fma_f32 v162, s43, v144, -v160
	v_fma_f32 v163, s43, v145, -v161
	v_fma_f32 v166, s43, v146, -v164
	v_fma_f32 v167, s43, v147, -v165
	v_cvt_pk_bf16_f32 v148, v154, v155
	v_cvt_pk_bf16_f32 v149, v158, v159
	v_cvt_pk_bf16_f32 v150, v162, v163
	v_cvt_pk_bf16_f32 v151, v166, v167
	global_store_dwordx4 v3, v[148:151], s[10:11]
	v_add_u32_e32 v3, 0x2000, v3
	s_waitcnt vmcnt(31)
	v_lshlrev_b32_e32 v152, 16, v52
	v_and_b32_e32 v153, 0xffff0000, v52
	v_lshlrev_b32_e32 v154, 16, v44
	v_and_b32_e32 v155, 0xffff0000, v44
	v_lshlrev_b32_e32 v156, 16, v53
	v_and_b32_e32 v157, 0xffff0000, v53
	v_lshlrev_b32_e32 v158, 16, v45
	v_and_b32_e32 v159, 0xffff0000, v45
	v_lshlrev_b32_e32 v160, 16, v54
	v_and_b32_e32 v161, 0xffff0000, v54
	v_lshlrev_b32_e32 v162, 16, v46
	v_and_b32_e32 v163, 0xffff0000, v46
	v_lshlrev_b32_e32 v164, 16, v55
	v_and_b32_e32 v165, 0xffff0000, v55
	v_lshlrev_b32_e32 v166, 16, v47
	v_and_b32_e32 v167, 0xffff0000, v47
	v_pk_add_f32 v[154:155], v[152:153], v[154:155] neg_lo:[0,1] neg_hi:[0,1]
	v_pk_add_f32 v[158:159], v[156:157], v[158:159] neg_lo:[0,1] neg_hi:[0,1]
	v_pk_add_f32 v[162:163], v[160:161], v[162:163] neg_lo:[0,1] neg_hi:[0,1]
	v_pk_add_f32 v[166:167], v[164:165], v[166:167] neg_lo:[0,1] neg_hi:[0,1]
	v_pk_add_f32 v[140:141], v[140:141], v[154:155]
	v_pk_add_f32 v[142:143], v[142:143], v[158:159]
	v_pk_add_f32 v[144:145], v[144:145], v[162:163]
	v_pk_add_f32 v[146:147], v[146:147], v[166:167]
	v_fma_f32 v154, s43, v140, -v152
	v_fma_f32 v155, s43, v141, -v153
	v_fma_f32 v158, s43, v142, -v156
	v_fma_f32 v159, s43, v143, -v157
	v_fma_f32 v162, s43, v144, -v160
	v_fma_f32 v163, s43, v145, -v161
	v_fma_f32 v166, s43, v146, -v164
	v_fma_f32 v167, s43, v147, -v165
	v_cvt_pk_bf16_f32 v148, v154, v155
	v_cvt_pk_bf16_f32 v149, v158, v159
	v_cvt_pk_bf16_f32 v150, v162, v163
	v_cvt_pk_bf16_f32 v151, v166, v167
	global_store_dwordx4 v3, v[148:151], s[10:11]
	v_add_u32_e32 v3, 0x2000, v3
	s_waitcnt vmcnt(31)
	v_lshlrev_b32_e32 v152, 16, v56
	v_and_b32_e32 v153, 0xffff0000, v56
	v_lshlrev_b32_e32 v154, 16, v48
	v_and_b32_e32 v155, 0xffff0000, v48
	v_lshlrev_b32_e32 v156, 16, v57
	v_and_b32_e32 v157, 0xffff0000, v57
	v_lshlrev_b32_e32 v158, 16, v49
	v_and_b32_e32 v159, 0xffff0000, v49
	v_lshlrev_b32_e32 v160, 16, v58
	v_and_b32_e32 v161, 0xffff0000, v58
	v_lshlrev_b32_e32 v162, 16, v50
	v_and_b32_e32 v163, 0xffff0000, v50
	v_lshlrev_b32_e32 v164, 16, v59
	v_and_b32_e32 v165, 0xffff0000, v59
	v_lshlrev_b32_e32 v166, 16, v51
	v_and_b32_e32 v167, 0xffff0000, v51
	v_pk_add_f32 v[154:155], v[152:153], v[154:155] neg_lo:[0,1] neg_hi:[0,1]
	v_pk_add_f32 v[158:159], v[156:157], v[158:159] neg_lo:[0,1] neg_hi:[0,1]
	v_pk_add_f32 v[162:163], v[160:161], v[162:163] neg_lo:[0,1] neg_hi:[0,1]
	v_pk_add_f32 v[166:167], v[164:165], v[166:167] neg_lo:[0,1] neg_hi:[0,1]
	v_pk_add_f32 v[140:141], v[140:141], v[154:155]
	v_pk_add_f32 v[142:143], v[142:143], v[158:159]
	v_pk_add_f32 v[144:145], v[144:145], v[162:163]
	v_pk_add_f32 v[146:147], v[146:147], v[166:167]
	v_fma_f32 v154, s43, v140, -v152
	v_fma_f32 v155, s43, v141, -v153
	v_fma_f32 v158, s43, v142, -v156
	v_fma_f32 v159, s43, v143, -v157
	v_fma_f32 v162, s43, v144, -v160
	v_fma_f32 v163, s43, v145, -v161
	v_fma_f32 v166, s43, v146, -v164
	v_fma_f32 v167, s43, v147, -v165
	v_cvt_pk_bf16_f32 v148, v154, v155
	v_cvt_pk_bf16_f32 v149, v158, v159
	v_cvt_pk_bf16_f32 v150, v162, v163
	v_cvt_pk_bf16_f32 v151, v166, v167
	global_store_dwordx4 v3, v[148:151], s[10:11]
	v_add_u32_e32 v3, 0x2000, v3
	s_waitcnt vmcnt(31)
; __device__ __forceinline__ unsigned cvt_pk_bf16(float lo, float hi) { unsigned r; asm volatile("v_cvt_pk_bf16_f32 %0, %1, %2" : "=v"(r) : "v"(lo), "v"(hi)); return r; }
; __device__ __forceinline__ float bf_lo(unsigned w) { return __uint_as_float(w << 16); }
; __device__ __forceinline__ float bf_hi(unsigned w) { return __uint_as_float(w & 0xffff0000u); }
; __device__ void phase_pool() {
;     ...
;         for (int r0 = 0; r0 < RB; r0 += 8) {
;             u32x4 vv[8], ov[8];
; #pragma unroll
;             for (int k = 0; k < 8; ++k) { const int row = row0 + r0 + k, tl = tl0 + r0 + k;
;                 vv[k] = *(const u32x4*)(uz + (size_t)row * DE2 + col);
;                 ov[k] = (tl >= w) ? *(const u32x4*)(uz + (size_t)(row - w) * DE2 + col) : (u32x4){0u, 0u, 0u, 0u}; }
; #pragma unroll
;             for (int k = 0; k < 8; ++k) { const int row = row0 + r0 + k, tl = tl0 + r0 + k; const u32x4 v = vv[k], o2 = ov[k];
;                 s[0] += bf_lo(v.x) - bf_lo(o2.x); s[1] += bf_hi(v.x) - bf_hi(o2.x); s[2] += bf_lo(v.y) - bf_lo(o2.y); s[3] += bf_hi(v.y) - bf_hi(o2.y);
;                 s[4] += bf_lo(v.z) - bf_lo(o2.z); s[5] += bf_hi(v.z) - bf_hi(o2.z); s[6] += bf_lo(v.w) - bf_lo(o2.w); s[7] += bf_hi(v.w) - bf_hi(o2.w);
;                 const float ic = 1.0f / (float)((tl + 1 < w) ? tl + 1 : w);
;                 u32x4 o;
;                 o.x = cvt_pk_bf16(s[0] * ic - bf_lo(v.x), s[1] * ic - bf_hi(v.x)); o.y = cvt_pk_bf16(s[2] * ic - bf_lo(v.y), s[3] * ic - bf_hi(v.y));
;                 o.z = cvt_pk_bf16(s[4] * ic - bf_lo(v.z), s[5] * ic - bf_hi(v.z)); o.w = cvt_pk_bf16(s[6] * ic - bf_lo(v.w), s[7] * ic - bf_hi(v.w));
;                 *(u32x4*)(pg + (size_t)row * DE + col) = o; }
	v_lshlrev_b32_e32 v152, 16, v60
	v_and_b32_e32 v153, 0xffff0000, v60
	v_lshlrev_b32_e32 v154, 16, v52
	v_and_b32_e32 v155, 0xffff0000, v52
	v_lshlrev_b32_e32 v156, 16, v61
	v_and_b32_e32 v157, 0xffff0000, v61
	v_lshlrev_b32_e32 v158, 16, v53
	v_and_b32_e32 v159, 0xffff0000, v53
	v_lshlrev_b32_e32 v160, 16, v62
	v_and_b32_e32 v161, 0xffff0000, v62
	v_lshlrev_b32_e32 v162, 16, v54
	v_and_b32_e32 v163, 0xffff0000, v54
	v_lshlrev_b32_e32 v164, 16, v63
	v_and_b32_e32 v165, 0xffff0000, v63
	v_lshlrev_b32_e32 v166, 16, v55
	v_and_b32_e32 v167, 0xffff0000, v55
	v_pk_add_f32 v[154:155], v[152:153], v[154:155] neg_lo:[0,1] neg_hi:[0,1]
	v_pk_add_f32 v[158:159], v[156:157], v[158:159] neg_lo:[0,1] neg_hi:[0,1]
	v_pk_add_f32 v[162:163], v[160:161], v[162:163] neg_lo:[0,1] neg_hi:[0,1]
	v_pk_add_f32 v[166:167], v[164:165], v[166:167] neg_lo:[0,1] neg_hi:[0,1]
	v_pk_add_f32 v[140:141], v[140:141], v[154:155]
	v_pk_add_f32 v[142:143], v[142:143], v[158:159]
	v_pk_add_f32 v[144:145], v[144:145], v[162:163]
	v_pk_add_f32 v[146:147], v[146:147], v[166:167]
	v_fma_f32 v154, s43, v140, -v152
	v_fma_f32 v155, s43, v141, -v153
	v_fma_f32 v158, s43, v142, -v156
	v_fma_f32 v159, s43, v143, -v157
	v_fma_f32 v162, s43, v144, -v160
	v_fma_f32 v163, s43, v145, -v161
	v_fma_f32 v166, s43, v146, -v164
	v_fma_f32 v167, s43, v147, -v165
	v_cvt_pk_bf16_f32 v148, v154, v155
	v_cvt_pk_bf16_f32 v149, v158, v159
	v_cvt_pk_bf16_f32 v150, v162, v163
	v_cvt_pk_bf16_f32 v151, v166, v167
	global_store_dwordx4 v3, v[148:151], s[10:11]
	v_add_u32_e32 v3, 0x2000, v3
	s_waitcnt vmcnt(31)
	v_lshlrev_b32_e32 v152, 16, v64
	v_and_b32_e32 v153, 0xffff0000, v64
	v_lshlrev_b32_e32 v154, 16, v56
	v_and_b32_e32 v155, 0xffff0000, v56
	v_lshlrev_b32_e32 v156, 16, v65
	v_and_b32_e32 v157, 0xffff0000, v65
	v_lshlrev_b32_e32 v158, 16, v57
	v_and_b32_e32 v159, 0xffff0000, v57
	v_lshlrev_b32_e32 v160, 16, v66
	v_and_b32_e32 v161, 0xffff0000, v66
	v_lshlrev_b32_e32 v162, 16, v58
	v_and_b32_e32 v163, 0xffff0000, v58
	v_lshlrev_b32_e32 v164, 16, v67
	v_and_b32_e32 v165, 0xffff0000, v67
	v_lshlrev_b32_e32 v166, 16, v59
	v_and_b32_e32 v167, 0xffff0000, v59
	v_pk_add_f32 v[154:155], v[152:153], v[154:155] neg_lo:[0,1] neg_hi:[0,1]
	v_pk_add_f32 v[158:159], v[156:157], v[158:159] neg_lo:[0,1] neg_hi:[0,1]
	v_pk_add_f32 v[162:163], v[160:161], v[162:163] neg_lo:[0,1] neg_hi:[0,1]
	v_pk_add_f32 v[166:167], v[164:165], v[166:167] neg_lo:[0,1] neg_hi:[0,1]
	v_pk_add_f32 v[140:141], v[140:141], v[154:155]
	v_pk_add_f32 v[142:143], v[142:143], v[158:159]
	v_pk_add_f32 v[144:145], v[144:145], v[162:163]
	v_pk_add_f32 v[146:147], v[146:147], v[166:167]
	v_fma_f32 v154, s43, v140, -v152
	v_fma_f32 v155, s43, v141, -v153
	v_fma_f32 v158, s43, v142, -v156
	v_fma_f32 v159, s43, v143, -v157
	v_fma_f32 v162, s43, v144, -v160
	v_fma_f32 v163, s43, v145, -v161
	v_fma_f32 v166, s43, v146, -v164
	v_fma_f32 v167, s43, v147, -v165
	v_cvt_pk_bf16_f32 v148, v154, v155
	v_cvt_pk_bf16_f32 v149, v158, v159
	v_cvt_pk_bf16_f32 v150, v162, v163
	v_cvt_pk_bf16_f32 v151, v166, v167
	global_store_dwordx4 v3, v[148:151], s[10:11]
	v_add_u32_e32 v3, 0x2000, v3
	s_waitcnt vmcnt(31)
	v_lshlrev_b32_e32 v152, 16, v68
	v_and_b32_e32 v153, 0xffff0000, v68
	v_lshlrev_b32_e32 v154, 16, v60
	v_and_b32_e32 v155, 0xffff0000, v60
	v_lshlrev_b32_e32 v156, 16, v69
	v_and_b32_e32 v157, 0xffff0000, v69
	v_lshlrev_b32_e32 v158, 16, v61
	v_and_b32_e32 v159, 0xffff0000, v61
	v_lshlrev_b32_e32 v160, 16, v70
	v_and_b32_e32 v161, 0xffff0000, v70
	v_lshlrev_b32_e32 v162, 16, v62
	v_and_b32_e32 v163, 0xffff0000, v62
	v_lshlrev_b32_e32 v164, 16, v71
	v_and_b32_e32 v165, 0xffff0000, v71
	v_lshlrev_b32_e32 v166, 16, v63
	v_and_b32_e32 v167, 0xffff0000, v63
	v_pk_add_f32 v[154:155], v[152:153], v[154:155] neg_lo:[0,1] neg_hi:[0,1]
	v_pk_add_f32 v[158:159], v[156:157], v[158:159] neg_lo:[0,1] neg_hi:[0,1]
	v_pk_add_f32 v[162:163], v[160:161], v[162:163] neg_lo:[0,1] neg_hi:[0,1]
	v_pk_add_f32 v[166:167], v[164:165], v[166:167] neg_lo:[0,1] neg_hi:[0,1]
	v_pk_add_f32 v[140:141], v[140:141], v[154:155]
	v_pk_add_f32 v[142:143], v[142:143], v[158:159]
	v_pk_add_f32 v[144:145], v[144:145], v[162:163]
	v_pk_add_f32 v[146:147], v[146:147], v[166:167]
	v_fma_f32 v154, s43, v140, -v152
	v_fma_f32 v155, s43, v141, -v153
	v_fma_f32 v158, s43, v142, -v156
	v_fma_f32 v159, s43, v143, -v157
	v_fma_f32 v162, s43, v144, -v160
	v_fma_f32 v163, s43, v145, -v161
	v_fma_f32 v166, s43, v146, -v164
	v_fma_f32 v167, s43, v147, -v165
	v_cvt_pk_bf16_f32 v148, v154, v155
	v_cvt_pk_bf16_f32 v149, v158, v159
	v_cvt_pk_bf16_f32 v150, v162, v163
	v_cvt_pk_bf16_f32 v151, v166, v167
	global_store_dwordx4 v3, v[148:151], s[10:11]
	v_add_u32_e32 v3, 0x2000, v3
	s_waitcnt vmcnt(31)
	v_lshlrev_b32_e32 v152, 16, v72
	v_and_b32_e32 v153, 0xffff0000, v72
	v_lshlrev_b32_e32 v154, 16, v64
	v_and_b32_e32 v155, 0xffff0000, v64
	v_lshlrev_b32_e32 v156, 16, v73
	v_and_b32_e32 v157, 0xffff0000, v73
	v_lshlrev_b32_e32 v158, 16, v65
	v_and_b32_e32 v159, 0xffff0000, v65
	v_lshlrev_b32_e32 v160, 16, v74
	v_and_b32_e32 v161, 0xffff0000, v74
	v_lshlrev_b32_e32 v162, 16, v66
	v_and_b32_e32 v163, 0xffff0000, v66
	v_lshlrev_b32_e32 v164, 16, v75
	v_and_b32_e32 v165, 0xffff0000, v75
	v_lshlrev_b32_e32 v166, 16, v67
	v_and_b32_e32 v167, 0xffff0000, v67
	v_pk_add_f32 v[154:155], v[152:153], v[154:155] neg_lo:[0,1] neg_hi:[0,1]
	v_pk_add_f32 v[158:159], v[156:157], v[158:159] neg_lo:[0,1] neg_hi:[0,1]
	v_pk_add_f32 v[162:163], v[160:161], v[162:163] neg_lo:[0,1] neg_hi:[0,1]
	v_pk_add_f32 v[166:167], v[164:165], v[166:167] neg_lo:[0,1] neg_hi:[0,1]
	v_pk_add_f32 v[140:141], v[140:141], v[154:155]
	v_pk_add_f32 v[142:143], v[142:143], v[158:159]
	v_pk_add_f32 v[144:145], v[144:145], v[162:163]
	v_pk_add_f32 v[146:147], v[146:147], v[166:167]
	v_fma_f32 v154, s43, v140, -v152
	v_fma_f32 v155, s43, v141, -v153
	v_fma_f32 v158, s43, v142, -v156
	v_fma_f32 v159, s43, v143, -v157
	v_fma_f32 v162, s43, v144, -v160
	v_fma_f32 v163, s43, v145, -v161
	v_fma_f32 v166, s43, v146, -v164
	v_fma_f32 v167, s43, v147, -v165
	v_cvt_pk_bf16_f32 v148, v154, v155
	v_cvt_pk_bf16_f32 v149, v158, v159
	v_cvt_pk_bf16_f32 v150, v162, v163
	v_cvt_pk_bf16_f32 v151, v166, v167
	global_store_dwordx4 v3, v[148:151], s[10:11]
	v_add_u32_e32 v3, 0x2000, v3
	s_waitcnt vmcnt(31)
; __device__ __forceinline__ unsigned cvt_pk_bf16(float lo, float hi) { unsigned r; asm volatile("v_cvt_pk_bf16_f32 %0, %1, %2" : "=v"(r) : "v"(lo), "v"(hi)); return r; }
; __device__ __forceinline__ float bf_lo(unsigned w) { return __uint_as_float(w << 16); }
; __device__ __forceinline__ float bf_hi(unsigned w) { return __uint_as_float(w & 0xffff0000u); }
; __device__ void phase_pool() {
;     ...
;         for (int r0 = 0; r0 < RB; r0 += 8) {
;             u32x4 vv[8], ov[8];
; #pragma unroll
;             for (int k = 0; k < 8; ++k) { const int row = row0 + r0 + k, tl = tl0 + r0 + k;
;                 vv[k] = *(const u32x4*)(uz + (size_t)row * DE2 + col);
;                 ov[k] = (tl >= w) ? *(const u32x4*)(uz + (size_t)(row - w) * DE2 + col) : (u32x4){0u, 0u, 0u, 0u}; }
; #pragma unroll
;             for (int k = 0; k < 8; ++k) { const int row = row0 + r0 + k, tl = tl0 + r0 + k; const u32x4 v = vv[k], o2 = ov[k];
;                 s[0] += bf_lo(v.x) - bf_lo(o2.x); s[1] += bf_hi(v.x) - bf_hi(o2.x); s[2] += bf_lo(v.y) - bf_lo(o2.y); s[3] += bf_hi(v.y) - bf_hi(o2.y);
;                 s[4] += bf_lo(v.z) - bf_lo(o2.z); s[5] += bf_hi(v.z) - bf_hi(o2.z); s[6] += bf_lo(v.w) - bf_lo(o2.w); s[7] += bf_hi(v.w) - bf_hi(o2.w);
;                 const float ic = 1.0f / (float)((tl + 1 < w) ? tl + 1 : w);
;                 u32x4 o;
;                 o.x = cvt_pk_bf16(s[0] * ic - bf_lo(v.x), s[1] * ic - bf_hi(v.x)); o.y = cvt_pk_bf16(s[2] * ic - bf_lo(v.y), s[3] * ic - bf_hi(v.y));
;                 o.z = cvt_pk_bf16(s[4] * ic - bf_lo(v.z), s[5] * ic - bf_hi(v.z)); o.w = cvt_pk_bf16(s[6] * ic - bf_lo(v.w), s[7] * ic - bf_hi(v.w));
;                 *(u32x4*)(pg + (size_t)row * DE + col) = o; }
	v_lshlrev_b32_e32 v152, 16, v76
	v_and_b32_e32 v153, 0xffff0000, v76
	v_lshlrev_b32_e32 v154, 16, v68
	v_and_b32_e32 v155, 0xffff0000, v68
	v_lshlrev_b32_e32 v156, 16, v77
	v_and_b32_e32 v157, 0xffff0000, v77
	v_lshlrev_b32_e32 v158, 16, v69
	v_and_b32_e32 v159, 0xffff0000, v69
	v_lshlrev_b32_e32 v160, 16, v78
	v_and_b32_e32 v161, 0xffff0000, v78
	v_lshlrev_b32_e32 v162, 16, v70
	v_and_b32_e32 v163, 0xffff0000, v70
	v_lshlrev_b32_e32 v164, 16, v79
	v_and_b32_e32 v165, 0xffff0000, v79
	v_lshlrev_b32_e32 v166, 16, v71
	v_and_b32_e32 v167, 0xffff0000, v71
	v_pk_add_f32 v[154:155], v[152:153], v[154:155] neg_lo:[0,1] neg_hi:[0,1]
	v_pk_add_f32 v[158:159], v[156:157], v[158:159] neg_lo:[0,1] neg_hi:[0,1]
	v_pk_add_f32 v[162:163], v[160:161], v[162:163] neg_lo:[0,1] neg_hi:[0,1]
	v_pk_add_f32 v[166:167], v[164:165], v[166:167] neg_lo:[0,1] neg_hi:[0,1]
	v_pk_add_f32 v[140:141], v[140:141], v[154:155]
	v_pk_add_f32 v[142:143], v[142:143], v[158:159]
	v_pk_add_f32 v[144:145], v[144:145], v[162:163]
	v_pk_add_f32 v[146:147], v[146:147], v[166:167]
	v_fma_f32 v154, s43, v140, -v152
	v_fma_f32 v155, s43, v141, -v153
	v_fma_f32 v158, s43, v142, -v156
	v_fma_f32 v159, s43, v143, -v157
	v_fma_f32 v162, s43, v144, -v160
	v_fma_f32 v163, s43, v145, -v161
	v_fma_f32 v166, s43, v146, -v164
	v_fma_f32 v167, s43, v147, -v165
	v_cvt_pk_bf16_f32 v148, v154, v155
	v_cvt_pk_bf16_f32 v149, v158, v159
	v_cvt_pk_bf16_f32 v150, v162, v163
	v_cvt_pk_bf16_f32 v151, v166, v167
	global_store_dwordx4 v3, v[148:151], s[10:11]
	v_add_u32_e32 v3, 0x2000, v3
	s_waitcnt vmcnt(31)
	v_lshlrev_b32_e32 v152, 16, v80
	v_and_b32_e32 v153, 0xffff0000, v80
	v_lshlrev_b32_e32 v154, 16, v72
	v_and_b32_e32 v155, 0xffff0000, v72
	v_lshlrev_b32_e32 v156, 16, v81
	v_and_b32_e32 v157, 0xffff0000, v81
	v_lshlrev_b32_e32 v158, 16, v73
	v_and_b32_e32 v159, 0xffff0000, v73
	v_lshlrev_b32_e32 v160, 16, v82
	v_and_b32_e32 v161, 0xffff0000, v82
	v_lshlrev_b32_e32 v162, 16, v74
	v_and_b32_e32 v163, 0xffff0000, v74
	v_lshlrev_b32_e32 v164, 16, v83
	v_and_b32_e32 v165, 0xffff0000, v83
	v_lshlrev_b32_e32 v166, 16, v75
	v_and_b32_e32 v167, 0xffff0000, v75
	v_pk_add_f32 v[154:155], v[152:153], v[154:155] neg_lo:[0,1] neg_hi:[0,1]
	v_pk_add_f32 v[158:159], v[156:157], v[158:159] neg_lo:[0,1] neg_hi:[0,1]
	v_pk_add_f32 v[162:163], v[160:161], v[162:163] neg_lo:[0,1] neg_hi:[0,1]
	v_pk_add_f32 v[166:167], v[164:165], v[166:167] neg_lo:[0,1] neg_hi:[0,1]
	v_pk_add_f32 v[140:141], v[140:141], v[154:155]
	v_pk_add_f32 v[142:143], v[142:143], v[158:159]
	v_pk_add_f32 v[144:145], v[144:145], v[162:163]
	v_pk_add_f32 v[146:147], v[146:147], v[166:167]
	v_fma_f32 v154, s43, v140, -v152
	v_fma_f32 v155, s43, v141, -v153
	v_fma_f32 v158, s43, v142, -v156
	v_fma_f32 v159, s43, v143, -v157
	v_fma_f32 v162, s43, v144, -v160
	v_fma_f32 v163, s43, v145, -v161
	v_fma_f32 v166, s43, v146, -v164
	v_fma_f32 v167, s43, v147, -v165
	v_cvt_pk_bf16_f32 v148, v154, v155
	v_cvt_pk_bf16_f32 v149, v158, v159
	v_cvt_pk_bf16_f32 v150, v162, v163
	v_cvt_pk_bf16_f32 v151, v166, v167
	global_store_dwordx4 v3, v[148:151], s[10:11]
	v_add_u32_e32 v3, 0x2000, v3
	s_waitcnt vmcnt(31)
	v_lshlrev_b32_e32 v152, 16, v84
	v_and_b32_e32 v153, 0xffff0000, v84
	v_lshlrev_b32_e32 v154, 16, v76
	v_and_b32_e32 v155, 0xffff0000, v76
	v_lshlrev_b32_e32 v156, 16, v85
	v_and_b32_e32 v157, 0xffff0000, v85
	v_lshlrev_b32_e32 v158, 16, v77
	v_and_b32_e32 v159, 0xffff0000, v77
	v_lshlrev_b32_e32 v160, 16, v86
	v_and_b32_e32 v161, 0xffff0000, v86
	v_lshlrev_b32_e32 v162, 16, v78
	v_and_b32_e32 v163, 0xffff0000, v78
	v_lshlrev_b32_e32 v164, 16, v87
	v_and_b32_e32 v165, 0xffff0000, v87
	v_lshlrev_b32_e32 v166, 16, v79
	v_and_b32_e32 v167, 0xffff0000, v79
	v_pk_add_f32 v[154:155], v[152:153], v[154:155] neg_lo:[0,1] neg_hi:[0,1]
	v_pk_add_f32 v[158:159], v[156:157], v[158:159] neg_lo:[0,1] neg_hi:[0,1]
	v_pk_add_f32 v[162:163], v[160:161], v[162:163] neg_lo:[0,1] neg_hi:[0,1]
	v_pk_add_f32 v[166:167], v[164:165], v[166:167] neg_lo:[0,1] neg_hi:[0,1]
	v_pk_add_f32 v[140:141], v[140:141], v[154:155]
	v_pk_add_f32 v[142:143], v[142:143], v[158:159]
	v_pk_add_f32 v[144:145], v[144:145], v[162:163]
	v_pk_add_f32 v[146:147], v[146:147], v[166:167]
	v_fma_f32 v154, s43, v140, -v152
	v_fma_f32 v155, s43, v141, -v153
	v_fma_f32 v158, s43, v142, -v156
	v_fma_f32 v159, s43, v143, -v157
	v_fma_f32 v162, s43, v144, -v160
	v_fma_f32 v163, s43, v145, -v161
	v_fma_f32 v166, s43, v146, -v164
	v_fma_f32 v167, s43, v147, -v165
	v_cvt_pk_bf16_f32 v148, v154, v155
	v_cvt_pk_bf16_f32 v149, v158, v159
	v_cvt_pk_bf16_f32 v150, v162, v163
	v_cvt_pk_bf16_f32 v151, v166, v167
	global_store_dwordx4 v3, v[148:151], s[10:11]
	v_add_u32_e32 v3, 0x2000, v3
	s_waitcnt vmcnt(31)
	v_lshlrev_b32_e32 v152, 16, v88
	v_and_b32_e32 v153, 0xffff0000, v88
	v_lshlrev_b32_e32 v154, 16, v80
	v_and_b32_e32 v155, 0xffff0000, v80
	v_lshlrev_b32_e32 v156, 16, v89
	v_and_b32_e32 v157, 0xffff0000, v89
	v_lshlrev_b32_e32 v158, 16, v81
	v_and_b32_e32 v159, 0xffff0000, v81
	v_lshlrev_b32_e32 v160, 16, v90
	v_and_b32_e32 v161, 0xffff0000, v90
	v_lshlrev_b32_e32 v162, 16, v82
	v_and_b32_e32 v163, 0xffff0000, v82
	v_lshlrev_b32_e32 v164, 16, v91
	v_and_b32_e32 v165, 0xffff0000, v91
	v_lshlrev_b32_e32 v166, 16, v83
	v_and_b32_e32 v167, 0xffff0000, v83
	v_pk_add_f32 v[154:155], v[152:153], v[154:155] neg_lo:[0,1] neg_hi:[0,1]
	v_pk_add_f32 v[158:159], v[156:157], v[158:159] neg_lo:[0,1] neg_hi:[0,1]
	v_pk_add_f32 v[162:163], v[160:161], v[162:163] neg_lo:[0,1] neg_hi:[0,1]
	v_pk_add_f32 v[166:167], v[164:165], v[166:167] neg_lo:[0,1] neg_hi:[0,1]
	v_pk_add_f32 v[140:141], v[140:141], v[154:155]
	v_pk_add_f32 v[142:143], v[142:143], v[158:159]
	v_pk_add_f32 v[144:145], v[144:145], v[162:163]
	v_pk_add_f32 v[146:147], v[146:147], v[166:167]
	v_fma_f32 v154, s43, v140, -v152
	v_fma_f32 v155, s43, v141, -v153
	v_fma_f32 v158, s43, v142, -v156
	v_fma_f32 v159, s43, v143, -v157
	v_fma_f32 v162, s43, v144, -v160
	v_fma_f32 v163, s43, v145, -v161
	v_fma_f32 v166, s43, v146, -v164
	v_fma_f32 v167, s43, v147, -v165
	v_cvt_pk_bf16_f32 v148, v154, v155
	v_cvt_pk_bf16_f32 v149, v158, v159
	v_cvt_pk_bf16_f32 v150, v162, v163
	v_cvt_pk_bf16_f32 v151, v166, v167
	global_store_dwordx4 v3, v[148:151], s[10:11]
	v_add_u32_e32 v3, 0x2000, v3
	s_waitcnt vmcnt(31)
; __device__ __forceinline__ unsigned cvt_pk_bf16(float lo, float hi) { unsigned r; asm volatile("v_cvt_pk_bf16_f32 %0, %1, %2" : "=v"(r) : "v"(lo), "v"(hi)); return r; }
; __device__ __forceinline__ float bf_lo(unsigned w) { return __uint_as_float(w << 16); }
; __device__ __forceinline__ float bf_hi(unsigned w) { return __uint_as_float(w & 0xffff0000u); }
; __device__ void phase_pool() {
;     ...
;         for (int r0 = 0; r0 < RB; r0 += 8) {
;             u32x4 vv[8], ov[8];
; #pragma unroll
;             for (int k = 0; k < 8; ++k) { const int row = row0 + r0 + k, tl = tl0 + r0 + k;
;                 vv[k] = *(const u32x4*)(uz + (size_t)row * DE2 + col);
;                 ov[k] = (tl >= w) ? *(const u32x4*)(uz + (size_t)(row - w) * DE2 + col) : (u32x4){0u, 0u, 0u, 0u}; }
; #pragma unroll
;             for (int k = 0; k < 8; ++k) { const int row = row0 + r0 + k, tl = tl0 + r0 + k; const u32x4 v = vv[k], o2 = ov[k];
;                 s[0] += bf_lo(v.x) - bf_lo(o2.x); s[1] += bf_hi(v.x) - bf_hi(o2.x); s[2] += bf_lo(v.y) - bf_lo(o2.y); s[3] += bf_hi(v.y) - bf_hi(o2.y);
;                 s[4] += bf_lo(v.z) - bf_lo(o2.z); s[5] += bf_hi(v.z) - bf_hi(o2.z); s[6] += bf_lo(v.w) - bf_lo(o2.w); s[7] += bf_hi(v.w) - bf_hi(o2.w);
;                 const float ic = 1.0f / (float)((tl + 1 < w) ? tl + 1 : w);
;                 u32x4 o;
;                 o.x = cvt_pk_bf16(s[0] * ic - bf_lo(v.x), s[1] * ic - bf_hi(v.x)); o.y = cvt_pk_bf16(s[2] * ic - bf_lo(v.y), s[3] * ic - bf_hi(v.y));
;                 o.z = cvt_pk_bf16(s[4] * ic - bf_lo(v.z), s[5] * ic - bf_hi(v.z)); o.w = cvt_pk_bf16(s[6] * ic - bf_lo(v.w), s[7] * ic - bf_hi(v.w));
;                 *(u32x4*)(pg + (size_t)row * DE + col) = o; }
	v_lshlrev_b32_e32 v152, 16, v92
	v_and_b32_e32 v153, 0xffff0000, v92
	v_lshlrev_b32_e32 v154, 16, v84
	v_and_b32_e32 v155, 0xffff0000, v84
	v_lshlrev_b32_e32 v156, 16, v93
	v_and_b32_e32 v157, 0xffff0000, v93
	v_lshlrev_b32_e32 v158, 16, v85
	v_and_b32_e32 v159, 0xffff0000, v85
	v_lshlrev_b32_e32 v160, 16, v94
	v_and_b32_e32 v161, 0xffff0000, v94
	v_lshlrev_b32_e32 v162, 16, v86
	v_and_b32_e32 v163, 0xffff0000, v86
	v_lshlrev_b32_e32 v164, 16, v95
	v_and_b32_e32 v165, 0xffff0000, v95
	v_lshlrev_b32_e32 v166, 16, v87
	v_and_b32_e32 v167, 0xffff0000, v87
	v_pk_add_f32 v[154:155], v[152:153], v[154:155] neg_lo:[0,1] neg_hi:[0,1]
	v_pk_add_f32 v[158:159], v[156:157], v[158:159] neg_lo:[0,1] neg_hi:[0,1]
	v_pk_add_f32 v[162:163], v[160:161], v[162:163] neg_lo:[0,1] neg_hi:[0,1]
	v_pk_add_f32 v[166:167], v[164:165], v[166:167] neg_lo:[0,1] neg_hi:[0,1]
	v_pk_add_f32 v[140:141], v[140:141], v[154:155]
	v_pk_add_f32 v[142:143], v[142:143], v[158:159]
	v_pk_add_f32 v[144:145], v[144:145], v[162:163]
	v_pk_add_f32 v[146:147], v[146:147], v[166:167]
	v_fma_f32 v154, s43, v140, -v152
	v_fma_f32 v155, s43, v141, -v153
	v_fma_f32 v158, s43, v142, -v156
	v_fma_f32 v159, s43, v143, -v157
	v_fma_f32 v162, s43, v144, -v160
	v_fma_f32 v163, s43, v145, -v161
	v_fma_f32 v166, s43, v146, -v164
	v_fma_f32 v167, s43, v147, -v165
	v_cvt_pk_bf16_f32 v148, v154, v155
	v_cvt_pk_bf16_f32 v149, v158, v159
	v_cvt_pk_bf16_f32 v150, v162, v163
	v_cvt_pk_bf16_f32 v151, v166, v167
	global_store_dwordx4 v3, v[148:151], s[10:11]
	v_add_u32_e32 v3, 0x2000, v3
	s_waitcnt vmcnt(31)
	v_lshlrev_b32_e32 v152, 16, v96
	v_and_b32_e32 v153, 0xffff0000, v96
	v_lshlrev_b32_e32 v154, 16, v88
	v_and_b32_e32 v155, 0xffff0000, v88
	v_lshlrev_b32_e32 v156, 16, v97
	v_and_b32_e32 v157, 0xffff0000, v97
	v_lshlrev_b32_e32 v158, 16, v89
	v_and_b32_e32 v159, 0xffff0000, v89
	v_lshlrev_b32_e32 v160, 16, v98
	v_and_b32_e32 v161, 0xffff0000, v98
	v_lshlrev_b32_e32 v162, 16, v90
	v_and_b32_e32 v163, 0xffff0000, v90
	v_lshlrev_b32_e32 v164, 16, v99
	v_and_b32_e32 v165, 0xffff0000, v99
	v_lshlrev_b32_e32 v166, 16, v91
	v_and_b32_e32 v167, 0xffff0000, v91
	v_pk_add_f32 v[154:155], v[152:153], v[154:155] neg_lo:[0,1] neg_hi:[0,1]
	v_pk_add_f32 v[158:159], v[156:157], v[158:159] neg_lo:[0,1] neg_hi:[0,1]
	v_pk_add_f32 v[162:163], v[160:161], v[162:163] neg_lo:[0,1] neg_hi:[0,1]
	v_pk_add_f32 v[166:167], v[164:165], v[166:167] neg_lo:[0,1] neg_hi:[0,1]
	v_pk_add_f32 v[140:141], v[140:141], v[154:155]
	v_pk_add_f32 v[142:143], v[142:143], v[158:159]
	v_pk_add_f32 v[144:145], v[144:145], v[162:163]
	v_pk_add_f32 v[146:147], v[146:147], v[166:167]
	v_fma_f32 v154, s43, v140, -v152
	v_fma_f32 v155, s43, v141, -v153
	v_fma_f32 v158, s43, v142, -v156
	v_fma_f32 v159, s43, v143, -v157
	v_fma_f32 v162, s43, v144, -v160
	v_fma_f32 v163, s43, v145, -v161
	v_fma_f32 v166, s43, v146, -v164
	v_fma_f32 v167, s43, v147, -v165
	v_cvt_pk_bf16_f32 v148, v154, v155
	v_cvt_pk_bf16_f32 v149, v158, v159
	v_cvt_pk_bf16_f32 v150, v162, v163
	v_cvt_pk_bf16_f32 v151, v166, v167
	global_store_dwordx4 v3, v[148:151], s[10:11]
	v_add_u32_e32 v3, 0x2000, v3
	s_waitcnt vmcnt(31)
	v_lshlrev_b32_e32 v152, 16, v100
	v_and_b32_e32 v153, 0xffff0000, v100
	v_lshlrev_b32_e32 v154, 16, v92
	v_and_b32_e32 v155, 0xffff0000, v92
	v_lshlrev_b32_e32 v156, 16, v101
	v_and_b32_e32 v157, 0xffff0000, v101
	v_lshlrev_b32_e32 v158, 16, v93
	v_and_b32_e32 v159, 0xffff0000, v93
	v_lshlrev_b32_e32 v160, 16, v102
	v_and_b32_e32 v161, 0xffff0000, v102
	v_lshlrev_b32_e32 v162, 16, v94
	v_and_b32_e32 v163, 0xffff0000, v94
	v_lshlrev_b32_e32 v164, 16, v103
	v_and_b32_e32 v165, 0xffff0000, v103
	v_lshlrev_b32_e32 v166, 16, v95
	v_and_b32_e32 v167, 0xffff0000, v95
	v_pk_add_f32 v[154:155], v[152:153], v[154:155] neg_lo:[0,1] neg_hi:[0,1]
	v_pk_add_f32 v[158:159], v[156:157], v[158:159] neg_lo:[0,1] neg_hi:[0,1]
	v_pk_add_f32 v[162:163], v[160:161], v[162:163] neg_lo:[0,1] neg_hi:[0,1]
	v_pk_add_f32 v[166:167], v[164:165], v[166:167] neg_lo:[0,1] neg_hi:[0,1]
	v_pk_add_f32 v[140:141], v[140:141], v[154:155]
	v_pk_add_f32 v[142:143], v[142:143], v[158:159]
	v_pk_add_f32 v[144:145], v[144:145], v[162:163]
	v_pk_add_f32 v[146:147], v[146:147], v[166:167]
	v_fma_f32 v154, s43, v140, -v152
	v_fma_f32 v155, s43, v141, -v153
	v_fma_f32 v158, s43, v142, -v156
	v_fma_f32 v159, s43, v143, -v157
	v_fma_f32 v162, s43, v144, -v160
	v_fma_f32 v163, s43, v145, -v161
	v_fma_f32 v166, s43, v146, -v164
	v_fma_f32 v167, s43, v147, -v165
	v_cvt_pk_bf16_f32 v148, v154, v155
	v_cvt_pk_bf16_f32 v149, v158, v159
	v_cvt_pk_bf16_f32 v150, v162, v163
	v_cvt_pk_bf16_f32 v151, v166, v167
	global_store_dwordx4 v3, v[148:151], s[10:11]
	v_add_u32_e32 v3, 0x2000, v3
	s_waitcnt vmcnt(31)
	v_lshlrev_b32_e32 v152, 16, v104
	v_and_b32_e32 v153, 0xffff0000, v104
	v_lshlrev_b32_e32 v154, 16, v96
	v_and_b32_e32 v155, 0xffff0000, v96
	v_lshlrev_b32_e32 v156, 16, v105
	v_and_b32_e32 v157, 0xffff0000, v105
	v_lshlrev_b32_e32 v158, 16, v97
	v_and_b32_e32 v159, 0xffff0000, v97
	v_lshlrev_b32_e32 v160, 16, v106
	v_and_b32_e32 v161, 0xffff0000, v106
	v_lshlrev_b32_e32 v162, 16, v98
	v_and_b32_e32 v163, 0xffff0000, v98
	v_lshlrev_b32_e32 v164, 16, v107
	v_and_b32_e32 v165, 0xffff0000, v107
	v_lshlrev_b32_e32 v166, 16, v99
	v_and_b32_e32 v167, 0xffff0000, v99
	v_pk_add_f32 v[154:155], v[152:153], v[154:155] neg_lo:[0,1] neg_hi:[0,1]
	v_pk_add_f32 v[158:159], v[156:157], v[158:159] neg_lo:[0,1] neg_hi:[0,1]
	v_pk_add_f32 v[162:163], v[160:161], v[162:163] neg_lo:[0,1] neg_hi:[0,1]
	v_pk_add_f32 v[166:167], v[164:165], v[166:167] neg_lo:[0,1] neg_hi:[0,1]
	v_pk_add_f32 v[140:141], v[140:141], v[154:155]
	v_pk_add_f32 v[142:143], v[142:143], v[158:159]
	v_pk_add_f32 v[144:145], v[144:145], v[162:163]
	v_pk_add_f32 v[146:147], v[146:147], v[166:167]
	v_fma_f32 v154, s43, v140, -v152
	v_fma_f32 v155, s43, v141, -v153
	v_fma_f32 v158, s43, v142, -v156
	v_fma_f32 v159, s43, v143, -v157
	v_fma_f32 v162, s43, v144, -v160
	v_fma_f32 v163, s43, v145, -v161
	v_fma_f32 v166, s43, v146, -v164
	v_fma_f32 v167, s43, v147, -v165
	v_cvt_pk_bf16_f32 v148, v154, v155
	v_cvt_pk_bf16_f32 v149, v158, v159
	v_cvt_pk_bf16_f32 v150, v162, v163
	v_cvt_pk_bf16_f32 v151, v166, v167
	global_store_dwordx4 v3, v[148:151], s[10:11]
	v_add_u32_e32 v3, 0x2000, v3
	s_waitcnt vmcnt(31)
; __device__ __forceinline__ unsigned cvt_pk_bf16(float lo, float hi) { unsigned r; asm volatile("v_cvt_pk_bf16_f32 %0, %1, %2" : "=v"(r) : "v"(lo), "v"(hi)); return r; }
; __device__ __forceinline__ float bf_lo(unsigned w) { return __uint_as_float(w << 16); }
; __device__ __forceinline__ float bf_hi(unsigned w) { return __uint_as_float(w & 0xffff0000u); }
; __device__ void phase_pool() {
;     ...
;         for (int r0 = 0; r0 < RB; r0 += 8) {
;             u32x4 vv[8], ov[8];
; #pragma unroll
;             for (int k = 0; k < 8; ++k) { const int row = row0 + r0 + k, tl = tl0 + r0 + k;
;                 vv[k] = *(const u32x4*)(uz + (size_t)row * DE2 + col);
;                 ov[k] = (tl >= w) ? *(const u32x4*)(uz + (size_t)(row - w) * DE2 + col) : (u32x4){0u, 0u, 0u, 0u}; }
; #pragma unroll
;             for (int k = 0; k < 8; ++k) { const int row = row0 + r0 + k, tl = tl0 + r0 + k; const u32x4 v = vv[k], o2 = ov[k];
;                 s[0] += bf_lo(v.x) - bf_lo(o2.x); s[1] += bf_hi(v.x) - bf_hi(o2.x); s[2] += bf_lo(v.y) - bf_lo(o2.y); s[3] += bf_hi(v.y) - bf_hi(o2.y);
;                 s[4] += bf_lo(v.z) - bf_lo(o2.z); s[5] += bf_hi(v.z) - bf_hi(o2.z); s[6] += bf_lo(v.w) - bf_lo(o2.w); s[7] += bf_hi(v.w) - bf_hi(o2.w);
;                 const float ic = 1.0f / (float)((tl + 1 < w) ? tl + 1 : w);
;                 u32x4 o;
;                 o.x = cvt_pk_bf16(s[0] * ic - bf_lo(v.x), s[1] * ic - bf_hi(v.x)); o.y = cvt_pk_bf16(s[2] * ic - bf_lo(v.y), s[3] * ic - bf_hi(v.y));
;                 o.z = cvt_pk_bf16(s[4] * ic - bf_lo(v.z), s[5] * ic - bf_hi(v.z)); o.w = cvt_pk_bf16(s[6] * ic - bf_lo(v.w), s[7] * ic - bf_hi(v.w));
;                 *(u32x4*)(pg + (size_t)row * DE + col) = o; }
	v_lshlrev_b32_e32 v152, 16, v108
	v_and_b32_e32 v153, 0xffff0000, v108
	v_lshlrev_b32_e32 v154, 16, v100
	v_and_b32_e32 v155, 0xffff0000, v100
	v_lshlrev_b32_e32 v156, 16, v109
	v_and_b32_e32 v157, 0xffff0000, v109
	v_lshlrev_b32_e32 v158, 16, v101
	v_and_b32_e32 v159, 0xffff0000, v101
	v_lshlrev_b32_e32 v160, 16, v110
	v_and_b32_e32 v161, 0xffff0000, v110
	v_lshlrev_b32_e32 v162, 16, v102
	v_and_b32_e32 v163, 0xffff0000, v102
	v_lshlrev_b32_e32 v164, 16, v111
	v_and_b32_e32 v165, 0xffff0000, v111
	v_lshlrev_b32_e32 v166, 16, v103
	v_and_b32_e32 v167, 0xffff0000, v103
	v_pk_add_f32 v[154:155], v[152:153], v[154:155] neg_lo:[0,1] neg_hi:[0,1]
	v_pk_add_f32 v[158:159], v[156:157], v[158:159] neg_lo:[0,1] neg_hi:[0,1]
	v_pk_add_f32 v[162:163], v[160:161], v[162:163] neg_lo:[0,1] neg_hi:[0,1]
	v_pk_add_f32 v[166:167], v[164:165], v[166:167] neg_lo:[0,1] neg_hi:[0,1]
	v_pk_add_f32 v[140:141], v[140:141], v[154:155]
	v_pk_add_f32 v[142:143], v[142:143], v[158:159]
	v_pk_add_f32 v[144:145], v[144:145], v[162:163]
	v_pk_add_f32 v[146:147], v[146:147], v[166:167]
	v_fma_f32 v154, s43, v140, -v152
	v_fma_f32 v155, s43, v141, -v153
	v_fma_f32 v158, s43, v142, -v156
	v_fma_f32 v159, s43, v143, -v157
	v_fma_f32 v162, s43, v144, -v160
	v_fma_f32 v163, s43, v145, -v161
	v_fma_f32 v166, s43, v146, -v164
	v_fma_f32 v167, s43, v147, -v165
	v_cvt_pk_bf16_f32 v148, v154, v155
	v_cvt_pk_bf16_f32 v149, v158, v159
	v_cvt_pk_bf16_f32 v150, v162, v163
	v_cvt_pk_bf16_f32 v151, v166, v167
	global_store_dwordx4 v3, v[148:151], s[10:11]
	v_add_u32_e32 v3, 0x2000, v3
	s_waitcnt vmcnt(31)
	v_lshlrev_b32_e32 v152, 16, v112
	v_and_b32_e32 v153, 0xffff0000, v112
	v_lshlrev_b32_e32 v154, 16, v104
	v_and_b32_e32 v155, 0xffff0000, v104
	v_lshlrev_b32_e32 v156, 16, v113
	v_and_b32_e32 v157, 0xffff0000, v113
	v_lshlrev_b32_e32 v158, 16, v105
	v_and_b32_e32 v159, 0xffff0000, v105
	v_lshlrev_b32_e32 v160, 16, v114
	v_and_b32_e32 v161, 0xffff0000, v114
	v_lshlrev_b32_e32 v162, 16, v106
	v_and_b32_e32 v163, 0xffff0000, v106
	v_lshlrev_b32_e32 v164, 16, v115
	v_and_b32_e32 v165, 0xffff0000, v115
	v_lshlrev_b32_e32 v166, 16, v107
	v_and_b32_e32 v167, 0xffff0000, v107
	v_pk_add_f32 v[154:155], v[152:153], v[154:155] neg_lo:[0,1] neg_hi:[0,1]
	v_pk_add_f32 v[158:159], v[156:157], v[158:159] neg_lo:[0,1] neg_hi:[0,1]
	v_pk_add_f32 v[162:163], v[160:161], v[162:163] neg_lo:[0,1] neg_hi:[0,1]
	v_pk_add_f32 v[166:167], v[164:165], v[166:167] neg_lo:[0,1] neg_hi:[0,1]
	v_pk_add_f32 v[140:141], v[140:141], v[154:155]
	v_pk_add_f32 v[142:143], v[142:143], v[158:159]
	v_pk_add_f32 v[144:145], v[144:145], v[162:163]
	v_pk_add_f32 v[146:147], v[146:147], v[166:167]
	v_fma_f32 v154, s43, v140, -v152
	v_fma_f32 v155, s43, v141, -v153
	v_fma_f32 v158, s43, v142, -v156
	v_fma_f32 v159, s43, v143, -v157
	v_fma_f32 v162, s43, v144, -v160
	v_fma_f32 v163, s43, v145, -v161
	v_fma_f32 v166, s43, v146, -v164
	v_fma_f32 v167, s43, v147, -v165
	v_cvt_pk_bf16_f32 v148, v154, v155
	v_cvt_pk_bf16_f32 v149, v158, v159
	v_cvt_pk_bf16_f32 v150, v162, v163
	v_cvt_pk_bf16_f32 v151, v166, v167
	global_store_dwordx4 v3, v[148:151], s[10:11]
	v_add_u32_e32 v3, 0x2000, v3
	s_waitcnt vmcnt(31)
	v_lshlrev_b32_e32 v152, 16, v116
	v_and_b32_e32 v153, 0xffff0000, v116
	v_lshlrev_b32_e32 v154, 16, v108
	v_and_b32_e32 v155, 0xffff0000, v108
	v_lshlrev_b32_e32 v156, 16, v117
	v_and_b32_e32 v157, 0xffff0000, v117
	v_lshlrev_b32_e32 v158, 16, v109
	v_and_b32_e32 v159, 0xffff0000, v109
	v_lshlrev_b32_e32 v160, 16, v118
	v_and_b32_e32 v161, 0xffff0000, v118
	v_lshlrev_b32_e32 v162, 16, v110
	v_and_b32_e32 v163, 0xffff0000, v110
	v_lshlrev_b32_e32 v164, 16, v119
	v_and_b32_e32 v165, 0xffff0000, v119
	v_lshlrev_b32_e32 v166, 16, v111
	v_and_b32_e32 v167, 0xffff0000, v111
	v_pk_add_f32 v[154:155], v[152:153], v[154:155] neg_lo:[0,1] neg_hi:[0,1]
	v_pk_add_f32 v[158:159], v[156:157], v[158:159] neg_lo:[0,1] neg_hi:[0,1]
	v_pk_add_f32 v[162:163], v[160:161], v[162:163] neg_lo:[0,1] neg_hi:[0,1]
	v_pk_add_f32 v[166:167], v[164:165], v[166:167] neg_lo:[0,1] neg_hi:[0,1]
	v_pk_add_f32 v[140:141], v[140:141], v[154:155]
	v_pk_add_f32 v[142:143], v[142:143], v[158:159]
	v_pk_add_f32 v[144:145], v[144:145], v[162:163]
	v_pk_add_f32 v[146:147], v[146:147], v[166:167]
	v_fma_f32 v154, s43, v140, -v152
	v_fma_f32 v155, s43, v141, -v153
	v_fma_f32 v158, s43, v142, -v156
	v_fma_f32 v159, s43, v143, -v157
	v_fma_f32 v162, s43, v144, -v160
	v_fma_f32 v163, s43, v145, -v161
	v_fma_f32 v166, s43, v146, -v164
	v_fma_f32 v167, s43, v147, -v165
	v_cvt_pk_bf16_f32 v148, v154, v155
	v_cvt_pk_bf16_f32 v149, v158, v159
	v_cvt_pk_bf16_f32 v150, v162, v163
	v_cvt_pk_bf16_f32 v151, v166, v167
	global_store_dwordx4 v3, v[148:151], s[10:11]
	v_add_u32_e32 v3, 0x2000, v3
	s_waitcnt vmcnt(31)
	v_lshlrev_b32_e32 v152, 16, v120
	v_and_b32_e32 v153, 0xffff0000, v120
	v_lshlrev_b32_e32 v154, 16, v112
	v_and_b32_e32 v155, 0xffff0000, v112
	v_lshlrev_b32_e32 v156, 16, v121
	v_and_b32_e32 v157, 0xffff0000, v121
	v_lshlrev_b32_e32 v158, 16, v113
	v_and_b32_e32 v159, 0xffff0000, v113
	v_lshlrev_b32_e32 v160, 16, v122
	v_and_b32_e32 v161, 0xffff0000, v122
	v_lshlrev_b32_e32 v162, 16, v114
	v_and_b32_e32 v163, 0xffff0000, v114
	v_lshlrev_b32_e32 v164, 16, v123
	v_and_b32_e32 v165, 0xffff0000, v123
	v_lshlrev_b32_e32 v166, 16, v115
	v_and_b32_e32 v167, 0xffff0000, v115
	v_pk_add_f32 v[154:155], v[152:153], v[154:155] neg_lo:[0,1] neg_hi:[0,1]
	v_pk_add_f32 v[158:159], v[156:157], v[158:159] neg_lo:[0,1] neg_hi:[0,1]
	v_pk_add_f32 v[162:163], v[160:161], v[162:163] neg_lo:[0,1] neg_hi:[0,1]
	v_pk_add_f32 v[166:167], v[164:165], v[166:167] neg_lo:[0,1] neg_hi:[0,1]
	v_pk_add_f32 v[140:141], v[140:141], v[154:155]
	v_pk_add_f32 v[142:143], v[142:143], v[158:159]
	v_pk_add_f32 v[144:145], v[144:145], v[162:163]
	v_pk_add_f32 v[146:147], v[146:147], v[166:167]
	v_fma_f32 v154, s43, v140, -v152
	v_fma_f32 v155, s43, v141, -v153
	v_fma_f32 v158, s43, v142, -v156
	v_fma_f32 v159, s43, v143, -v157
	v_fma_f32 v162, s43, v144, -v160
	v_fma_f32 v163, s43, v145, -v161
	v_fma_f32 v166, s43, v146, -v164
	v_fma_f32 v167, s43, v147, -v165
	v_cvt_pk_bf16_f32 v148, v154, v155
	v_cvt_pk_bf16_f32 v149, v158, v159
	v_cvt_pk_bf16_f32 v150, v162, v163
	v_cvt_pk_bf16_f32 v151, v166, v167
	global_store_dwordx4 v3, v[148:151], s[10:11]
	v_add_u32_e32 v3, 0x2000, v3
	s_waitcnt vmcnt(31)
; __device__ __forceinline__ unsigned cvt_pk_bf16(float lo, float hi) { unsigned r; asm volatile("v_cvt_pk_bf16_f32 %0, %1, %2" : "=v"(r) : "v"(lo), "v"(hi)); return r; }
; __device__ __forceinline__ float bf_lo(unsigned w) { return __uint_as_float(w << 16); }
; __device__ __forceinline__ float bf_hi(unsigned w) { return __uint_as_float(w & 0xffff0000u); }
; __device__ void phase_pool() {
;     ...
;         for (int r0 = 0; r0 < RB; r0 += 8) {
;             u32x4 vv[8], ov[8];
; #pragma unroll
;             for (int k = 0; k < 8; ++k) { const int row = row0 + r0 + k, tl = tl0 + r0 + k;
;                 vv[k] = *(const u32x4*)(uz + (size_t)row * DE2 + col);
;                 ov[k] = (tl >= w) ? *(const u32x4*)(uz + (size_t)(row - w) * DE2 + col) : (u32x4){0u, 0u, 0u, 0u}; }
; #pragma unroll
;             for (int k = 0; k < 8; ++k) { const int row = row0 + r0 + k, tl = tl0 + r0 + k; const u32x4 v = vv[k], o2 = ov[k];
;                 s[0] += bf_lo(v.x) - bf_lo(o2.x); s[1] += bf_hi(v.x) - bf_hi(o2.x); s[2] += bf_lo(v.y) - bf_lo(o2.y); s[3] += bf_hi(v.y) - bf_hi(o2.y);
;                 s[4] += bf_lo(v.z) - bf_lo(o2.z); s[5] += bf_hi(v.z) - bf_hi(o2.z); s[6] += bf_lo(v.w) - bf_lo(o2.w); s[7] += bf_hi(v.w) - bf_hi(o2.w);
;                 const float ic = 1.0f / (float)((tl + 1 < w) ? tl + 1 : w);
;                 u32x4 o;
;                 o.x = cvt_pk_bf16(s[0] * ic - bf_lo(v.x), s[1] * ic - bf_hi(v.x)); o.y = cvt_pk_bf16(s[2] * ic - bf_lo(v.y), s[3] * ic - bf_hi(v.y));
;                 o.z = cvt_pk_bf16(s[4] * ic - bf_lo(v.z), s[5] * ic - bf_hi(v.z)); o.w = cvt_pk_bf16(s[6] * ic - bf_lo(v.w), s[7] * ic - bf_hi(v.w));
;                 *(u32x4*)(pg + (size_t)row * DE + col) = o; }
;         }
;     }
	v_lshlrev_b32_e32 v152, 16, v124
	v_and_b32_e32 v153, 0xffff0000, v124
	v_lshlrev_b32_e32 v154, 16, v116
	v_and_b32_e32 v155, 0xffff0000, v116
	v_lshlrev_b32_e32 v156, 16, v125
	v_and_b32_e32 v157, 0xffff0000, v125
	v_lshlrev_b32_e32 v158, 16, v117
	v_and_b32_e32 v159, 0xffff0000, v117
	v_lshlrev_b32_e32 v160, 16, v126
	v_and_b32_e32 v161, 0xffff0000, v126
	v_lshlrev_b32_e32 v162, 16, v118
	v_and_b32_e32 v163, 0xffff0000, v118
	v_lshlrev_b32_e32 v164, 16, v127
	v_and_b32_e32 v165, 0xffff0000, v127
	v_lshlrev_b32_e32 v166, 16, v119
	v_and_b32_e32 v167, 0xffff0000, v119
	v_pk_add_f32 v[154:155], v[152:153], v[154:155] neg_lo:[0,1] neg_hi:[0,1]
	v_pk_add_f32 v[158:159], v[156:157], v[158:159] neg_lo:[0,1] neg_hi:[0,1]
	v_pk_add_f32 v[162:163], v[160:161], v[162:163] neg_lo:[0,1] neg_hi:[0,1]
	v_pk_add_f32 v[166:167], v[164:165], v[166:167] neg_lo:[0,1] neg_hi:[0,1]
	v_pk_add_f32 v[140:141], v[140:141], v[154:155]
	v_pk_add_f32 v[142:143], v[142:143], v[158:159]
	v_pk_add_f32 v[144:145], v[144:145], v[162:163]
	v_pk_add_f32 v[146:147], v[146:147], v[166:167]
	v_fma_f32 v154, s43, v140, -v152
	v_fma_f32 v155, s43, v141, -v153
	v_fma_f32 v158, s43, v142, -v156
	v_fma_f32 v159, s43, v143, -v157
	v_fma_f32 v162, s43, v144, -v160
	v_fma_f32 v163, s43, v145, -v161
	v_fma_f32 v166, s43, v146, -v164
	v_fma_f32 v167, s43, v147, -v165
	v_cvt_pk_bf16_f32 v148, v154, v155
	v_cvt_pk_bf16_f32 v149, v158, v159
	v_cvt_pk_bf16_f32 v150, v162, v163
	v_cvt_pk_bf16_f32 v151, v166, v167
	global_store_dwordx4 v3, v[148:151], s[10:11]
	v_add_u32_e32 v3, 0x2000, v3
	s_waitcnt vmcnt(31)
	v_lshlrev_b32_e32 v152, 16, v128
	v_and_b32_e32 v153, 0xffff0000, v128
	v_lshlrev_b32_e32 v154, 16, v120
	v_and_b32_e32 v155, 0xffff0000, v120
	v_lshlrev_b32_e32 v156, 16, v129
	v_and_b32_e32 v157, 0xffff0000, v129
	v_lshlrev_b32_e32 v158, 16, v121
	v_and_b32_e32 v159, 0xffff0000, v121
	v_lshlrev_b32_e32 v160, 16, v130
	v_and_b32_e32 v161, 0xffff0000, v130
	v_lshlrev_b32_e32 v162, 16, v122
	v_and_b32_e32 v163, 0xffff0000, v122
	v_lshlrev_b32_e32 v164, 16, v131
	v_and_b32_e32 v165, 0xffff0000, v131
	v_lshlrev_b32_e32 v166, 16, v123
	v_and_b32_e32 v167, 0xffff0000, v123
	v_pk_add_f32 v[154:155], v[152:153], v[154:155] neg_lo:[0,1] neg_hi:[0,1]
	v_pk_add_f32 v[158:159], v[156:157], v[158:159] neg_lo:[0,1] neg_hi:[0,1]
	v_pk_add_f32 v[162:163], v[160:161], v[162:163] neg_lo:[0,1] neg_hi:[0,1]
	v_pk_add_f32 v[166:167], v[164:165], v[166:167] neg_lo:[0,1] neg_hi:[0,1]
	v_pk_add_f32 v[140:141], v[140:141], v[154:155]
	v_pk_add_f32 v[142:143], v[142:143], v[158:159]
	v_pk_add_f32 v[144:145], v[144:145], v[162:163]
	v_pk_add_f32 v[146:147], v[146:147], v[166:167]
	v_fma_f32 v154, s43, v140, -v152
	v_fma_f32 v155, s43, v141, -v153
	v_fma_f32 v158, s43, v142, -v156
	v_fma_f32 v159, s43, v143, -v157
	v_fma_f32 v162, s43, v144, -v160
	v_fma_f32 v163, s43, v145, -v161
	v_fma_f32 v166, s43, v146, -v164
	v_fma_f32 v167, s43, v147, -v165
	v_cvt_pk_bf16_f32 v148, v154, v155
	v_cvt_pk_bf16_f32 v149, v158, v159
	v_cvt_pk_bf16_f32 v150, v162, v163
	v_cvt_pk_bf16_f32 v151, v166, v167
	global_store_dwordx4 v3, v[148:151], s[10:11]
	v_add_u32_e32 v3, 0x2000, v3
	s_waitcnt vmcnt(31)
	v_lshlrev_b32_e32 v152, 16, v132
	v_and_b32_e32 v153, 0xffff0000, v132
	v_lshlrev_b32_e32 v154, 16, v124
	v_and_b32_e32 v155, 0xffff0000, v124
	v_lshlrev_b32_e32 v156, 16, v133
	v_and_b32_e32 v157, 0xffff0000, v133
	v_lshlrev_b32_e32 v158, 16, v125
	v_and_b32_e32 v159, 0xffff0000, v125
	v_lshlrev_b32_e32 v160, 16, v134
	v_and_b32_e32 v161, 0xffff0000, v134
	v_lshlrev_b32_e32 v162, 16, v126
	v_and_b32_e32 v163, 0xffff0000, v126
	v_lshlrev_b32_e32 v164, 16, v135
	v_and_b32_e32 v165, 0xffff0000, v135
	v_lshlrev_b32_e32 v166, 16, v127
	v_and_b32_e32 v167, 0xffff0000, v127
	v_pk_add_f32 v[154:155], v[152:153], v[154:155] neg_lo:[0,1] neg_hi:[0,1]
	v_pk_add_f32 v[158:159], v[156:157], v[158:159] neg_lo:[0,1] neg_hi:[0,1]
	v_pk_add_f32 v[162:163], v[160:161], v[162:163] neg_lo:[0,1] neg_hi:[0,1]
	v_pk_add_f32 v[166:167], v[164:165], v[166:167] neg_lo:[0,1] neg_hi:[0,1]
	v_pk_add_f32 v[140:141], v[140:141], v[154:155]
	v_pk_add_f32 v[142:143], v[142:143], v[158:159]
	v_pk_add_f32 v[144:145], v[144:145], v[162:163]
	v_pk_add_f32 v[146:147], v[146:147], v[166:167]
	v_fma_f32 v154, s43, v140, -v152
	v_fma_f32 v155, s43, v141, -v153
	v_fma_f32 v158, s43, v142, -v156
	v_fma_f32 v159, s43, v143, -v157
	v_fma_f32 v162, s43, v144, -v160
	v_fma_f32 v163, s43, v145, -v161
	v_fma_f32 v166, s43, v146, -v164
	v_fma_f32 v167, s43, v147, -v165
	v_cvt_pk_bf16_f32 v148, v154, v155
	v_cvt_pk_bf16_f32 v149, v158, v159
	v_cvt_pk_bf16_f32 v150, v162, v163
	v_cvt_pk_bf16_f32 v151, v166, v167
	global_store_dwordx4 v3, v[148:151], s[10:11]
	v_add_u32_e32 v3, 0x2000, v3
	s_waitcnt vmcnt(31)
	v_lshlrev_b32_e32 v152, 16, v136
	v_and_b32_e32 v153, 0xffff0000, v136
	v_lshlrev_b32_e32 v154, 16, v128
	v_and_b32_e32 v155, 0xffff0000, v128
	v_lshlrev_b32_e32 v156, 16, v137
	v_and_b32_e32 v157, 0xffff0000, v137
	v_lshlrev_b32_e32 v158, 16, v129
	v_and_b32_e32 v159, 0xffff0000, v129
	v_lshlrev_b32_e32 v160, 16, v138
	v_and_b32_e32 v161, 0xffff0000, v138
	v_lshlrev_b32_e32 v162, 16, v130
	v_and_b32_e32 v163, 0xffff0000, v130
	v_lshlrev_b32_e32 v164, 16, v139
	v_and_b32_e32 v165, 0xffff0000, v139
	v_lshlrev_b32_e32 v166, 16, v131
	v_and_b32_e32 v167, 0xffff0000, v131
	v_pk_add_f32 v[154:155], v[152:153], v[154:155] neg_lo:[0,1] neg_hi:[0,1]
	v_pk_add_f32 v[158:159], v[156:157], v[158:159] neg_lo:[0,1] neg_hi:[0,1]
	v_pk_add_f32 v[162:163], v[160:161], v[162:163] neg_lo:[0,1] neg_hi:[0,1]
	v_pk_add_f32 v[166:167], v[164:165], v[166:167] neg_lo:[0,1] neg_hi:[0,1]
	v_pk_add_f32 v[140:141], v[140:141], v[154:155]
	v_pk_add_f32 v[142:143], v[142:143], v[158:159]
	v_pk_add_f32 v[144:145], v[144:145], v[162:163]
	v_pk_add_f32 v[146:147], v[146:147], v[166:167]
	v_fma_f32 v154, s43, v140, -v152
	v_fma_f32 v155, s43, v141, -v153
	v_fma_f32 v158, s43, v142, -v156
	v_fma_f32 v159, s43, v143, -v157
	v_fma_f32 v162, s43, v144, -v160
	v_fma_f32 v163, s43, v145, -v161
	v_fma_f32 v166, s43, v146, -v164
	v_fma_f32 v167, s43, v147, -v165
	v_cvt_pk_bf16_f32 v148, v154, v155
	v_cvt_pk_bf16_f32 v149, v158, v159
	v_cvt_pk_bf16_f32 v150, v162, v163
	v_cvt_pk_bf16_f32 v151, v166, v167
	global_store_dwordx4 v3, v[148:151], s[10:11]
	s_branch .LBB0_441
; __device__ __forceinline__ float bf_lo(unsigned w) { return __uint_as_float(w << 16); }
; __device__ __forceinline__ float bf_hi(unsigned w) { return __uint_as_float(w & 0xffff0000u); }
; __device__ void phase_pool() {
;     ...
;         const int c8 = idx % (DE / 8), rb = idx / (DE / 8), col = c8 * 8, g = col >> 10, w = 2 << g, row0 = rb * RB, tl0 = row0 & (SEQ - 1);
;         float s[8];
; #pragma unroll
;         for (int i = 0; i < 8; ++i) s[i] = 0.f;
;         const int nh = (tl0 < w) ? tl0 : w;
;         { u32x4 hv[16];
; #pragma unroll
;           for (int k = 1; k <= 16; ++k) hv[k - 1] = (k <= nh) ? *(const u32x4*)(uz + (size_t)(row0 - k) * DE2 + col) : (u32x4){0u, 0u, 0u, 0u};
; #pragma unroll
;           for (int k = 0; k < 16; ++k) { const u32x4 v = hv[k];
;             s[0] += bf_lo(v.x); s[1] += bf_hi(v.x); s[2] += bf_lo(v.y); s[3] += bf_hi(v.y); s[4] += bf_lo(v.z); s[5] += bf_hi(v.z); s[6] += bf_lo(v.w); s[7] += bf_hi(v.w); } }
.Lpool_w4:
	s_cmp_eq_u32 s16, 0
	s_cbranch_scc1 .Lpool_w4_nohist
	s_sub_u32 s0, s15, 4
	s_lshl_b32 s0, s0, 14
	s_add_u32 s8, s4, s0
	s_addc_u32 s9, s5, 0
	global_load_dwordx4 v[4:7], v2, s[8:9]
	v_add_u32_e32 v2, 0x4000, v2
	global_load_dwordx4 v[8:11], v2, s[8:9]
	v_add_u32_e32 v2, 0x4000, v2
	global_load_dwordx4 v[12:15], v2, s[8:9]
	v_add_u32_e32 v2, 0x4000, v2
	global_load_dwordx4 v[16:19], v2, s[8:9]
	v_add_u32_e32 v2, 0x4000, v2
	s_branch .Lpool_w4_main
.Lpool_w4_nohist:
	v_mov_b32_e32 v4, 0
	v_mov_b32_e32 v5, 0
	v_mov_b32_e32 v6, 0
	v_mov_b32_e32 v7, 0
	v_mov_b32_e32 v8, 0
	v_mov_b32_e32 v9, 0
	v_mov_b32_e32 v10, 0
	v_mov_b32_e32 v11, 0
	v_mov_b32_e32 v12, 0
	v_mov_b32_e32 v13, 0
	v_mov_b32_e32 v14, 0
	v_mov_b32_e32 v15, 0
	v_mov_b32_e32 v16, 0
	v_mov_b32_e32 v17, 0
	v_mov_b32_e32 v18, 0
	v_mov_b32_e32 v19, 0
	s_lshl_b32 s0, s15, 14
	s_add_u32 s8, s4, s0
	s_addc_u32 s9, s5, 0
.Lpool_w4_main:
	global_load_dwordx4 v[20:23], v2, s[8:9]
	v_add_u32_e32 v2, 0x4000, v2
	global_load_dwordx4 v[24:27], v2, s[8:9]
	v_add_u32_e32 v2, 0x4000, v2
	global_load_dwordx4 v[28:31], v2, s[8:9]
	v_add_u32_e32 v2, 0x4000, v2
	global_load_dwordx4 v[32:35], v2, s[8:9]
	v_add_u32_e32 v2, 0x4000, v2
	global_load_dwordx4 v[36:39], v2, s[8:9]
	v_add_u32_e32 v2, 0x4000, v2
	global_load_dwordx4 v[40:43], v2, s[8:9]
	v_add_u32_e32 v2, 0x4000, v2
	global_load_dwordx4 v[44:47], v2, s[8:9]
	v_add_u32_e32 v2, 0x4000, v2
	global_load_dwordx4 v[48:51], v2, s[8:9]
	v_add_u32_e32 v2, 0x4000, v2
	global_load_dwordx4 v[52:55], v2, s[8:9]
	v_add_u32_e32 v2, 0x4000, v2
	global_load_dwordx4 v[56:59], v2, s[8:9]
	v_add_u32_e32 v2, 0x4000, v2
	global_load_dwordx4 v[60:63], v2, s[8:9]
	v_add_u32_e32 v2, 0x4000, v2
	global_load_dwordx4 v[64:67], v2, s[8:9]
	v_add_u32_e32 v2, 0x4000, v2
	global_load_dwordx4 v[68:71], v2, s[8:9]
	v_add_u32_e32 v2, 0x4000, v2
	global_load_dwordx4 v[72:75], v2, s[8:9]
	v_add_u32_e32 v2, 0x4000, v2
	global_load_dwordx4 v[76:79], v2, s[8:9]
	v_add_u32_e32 v2, 0x4000, v2
	global_load_dwordx4 v[80:83], v2, s[8:9]
	v_add_u32_e32 v2, 0x4000, v2
	global_load_dwordx4 v[84:87], v2, s[8:9]
	v_add_u32_e32 v2, 0x4000, v2
	global_load_dwordx4 v[88:91], v2, s[8:9]
	v_add_u32_e32 v2, 0x4000, v2
	global_load_dwordx4 v[92:95], v2, s[8:9]
	v_add_u32_e32 v2, 0x4000, v2
	global_load_dwordx4 v[96:99], v2, s[8:9]
	v_add_u32_e32 v2, 0x4000, v2
	global_load_dwordx4 v[100:103], v2, s[8:9]
	v_add_u32_e32 v2, 0x4000, v2
	global_load_dwordx4 v[104:107], v2, s[8:9]
	v_add_u32_e32 v2, 0x4000, v2
	global_load_dwordx4 v[108:111], v2, s[8:9]
	v_add_u32_e32 v2, 0x4000, v2
	global_load_dwordx4 v[112:115], v2, s[8:9]
	v_add_u32_e32 v2, 0x4000, v2
	global_load_dwordx4 v[116:119], v2, s[8:9]
	v_add_u32_e32 v2, 0x4000, v2
	global_load_dwordx4 v[120:123], v2, s[8:9]
	v_add_u32_e32 v2, 0x4000, v2
	global_load_dwordx4 v[124:127], v2, s[8:9]
	v_add_u32_e32 v2, 0x4000, v2
	global_load_dwordx4 v[128:131], v2, s[8:9]
	v_add_u32_e32 v2, 0x4000, v2
	global_load_dwordx4 v[132:135], v2, s[8:9]
	v_add_u32_e32 v2, 0x4000, v2
	global_load_dwordx4 v[136:139], v2, s[8:9]
	v_add_u32_e32 v2, 0x4000, v2
	global_load_dwordx4 v[140:143], v2, s[8:9]
	v_add_u32_e32 v2, 0x4000, v2
	global_load_dwordx4 v[144:147], v2, s[8:9]
	v_mov_b32_e32 v148, 0
	v_mov_b32_e32 v149, 0
	v_mov_b32_e32 v150, 0
	v_mov_b32_e32 v151, 0
	v_mov_b32_e32 v152, 0
	v_mov_b32_e32 v153, 0
	v_mov_b32_e32 v154, 0
	v_mov_b32_e32 v155, 0
	s_mov_b32 s43, 0x3e800000
	s_cmp_eq_u32 s16, 0
	s_waitcnt vmcnt(32)
	v_lshlrev_b32_e32 v160, 16, v16
	v_and_b32_e32 v161, 0xffff0000, v16
	v_lshlrev_b32_e32 v164, 16, v17
	v_and_b32_e32 v165, 0xffff0000, v17
	v_lshlrev_b32_e32 v168, 16, v18
	v_and_b32_e32 v169, 0xffff0000, v18
	v_lshlrev_b32_e32 v172, 16, v19
	v_and_b32_e32 v173, 0xffff0000, v19
	v_pk_add_f32 v[148:149], v[148:149], v[160:161]
	v_pk_add_f32 v[150:151], v[150:151], v[164:165]
	v_pk_add_f32 v[152:153], v[152:153], v[168:169]
	v_pk_add_f32 v[154:155], v[154:155], v[172:173]
	v_lshlrev_b32_e32 v160, 16, v12
	v_and_b32_e32 v161, 0xffff0000, v12
	v_lshlrev_b32_e32 v164, 16, v13
	v_and_b32_e32 v165, 0xffff0000, v13
	v_lshlrev_b32_e32 v168, 16, v14
	v_and_b32_e32 v169, 0xffff0000, v14
	v_lshlrev_b32_e32 v172, 16, v15
	v_and_b32_e32 v173, 0xffff0000, v15
	v_pk_add_f32 v[148:149], v[148:149], v[160:161]
	v_pk_add_f32 v[150:151], v[150:151], v[164:165]
	v_pk_add_f32 v[152:153], v[152:153], v[168:169]
	v_pk_add_f32 v[154:155], v[154:155], v[172:173]
	v_lshlrev_b32_e32 v160, 16, v8
	v_and_b32_e32 v161, 0xffff0000, v8
	v_lshlrev_b32_e32 v164, 16, v9
	v_and_b32_e32 v165, 0xffff0000, v9
	v_lshlrev_b32_e32 v168, 16, v10
	v_and_b32_e32 v169, 0xffff0000, v10
	v_lshlrev_b32_e32 v172, 16, v11
	v_and_b32_e32 v173, 0xffff0000, v11
	v_pk_add_f32 v[148:149], v[148:149], v[160:161]
	v_pk_add_f32 v[150:151], v[150:151], v[164:165]
	v_pk_add_f32 v[152:153], v[152:153], v[168:169]
	v_pk_add_f32 v[154:155], v[154:155], v[172:173]
	v_lshlrev_b32_e32 v160, 16, v4
	v_and_b32_e32 v161, 0xffff0000, v4
	v_lshlrev_b32_e32 v164, 16, v5
	v_and_b32_e32 v165, 0xffff0000, v5
	v_lshlrev_b32_e32 v168, 16, v6
	v_and_b32_e32 v169, 0xffff0000, v6
	v_lshlrev_b32_e32 v172, 16, v7
	v_and_b32_e32 v173, 0xffff0000, v7
	v_pk_add_f32 v[148:149], v[148:149], v[160:161]
	v_pk_add_f32 v[150:151], v[150:151], v[164:165]
	v_pk_add_f32 v[152:153], v[152:153], v[168:169]
	v_pk_add_f32 v[154:155], v[154:155], v[172:173]
	s_waitcnt vmcnt(31)
; __device__ __forceinline__ unsigned cvt_pk_bf16(float lo, float hi) { unsigned r; asm volatile("v_cvt_pk_bf16_f32 %0, %1, %2" : "=v"(r) : "v"(lo), "v"(hi)); return r; }
; __device__ __forceinline__ float bf_lo(unsigned w) { return __uint_as_float(w << 16); }
; __device__ __forceinline__ float bf_hi(unsigned w) { return __uint_as_float(w & 0xffff0000u); }
; __device__ void phase_pool() {
;     ...
;         for (int r0 = 0; r0 < RB; r0 += 8) {
;             u32x4 vv[8], ov[8];
; #pragma unroll
;             for (int k = 0; k < 8; ++k) { const int row = row0 + r0 + k, tl = tl0 + r0 + k;
;                 vv[k] = *(const u32x4*)(uz + (size_t)row * DE2 + col);
;                 ov[k] = (tl >= w) ? *(const u32x4*)(uz + (size_t)(row - w) * DE2 + col) : (u32x4){0u, 0u, 0u, 0u}; }
; #pragma unroll
;             for (int k = 0; k < 8; ++k) { const int row = row0 + r0 + k, tl = tl0 + r0 + k; const u32x4 v = vv[k], o2 = ov[k];
;                 s[0] += bf_lo(v.x) - bf_lo(o2.x); s[1] += bf_hi(v.x) - bf_hi(o2.x); s[2] += bf_lo(v.y) - bf_lo(o2.y); s[3] += bf_hi(v.y) - bf_hi(o2.y);
;                 s[4] += bf_lo(v.z) - bf_lo(o2.z); s[5] += bf_hi(v.z) - bf_hi(o2.z); s[6] += bf_lo(v.w) - bf_lo(o2.w); s[7] += bf_hi(v.w) - bf_hi(o2.w);
;                 const float ic = 1.0f / (float)((tl + 1 < w) ? tl + 1 : w);
;                 u32x4 o;
;                 o.x = cvt_pk_bf16(s[0] * ic - bf_lo(v.x), s[1] * ic - bf_hi(v.x)); o.y = cvt_pk_bf16(s[2] * ic - bf_lo(v.y), s[3] * ic - bf_hi(v.y));
;                 o.z = cvt_pk_bf16(s[4] * ic - bf_lo(v.z), s[5] * ic - bf_hi(v.z)); o.w = cvt_pk_bf16(s[6] * ic - bf_lo(v.w), s[7] * ic - bf_hi(v.w));
;                 *(u32x4*)(pg + (size_t)row * DE + col) = o; }
	s_cselect_b32 s42, 0x3f800000, s43
	v_lshlrev_b32_e32 v160, 16, v20
	v_and_b32_e32 v161, 0xffff0000, v20
	v_lshlrev_b32_e32 v162, 16, v4
	v_and_b32_e32 v163, 0xffff0000, v4
	v_lshlrev_b32_e32 v164, 16, v21
	v_and_b32_e32 v165, 0xffff0000, v21
	v_lshlrev_b32_e32 v166, 16, v5
	v_and_b32_e32 v167, 0xffff0000, v5
	v_lshlrev_b32_e32 v168, 16, v22
	v_and_b32_e32 v169, 0xffff0000, v22
	v_lshlrev_b32_e32 v170, 16, v6
	v_and_b32_e32 v171, 0xffff0000, v6
	v_lshlrev_b32_e32 v172, 16, v23
	v_and_b32_e32 v173, 0xffff0000, v23
	v_lshlrev_b32_e32 v174, 16, v7
	v_and_b32_e32 v175, 0xffff0000, v7
	v_pk_add_f32 v[162:163], v[160:161], v[162:163] neg_lo:[0,1] neg_hi:[0,1]
	v_pk_add_f32 v[166:167], v[164:165], v[166:167] neg_lo:[0,1] neg_hi:[0,1]
	v_pk_add_f32 v[170:171], v[168:169], v[170:171] neg_lo:[0,1] neg_hi:[0,1]
	v_pk_add_f32 v[174:175], v[172:173], v[174:175] neg_lo:[0,1] neg_hi:[0,1]
	v_pk_add_f32 v[148:149], v[148:149], v[162:163]
	v_pk_add_f32 v[150:151], v[150:151], v[166:167]
	v_pk_add_f32 v[152:153], v[152:153], v[170:171]
	v_pk_add_f32 v[154:155], v[154:155], v[174:175]
	v_fma_f32 v162, s42, v148, -v160
	v_fma_f32 v163, s42, v149, -v161
	v_fma_f32 v166, s42, v150, -v164
	v_fma_f32 v167, s42, v151, -v165
	v_fma_f32 v170, s42, v152, -v168
	v_fma_f32 v171, s42, v153, -v169
	v_fma_f32 v174, s42, v154, -v172
	v_fma_f32 v175, s42, v155, -v173
	v_cvt_pk_bf16_f32 v156, v162, v163
	v_cvt_pk_bf16_f32 v157, v166, v167
	v_cvt_pk_bf16_f32 v158, v170, v171
	v_cvt_pk_bf16_f32 v159, v174, v175
	global_store_dwordx4 v3, v[156:159], s[10:11]
	v_add_u32_e32 v3, 0x2000, v3
	s_waitcnt vmcnt(31)
	s_cselect_b32 s42, 0x3f000000, s43
	v_lshlrev_b32_e32 v160, 16, v24
	v_and_b32_e32 v161, 0xffff0000, v24
	v_lshlrev_b32_e32 v162, 16, v8
	v_and_b32_e32 v163, 0xffff0000, v8
	v_lshlrev_b32_e32 v164, 16, v25
	v_and_b32_e32 v165, 0xffff0000, v25
	v_lshlrev_b32_e32 v166, 16, v9
	v_and_b32_e32 v167, 0xffff0000, v9
	v_lshlrev_b32_e32 v168, 16, v26
	v_and_b32_e32 v169, 0xffff0000, v26
	v_lshlrev_b32_e32 v170, 16, v10
	v_and_b32_e32 v171, 0xffff0000, v10
	v_lshlrev_b32_e32 v172, 16, v27
	v_and_b32_e32 v173, 0xffff0000, v27
	v_lshlrev_b32_e32 v174, 16, v11
	v_and_b32_e32 v175, 0xffff0000, v11
	v_pk_add_f32 v[162:163], v[160:161], v[162:163] neg_lo:[0,1] neg_hi:[0,1]
	v_pk_add_f32 v[166:167], v[164:165], v[166:167] neg_lo:[0,1] neg_hi:[0,1]
	v_pk_add_f32 v[170:171], v[168:169], v[170:171] neg_lo:[0,1] neg_hi:[0,1]
	v_pk_add_f32 v[174:175], v[172:173], v[174:175] neg_lo:[0,1] neg_hi:[0,1]
	v_pk_add_f32 v[148:149], v[148:149], v[162:163]
	v_pk_add_f32 v[150:151], v[150:151], v[166:167]
	v_pk_add_f32 v[152:153], v[152:153], v[170:171]
	v_pk_add_f32 v[154:155], v[154:155], v[174:175]
	v_fma_f32 v162, s42, v148, -v160
	v_fma_f32 v163, s42, v149, -v161
	v_fma_f32 v166, s42, v150, -v164
	v_fma_f32 v167, s42, v151, -v165
	v_fma_f32 v170, s42, v152, -v168
	v_fma_f32 v171, s42, v153, -v169
	v_fma_f32 v174, s42, v154, -v172
	v_fma_f32 v175, s42, v155, -v173
	v_cvt_pk_bf16_f32 v156, v162, v163
	v_cvt_pk_bf16_f32 v157, v166, v167
	v_cvt_pk_bf16_f32 v158, v170, v171
	v_cvt_pk_bf16_f32 v159, v174, v175
	global_store_dwordx4 v3, v[156:159], s[10:11]
	v_add_u32_e32 v3, 0x2000, v3
	s_waitcnt vmcnt(31)
	s_cselect_b32 s42, 0x3eaaaaab, s43
	v_lshlrev_b32_e32 v160, 16, v28
	v_and_b32_e32 v161, 0xffff0000, v28
	v_lshlrev_b32_e32 v162, 16, v12
	v_and_b32_e32 v163, 0xffff0000, v12
	v_lshlrev_b32_e32 v164, 16, v29
	v_and_b32_e32 v165, 0xffff0000, v29
	v_lshlrev_b32_e32 v166, 16, v13
	v_and_b32_e32 v167, 0xffff0000, v13
	v_lshlrev_b32_e32 v168, 16, v30
	v_and_b32_e32 v169, 0xffff0000, v30
	v_lshlrev_b32_e32 v170, 16, v14
	v_and_b32_e32 v171, 0xffff0000, v14
	v_lshlrev_b32_e32 v172, 16, v31
	v_and_b32_e32 v173, 0xffff0000, v31
	v_lshlrev_b32_e32 v174, 16, v15
	v_and_b32_e32 v175, 0xffff0000, v15
	v_pk_add_f32 v[162:163], v[160:161], v[162:163] neg_lo:[0,1] neg_hi:[0,1]
	v_pk_add_f32 v[166:167], v[164:165], v[166:167] neg_lo:[0,1] neg_hi:[0,1]
	v_pk_add_f32 v[170:171], v[168:169], v[170:171] neg_lo:[0,1] neg_hi:[0,1]
	v_pk_add_f32 v[174:175], v[172:173], v[174:175] neg_lo:[0,1] neg_hi:[0,1]
	v_pk_add_f32 v[148:149], v[148:149], v[162:163]
	v_pk_add_f32 v[150:151], v[150:151], v[166:167]
	v_pk_add_f32 v[152:153], v[152:153], v[170:171]
	v_pk_add_f32 v[154:155], v[154:155], v[174:175]
	v_fma_f32 v162, s42, v148, -v160
	v_fma_f32 v163, s42, v149, -v161
	v_fma_f32 v166, s42, v150, -v164
	v_fma_f32 v167, s42, v151, -v165
	v_fma_f32 v170, s42, v152, -v168
	v_fma_f32 v171, s42, v153, -v169
	v_fma_f32 v174, s42, v154, -v172
	v_fma_f32 v175, s42, v155, -v173
	v_cvt_pk_bf16_f32 v156, v162, v163
	v_cvt_pk_bf16_f32 v157, v166, v167
	v_cvt_pk_bf16_f32 v158, v170, v171
	v_cvt_pk_bf16_f32 v159, v174, v175
	global_store_dwordx4 v3, v[156:159], s[10:11]
	v_add_u32_e32 v3, 0x2000, v3
	s_waitcnt vmcnt(31)
	v_lshlrev_b32_e32 v160, 16, v32
	v_and_b32_e32 v161, 0xffff0000, v32
	v_lshlrev_b32_e32 v162, 16, v16
	v_and_b32_e32 v163, 0xffff0000, v16
	v_lshlrev_b32_e32 v164, 16, v33
	v_and_b32_e32 v165, 0xffff0000, v33
	v_lshlrev_b32_e32 v166, 16, v17
	v_and_b32_e32 v167, 0xffff0000, v17
	v_lshlrev_b32_e32 v168, 16, v34
	v_and_b32_e32 v169, 0xffff0000, v34
	v_lshlrev_b32_e32 v170, 16, v18
	v_and_b32_e32 v171, 0xffff0000, v18
	v_lshlrev_b32_e32 v172, 16, v35
	v_and_b32_e32 v173, 0xffff0000, v35
	v_lshlrev_b32_e32 v174, 16, v19
	v_and_b32_e32 v175, 0xffff0000, v19
	v_pk_add_f32 v[162:163], v[160:161], v[162:163] neg_lo:[0,1] neg_hi:[0,1]
	v_pk_add_f32 v[166:167], v[164:165], v[166:167] neg_lo:[0,1] neg_hi:[0,1]
	v_pk_add_f32 v[170:171], v[168:169], v[170:171] neg_lo:[0,1] neg_hi:[0,1]
	v_pk_add_f32 v[174:175], v[172:173], v[174:175] neg_lo:[0,1] neg_hi:[0,1]
	v_pk_add_f32 v[148:149], v[148:149], v[162:163]
	v_pk_add_f32 v[150:151], v[150:151], v[166:167]
	v_pk_add_f32 v[152:153], v[152:153], v[170:171]
	v_pk_add_f32 v[154:155], v[154:155], v[174:175]
	v_fma_f32 v162, s43, v148, -v160
	v_fma_f32 v163, s43, v149, -v161
	v_fma_f32 v166, s43, v150, -v164
	v_fma_f32 v167, s43, v151, -v165
	v_fma_f32 v170, s43, v152, -v168
	v_fma_f32 v171, s43, v153, -v169
	v_fma_f32 v174, s43, v154, -v172
	v_fma_f32 v175, s43, v155, -v173
	v_cvt_pk_bf16_f32 v156, v162, v163
	v_cvt_pk_bf16_f32 v157, v166, v167
	v_cvt_pk_bf16_f32 v158, v170, v171
	v_cvt_pk_bf16_f32 v159, v174, v175
	global_store_dwordx4 v3, v[156:159], s[10:11]
	v_add_u32_e32 v3, 0x2000, v3
	s_waitcnt vmcnt(31)
; __device__ __forceinline__ unsigned cvt_pk_bf16(float lo, float hi) { unsigned r; asm volatile("v_cvt_pk_bf16_f32 %0, %1, %2" : "=v"(r) : "v"(lo), "v"(hi)); return r; }
; __device__ __forceinline__ float bf_lo(unsigned w) { return __uint_as_float(w << 16); }
; __device__ __forceinline__ float bf_hi(unsigned w) { return __uint_as_float(w & 0xffff0000u); }
; __device__ void phase_pool() {
;     ...
;         for (int r0 = 0; r0 < RB; r0 += 8) {
;             u32x4 vv[8], ov[8];
; #pragma unroll
;             for (int k = 0; k < 8; ++k) { const int row = row0 + r0 + k, tl = tl0 + r0 + k;
;                 vv[k] = *(const u32x4*)(uz + (size_t)row * DE2 + col);
;                 ov[k] = (tl >= w) ? *(const u32x4*)(uz + (size_t)(row - w) * DE2 + col) : (u32x4){0u, 0u, 0u, 0u}; }
; #pragma unroll
;             for (int k = 0; k < 8; ++k) { const int row = row0 + r0 + k, tl = tl0 + r0 + k; const u32x4 v = vv[k], o2 = ov[k];
;                 s[0] += bf_lo(v.x) - bf_lo(o2.x); s[1] += bf_hi(v.x) - bf_hi(o2.x); s[2] += bf_lo(v.y) - bf_lo(o2.y); s[3] += bf_hi(v.y) - bf_hi(o2.y);
;                 s[4] += bf_lo(v.z) - bf_lo(o2.z); s[5] += bf_hi(v.z) - bf_hi(o2.z); s[6] += bf_lo(v.w) - bf_lo(o2.w); s[7] += bf_hi(v.w) - bf_hi(o2.w);
;                 const float ic = 1.0f / (float)((tl + 1 < w) ? tl + 1 : w);
;                 u32x4 o;
;                 o.x = cvt_pk_bf16(s[0] * ic - bf_lo(v.x), s[1] * ic - bf_hi(v.x)); o.y = cvt_pk_bf16(s[2] * ic - bf_lo(v.y), s[3] * ic - bf_hi(v.y));
;                 o.z = cvt_pk_bf16(s[4] * ic - bf_lo(v.z), s[5] * ic - bf_hi(v.z)); o.w = cvt_pk_bf16(s[6] * ic - bf_lo(v.w), s[7] * ic - bf_hi(v.w));
;                 *(u32x4*)(pg + (size_t)row * DE + col) = o; }
	v_lshlrev_b32_e32 v160, 16, v36
	v_and_b32_e32 v161, 0xffff0000, v36
	v_lshlrev_b32_e32 v162, 16, v20
	v_and_b32_e32 v163, 0xffff0000, v20
	v_lshlrev_b32_e32 v164, 16, v37
	v_and_b32_e32 v165, 0xffff0000, v37
	v_lshlrev_b32_e32 v166, 16, v21
	v_and_b32_e32 v167, 0xffff0000, v21
	v_lshlrev_b32_e32 v168, 16, v38
	v_and_b32_e32 v169, 0xffff0000, v38
	v_lshlrev_b32_e32 v170, 16, v22
	v_and_b32_e32 v171, 0xffff0000, v22
	v_lshlrev_b32_e32 v172, 16, v39
	v_and_b32_e32 v173, 0xffff0000, v39
	v_lshlrev_b32_e32 v174, 16, v23
	v_and_b32_e32 v175, 0xffff0000, v23
	v_pk_add_f32 v[162:163], v[160:161], v[162:163] neg_lo:[0,1] neg_hi:[0,1]
	v_pk_add_f32 v[166:167], v[164:165], v[166:167] neg_lo:[0,1] neg_hi:[0,1]
	v_pk_add_f32 v[170:171], v[168:169], v[170:171] neg_lo:[0,1] neg_hi:[0,1]
	v_pk_add_f32 v[174:175], v[172:173], v[174:175] neg_lo:[0,1] neg_hi:[0,1]
	v_pk_add_f32 v[148:149], v[148:149], v[162:163]
	v_pk_add_f32 v[150:151], v[150:151], v[166:167]
	v_pk_add_f32 v[152:153], v[152:153], v[170:171]
	v_pk_add_f32 v[154:155], v[154:155], v[174:175]
	v_fma_f32 v162, s43, v148, -v160
	v_fma_f32 v163, s43, v149, -v161
	v_fma_f32 v166, s43, v150, -v164
	v_fma_f32 v167, s43, v151, -v165
	v_fma_f32 v170, s43, v152, -v168
	v_fma_f32 v171, s43, v153, -v169
	v_fma_f32 v174, s43, v154, -v172
	v_fma_f32 v175, s43, v155, -v173
	v_cvt_pk_bf16_f32 v156, v162, v163
	v_cvt_pk_bf16_f32 v157, v166, v167
	v_cvt_pk_bf16_f32 v158, v170, v171
	v_cvt_pk_bf16_f32 v159, v174, v175
	global_store_dwordx4 v3, v[156:159], s[10:11]
	v_add_u32_e32 v3, 0x2000, v3
	s_waitcnt vmcnt(31)
	v_lshlrev_b32_e32 v160, 16, v40
	v_and_b32_e32 v161, 0xffff0000, v40
	v_lshlrev_b32_e32 v162, 16, v24
	v_and_b32_e32 v163, 0xffff0000, v24
	v_lshlrev_b32_e32 v164, 16, v41
	v_and_b32_e32 v165, 0xffff0000, v41
	v_lshlrev_b32_e32 v166, 16, v25
	v_and_b32_e32 v167, 0xffff0000, v25
	v_lshlrev_b32_e32 v168, 16, v42
	v_and_b32_e32 v169, 0xffff0000, v42
	v_lshlrev_b32_e32 v170, 16, v26
	v_and_b32_e32 v171, 0xffff0000, v26
	v_lshlrev_b32_e32 v172, 16, v43
	v_and_b32_e32 v173, 0xffff0000, v43
	v_lshlrev_b32_e32 v174, 16, v27
	v_and_b32_e32 v175, 0xffff0000, v27
	v_pk_add_f32 v[162:163], v[160:161], v[162:163] neg_lo:[0,1] neg_hi:[0,1]
	v_pk_add_f32 v[166:167], v[164:165], v[166:167] neg_lo:[0,1] neg_hi:[0,1]
	v_pk_add_f32 v[170:171], v[168:169], v[170:171] neg_lo:[0,1] neg_hi:[0,1]
	v_pk_add_f32 v[174:175], v[172:173], v[174:175] neg_lo:[0,1] neg_hi:[0,1]
	v_pk_add_f32 v[148:149], v[148:149], v[162:163]
	v_pk_add_f32 v[150:151], v[150:151], v[166:167]
	v_pk_add_f32 v[152:153], v[152:153], v[170:171]
	v_pk_add_f32 v[154:155], v[154:155], v[174:175]
	v_fma_f32 v162, s43, v148, -v160
	v_fma_f32 v163, s43, v149, -v161
	v_fma_f32 v166, s43, v150, -v164
	v_fma_f32 v167, s43, v151, -v165
	v_fma_f32 v170, s43, v152, -v168
	v_fma_f32 v171, s43, v153, -v169
	v_fma_f32 v174, s43, v154, -v172
	v_fma_f32 v175, s43, v155, -v173
	v_cvt_pk_bf16_f32 v156, v162, v163
	v_cvt_pk_bf16_f32 v157, v166, v167
	v_cvt_pk_bf16_f32 v158, v170, v171
	v_cvt_pk_bf16_f32 v159, v174, v175
	global_store_dwordx4 v3, v[156:159], s[10:11]
	v_add_u32_e32 v3, 0x2000, v3
	s_waitcnt vmcnt(31)
	v_lshlrev_b32_e32 v160, 16, v44
	v_and_b32_e32 v161, 0xffff0000, v44
	v_lshlrev_b32_e32 v162, 16, v28
	v_and_b32_e32 v163, 0xffff0000, v28
	v_lshlrev_b32_e32 v164, 16, v45
	v_and_b32_e32 v165, 0xffff0000, v45
	v_lshlrev_b32_e32 v166, 16, v29
	v_and_b32_e32 v167, 0xffff0000, v29
	v_lshlrev_b32_e32 v168, 16, v46
	v_and_b32_e32 v169, 0xffff0000, v46
	v_lshlrev_b32_e32 v170, 16, v30
	v_and_b32_e32 v171, 0xffff0000, v30
	v_lshlrev_b32_e32 v172, 16, v47
	v_and_b32_e32 v173, 0xffff0000, v47
	v_lshlrev_b32_e32 v174, 16, v31
	v_and_b32_e32 v175, 0xffff0000, v31
	v_pk_add_f32 v[162:163], v[160:161], v[162:163] neg_lo:[0,1] neg_hi:[0,1]
	v_pk_add_f32 v[166:167], v[164:165], v[166:167] neg_lo:[0,1] neg_hi:[0,1]
	v_pk_add_f32 v[170:171], v[168:169], v[170:171] neg_lo:[0,1] neg_hi:[0,1]
	v_pk_add_f32 v[174:175], v[172:173], v[174:175] neg_lo:[0,1] neg_hi:[0,1]
	v_pk_add_f32 v[148:149], v[148:149], v[162:163]
	v_pk_add_f32 v[150:151], v[150:151], v[166:167]
	v_pk_add_f32 v[152:153], v[152:153], v[170:171]
	v_pk_add_f32 v[154:155], v[154:155], v[174:175]
	v_fma_f32 v162, s43, v148, -v160
	v_fma_f32 v163, s43, v149, -v161
	v_fma_f32 v166, s43, v150, -v164
	v_fma_f32 v167, s43, v151, -v165
	v_fma_f32 v170, s43, v152, -v168
	v_fma_f32 v171, s43, v153, -v169
	v_fma_f32 v174, s43, v154, -v172
	v_fma_f32 v175, s43, v155, -v173
	v_cvt_pk_bf16_f32 v156, v162, v163
	v_cvt_pk_bf16_f32 v157, v166, v167
	v_cvt_pk_bf16_f32 v158, v170, v171
	v_cvt_pk_bf16_f32 v159, v174, v175
	global_store_dwordx4 v3, v[156:159], s[10:11]
	v_add_u32_e32 v3, 0x2000, v3
	s_waitcnt vmcnt(31)
	v_lshlrev_b32_e32 v160, 16, v48
	v_and_b32_e32 v161, 0xffff0000, v48
	v_lshlrev_b32_e32 v162, 16, v32
	v_and_b32_e32 v163, 0xffff0000, v32
	v_lshlrev_b32_e32 v164, 16, v49
	v_and_b32_e32 v165, 0xffff0000, v49
	v_lshlrev_b32_e32 v166, 16, v33
	v_and_b32_e32 v167, 0xffff0000, v33
	v_lshlrev_b32_e32 v168, 16, v50
	v_and_b32_e32 v169, 0xffff0000, v50
	v_lshlrev_b32_e32 v170, 16, v34
	v_and_b32_e32 v171, 0xffff0000, v34
	v_lshlrev_b32_e32 v172, 16, v51
	v_and_b32_e32 v173, 0xffff0000, v51
	v_lshlrev_b32_e32 v174, 16, v35
	v_and_b32_e32 v175, 0xffff0000, v35
	v_pk_add_f32 v[162:163], v[160:161], v[162:163] neg_lo:[0,1] neg_hi:[0,1]
	v_pk_add_f32 v[166:167], v[164:165], v[166:167] neg_lo:[0,1] neg_hi:[0,1]
	v_pk_add_f32 v[170:171], v[168:169], v[170:171] neg_lo:[0,1] neg_hi:[0,1]
	v_pk_add_f32 v[174:175], v[172:173], v[174:175] neg_lo:[0,1] neg_hi:[0,1]
	v_pk_add_f32 v[148:149], v[148:149], v[162:163]
	v_pk_add_f32 v[150:151], v[150:151], v[166:167]
	v_pk_add_f32 v[152:153], v[152:153], v[170:171]
	v_pk_add_f32 v[154:155], v[154:155], v[174:175]
	v_fma_f32 v162, s43, v148, -v160
	v_fma_f32 v163, s43, v149, -v161
	v_fma_f32 v166, s43, v150, -v164
	v_fma_f32 v167, s43, v151, -v165
	v_fma_f32 v170, s43, v152, -v168
	v_fma_f32 v171, s43, v153, -v169
	v_fma_f32 v174, s43, v154, -v172
	v_fma_f32 v175, s43, v155, -v173
	v_cvt_pk_bf16_f32 v156, v162, v163
	v_cvt_pk_bf16_f32 v157, v166, v167
	v_cvt_pk_bf16_f32 v158, v170, v171
	v_cvt_pk_bf16_f32 v159, v174, v175
	global_store_dwordx4 v3, v[156:159], s[10:11]
	v_add_u32_e32 v3, 0x2000, v3
	s_waitcnt vmcnt(31)
; __device__ __forceinline__ unsigned cvt_pk_bf16(float lo, float hi) { unsigned r; asm volatile("v_cvt_pk_bf16_f32 %0, %1, %2" : "=v"(r) : "v"(lo), "v"(hi)); return r; }
; __device__ __forceinline__ float bf_lo(unsigned w) { return __uint_as_float(w << 16); }
; __device__ __forceinline__ float bf_hi(unsigned w) { return __uint_as_float(w & 0xffff0000u); }
; __device__ void phase_pool() {
;     ...
;         for (int r0 = 0; r0 < RB; r0 += 8) {
;             u32x4 vv[8], ov[8];
; #pragma unroll
;             for (int k = 0; k < 8; ++k) { const int row = row0 + r0 + k, tl = tl0 + r0 + k;
;                 vv[k] = *(const u32x4*)(uz + (size_t)row * DE2 + col);
;                 ov[k] = (tl >= w) ? *(const u32x4*)(uz + (size_t)(row - w) * DE2 + col) : (u32x4){0u, 0u, 0u, 0u}; }
; #pragma unroll
;             for (int k = 0; k < 8; ++k) { const int row = row0 + r0 + k, tl = tl0 + r0 + k; const u32x4 v = vv[k], o2 = ov[k];
;                 s[0] += bf_lo(v.x) - bf_lo(o2.x); s[1] += bf_hi(v.x) - bf_hi(o2.x); s[2] += bf_lo(v.y) - bf_lo(o2.y); s[3] += bf_hi(v.y) - bf_hi(o2.y);
;                 s[4] += bf_lo(v.z) - bf_lo(o2.z); s[5] += bf_hi(v.z) - bf_hi(o2.z); s[6] += bf_lo(v.w) - bf_lo(o2.w); s[7] += bf_hi(v.w) - bf_hi(o2.w);
;                 const float ic = 1.0f / (float)((tl + 1 < w) ? tl + 1 : w);
;                 u32x4 o;
;                 o.x = cvt_pk_bf16(s[0] * ic - bf_lo(v.x), s[1] * ic - bf_hi(v.x)); o.y = cvt_pk_bf16(s[2] * ic - bf_lo(v.y), s[3] * ic - bf_hi(v.y));
;                 o.z = cvt_pk_bf16(s[4] * ic - bf_lo(v.z), s[5] * ic - bf_hi(v.z)); o.w = cvt_pk_bf16(s[6] * ic - bf_lo(v.w), s[7] * ic - bf_hi(v.w));
;                 *(u32x4*)(pg + (size_t)row * DE + col) = o; }
	v_lshlrev_b32_e32 v160, 16, v52
	v_and_b32_e32 v161, 0xffff0000, v52
	v_lshlrev_b32_e32 v162, 16, v36
	v_and_b32_e32 v163, 0xffff0000, v36
	v_lshlrev_b32_e32 v164, 16, v53
	v_and_b32_e32 v165, 0xffff0000, v53
	v_lshlrev_b32_e32 v166, 16, v37
	v_and_b32_e32 v167, 0xffff0000, v37
	v_lshlrev_b32_e32 v168, 16, v54
	v_and_b32_e32 v169, 0xffff0000, v54
	v_lshlrev_b32_e32 v170, 16, v38
	v_and_b32_e32 v171, 0xffff0000, v38
	v_lshlrev_b32_e32 v172, 16, v55
	v_and_b32_e32 v173, 0xffff0000, v55
	v_lshlrev_b32_e32 v174, 16, v39
	v_and_b32_e32 v175, 0xffff0000, v39
	v_pk_add_f32 v[162:163], v[160:161], v[162:163] neg_lo:[0,1] neg_hi:[0,1]
	v_pk_add_f32 v[166:167], v[164:165], v[166:167] neg_lo:[0,1] neg_hi:[0,1]
	v_pk_add_f32 v[170:171], v[168:169], v[170:171] neg_lo:[0,1] neg_hi:[0,1]
	v_pk_add_f32 v[174:175], v[172:173], v[174:175] neg_lo:[0,1] neg_hi:[0,1]
	v_pk_add_f32 v[148:149], v[148:149], v[162:163]
	v_pk_add_f32 v[150:151], v[150:151], v[166:167]
	v_pk_add_f32 v[152:153], v[152:153], v[170:171]
	v_pk_add_f32 v[154:155], v[154:155], v[174:175]
	v_fma_f32 v162, s43, v148, -v160
	v_fma_f32 v163, s43, v149, -v161
	v_fma_f32 v166, s43, v150, -v164
	v_fma_f32 v167, s43, v151, -v165
	v_fma_f32 v170, s43, v152, -v168
	v_fma_f32 v171, s43, v153, -v169
	v_fma_f32 v174, s43, v154, -v172
	v_fma_f32 v175, s43, v155, -v173
	v_cvt_pk_bf16_f32 v156, v162, v163
	v_cvt_pk_bf16_f32 v157, v166, v167
	v_cvt_pk_bf16_f32 v158, v170, v171
	v_cvt_pk_bf16_f32 v159, v174, v175
	global_store_dwordx4 v3, v[156:159], s[10:11]
	v_add_u32_e32 v3, 0x2000, v3
	s_waitcnt vmcnt(31)
	v_lshlrev_b32_e32 v160, 16, v56
	v_and_b32_e32 v161, 0xffff0000, v56
	v_lshlrev_b32_e32 v162, 16, v40
	v_and_b32_e32 v163, 0xffff0000, v40
	v_lshlrev_b32_e32 v164, 16, v57
	v_and_b32_e32 v165, 0xffff0000, v57
	v_lshlrev_b32_e32 v166, 16, v41
	v_and_b32_e32 v167, 0xffff0000, v41
	v_lshlrev_b32_e32 v168, 16, v58
	v_and_b32_e32 v169, 0xffff0000, v58
	v_lshlrev_b32_e32 v170, 16, v42
	v_and_b32_e32 v171, 0xffff0000, v42
	v_lshlrev_b32_e32 v172, 16, v59
	v_and_b32_e32 v173, 0xffff0000, v59
	v_lshlrev_b32_e32 v174, 16, v43
	v_and_b32_e32 v175, 0xffff0000, v43
	v_pk_add_f32 v[162:163], v[160:161], v[162:163] neg_lo:[0,1] neg_hi:[0,1]
	v_pk_add_f32 v[166:167], v[164:165], v[166:167] neg_lo:[0,1] neg_hi:[0,1]
	v_pk_add_f32 v[170:171], v[168:169], v[170:171] neg_lo:[0,1] neg_hi:[0,1]
	v_pk_add_f32 v[174:175], v[172:173], v[174:175] neg_lo:[0,1] neg_hi:[0,1]
	v_pk_add_f32 v[148:149], v[148:149], v[162:163]
	v_pk_add_f32 v[150:151], v[150:151], v[166:167]
	v_pk_add_f32 v[152:153], v[152:153], v[170:171]
	v_pk_add_f32 v[154:155], v[154:155], v[174:175]
	v_fma_f32 v162, s43, v148, -v160
	v_fma_f32 v163, s43, v149, -v161
	v_fma_f32 v166, s43, v150, -v164
	v_fma_f32 v167, s43, v151, -v165
	v_fma_f32 v170, s43, v152, -v168
	v_fma_f32 v171, s43, v153, -v169
	v_fma_f32 v174, s43, v154, -v172
	v_fma_f32 v175, s43, v155, -v173
	v_cvt_pk_bf16_f32 v156, v162, v163
	v_cvt_pk_bf16_f32 v157, v166, v167
	v_cvt_pk_bf16_f32 v158, v170, v171
	v_cvt_pk_bf16_f32 v159, v174, v175
	global_store_dwordx4 v3, v[156:159], s[10:11]
	v_add_u32_e32 v3, 0x2000, v3
	s_waitcnt vmcnt(31)
	v_lshlrev_b32_e32 v160, 16, v60
	v_and_b32_e32 v161, 0xffff0000, v60
	v_lshlrev_b32_e32 v162, 16, v44
	v_and_b32_e32 v163, 0xffff0000, v44
	v_lshlrev_b32_e32 v164, 16, v61
	v_and_b32_e32 v165, 0xffff0000, v61
	v_lshlrev_b32_e32 v166, 16, v45
	v_and_b32_e32 v167, 0xffff0000, v45
	v_lshlrev_b32_e32 v168, 16, v62
	v_and_b32_e32 v169, 0xffff0000, v62
	v_lshlrev_b32_e32 v170, 16, v46
	v_and_b32_e32 v171, 0xffff0000, v46
	v_lshlrev_b32_e32 v172, 16, v63
	v_and_b32_e32 v173, 0xffff0000, v63
	v_lshlrev_b32_e32 v174, 16, v47
	v_and_b32_e32 v175, 0xffff0000, v47
	v_pk_add_f32 v[162:163], v[160:161], v[162:163] neg_lo:[0,1] neg_hi:[0,1]
	v_pk_add_f32 v[166:167], v[164:165], v[166:167] neg_lo:[0,1] neg_hi:[0,1]
	v_pk_add_f32 v[170:171], v[168:169], v[170:171] neg_lo:[0,1] neg_hi:[0,1]
	v_pk_add_f32 v[174:175], v[172:173], v[174:175] neg_lo:[0,1] neg_hi:[0,1]
	v_pk_add_f32 v[148:149], v[148:149], v[162:163]
	v_pk_add_f32 v[150:151], v[150:151], v[166:167]
	v_pk_add_f32 v[152:153], v[152:153], v[170:171]
	v_pk_add_f32 v[154:155], v[154:155], v[174:175]
	v_fma_f32 v162, s43, v148, -v160
	v_fma_f32 v163, s43, v149, -v161
	v_fma_f32 v166, s43, v150, -v164
	v_fma_f32 v167, s43, v151, -v165
	v_fma_f32 v170, s43, v152, -v168
	v_fma_f32 v171, s43, v153, -v169
	v_fma_f32 v174, s43, v154, -v172
	v_fma_f32 v175, s43, v155, -v173
	v_cvt_pk_bf16_f32 v156, v162, v163
	v_cvt_pk_bf16_f32 v157, v166, v167
	v_cvt_pk_bf16_f32 v158, v170, v171
	v_cvt_pk_bf16_f32 v159, v174, v175
	global_store_dwordx4 v3, v[156:159], s[10:11]
	v_add_u32_e32 v3, 0x2000, v3
	s_waitcnt vmcnt(31)
	v_lshlrev_b32_e32 v160, 16, v64
	v_and_b32_e32 v161, 0xffff0000, v64
	v_lshlrev_b32_e32 v162, 16, v48
	v_and_b32_e32 v163, 0xffff0000, v48
	v_lshlrev_b32_e32 v164, 16, v65
	v_and_b32_e32 v165, 0xffff0000, v65
	v_lshlrev_b32_e32 v166, 16, v49
	v_and_b32_e32 v167, 0xffff0000, v49
	v_lshlrev_b32_e32 v168, 16, v66
	v_and_b32_e32 v169, 0xffff0000, v66
	v_lshlrev_b32_e32 v170, 16, v50
	v_and_b32_e32 v171, 0xffff0000, v50
	v_lshlrev_b32_e32 v172, 16, v67
	v_and_b32_e32 v173, 0xffff0000, v67
	v_lshlrev_b32_e32 v174, 16, v51
	v_and_b32_e32 v175, 0xffff0000, v51
	v_pk_add_f32 v[162:163], v[160:161], v[162:163] neg_lo:[0,1] neg_hi:[0,1]
	v_pk_add_f32 v[166:167], v[164:165], v[166:167] neg_lo:[0,1] neg_hi:[0,1]
	v_pk_add_f32 v[170:171], v[168:169], v[170:171] neg_lo:[0,1] neg_hi:[0,1]
	v_pk_add_f32 v[174:175], v[172:173], v[174:175] neg_lo:[0,1] neg_hi:[0,1]
	v_pk_add_f32 v[148:149], v[148:149], v[162:163]
	v_pk_add_f32 v[150:151], v[150:151], v[166:167]
	v_pk_add_f32 v[152:153], v[152:153], v[170:171]
	v_pk_add_f32 v[154:155], v[154:155], v[174:175]
	v_fma_f32 v162, s43, v148, -v160
	v_fma_f32 v163, s43, v149, -v161
	v_fma_f32 v166, s43, v150, -v164
	v_fma_f32 v167, s43, v151, -v165
	v_fma_f32 v170, s43, v152, -v168
	v_fma_f32 v171, s43, v153, -v169
	v_fma_f32 v174, s43, v154, -v172
	v_fma_f32 v175, s43, v155, -v173
	v_cvt_pk_bf16_f32 v156, v162, v163
	v_cvt_pk_bf16_f32 v157, v166, v167
	v_cvt_pk_bf16_f32 v158, v170, v171
	v_cvt_pk_bf16_f32 v159, v174, v175
	global_store_dwordx4 v3, v[156:159], s[10:11]
	v_add_u32_e32 v3, 0x2000, v3
	s_waitcnt vmcnt(31)
; __device__ __forceinline__ unsigned cvt_pk_bf16(float lo, float hi) { unsigned r; asm volatile("v_cvt_pk_bf16_f32 %0, %1, %2" : "=v"(r) : "v"(lo), "v"(hi)); return r; }
; __device__ __forceinline__ float bf_lo(unsigned w) { return __uint_as_float(w << 16); }
; __device__ __forceinline__ float bf_hi(unsigned w) { return __uint_as_float(w & 0xffff0000u); }
; __device__ void phase_pool() {
;     ...
;         for (int r0 = 0; r0 < RB; r0 += 8) {
;             u32x4 vv[8], ov[8];
; #pragma unroll
;             for (int k = 0; k < 8; ++k) { const int row = row0 + r0 + k, tl = tl0 + r0 + k;
;                 vv[k] = *(const u32x4*)(uz + (size_t)row * DE2 + col);
;                 ov[k] = (tl >= w) ? *(const u32x4*)(uz + (size_t)(row - w) * DE2 + col) : (u32x4){0u, 0u, 0u, 0u}; }
; #pragma unroll
;             for (int k = 0; k < 8; ++k) { const int row = row0 + r0 + k, tl = tl0 + r0 + k; const u32x4 v = vv[k], o2 = ov[k];
;                 s[0] += bf_lo(v.x) - bf_lo(o2.x); s[1] += bf_hi(v.x) - bf_hi(o2.x); s[2] += bf_lo(v.y) - bf_lo(o2.y); s[3] += bf_hi(v.y) - bf_hi(o2.y);
;                 s[4] += bf_lo(v.z) - bf_lo(o2.z); s[5] += bf_hi(v.z) - bf_hi(o2.z); s[6] += bf_lo(v.w) - bf_lo(o2.w); s[7] += bf_hi(v.w) - bf_hi(o2.w);
;                 const float ic = 1.0f / (float)((tl + 1 < w) ? tl + 1 : w);
;                 u32x4 o;
;                 o.x = cvt_pk_bf16(s[0] * ic - bf_lo(v.x), s[1] * ic - bf_hi(v.x)); o.y = cvt_pk_bf16(s[2] * ic - bf_lo(v.y), s[3] * ic - bf_hi(v.y));
;                 o.z = cvt_pk_bf16(s[4] * ic - bf_lo(v.z), s[5] * ic - bf_hi(v.z)); o.w = cvt_pk_bf16(s[6] * ic - bf_lo(v.w), s[7] * ic - bf_hi(v.w));
;                 *(u32x4*)(pg + (size_t)row * DE + col) = o; }
	v_lshlrev_b32_e32 v160, 16, v68
	v_and_b32_e32 v161, 0xffff0000, v68
	v_lshlrev_b32_e32 v162, 16, v52
	v_and_b32_e32 v163, 0xffff0000, v52
	v_lshlrev_b32_e32 v164, 16, v69
	v_and_b32_e32 v165, 0xffff0000, v69
	v_lshlrev_b32_e32 v166, 16, v53
	v_and_b32_e32 v167, 0xffff0000, v53
	v_lshlrev_b32_e32 v168, 16, v70
	v_and_b32_e32 v169, 0xffff0000, v70
	v_lshlrev_b32_e32 v170, 16, v54
	v_and_b32_e32 v171, 0xffff0000, v54
	v_lshlrev_b32_e32 v172, 16, v71
	v_and_b32_e32 v173, 0xffff0000, v71
	v_lshlrev_b32_e32 v174, 16, v55
	v_and_b32_e32 v175, 0xffff0000, v55
	v_pk_add_f32 v[162:163], v[160:161], v[162:163] neg_lo:[0,1] neg_hi:[0,1]
	v_pk_add_f32 v[166:167], v[164:165], v[166:167] neg_lo:[0,1] neg_hi:[0,1]
	v_pk_add_f32 v[170:171], v[168:169], v[170:171] neg_lo:[0,1] neg_hi:[0,1]
	v_pk_add_f32 v[174:175], v[172:173], v[174:175] neg_lo:[0,1] neg_hi:[0,1]
	v_pk_add_f32 v[148:149], v[148:149], v[162:163]
	v_pk_add_f32 v[150:151], v[150:151], v[166:167]
	v_pk_add_f32 v[152:153], v[152:153], v[170:171]
	v_pk_add_f32 v[154:155], v[154:155], v[174:175]
	v_fma_f32 v162, s43, v148, -v160
	v_fma_f32 v163, s43, v149, -v161
	v_fma_f32 v166, s43, v150, -v164
	v_fma_f32 v167, s43, v151, -v165
	v_fma_f32 v170, s43, v152, -v168
	v_fma_f32 v171, s43, v153, -v169
	v_fma_f32 v174, s43, v154, -v172
	v_fma_f32 v175, s43, v155, -v173
	v_cvt_pk_bf16_f32 v156, v162, v163
	v_cvt_pk_bf16_f32 v157, v166, v167
	v_cvt_pk_bf16_f32 v158, v170, v171
	v_cvt_pk_bf16_f32 v159, v174, v175
	global_store_dwordx4 v3, v[156:159], s[10:11]
	v_add_u32_e32 v3, 0x2000, v3
	s_waitcnt vmcnt(31)
	v_lshlrev_b32_e32 v160, 16, v72
	v_and_b32_e32 v161, 0xffff0000, v72
	v_lshlrev_b32_e32 v162, 16, v56
	v_and_b32_e32 v163, 0xffff0000, v56
	v_lshlrev_b32_e32 v164, 16, v73
	v_and_b32_e32 v165, 0xffff0000, v73
	v_lshlrev_b32_e32 v166, 16, v57
	v_and_b32_e32 v167, 0xffff0000, v57
	v_lshlrev_b32_e32 v168, 16, v74
	v_and_b32_e32 v169, 0xffff0000, v74
	v_lshlrev_b32_e32 v170, 16, v58
	v_and_b32_e32 v171, 0xffff0000, v58
	v_lshlrev_b32_e32 v172, 16, v75
	v_and_b32_e32 v173, 0xffff0000, v75
	v_lshlrev_b32_e32 v174, 16, v59
	v_and_b32_e32 v175, 0xffff0000, v59
	v_pk_add_f32 v[162:163], v[160:161], v[162:163] neg_lo:[0,1] neg_hi:[0,1]
	v_pk_add_f32 v[166:167], v[164:165], v[166:167] neg_lo:[0,1] neg_hi:[0,1]
	v_pk_add_f32 v[170:171], v[168:169], v[170:171] neg_lo:[0,1] neg_hi:[0,1]
	v_pk_add_f32 v[174:175], v[172:173], v[174:175] neg_lo:[0,1] neg_hi:[0,1]
	v_pk_add_f32 v[148:149], v[148:149], v[162:163]
	v_pk_add_f32 v[150:151], v[150:151], v[166:167]
	v_pk_add_f32 v[152:153], v[152:153], v[170:171]
	v_pk_add_f32 v[154:155], v[154:155], v[174:175]
	v_fma_f32 v162, s43, v148, -v160
	v_fma_f32 v163, s43, v149, -v161
	v_fma_f32 v166, s43, v150, -v164
	v_fma_f32 v167, s43, v151, -v165
	v_fma_f32 v170, s43, v152, -v168
	v_fma_f32 v171, s43, v153, -v169
	v_fma_f32 v174, s43, v154, -v172
	v_fma_f32 v175, s43, v155, -v173
	v_cvt_pk_bf16_f32 v156, v162, v163
	v_cvt_pk_bf16_f32 v157, v166, v167
	v_cvt_pk_bf16_f32 v158, v170, v171
	v_cvt_pk_bf16_f32 v159, v174, v175
	global_store_dwordx4 v3, v[156:159], s[10:11]
	v_add_u32_e32 v3, 0x2000, v3
	s_waitcnt vmcnt(31)
	v_lshlrev_b32_e32 v160, 16, v76
	v_and_b32_e32 v161, 0xffff0000, v76
	v_lshlrev_b32_e32 v162, 16, v60
	v_and_b32_e32 v163, 0xffff0000, v60
	v_lshlrev_b32_e32 v164, 16, v77
	v_and_b32_e32 v165, 0xffff0000, v77
	v_lshlrev_b32_e32 v166, 16, v61
	v_and_b32_e32 v167, 0xffff0000, v61
	v_lshlrev_b32_e32 v168, 16, v78
	v_and_b32_e32 v169, 0xffff0000, v78
	v_lshlrev_b32_e32 v170, 16, v62
	v_and_b32_e32 v171, 0xffff0000, v62
	v_lshlrev_b32_e32 v172, 16, v79
	v_and_b32_e32 v173, 0xffff0000, v79
	v_lshlrev_b32_e32 v174, 16, v63
	v_and_b32_e32 v175, 0xffff0000, v63
	v_pk_add_f32 v[162:163], v[160:161], v[162:163] neg_lo:[0,1] neg_hi:[0,1]
	v_pk_add_f32 v[166:167], v[164:165], v[166:167] neg_lo:[0,1] neg_hi:[0,1]
	v_pk_add_f32 v[170:171], v[168:169], v[170:171] neg_lo:[0,1] neg_hi:[0,1]
	v_pk_add_f32 v[174:175], v[172:173], v[174:175] neg_lo:[0,1] neg_hi:[0,1]
	v_pk_add_f32 v[148:149], v[148:149], v[162:163]
	v_pk_add_f32 v[150:151], v[150:151], v[166:167]
	v_pk_add_f32 v[152:153], v[152:153], v[170:171]
	v_pk_add_f32 v[154:155], v[154:155], v[174:175]
	v_fma_f32 v162, s43, v148, -v160
	v_fma_f32 v163, s43, v149, -v161
	v_fma_f32 v166, s43, v150, -v164
	v_fma_f32 v167, s43, v151, -v165
	v_fma_f32 v170, s43, v152, -v168
	v_fma_f32 v171, s43, v153, -v169
	v_fma_f32 v174, s43, v154, -v172
	v_fma_f32 v175, s43, v155, -v173
	v_cvt_pk_bf16_f32 v156, v162, v163
	v_cvt_pk_bf16_f32 v157, v166, v167
	v_cvt_pk_bf16_f32 v158, v170, v171
	v_cvt_pk_bf16_f32 v159, v174, v175
	global_store_dwordx4 v3, v[156:159], s[10:11]
	v_add_u32_e32 v3, 0x2000, v3
	s_waitcnt vmcnt(31)
	v_lshlrev_b32_e32 v160, 16, v80
	v_and_b32_e32 v161, 0xffff0000, v80
	v_lshlrev_b32_e32 v162, 16, v64
	v_and_b32_e32 v163, 0xffff0000, v64
	v_lshlrev_b32_e32 v164, 16, v81
	v_and_b32_e32 v165, 0xffff0000, v81
	v_lshlrev_b32_e32 v166, 16, v65
	v_and_b32_e32 v167, 0xffff0000, v65
	v_lshlrev_b32_e32 v168, 16, v82
	v_and_b32_e32 v169, 0xffff0000, v82
	v_lshlrev_b32_e32 v170, 16, v66
	v_and_b32_e32 v171, 0xffff0000, v66
	v_lshlrev_b32_e32 v172, 16, v83
	v_and_b32_e32 v173, 0xffff0000, v83
	v_lshlrev_b32_e32 v174, 16, v67
	v_and_b32_e32 v175, 0xffff0000, v67
	v_pk_add_f32 v[162:163], v[160:161], v[162:163] neg_lo:[0,1] neg_hi:[0,1]
	v_pk_add_f32 v[166:167], v[164:165], v[166:167] neg_lo:[0,1] neg_hi:[0,1]
	v_pk_add_f32 v[170:171], v[168:169], v[170:171] neg_lo:[0,1] neg_hi:[0,1]
	v_pk_add_f32 v[174:175], v[172:173], v[174:175] neg_lo:[0,1] neg_hi:[0,1]
	v_pk_add_f32 v[148:149], v[148:149], v[162:163]
	v_pk_add_f32 v[150:151], v[150:151], v[166:167]
	v_pk_add_f32 v[152:153], v[152:153], v[170:171]
	v_pk_add_f32 v[154:155], v[154:155], v[174:175]
	v_fma_f32 v162, s43, v148, -v160
	v_fma_f32 v163, s43, v149, -v161
	v_fma_f32 v166, s43, v150, -v164
	v_fma_f32 v167, s43, v151, -v165
	v_fma_f32 v170, s43, v152, -v168
	v_fma_f32 v171, s43, v153, -v169
	v_fma_f32 v174, s43, v154, -v172
	v_fma_f32 v175, s43, v155, -v173
	v_cvt_pk_bf16_f32 v156, v162, v163
	v_cvt_pk_bf16_f32 v157, v166, v167
	v_cvt_pk_bf16_f32 v158, v170, v171
	v_cvt_pk_bf16_f32 v159, v174, v175
	global_store_dwordx4 v3, v[156:159], s[10:11]
	v_add_u32_e32 v3, 0x2000, v3
	s_waitcnt vmcnt(31)
; __device__ __forceinline__ unsigned cvt_pk_bf16(float lo, float hi) { unsigned r; asm volatile("v_cvt_pk_bf16_f32 %0, %1, %2" : "=v"(r) : "v"(lo), "v"(hi)); return r; }
; __device__ __forceinline__ float bf_lo(unsigned w) { return __uint_as_float(w << 16); }
; __device__ __forceinline__ float bf_hi(unsigned w) { return __uint_as_float(w & 0xffff0000u); }
; __device__ void phase_pool() {
;     ...
;         for (int r0 = 0; r0 < RB; r0 += 8) {
;             u32x4 vv[8], ov[8];
; #pragma unroll
;             for (int k = 0; k < 8; ++k) { const int row = row0 + r0 + k, tl = tl0 + r0 + k;
;                 vv[k] = *(const u32x4*)(uz + (size_t)row * DE2 + col);
;                 ov[k] = (tl >= w) ? *(const u32x4*)(uz + (size_t)(row - w) * DE2 + col) : (u32x4){0u, 0u, 0u, 0u}; }
; #pragma unroll
;             for (int k = 0; k < 8; ++k) { const int row = row0 + r0 + k, tl = tl0 + r0 + k; const u32x4 v = vv[k], o2 = ov[k];
;                 s[0] += bf_lo(v.x) - bf_lo(o2.x); s[1] += bf_hi(v.x) - bf_hi(o2.x); s[2] += bf_lo(v.y) - bf_lo(o2.y); s[3] += bf_hi(v.y) - bf_hi(o2.y);
;                 s[4] += bf_lo(v.z) - bf_lo(o2.z); s[5] += bf_hi(v.z) - bf_hi(o2.z); s[6] += bf_lo(v.w) - bf_lo(o2.w); s[7] += bf_hi(v.w) - bf_hi(o2.w);
;                 const float ic = 1.0f / (float)((tl + 1 < w) ? tl + 1 : w);
;                 u32x4 o;
;                 o.x = cvt_pk_bf16(s[0] * ic - bf_lo(v.x), s[1] * ic - bf_hi(v.x)); o.y = cvt_pk_bf16(s[2] * ic - bf_lo(v.y), s[3] * ic - bf_hi(v.y));
;                 o.z = cvt_pk_bf16(s[4] * ic - bf_lo(v.z), s[5] * ic - bf_hi(v.z)); o.w = cvt_pk_bf16(s[6] * ic - bf_lo(v.w), s[7] * ic - bf_hi(v.w));
;                 *(u32x4*)(pg + (size_t)row * DE + col) = o; }
	v_lshlrev_b32_e32 v160, 16, v84
	v_and_b32_e32 v161, 0xffff0000, v84
	v_lshlrev_b32_e32 v162, 16, v68
	v_and_b32_e32 v163, 0xffff0000, v68
	v_lshlrev_b32_e32 v164, 16, v85
	v_and_b32_e32 v165, 0xffff0000, v85
	v_lshlrev_b32_e32 v166, 16, v69
	v_and_b32_e32 v167, 0xffff0000, v69
	v_lshlrev_b32_e32 v168, 16, v86
	v_and_b32_e32 v169, 0xffff0000, v86
	v_lshlrev_b32_e32 v170, 16, v70
	v_and_b32_e32 v171, 0xffff0000, v70
	v_lshlrev_b32_e32 v172, 16, v87
	v_and_b32_e32 v173, 0xffff0000, v87
	v_lshlrev_b32_e32 v174, 16, v71
	v_and_b32_e32 v175, 0xffff0000, v71
	v_pk_add_f32 v[162:163], v[160:161], v[162:163] neg_lo:[0,1] neg_hi:[0,1]
	v_pk_add_f32 v[166:167], v[164:165], v[166:167] neg_lo:[0,1] neg_hi:[0,1]
	v_pk_add_f32 v[170:171], v[168:169], v[170:171] neg_lo:[0,1] neg_hi:[0,1]
	v_pk_add_f32 v[174:175], v[172:173], v[174:175] neg_lo:[0,1] neg_hi:[0,1]
	v_pk_add_f32 v[148:149], v[148:149], v[162:163]
	v_pk_add_f32 v[150:151], v[150:151], v[166:167]
	v_pk_add_f32 v[152:153], v[152:153], v[170:171]
	v_pk_add_f32 v[154:155], v[154:155], v[174:175]
	v_fma_f32 v162, s43, v148, -v160
	v_fma_f32 v163, s43, v149, -v161
	v_fma_f32 v166, s43, v150, -v164
	v_fma_f32 v167, s43, v151, -v165
	v_fma_f32 v170, s43, v152, -v168
	v_fma_f32 v171, s43, v153, -v169
	v_fma_f32 v174, s43, v154, -v172
	v_fma_f32 v175, s43, v155, -v173
	v_cvt_pk_bf16_f32 v156, v162, v163
	v_cvt_pk_bf16_f32 v157, v166, v167
	v_cvt_pk_bf16_f32 v158, v170, v171
	v_cvt_pk_bf16_f32 v159, v174, v175
	global_store_dwordx4 v3, v[156:159], s[10:11]
	v_add_u32_e32 v3, 0x2000, v3
	s_waitcnt vmcnt(31)
	v_lshlrev_b32_e32 v160, 16, v88
	v_and_b32_e32 v161, 0xffff0000, v88
	v_lshlrev_b32_e32 v162, 16, v72
	v_and_b32_e32 v163, 0xffff0000, v72
	v_lshlrev_b32_e32 v164, 16, v89
	v_and_b32_e32 v165, 0xffff0000, v89
	v_lshlrev_b32_e32 v166, 16, v73
	v_and_b32_e32 v167, 0xffff0000, v73
	v_lshlrev_b32_e32 v168, 16, v90
	v_and_b32_e32 v169, 0xffff0000, v90
	v_lshlrev_b32_e32 v170, 16, v74
	v_and_b32_e32 v171, 0xffff0000, v74
	v_lshlrev_b32_e32 v172, 16, v91
	v_and_b32_e32 v173, 0xffff0000, v91
	v_lshlrev_b32_e32 v174, 16, v75
	v_and_b32_e32 v175, 0xffff0000, v75
	v_pk_add_f32 v[162:163], v[160:161], v[162:163] neg_lo:[0,1] neg_hi:[0,1]
	v_pk_add_f32 v[166:167], v[164:165], v[166:167] neg_lo:[0,1] neg_hi:[0,1]
	v_pk_add_f32 v[170:171], v[168:169], v[170:171] neg_lo:[0,1] neg_hi:[0,1]
	v_pk_add_f32 v[174:175], v[172:173], v[174:175] neg_lo:[0,1] neg_hi:[0,1]
	v_pk_add_f32 v[148:149], v[148:149], v[162:163]
	v_pk_add_f32 v[150:151], v[150:151], v[166:167]
	v_pk_add_f32 v[152:153], v[152:153], v[170:171]
	v_pk_add_f32 v[154:155], v[154:155], v[174:175]
	v_fma_f32 v162, s43, v148, -v160
	v_fma_f32 v163, s43, v149, -v161
	v_fma_f32 v166, s43, v150, -v164
	v_fma_f32 v167, s43, v151, -v165
	v_fma_f32 v170, s43, v152, -v168
	v_fma_f32 v171, s43, v153, -v169
	v_fma_f32 v174, s43, v154, -v172
	v_fma_f32 v175, s43, v155, -v173
	v_cvt_pk_bf16_f32 v156, v162, v163
	v_cvt_pk_bf16_f32 v157, v166, v167
	v_cvt_pk_bf16_f32 v158, v170, v171
	v_cvt_pk_bf16_f32 v159, v174, v175
	global_store_dwordx4 v3, v[156:159], s[10:11]
	v_add_u32_e32 v3, 0x2000, v3
	s_waitcnt vmcnt(31)
	v_lshlrev_b32_e32 v160, 16, v92
	v_and_b32_e32 v161, 0xffff0000, v92
	v_lshlrev_b32_e32 v162, 16, v76
	v_and_b32_e32 v163, 0xffff0000, v76
	v_lshlrev_b32_e32 v164, 16, v93
	v_and_b32_e32 v165, 0xffff0000, v93
	v_lshlrev_b32_e32 v166, 16, v77
	v_and_b32_e32 v167, 0xffff0000, v77
	v_lshlrev_b32_e32 v168, 16, v94
	v_and_b32_e32 v169, 0xffff0000, v94
	v_lshlrev_b32_e32 v170, 16, v78
	v_and_b32_e32 v171, 0xffff0000, v78
	v_lshlrev_b32_e32 v172, 16, v95
	v_and_b32_e32 v173, 0xffff0000, v95
	v_lshlrev_b32_e32 v174, 16, v79
	v_and_b32_e32 v175, 0xffff0000, v79
	v_pk_add_f32 v[162:163], v[160:161], v[162:163] neg_lo:[0,1] neg_hi:[0,1]
	v_pk_add_f32 v[166:167], v[164:165], v[166:167] neg_lo:[0,1] neg_hi:[0,1]
	v_pk_add_f32 v[170:171], v[168:169], v[170:171] neg_lo:[0,1] neg_hi:[0,1]
	v_pk_add_f32 v[174:175], v[172:173], v[174:175] neg_lo:[0,1] neg_hi:[0,1]
	v_pk_add_f32 v[148:149], v[148:149], v[162:163]
	v_pk_add_f32 v[150:151], v[150:151], v[166:167]
	v_pk_add_f32 v[152:153], v[152:153], v[170:171]
	v_pk_add_f32 v[154:155], v[154:155], v[174:175]
	v_fma_f32 v162, s43, v148, -v160
	v_fma_f32 v163, s43, v149, -v161
	v_fma_f32 v166, s43, v150, -v164
	v_fma_f32 v167, s43, v151, -v165
	v_fma_f32 v170, s43, v152, -v168
	v_fma_f32 v171, s43, v153, -v169
	v_fma_f32 v174, s43, v154, -v172
	v_fma_f32 v175, s43, v155, -v173
	v_cvt_pk_bf16_f32 v156, v162, v163
	v_cvt_pk_bf16_f32 v157, v166, v167
	v_cvt_pk_bf16_f32 v158, v170, v171
	v_cvt_pk_bf16_f32 v159, v174, v175
	global_store_dwordx4 v3, v[156:159], s[10:11]
	v_add_u32_e32 v3, 0x2000, v3
	s_waitcnt vmcnt(31)
	v_lshlrev_b32_e32 v160, 16, v96
	v_and_b32_e32 v161, 0xffff0000, v96
	v_lshlrev_b32_e32 v162, 16, v80
	v_and_b32_e32 v163, 0xffff0000, v80
	v_lshlrev_b32_e32 v164, 16, v97
	v_and_b32_e32 v165, 0xffff0000, v97
	v_lshlrev_b32_e32 v166, 16, v81
	v_and_b32_e32 v167, 0xffff0000, v81
	v_lshlrev_b32_e32 v168, 16, v98
	v_and_b32_e32 v169, 0xffff0000, v98
	v_lshlrev_b32_e32 v170, 16, v82
	v_and_b32_e32 v171, 0xffff0000, v82
	v_lshlrev_b32_e32 v172, 16, v99
	v_and_b32_e32 v173, 0xffff0000, v99
	v_lshlrev_b32_e32 v174, 16, v83
	v_and_b32_e32 v175, 0xffff0000, v83
	v_pk_add_f32 v[162:163], v[160:161], v[162:163] neg_lo:[0,1] neg_hi:[0,1]
	v_pk_add_f32 v[166:167], v[164:165], v[166:167] neg_lo:[0,1] neg_hi:[0,1]
	v_pk_add_f32 v[170:171], v[168:169], v[170:171] neg_lo:[0,1] neg_hi:[0,1]
	v_pk_add_f32 v[174:175], v[172:173], v[174:175] neg_lo:[0,1] neg_hi:[0,1]
	v_pk_add_f32 v[148:149], v[148:149], v[162:163]
	v_pk_add_f32 v[150:151], v[150:151], v[166:167]
	v_pk_add_f32 v[152:153], v[152:153], v[170:171]
	v_pk_add_f32 v[154:155], v[154:155], v[174:175]
	v_fma_f32 v162, s43, v148, -v160
	v_fma_f32 v163, s43, v149, -v161
	v_fma_f32 v166, s43, v150, -v164
	v_fma_f32 v167, s43, v151, -v165
	v_fma_f32 v170, s43, v152, -v168
	v_fma_f32 v171, s43, v153, -v169
	v_fma_f32 v174, s43, v154, -v172
	v_fma_f32 v175, s43, v155, -v173
	v_cvt_pk_bf16_f32 v156, v162, v163
	v_cvt_pk_bf16_f32 v157, v166, v167
	v_cvt_pk_bf16_f32 v158, v170, v171
	v_cvt_pk_bf16_f32 v159, v174, v175
	global_store_dwordx4 v3, v[156:159], s[10:11]
	v_add_u32_e32 v3, 0x2000, v3
	s_waitcnt vmcnt(31)
; __device__ __forceinline__ unsigned cvt_pk_bf16(float lo, float hi) { unsigned r; asm volatile("v_cvt_pk_bf16_f32 %0, %1, %2" : "=v"(r) : "v"(lo), "v"(hi)); return r; }
; __device__ __forceinline__ float bf_lo(unsigned w) { return __uint_as_float(w << 16); }
; __device__ __forceinline__ float bf_hi(unsigned w) { return __uint_as_float(w & 0xffff0000u); }
; __device__ void phase_pool() {
;     ...
;         for (int r0 = 0; r0 < RB; r0 += 8) {
;             u32x4 vv[8], ov[8];
; #pragma unroll
;             for (int k = 0; k < 8; ++k) { const int row = row0 + r0 + k, tl = tl0 + r0 + k;
;                 vv[k] = *(const u32x4*)(uz + (size_t)row * DE2 + col);
;                 ov[k] = (tl >= w) ? *(const u32x4*)(uz + (size_t)(row - w) * DE2 + col) : (u32x4){0u, 0u, 0u, 0u}; }
; #pragma unroll
;             for (int k = 0; k < 8; ++k) { const int row = row0 + r0 + k, tl = tl0 + r0 + k; const u32x4 v = vv[k], o2 = ov[k];
;                 s[0] += bf_lo(v.x) - bf_lo(o2.x); s[1] += bf_hi(v.x) - bf_hi(o2.x); s[2] += bf_lo(v.y) - bf_lo(o2.y); s[3] += bf_hi(v.y) - bf_hi(o2.y);
;                 s[4] += bf_lo(v.z) - bf_lo(o2.z); s[5] += bf_hi(v.z) - bf_hi(o2.z); s[6] += bf_lo(v.w) - bf_lo(o2.w); s[7] += bf_hi(v.w) - bf_hi(o2.w);
;                 const float ic = 1.0f / (float)((tl + 1 < w) ? tl + 1 : w);
;                 u32x4 o;
;                 o.x = cvt_pk_bf16(s[0] * ic - bf_lo(v.x), s[1] * ic - bf_hi(v.x)); o.y = cvt_pk_bf16(s[2] * ic - bf_lo(v.y), s[3] * ic - bf_hi(v.y));
;                 o.z = cvt_pk_bf16(s[4] * ic - bf_lo(v.z), s[5] * ic - bf_hi(v.z)); o.w = cvt_pk_bf16(s[6] * ic - bf_lo(v.w), s[7] * ic - bf_hi(v.w));
;                 *(u32x4*)(pg + (size_t)row * DE + col) = o; }
	v_lshlrev_b32_e32 v160, 16, v100
	v_and_b32_e32 v161, 0xffff0000, v100
	v_lshlrev_b32_e32 v162, 16, v84
	v_and_b32_e32 v163, 0xffff0000, v84
	v_lshlrev_b32_e32 v164, 16, v101
	v_and_b32_e32 v165, 0xffff0000, v101
	v_lshlrev_b32_e32 v166, 16, v85
	v_and_b32_e32 v167, 0xffff0000, v85
	v_lshlrev_b32_e32 v168, 16, v102
	v_and_b32_e32 v169, 0xffff0000, v102
	v_lshlrev_b32_e32 v170, 16, v86
	v_and_b32_e32 v171, 0xffff0000, v86
	v_lshlrev_b32_e32 v172, 16, v103
	v_and_b32_e32 v173, 0xffff0000, v103
	v_lshlrev_b32_e32 v174, 16, v87
	v_and_b32_e32 v175, 0xffff0000, v87
	v_pk_add_f32 v[162:163], v[160:161], v[162:163] neg_lo:[0,1] neg_hi:[0,1]
	v_pk_add_f32 v[166:167], v[164:165], v[166:167] neg_lo:[0,1] neg_hi:[0,1]
	v_pk_add_f32 v[170:171], v[168:169], v[170:171] neg_lo:[0,1] neg_hi:[0,1]
	v_pk_add_f32 v[174:175], v[172:173], v[174:175] neg_lo:[0,1] neg_hi:[0,1]
	v_pk_add_f32 v[148:149], v[148:149], v[162:163]
	v_pk_add_f32 v[150:151], v[150:151], v[166:167]
	v_pk_add_f32 v[152:153], v[152:153], v[170:171]
	v_pk_add_f32 v[154:155], v[154:155], v[174:175]
	v_fma_f32 v162, s43, v148, -v160
	v_fma_f32 v163, s43, v149, -v161
	v_fma_f32 v166, s43, v150, -v164
	v_fma_f32 v167, s43, v151, -v165
	v_fma_f32 v170, s43, v152, -v168
	v_fma_f32 v171, s43, v153, -v169
	v_fma_f32 v174, s43, v154, -v172
	v_fma_f32 v175, s43, v155, -v173
	v_cvt_pk_bf16_f32 v156, v162, v163
	v_cvt_pk_bf16_f32 v157, v166, v167
	v_cvt_pk_bf16_f32 v158, v170, v171
	v_cvt_pk_bf16_f32 v159, v174, v175
	global_store_dwordx4 v3, v[156:159], s[10:11]
	v_add_u32_e32 v3, 0x2000, v3
	s_waitcnt vmcnt(31)
	v_lshlrev_b32_e32 v160, 16, v104
	v_and_b32_e32 v161, 0xffff0000, v104
	v_lshlrev_b32_e32 v162, 16, v88
	v_and_b32_e32 v163, 0xffff0000, v88
	v_lshlrev_b32_e32 v164, 16, v105
	v_and_b32_e32 v165, 0xffff0000, v105
	v_lshlrev_b32_e32 v166, 16, v89
	v_and_b32_e32 v167, 0xffff0000, v89
	v_lshlrev_b32_e32 v168, 16, v106
	v_and_b32_e32 v169, 0xffff0000, v106
	v_lshlrev_b32_e32 v170, 16, v90
	v_and_b32_e32 v171, 0xffff0000, v90
	v_lshlrev_b32_e32 v172, 16, v107
	v_and_b32_e32 v173, 0xffff0000, v107
	v_lshlrev_b32_e32 v174, 16, v91
	v_and_b32_e32 v175, 0xffff0000, v91
	v_pk_add_f32 v[162:163], v[160:161], v[162:163] neg_lo:[0,1] neg_hi:[0,1]
	v_pk_add_f32 v[166:167], v[164:165], v[166:167] neg_lo:[0,1] neg_hi:[0,1]
	v_pk_add_f32 v[170:171], v[168:169], v[170:171] neg_lo:[0,1] neg_hi:[0,1]
	v_pk_add_f32 v[174:175], v[172:173], v[174:175] neg_lo:[0,1] neg_hi:[0,1]
	v_pk_add_f32 v[148:149], v[148:149], v[162:163]
	v_pk_add_f32 v[150:151], v[150:151], v[166:167]
	v_pk_add_f32 v[152:153], v[152:153], v[170:171]
	v_pk_add_f32 v[154:155], v[154:155], v[174:175]
	v_fma_f32 v162, s43, v148, -v160
	v_fma_f32 v163, s43, v149, -v161
	v_fma_f32 v166, s43, v150, -v164
	v_fma_f32 v167, s43, v151, -v165
	v_fma_f32 v170, s43, v152, -v168
	v_fma_f32 v171, s43, v153, -v169
	v_fma_f32 v174, s43, v154, -v172
	v_fma_f32 v175, s43, v155, -v173
	v_cvt_pk_bf16_f32 v156, v162, v163
	v_cvt_pk_bf16_f32 v157, v166, v167
	v_cvt_pk_bf16_f32 v158, v170, v171
	v_cvt_pk_bf16_f32 v159, v174, v175
	global_store_dwordx4 v3, v[156:159], s[10:11]
	v_add_u32_e32 v3, 0x2000, v3
	s_waitcnt vmcnt(31)
	v_lshlrev_b32_e32 v160, 16, v108
	v_and_b32_e32 v161, 0xffff0000, v108
	v_lshlrev_b32_e32 v162, 16, v92
	v_and_b32_e32 v163, 0xffff0000, v92
	v_lshlrev_b32_e32 v164, 16, v109
	v_and_b32_e32 v165, 0xffff0000, v109
	v_lshlrev_b32_e32 v166, 16, v93
	v_and_b32_e32 v167, 0xffff0000, v93
	v_lshlrev_b32_e32 v168, 16, v110
	v_and_b32_e32 v169, 0xffff0000, v110
	v_lshlrev_b32_e32 v170, 16, v94
	v_and_b32_e32 v171, 0xffff0000, v94
	v_lshlrev_b32_e32 v172, 16, v111
	v_and_b32_e32 v173, 0xffff0000, v111
	v_lshlrev_b32_e32 v174, 16, v95
	v_and_b32_e32 v175, 0xffff0000, v95
	v_pk_add_f32 v[162:163], v[160:161], v[162:163] neg_lo:[0,1] neg_hi:[0,1]
	v_pk_add_f32 v[166:167], v[164:165], v[166:167] neg_lo:[0,1] neg_hi:[0,1]
	v_pk_add_f32 v[170:171], v[168:169], v[170:171] neg_lo:[0,1] neg_hi:[0,1]
	v_pk_add_f32 v[174:175], v[172:173], v[174:175] neg_lo:[0,1] neg_hi:[0,1]
	v_pk_add_f32 v[148:149], v[148:149], v[162:163]
	v_pk_add_f32 v[150:151], v[150:151], v[166:167]
	v_pk_add_f32 v[152:153], v[152:153], v[170:171]
	v_pk_add_f32 v[154:155], v[154:155], v[174:175]
	v_fma_f32 v162, s43, v148, -v160
	v_fma_f32 v163, s43, v149, -v161
	v_fma_f32 v166, s43, v150, -v164
	v_fma_f32 v167, s43, v151, -v165
	v_fma_f32 v170, s43, v152, -v168
	v_fma_f32 v171, s43, v153, -v169
	v_fma_f32 v174, s43, v154, -v172
	v_fma_f32 v175, s43, v155, -v173
	v_cvt_pk_bf16_f32 v156, v162, v163
	v_cvt_pk_bf16_f32 v157, v166, v167
	v_cvt_pk_bf16_f32 v158, v170, v171
	v_cvt_pk_bf16_f32 v159, v174, v175
	global_store_dwordx4 v3, v[156:159], s[10:11]
	v_add_u32_e32 v3, 0x2000, v3
	s_waitcnt vmcnt(31)
	v_lshlrev_b32_e32 v160, 16, v112
	v_and_b32_e32 v161, 0xffff0000, v112
	v_lshlrev_b32_e32 v162, 16, v96
	v_and_b32_e32 v163, 0xffff0000, v96
	v_lshlrev_b32_e32 v164, 16, v113
	v_and_b32_e32 v165, 0xffff0000, v113
	v_lshlrev_b32_e32 v166, 16, v97
	v_and_b32_e32 v167, 0xffff0000, v97
	v_lshlrev_b32_e32 v168, 16, v114
	v_and_b32_e32 v169, 0xffff0000, v114
	v_lshlrev_b32_e32 v170, 16, v98
	v_and_b32_e32 v171, 0xffff0000, v98
	v_lshlrev_b32_e32 v172, 16, v115
	v_and_b32_e32 v173, 0xffff0000, v115
	v_lshlrev_b32_e32 v174, 16, v99
	v_and_b32_e32 v175, 0xffff0000, v99
	v_pk_add_f32 v[162:163], v[160:161], v[162:163] neg_lo:[0,1] neg_hi:[0,1]
	v_pk_add_f32 v[166:167], v[164:165], v[166:167] neg_lo:[0,1] neg_hi:[0,1]
	v_pk_add_f32 v[170:171], v[168:169], v[170:171] neg_lo:[0,1] neg_hi:[0,1]
	v_pk_add_f32 v[174:175], v[172:173], v[174:175] neg_lo:[0,1] neg_hi:[0,1]
	v_pk_add_f32 v[148:149], v[148:149], v[162:163]
	v_pk_add_f32 v[150:151], v[150:151], v[166:167]
	v_pk_add_f32 v[152:153], v[152:153], v[170:171]
	v_pk_add_f32 v[154:155], v[154:155], v[174:175]
	v_fma_f32 v162, s43, v148, -v160
	v_fma_f32 v163, s43, v149, -v161
	v_fma_f32 v166, s43, v150, -v164
	v_fma_f32 v167, s43, v151, -v165
	v_fma_f32 v170, s43, v152, -v168
	v_fma_f32 v171, s43, v153, -v169
	v_fma_f32 v174, s43, v154, -v172
	v_fma_f32 v175, s43, v155, -v173
	v_cvt_pk_bf16_f32 v156, v162, v163
	v_cvt_pk_bf16_f32 v157, v166, v167
	v_cvt_pk_bf16_f32 v158, v170, v171
	v_cvt_pk_bf16_f32 v159, v174, v175
	global_store_dwordx4 v3, v[156:159], s[10:11]
	v_add_u32_e32 v3, 0x2000, v3
	s_waitcnt vmcnt(31)
; __device__ __forceinline__ unsigned cvt_pk_bf16(float lo, float hi) { unsigned r; asm volatile("v_cvt_pk_bf16_f32 %0, %1, %2" : "=v"(r) : "v"(lo), "v"(hi)); return r; }
; __device__ __forceinline__ float bf_lo(unsigned w) { return __uint_as_float(w << 16); }
; __device__ __forceinline__ float bf_hi(unsigned w) { return __uint_as_float(w & 0xffff0000u); }
; __device__ void phase_pool() {
;     ...
;         for (int r0 = 0; r0 < RB; r0 += 8) {
;             u32x4 vv[8], ov[8];
; #pragma unroll
;             for (int k = 0; k < 8; ++k) { const int row = row0 + r0 + k, tl = tl0 + r0 + k;
;                 vv[k] = *(const u32x4*)(uz + (size_t)row * DE2 + col);
;                 ov[k] = (tl >= w) ? *(const u32x4*)(uz + (size_t)(row - w) * DE2 + col) : (u32x4){0u, 0u, 0u, 0u}; }
; #pragma unroll
;             for (int k = 0; k < 8; ++k) { const int row = row0 + r0 + k, tl = tl0 + r0 + k; const u32x4 v = vv[k], o2 = ov[k];
;                 s[0] += bf_lo(v.x) - bf_lo(o2.x); s[1] += bf_hi(v.x) - bf_hi(o2.x); s[2] += bf_lo(v.y) - bf_lo(o2.y); s[3] += bf_hi(v.y) - bf_hi(o2.y);
;                 s[4] += bf_lo(v.z) - bf_lo(o2.z); s[5] += bf_hi(v.z) - bf_hi(o2.z); s[6] += bf_lo(v.w) - bf_lo(o2.w); s[7] += bf_hi(v.w) - bf_hi(o2.w);
;                 const float ic = 1.0f / (float)((tl + 1 < w) ? tl + 1 : w);
;                 u32x4 o;
;                 o.x = cvt_pk_bf16(s[0] * ic - bf_lo(v.x), s[1] * ic - bf_hi(v.x)); o.y = cvt_pk_bf16(s[2] * ic - bf_lo(v.y), s[3] * ic - bf_hi(v.y));
;                 o.z = cvt_pk_bf16(s[4] * ic - bf_lo(v.z), s[5] * ic - bf_hi(v.z)); o.w = cvt_pk_bf16(s[6] * ic - bf_lo(v.w), s[7] * ic - bf_hi(v.w));
;                 *(u32x4*)(pg + (size_t)row * DE + col) = o; }
	v_lshlrev_b32_e32 v160, 16, v116
	v_and_b32_e32 v161, 0xffff0000, v116
	v_lshlrev_b32_e32 v162, 16, v100
	v_and_b32_e32 v163, 0xffff0000, v100
	v_lshlrev_b32_e32 v164, 16, v117
	v_and_b32_e32 v165, 0xffff0000, v117
	v_lshlrev_b32_e32 v166, 16, v101
	v_and_b32_e32 v167, 0xffff0000, v101
	v_lshlrev_b32_e32 v168, 16, v118
	v_and_b32_e32 v169, 0xffff0000, v118
	v_lshlrev_b32_e32 v170, 16, v102
	v_and_b32_e32 v171, 0xffff0000, v102
	v_lshlrev_b32_e32 v172, 16, v119
	v_and_b32_e32 v173, 0xffff0000, v119
	v_lshlrev_b32_e32 v174, 16, v103
	v_and_b32_e32 v175, 0xffff0000, v103
	v_pk_add_f32 v[162:163], v[160:161], v[162:163] neg_lo:[0,1] neg_hi:[0,1]
	v_pk_add_f32 v[166:167], v[164:165], v[166:167] neg_lo:[0,1] neg_hi:[0,1]
	v_pk_add_f32 v[170:171], v[168:169], v[170:171] neg_lo:[0,1] neg_hi:[0,1]
	v_pk_add_f32 v[174:175], v[172:173], v[174:175] neg_lo:[0,1] neg_hi:[0,1]
	v_pk_add_f32 v[148:149], v[148:149], v[162:163]
	v_pk_add_f32 v[150:151], v[150:151], v[166:167]
	v_pk_add_f32 v[152:153], v[152:153], v[170:171]
	v_pk_add_f32 v[154:155], v[154:155], v[174:175]
	v_fma_f32 v162, s43, v148, -v160
	v_fma_f32 v163, s43, v149, -v161
	v_fma_f32 v166, s43, v150, -v164
	v_fma_f32 v167, s43, v151, -v165
	v_fma_f32 v170, s43, v152, -v168
	v_fma_f32 v171, s43, v153, -v169
	v_fma_f32 v174, s43, v154, -v172
	v_fma_f32 v175, s43, v155, -v173
	v_cvt_pk_bf16_f32 v156, v162, v163
	v_cvt_pk_bf16_f32 v157, v166, v167
	v_cvt_pk_bf16_f32 v158, v170, v171
	v_cvt_pk_bf16_f32 v159, v174, v175
	global_store_dwordx4 v3, v[156:159], s[10:11]
	v_add_u32_e32 v3, 0x2000, v3
	s_waitcnt vmcnt(31)
	v_lshlrev_b32_e32 v160, 16, v120
	v_and_b32_e32 v161, 0xffff0000, v120
	v_lshlrev_b32_e32 v162, 16, v104
	v_and_b32_e32 v163, 0xffff0000, v104
	v_lshlrev_b32_e32 v164, 16, v121
	v_and_b32_e32 v165, 0xffff0000, v121
	v_lshlrev_b32_e32 v166, 16, v105
	v_and_b32_e32 v167, 0xffff0000, v105
	v_lshlrev_b32_e32 v168, 16, v122
	v_and_b32_e32 v169, 0xffff0000, v122
	v_lshlrev_b32_e32 v170, 16, v106
	v_and_b32_e32 v171, 0xffff0000, v106
	v_lshlrev_b32_e32 v172, 16, v123
	v_and_b32_e32 v173, 0xffff0000, v123
	v_lshlrev_b32_e32 v174, 16, v107
	v_and_b32_e32 v175, 0xffff0000, v107
	v_pk_add_f32 v[162:163], v[160:161], v[162:163] neg_lo:[0,1] neg_hi:[0,1]
	v_pk_add_f32 v[166:167], v[164:165], v[166:167] neg_lo:[0,1] neg_hi:[0,1]
	v_pk_add_f32 v[170:171], v[168:169], v[170:171] neg_lo:[0,1] neg_hi:[0,1]
	v_pk_add_f32 v[174:175], v[172:173], v[174:175] neg_lo:[0,1] neg_hi:[0,1]
	v_pk_add_f32 v[148:149], v[148:149], v[162:163]
	v_pk_add_f32 v[150:151], v[150:151], v[166:167]
	v_pk_add_f32 v[152:153], v[152:153], v[170:171]
	v_pk_add_f32 v[154:155], v[154:155], v[174:175]
	v_fma_f32 v162, s43, v148, -v160
	v_fma_f32 v163, s43, v149, -v161
	v_fma_f32 v166, s43, v150, -v164
	v_fma_f32 v167, s43, v151, -v165
	v_fma_f32 v170, s43, v152, -v168
	v_fma_f32 v171, s43, v153, -v169
	v_fma_f32 v174, s43, v154, -v172
	v_fma_f32 v175, s43, v155, -v173
	v_cvt_pk_bf16_f32 v156, v162, v163
	v_cvt_pk_bf16_f32 v157, v166, v167
	v_cvt_pk_bf16_f32 v158, v170, v171
	v_cvt_pk_bf16_f32 v159, v174, v175
	global_store_dwordx4 v3, v[156:159], s[10:11]
	v_add_u32_e32 v3, 0x2000, v3
	s_waitcnt vmcnt(31)
	v_lshlrev_b32_e32 v160, 16, v124
	v_and_b32_e32 v161, 0xffff0000, v124
	v_lshlrev_b32_e32 v162, 16, v108
	v_and_b32_e32 v163, 0xffff0000, v108
	v_lshlrev_b32_e32 v164, 16, v125
	v_and_b32_e32 v165, 0xffff0000, v125
	v_lshlrev_b32_e32 v166, 16, v109
	v_and_b32_e32 v167, 0xffff0000, v109
	v_lshlrev_b32_e32 v168, 16, v126
	v_and_b32_e32 v169, 0xffff0000, v126
	v_lshlrev_b32_e32 v170, 16, v110
	v_and_b32_e32 v171, 0xffff0000, v110
	v_lshlrev_b32_e32 v172, 16, v127
	v_and_b32_e32 v173, 0xffff0000, v127
	v_lshlrev_b32_e32 v174, 16, v111
	v_and_b32_e32 v175, 0xffff0000, v111
	v_pk_add_f32 v[162:163], v[160:161], v[162:163] neg_lo:[0,1] neg_hi:[0,1]
	v_pk_add_f32 v[166:167], v[164:165], v[166:167] neg_lo:[0,1] neg_hi:[0,1]
	v_pk_add_f32 v[170:171], v[168:169], v[170:171] neg_lo:[0,1] neg_hi:[0,1]
	v_pk_add_f32 v[174:175], v[172:173], v[174:175] neg_lo:[0,1] neg_hi:[0,1]
	v_pk_add_f32 v[148:149], v[148:149], v[162:163]
	v_pk_add_f32 v[150:151], v[150:151], v[166:167]
	v_pk_add_f32 v[152:153], v[152:153], v[170:171]
	v_pk_add_f32 v[154:155], v[154:155], v[174:175]
	v_fma_f32 v162, s43, v148, -v160
	v_fma_f32 v163, s43, v149, -v161
	v_fma_f32 v166, s43, v150, -v164
	v_fma_f32 v167, s43, v151, -v165
	v_fma_f32 v170, s43, v152, -v168
	v_fma_f32 v171, s43, v153, -v169
	v_fma_f32 v174, s43, v154, -v172
	v_fma_f32 v175, s43, v155, -v173
	v_cvt_pk_bf16_f32 v156, v162, v163
	v_cvt_pk_bf16_f32 v157, v166, v167
	v_cvt_pk_bf16_f32 v158, v170, v171
	v_cvt_pk_bf16_f32 v159, v174, v175
	global_store_dwordx4 v3, v[156:159], s[10:11]
	v_add_u32_e32 v3, 0x2000, v3
	s_waitcnt vmcnt(31)
	v_lshlrev_b32_e32 v160, 16, v128
	v_and_b32_e32 v161, 0xffff0000, v128
	v_lshlrev_b32_e32 v162, 16, v112
	v_and_b32_e32 v163, 0xffff0000, v112
	v_lshlrev_b32_e32 v164, 16, v129
	v_and_b32_e32 v165, 0xffff0000, v129
	v_lshlrev_b32_e32 v166, 16, v113
	v_and_b32_e32 v167, 0xffff0000, v113
	v_lshlrev_b32_e32 v168, 16, v130
	v_and_b32_e32 v169, 0xffff0000, v130
	v_lshlrev_b32_e32 v170, 16, v114
	v_and_b32_e32 v171, 0xffff0000, v114
	v_lshlrev_b32_e32 v172, 16, v131
	v_and_b32_e32 v173, 0xffff0000, v131
	v_lshlrev_b32_e32 v174, 16, v115
	v_and_b32_e32 v175, 0xffff0000, v115
	v_pk_add_f32 v[162:163], v[160:161], v[162:163] neg_lo:[0,1] neg_hi:[0,1]
	v_pk_add_f32 v[166:167], v[164:165], v[166:167] neg_lo:[0,1] neg_hi:[0,1]
	v_pk_add_f32 v[170:171], v[168:169], v[170:171] neg_lo:[0,1] neg_hi:[0,1]
	v_pk_add_f32 v[174:175], v[172:173], v[174:175] neg_lo:[0,1] neg_hi:[0,1]
	v_pk_add_f32 v[148:149], v[148:149], v[162:163]
	v_pk_add_f32 v[150:151], v[150:151], v[166:167]
	v_pk_add_f32 v[152:153], v[152:153], v[170:171]
	v_pk_add_f32 v[154:155], v[154:155], v[174:175]
	v_fma_f32 v162, s43, v148, -v160
	v_fma_f32 v163, s43, v149, -v161
	v_fma_f32 v166, s43, v150, -v164
	v_fma_f32 v167, s43, v151, -v165
	v_fma_f32 v170, s43, v152, -v168
	v_fma_f32 v171, s43, v153, -v169
	v_fma_f32 v174, s43, v154, -v172
	v_fma_f32 v175, s43, v155, -v173
	v_cvt_pk_bf16_f32 v156, v162, v163
	v_cvt_pk_bf16_f32 v157, v166, v167
	v_cvt_pk_bf16_f32 v158, v170, v171
	v_cvt_pk_bf16_f32 v159, v174, v175
	global_store_dwordx4 v3, v[156:159], s[10:11]
	v_add_u32_e32 v3, 0x2000, v3
	s_waitcnt vmcnt(31)
; __device__ __forceinline__ unsigned cvt_pk_bf16(float lo, float hi) { unsigned r; asm volatile("v_cvt_pk_bf16_f32 %0, %1, %2" : "=v"(r) : "v"(lo), "v"(hi)); return r; }
; __device__ __forceinline__ float bf_lo(unsigned w) { return __uint_as_float(w << 16); }
; __device__ __forceinline__ float bf_hi(unsigned w) { return __uint_as_float(w & 0xffff0000u); }
; __device__ void phase_pool() {
;     ...
;             for (int k = 0; k < 8; ++k) { const int row = row0 + r0 + k, tl = tl0 + r0 + k; const u32x4 v = vv[k], o2 = ov[k];
;                 s[0] += bf_lo(v.x) - bf_lo(o2.x); s[1] += bf_hi(v.x) - bf_hi(o2.x); s[2] += bf_lo(v.y) - bf_lo(o2.y); s[3] += bf_hi(v.y) - bf_hi(o2.y);
;                 s[4] += bf_lo(v.z) - bf_lo(o2.z); s[5] += bf_hi(v.z) - bf_hi(o2.z); s[6] += bf_lo(v.w) - bf_lo(o2.w); s[7] += bf_hi(v.w) - bf_hi(o2.w);
;                 const float ic = 1.0f / (float)((tl + 1 < w) ? tl + 1 : w);
;                 u32x4 o;
;                 o.x = cvt_pk_bf16(s[0] * ic - bf_lo(v.x), s[1] * ic - bf_hi(v.x)); o.y = cvt_pk_bf16(s[2] * ic - bf_lo(v.y), s[3] * ic - bf_hi(v.y));
;                 o.z = cvt_pk_bf16(s[4] * ic - bf_lo(v.z), s[5] * ic - bf_hi(v.z)); o.w = cvt_pk_bf16(s[6] * ic - bf_lo(v.w), s[7] * ic - bf_hi(v.w));
;                 *(u32x4*)(pg + (size_t)row * DE + col) = o; }
	v_lshlrev_b32_e32 v160, 16, v132
	v_and_b32_e32 v161, 0xffff0000, v132
	v_lshlrev_b32_e32 v162, 16, v116
	v_and_b32_e32 v163, 0xffff0000, v116
	v_lshlrev_b32_e32 v164, 16, v133
	v_and_b32_e32 v165, 0xffff0000, v133
	v_lshlrev_b32_e32 v166, 16, v117
	v_and_b32_e32 v167, 0xffff0000, v117
	v_lshlrev_b32_e32 v168, 16, v134
	v_and_b32_e32 v169, 0xffff0000, v134
	v_lshlrev_b32_e32 v170, 16, v118
	v_and_b32_e32 v171, 0xffff0000, v118
	v_lshlrev_b32_e32 v172, 16, v135
	v_and_b32_e32 v173, 0xffff0000, v135
	v_lshlrev_b32_e32 v174, 16, v119
	v_and_b32_e32 v175, 0xffff0000, v119
	v_pk_add_f32 v[162:163], v[160:161], v[162:163] neg_lo:[0,1] neg_hi:[0,1]
	v_pk_add_f32 v[166:167], v[164:165], v[166:167] neg_lo:[0,1] neg_hi:[0,1]
	v_pk_add_f32 v[170:171], v[168:169], v[170:171] neg_lo:[0,1] neg_hi:[0,1]
	v_pk_add_f32 v[174:175], v[172:173], v[174:175] neg_lo:[0,1] neg_hi:[0,1]
	v_pk_add_f32 v[148:149], v[148:149], v[162:163]
	v_pk_add_f32 v[150:151], v[150:151], v[166:167]
	v_pk_add_f32 v[152:153], v[152:153], v[170:171]
	v_pk_add_f32 v[154:155], v[154:155], v[174:175]
	v_fma_f32 v162, s43, v148, -v160
	v_fma_f32 v163, s43, v149, -v161
	v_fma_f32 v166, s43, v150, -v164
	v_fma_f32 v167, s43, v151, -v165
	v_fma_f32 v170, s43, v152, -v168
	v_fma_f32 v171, s43, v153, -v169
	v_fma_f32 v174, s43, v154, -v172
	v_fma_f32 v175, s43, v155, -v173
	v_cvt_pk_bf16_f32 v156, v162, v163
	v_cvt_pk_bf16_f32 v157, v166, v167
	v_cvt_pk_bf16_f32 v158, v170, v171
	v_cvt_pk_bf16_f32 v159, v174, v175
	global_store_dwordx4 v3, v[156:159], s[10:11]
	v_add_u32_e32 v3, 0x2000, v3
	s_waitcnt vmcnt(31)
	v_lshlrev_b32_e32 v160, 16, v136
	v_and_b32_e32 v161, 0xffff0000, v136
	v_lshlrev_b32_e32 v162, 16, v120
	v_and_b32_e32 v163, 0xffff0000, v120
	v_lshlrev_b32_e32 v164, 16, v137
	v_and_b32_e32 v165, 0xffff0000, v137
	v_lshlrev_b32_e32 v166, 16, v121
	v_and_b32_e32 v167, 0xffff0000, v121
	v_lshlrev_b32_e32 v168, 16, v138
	v_and_b32_e32 v169, 0xffff0000, v138
	v_lshlrev_b32_e32 v170, 16, v122
	v_and_b32_e32 v171, 0xffff0000, v122
	v_lshlrev_b32_e32 v172, 16, v139
	v_and_b32_e32 v173, 0xffff0000, v139
	v_lshlrev_b32_e32 v174, 16, v123
	v_and_b32_e32 v175, 0xffff0000, v123
	v_pk_add_f32 v[162:163], v[160:161], v[162:163] neg_lo:[0,1] neg_hi:[0,1]
	v_pk_add_f32 v[166:167], v[164:165], v[166:167] neg_lo:[0,1] neg_hi:[0,1]
	v_pk_add_f32 v[170:171], v[168:169], v[170:171] neg_lo:[0,1] neg_hi:[0,1]
	v_pk_add_f32 v[174:175], v[172:173], v[174:175] neg_lo:[0,1] neg_hi:[0,1]
	v_pk_add_f32 v[148:149], v[148:149], v[162:163]
	v_pk_add_f32 v[150:151], v[150:151], v[166:167]
	v_pk_add_f32 v[152:153], v[152:153], v[170:171]
	v_pk_add_f32 v[154:155], v[154:155], v[174:175]
	v_fma_f32 v162, s43, v148, -v160
	v_fma_f32 v163, s43, v149, -v161
	v_fma_f32 v166, s43, v150, -v164
	v_fma_f32 v167, s43, v151, -v165
	v_fma_f32 v170, s43, v152, -v168
	v_fma_f32 v171, s43, v153, -v169
	v_fma_f32 v174, s43, v154, -v172
	v_fma_f32 v175, s43, v155, -v173
	v_cvt_pk_bf16_f32 v156, v162, v163
	v_cvt_pk_bf16_f32 v157, v166, v167
	v_cvt_pk_bf16_f32 v158, v170, v171
	v_cvt_pk_bf16_f32 v159, v174, v175
	global_store_dwordx4 v3, v[156:159], s[10:11]
	v_add_u32_e32 v3, 0x2000, v3
	s_waitcnt vmcnt(31)
	v_lshlrev_b32_e32 v160, 16, v140
	v_and_b32_e32 v161, 0xffff0000, v140
	v_lshlrev_b32_e32 v162, 16, v124
	v_and_b32_e32 v163, 0xffff0000, v124
	v_lshlrev_b32_e32 v164, 16, v141
	v_and_b32_e32 v165, 0xffff0000, v141
	v_lshlrev_b32_e32 v166, 16, v125
	v_and_b32_e32 v167, 0xffff0000, v125
	v_lshlrev_b32_e32 v168, 16, v142
	v_and_b32_e32 v169, 0xffff0000, v142
	v_lshlrev_b32_e32 v170, 16, v126
	v_and_b32_e32 v171, 0xffff0000, v126
	v_lshlrev_b32_e32 v172, 16, v143
	v_and_b32_e32 v173, 0xffff0000, v143
	v_lshlrev_b32_e32 v174, 16, v127
	v_and_b32_e32 v175, 0xffff0000, v127
	v_pk_add_f32 v[162:163], v[160:161], v[162:163] neg_lo:[0,1] neg_hi:[0,1]
	v_pk_add_f32 v[166:167], v[164:165], v[166:167] neg_lo:[0,1] neg_hi:[0,1]
	v_pk_add_f32 v[170:171], v[168:169], v[170:171] neg_lo:[0,1] neg_hi:[0,1]
	v_pk_add_f32 v[174:175], v[172:173], v[174:175] neg_lo:[0,1] neg_hi:[0,1]
	v_pk_add_f32 v[148:149], v[148:149], v[162:163]
	v_pk_add_f32 v[150:151], v[150:151], v[166:167]
	v_pk_add_f32 v[152:153], v[152:153], v[170:171]
	v_pk_add_f32 v[154:155], v[154:155], v[174:175]
	v_fma_f32 v162, s43, v148, -v160
	v_fma_f32 v163, s43, v149, -v161
	v_fma_f32 v166, s43, v150, -v164
	v_fma_f32 v167, s43, v151, -v165
	v_fma_f32 v170, s43, v152, -v168
	v_fma_f32 v171, s43, v153, -v169
	v_fma_f32 v174, s43, v154, -v172
	v_fma_f32 v175, s43, v155, -v173
	v_cvt_pk_bf16_f32 v156, v162, v163
	v_cvt_pk_bf16_f32 v157, v166, v167
	v_cvt_pk_bf16_f32 v158, v170, v171
	v_cvt_pk_bf16_f32 v159, v174, v175
	global_store_dwordx4 v3, v[156:159], s[10:11]
	v_add_u32_e32 v3, 0x2000, v3
	s_waitcnt vmcnt(31)
	v_lshlrev_b32_e32 v160, 16, v144
	v_and_b32_e32 v161, 0xffff0000, v144
	v_lshlrev_b32_e32 v162, 16, v128
	v_and_b32_e32 v163, 0xffff0000, v128
	v_lshlrev_b32_e32 v164, 16, v145
	v_and_b32_e32 v165, 0xffff0000, v145
	v_lshlrev_b32_e32 v166, 16, v129
	v_and_b32_e32 v167, 0xffff0000, v129
	v_lshlrev_b32_e32 v168, 16, v146
	v_and_b32_e32 v169, 0xffff0000, v146
	v_lshlrev_b32_e32 v170, 16, v130
	v_and_b32_e32 v171, 0xffff0000, v130
	v_lshlrev_b32_e32 v172, 16, v147
	v_and_b32_e32 v173, 0xffff0000, v147
	v_lshlrev_b32_e32 v174, 16, v131
	v_and_b32_e32 v175, 0xffff0000, v131
	v_pk_add_f32 v[162:163], v[160:161], v[162:163] neg_lo:[0,1] neg_hi:[0,1]
	v_pk_add_f32 v[166:167], v[164:165], v[166:167] neg_lo:[0,1] neg_hi:[0,1]
	v_pk_add_f32 v[170:171], v[168:169], v[170:171] neg_lo:[0,1] neg_hi:[0,1]
	v_pk_add_f32 v[174:175], v[172:173], v[174:175] neg_lo:[0,1] neg_hi:[0,1]
	v_pk_add_f32 v[148:149], v[148:149], v[162:163]
	v_pk_add_f32 v[150:151], v[150:151], v[166:167]
	v_pk_add_f32 v[152:153], v[152:153], v[170:171]
	v_pk_add_f32 v[154:155], v[154:155], v[174:175]
	v_fma_f32 v162, s43, v148, -v160
	v_fma_f32 v163, s43, v149, -v161
	v_fma_f32 v166, s43, v150, -v164
	v_fma_f32 v167, s43, v151, -v165
	v_fma_f32 v170, s43, v152, -v168
	v_fma_f32 v171, s43, v153, -v169
	v_fma_f32 v174, s43, v154, -v172
	v_fma_f32 v175, s43, v155, -v173
	v_cvt_pk_bf16_f32 v156, v162, v163
	v_cvt_pk_bf16_f32 v157, v166, v167
	v_cvt_pk_bf16_f32 v158, v170, v171
	v_cvt_pk_bf16_f32 v159, v174, v175
	global_store_dwordx4 v3, v[156:159], s[10:11]
	s_branch .LBB0_441
; __device__ __forceinline__ float bf_lo(unsigned w) { return __uint_as_float(w << 16); }
; __device__ __forceinline__ float bf_hi(unsigned w) { return __uint_as_float(w & 0xffff0000u); }
; __device__ void phase_pool() {
;     ...
;         const int nh = (tl0 < w) ? tl0 : w;
;         { u32x4 hv[16];
; #pragma unroll
;           for (int k = 1; k <= 16; ++k) hv[k - 1] = (k <= nh) ? *(const u32x4*)(uz + (size_t)(row0 - k) * DE2 + col) : (u32x4){0u, 0u, 0u, 0u};
; #pragma unroll
;           for (int k = 0; k < 16; ++k) { const u32x4 v = hv[k];
;             s[0] += bf_lo(v.x); s[1] += bf_hi(v.x); s[2] += bf_lo(v.y); s[3] += bf_hi(v.y); s[4] += bf_lo(v.z); s[5] += bf_hi(v.z); s[6] += bf_lo(v.w); s[7] += bf_hi(v.w); } }
; #pragma unroll 1
;         for (int r0 = 0; r0 < RB; r0 += 8) {
;             u32x4 vv[8], ov[8];
; #pragma unroll
;             for (int k = 0; k < 8; ++k) { const int row = row0 + r0 + k, tl = tl0 + r0 + k;
;                 vv[k] = *(const u32x4*)(uz + (size_t)row * DE2 + col);
;                 ov[k] = (tl >= w) ? *(const u32x4*)(uz + (size_t)(row - w) * DE2 + col) : (u32x4){0u, 0u, 0u, 0u}; }
.Lpool_w8:
	s_cmp_eq_u32 s16, 0
	s_cbranch_scc1 .Lpool_w8_nohist
	s_sub_u32 s0, s15, 8
	s_lshl_b32 s0, s0, 14
	s_add_u32 s8, s4, s0
	s_addc_u32 s9, s5, 0
	global_load_dwordx4 v[4:7], v2, s[8:9]
	v_add_u32_e32 v2, 0x4000, v2
	global_load_dwordx4 v[8:11], v2, s[8:9]
	v_add_u32_e32 v2, 0x4000, v2
	global_load_dwordx4 v[12:15], v2, s[8:9]
	v_add_u32_e32 v2, 0x4000, v2
	global_load_dwordx4 v[16:19], v2, s[8:9]
	v_add_u32_e32 v2, 0x4000, v2
	global_load_dwordx4 v[20:23], v2, s[8:9]
	v_add_u32_e32 v2, 0x4000, v2
	global_load_dwordx4 v[24:27], v2, s[8:9]
	v_add_u32_e32 v2, 0x4000, v2
	global_load_dwordx4 v[28:31], v2, s[8:9]
	v_add_u32_e32 v2, 0x4000, v2
	global_load_dwordx4 v[32:35], v2, s[8:9]
	v_add_u32_e32 v2, 0x4000, v2
	s_branch .Lpool_w8_main
.Lpool_w8_nohist:
	v_mov_b32_e32 v4, 0
	v_mov_b32_e32 v5, 0
	v_mov_b32_e32 v6, 0
	v_mov_b32_e32 v7, 0
	v_mov_b32_e32 v8, 0
	v_mov_b32_e32 v9, 0
	v_mov_b32_e32 v10, 0
	v_mov_b32_e32 v11, 0
	v_mov_b32_e32 v12, 0
	v_mov_b32_e32 v13, 0
	v_mov_b32_e32 v14, 0
	v_mov_b32_e32 v15, 0
	v_mov_b32_e32 v16, 0
	v_mov_b32_e32 v17, 0
	v_mov_b32_e32 v18, 0
	v_mov_b32_e32 v19, 0
	v_mov_b32_e32 v20, 0
	v_mov_b32_e32 v21, 0
	v_mov_b32_e32 v22, 0
	v_mov_b32_e32 v23, 0
	v_mov_b32_e32 v24, 0
	v_mov_b32_e32 v25, 0
	v_mov_b32_e32 v26, 0
	v_mov_b32_e32 v27, 0
	v_mov_b32_e32 v28, 0
	v_mov_b32_e32 v29, 0
	v_mov_b32_e32 v30, 0
	v_mov_b32_e32 v31, 0
	v_mov_b32_e32 v32, 0
	v_mov_b32_e32 v33, 0
	v_mov_b32_e32 v34, 0
	v_mov_b32_e32 v35, 0
	s_lshl_b32 s0, s15, 14
	s_add_u32 s8, s4, s0
	s_addc_u32 s9, s5, 0
.Lpool_w8_main:
	global_load_dwordx4 v[36:39], v2, s[8:9]
	v_add_u32_e32 v2, 0x4000, v2
	global_load_dwordx4 v[40:43], v2, s[8:9]
	v_add_u32_e32 v2, 0x4000, v2
	global_load_dwordx4 v[44:47], v2, s[8:9]
	v_add_u32_e32 v2, 0x4000, v2
	global_load_dwordx4 v[48:51], v2, s[8:9]
	v_add_u32_e32 v2, 0x4000, v2
	global_load_dwordx4 v[52:55], v2, s[8:9]
	v_add_u32_e32 v2, 0x4000, v2
	global_load_dwordx4 v[56:59], v2, s[8:9]
	v_add_u32_e32 v2, 0x4000, v2
	global_load_dwordx4 v[60:63], v2, s[8:9]
	v_add_u32_e32 v2, 0x4000, v2
	global_load_dwordx4 v[64:67], v2, s[8:9]
	v_add_u32_e32 v2, 0x4000, v2
	global_load_dwordx4 v[68:71], v2, s[8:9]
	v_add_u32_e32 v2, 0x4000, v2
	global_load_dwordx4 v[72:75], v2, s[8:9]
	v_add_u32_e32 v2, 0x4000, v2
	global_load_dwordx4 v[76:79], v2, s[8:9]
	v_add_u32_e32 v2, 0x4000, v2
	global_load_dwordx4 v[80:83], v2, s[8:9]
	v_add_u32_e32 v2, 0x4000, v2
	global_load_dwordx4 v[84:87], v2, s[8:9]
	v_add_u32_e32 v2, 0x4000, v2
	global_load_dwordx4 v[88:91], v2, s[8:9]
	v_add_u32_e32 v2, 0x4000, v2
	global_load_dwordx4 v[92:95], v2, s[8:9]
	v_add_u32_e32 v2, 0x4000, v2
	global_load_dwordx4 v[96:99], v2, s[8:9]
	v_add_u32_e32 v2, 0x4000, v2
	global_load_dwordx4 v[100:103], v2, s[8:9]
	v_add_u32_e32 v2, 0x4000, v2
	global_load_dwordx4 v[104:107], v2, s[8:9]
	v_add_u32_e32 v2, 0x4000, v2
	global_load_dwordx4 v[108:111], v2, s[8:9]
	v_add_u32_e32 v2, 0x4000, v2
	global_load_dwordx4 v[112:115], v2, s[8:9]
	v_add_u32_e32 v2, 0x4000, v2
	global_load_dwordx4 v[116:119], v2, s[8:9]
	v_add_u32_e32 v2, 0x4000, v2
	global_load_dwordx4 v[120:123], v2, s[8:9]
	v_add_u32_e32 v2, 0x4000, v2
	global_load_dwordx4 v[124:127], v2, s[8:9]
	v_add_u32_e32 v2, 0x4000, v2
	global_load_dwordx4 v[128:131], v2, s[8:9]
	v_add_u32_e32 v2, 0x4000, v2
	global_load_dwordx4 v[132:135], v2, s[8:9]
	v_add_u32_e32 v2, 0x4000, v2
	global_load_dwordx4 v[136:139], v2, s[8:9]
	v_add_u32_e32 v2, 0x4000, v2
	global_load_dwordx4 v[140:143], v2, s[8:9]
	v_add_u32_e32 v2, 0x4000, v2
	global_load_dwordx4 v[144:147], v2, s[8:9]
	v_add_u32_e32 v2, 0x4000, v2
	global_load_dwordx4 v[148:151], v2, s[8:9]
	v_add_u32_e32 v2, 0x4000, v2
	global_load_dwordx4 v[152:155], v2, s[8:9]
	v_add_u32_e32 v2, 0x4000, v2
	global_load_dwordx4 v[156:159], v2, s[8:9]
	v_add_u32_e32 v2, 0x4000, v2
	global_load_dwordx4 v[160:163], v2, s[8:9]
	v_mov_b32_e32 v164, 0
	v_mov_b32_e32 v165, 0
	v_mov_b32_e32 v166, 0
	v_mov_b32_e32 v167, 0
	v_mov_b32_e32 v168, 0
	v_mov_b32_e32 v169, 0
	v_mov_b32_e32 v170, 0
	v_mov_b32_e32 v171, 0
	s_mov_b32 s43, 0x3e000000
	s_cmp_eq_u32 s16, 0
	s_waitcnt vmcnt(32)
	v_lshlrev_b32_e32 v184, 16, v32
	v_and_b32_e32 v185, 0xffff0000, v32
	v_lshlrev_b32_e32 v188, 16, v33
	v_and_b32_e32 v189, 0xffff0000, v33
	v_lshlrev_b32_e32 v192, 16, v34
	v_and_b32_e32 v193, 0xffff0000, v34
	v_lshlrev_b32_e32 v196, 16, v35
	v_and_b32_e32 v197, 0xffff0000, v35
	v_pk_add_f32 v[164:165], v[164:165], v[184:185]
	v_pk_add_f32 v[166:167], v[166:167], v[188:189]
	v_pk_add_f32 v[168:169], v[168:169], v[192:193]
	v_pk_add_f32 v[170:171], v[170:171], v[196:197]
	v_lshlrev_b32_e32 v184, 16, v28
	v_and_b32_e32 v185, 0xffff0000, v28
	v_lshlrev_b32_e32 v188, 16, v29
	v_and_b32_e32 v189, 0xffff0000, v29
	v_lshlrev_b32_e32 v192, 16, v30
	v_and_b32_e32 v193, 0xffff0000, v30
	v_lshlrev_b32_e32 v196, 16, v31
	v_and_b32_e32 v197, 0xffff0000, v31
	v_pk_add_f32 v[164:165], v[164:165], v[184:185]
	v_pk_add_f32 v[166:167], v[166:167], v[188:189]
	v_pk_add_f32 v[168:169], v[168:169], v[192:193]
	v_pk_add_f32 v[170:171], v[170:171], v[196:197]
	v_lshlrev_b32_e32 v184, 16, v24
	v_and_b32_e32 v185, 0xffff0000, v24
	v_lshlrev_b32_e32 v188, 16, v25
	v_and_b32_e32 v189, 0xffff0000, v25
	v_lshlrev_b32_e32 v192, 16, v26
	v_and_b32_e32 v193, 0xffff0000, v26
	v_lshlrev_b32_e32 v196, 16, v27
	v_and_b32_e32 v197, 0xffff0000, v27
	v_pk_add_f32 v[164:165], v[164:165], v[184:185]
	v_pk_add_f32 v[166:167], v[166:167], v[188:189]
	v_pk_add_f32 v[168:169], v[168:169], v[192:193]
	v_pk_add_f32 v[170:171], v[170:171], v[196:197]
	v_lshlrev_b32_e32 v184, 16, v20
	v_and_b32_e32 v185, 0xffff0000, v20
	v_lshlrev_b32_e32 v188, 16, v21
; __device__ __forceinline__ unsigned cvt_pk_bf16(float lo, float hi) { unsigned r; asm volatile("v_cvt_pk_bf16_f32 %0, %1, %2" : "=v"(r) : "v"(lo), "v"(hi)); return r; }
; __device__ __forceinline__ float bf_lo(unsigned w) { return __uint_as_float(w << 16); }
; __device__ __forceinline__ float bf_hi(unsigned w) { return __uint_as_float(w & 0xffff0000u); }
; __device__ void phase_pool() {
;     ...
;           for (int k = 1; k <= 16; ++k) hv[k - 1] = (k <= nh) ? *(const u32x4*)(uz + (size_t)(row0 - k) * DE2 + col) : (u32x4){0u, 0u, 0u, 0u};
; #pragma unroll
;           for (int k = 0; k < 16; ++k) { const u32x4 v = hv[k];
;             s[0] += bf_lo(v.x); s[1] += bf_hi(v.x); s[2] += bf_lo(v.y); s[3] += bf_hi(v.y); s[4] += bf_lo(v.z); s[5] += bf_hi(v.z); s[6] += bf_lo(v.w); s[7] += bf_hi(v.w); } }
; #pragma unroll 1
;         for (int r0 = 0; r0 < RB; r0 += 8) {
;             u32x4 vv[8], ov[8];
; #pragma unroll
;             for (int k = 0; k < 8; ++k) { const int row = row0 + r0 + k, tl = tl0 + r0 + k;
;                 vv[k] = *(const u32x4*)(uz + (size_t)row * DE2 + col);
;                 ov[k] = (tl >= w) ? *(const u32x4*)(uz + (size_t)(row - w) * DE2 + col) : (u32x4){0u, 0u, 0u, 0u}; }
; #pragma unroll
;             for (int k = 0; k < 8; ++k) { const int row = row0 + r0 + k, tl = tl0 + r0 + k; const u32x4 v = vv[k], o2 = ov[k];
;                 s[0] += bf_lo(v.x) - bf_lo(o2.x); s[1] += bf_hi(v.x) - bf_hi(o2.x); s[2] += bf_lo(v.y) - bf_lo(o2.y); s[3] += bf_hi(v.y) - bf_hi(o2.y);
;                 s[4] += bf_lo(v.z) - bf_lo(o2.z); s[5] += bf_hi(v.z) - bf_hi(o2.z); s[6] += bf_lo(v.w) - bf_lo(o2.w); s[7] += bf_hi(v.w) - bf_hi(o2.w);
;                 const float ic = 1.0f / (float)((tl + 1 < w) ? tl + 1 : w);
;                 u32x4 o;
;                 o.x = cvt_pk_bf16(s[0] * ic - bf_lo(v.x), s[1] * ic - bf_hi(v.x)); o.y = cvt_pk_bf16(s[2] * ic - bf_lo(v.y), s[3] * ic - bf_hi(v.y));
;                 o.z = cvt_pk_bf16(s[4] * ic - bf_lo(v.z), s[5] * ic - bf_hi(v.z)); o.w = cvt_pk_bf16(s[6] * ic - bf_lo(v.w), s[7] * ic - bf_hi(v.w));
;                 *(u32x4*)(pg + (size_t)row * DE + col) = o; }
	v_and_b32_e32 v189, 0xffff0000, v21
	v_lshlrev_b32_e32 v192, 16, v22
	v_and_b32_e32 v193, 0xffff0000, v22
	v_lshlrev_b32_e32 v196, 16, v23
	v_and_b32_e32 v197, 0xffff0000, v23
	v_pk_add_f32 v[164:165], v[164:165], v[184:185]
	v_pk_add_f32 v[166:167], v[166:167], v[188:189]
	v_pk_add_f32 v[168:169], v[168:169], v[192:193]
	v_pk_add_f32 v[170:171], v[170:171], v[196:197]
	v_lshlrev_b32_e32 v184, 16, v16
	v_and_b32_e32 v185, 0xffff0000, v16
	v_lshlrev_b32_e32 v188, 16, v17
	v_and_b32_e32 v189, 0xffff0000, v17
	v_lshlrev_b32_e32 v192, 16, v18
	v_and_b32_e32 v193, 0xffff0000, v18
	v_lshlrev_b32_e32 v196, 16, v19
	v_and_b32_e32 v197, 0xffff0000, v19
	v_pk_add_f32 v[164:165], v[164:165], v[184:185]
	v_pk_add_f32 v[166:167], v[166:167], v[188:189]
	v_pk_add_f32 v[168:169], v[168:169], v[192:193]
	v_pk_add_f32 v[170:171], v[170:171], v[196:197]
	v_lshlrev_b32_e32 v184, 16, v12
	v_and_b32_e32 v185, 0xffff0000, v12
	v_lshlrev_b32_e32 v188, 16, v13
	v_and_b32_e32 v189, 0xffff0000, v13
	v_lshlrev_b32_e32 v192, 16, v14
	v_and_b32_e32 v193, 0xffff0000, v14
	v_lshlrev_b32_e32 v196, 16, v15
	v_and_b32_e32 v197, 0xffff0000, v15
	v_pk_add_f32 v[164:165], v[164:165], v[184:185]
	v_pk_add_f32 v[166:167], v[166:167], v[188:189]
	v_pk_add_f32 v[168:169], v[168:169], v[192:193]
	v_pk_add_f32 v[170:171], v[170:171], v[196:197]
	v_lshlrev_b32_e32 v184, 16, v8
	v_and_b32_e32 v185, 0xffff0000, v8
	v_lshlrev_b32_e32 v188, 16, v9
	v_and_b32_e32 v189, 0xffff0000, v9
	v_lshlrev_b32_e32 v192, 16, v10
	v_and_b32_e32 v193, 0xffff0000, v10
	v_lshlrev_b32_e32 v196, 16, v11
	v_and_b32_e32 v197, 0xffff0000, v11
	v_pk_add_f32 v[164:165], v[164:165], v[184:185]
	v_pk_add_f32 v[166:167], v[166:167], v[188:189]
	v_pk_add_f32 v[168:169], v[168:169], v[192:193]
	v_pk_add_f32 v[170:171], v[170:171], v[196:197]
	v_lshlrev_b32_e32 v184, 16, v4
	v_and_b32_e32 v185, 0xffff0000, v4
	v_lshlrev_b32_e32 v188, 16, v5
	v_and_b32_e32 v189, 0xffff0000, v5
	v_lshlrev_b32_e32 v192, 16, v6
	v_and_b32_e32 v193, 0xffff0000, v6
	v_lshlrev_b32_e32 v196, 16, v7
	v_and_b32_e32 v197, 0xffff0000, v7
	v_pk_add_f32 v[164:165], v[164:165], v[184:185]
	v_pk_add_f32 v[166:167], v[166:167], v[188:189]
	v_pk_add_f32 v[168:169], v[168:169], v[192:193]
	v_pk_add_f32 v[170:171], v[170:171], v[196:197]
	s_waitcnt vmcnt(31)
	s_cselect_b32 s42, 0x3f800000, s43
	v_lshlrev_b32_e32 v184, 16, v36
	v_and_b32_e32 v185, 0xffff0000, v36
	v_lshlrev_b32_e32 v186, 16, v4
	v_and_b32_e32 v187, 0xffff0000, v4
	v_lshlrev_b32_e32 v188, 16, v37
	v_and_b32_e32 v189, 0xffff0000, v37
	v_lshlrev_b32_e32 v190, 16, v5
	v_and_b32_e32 v191, 0xffff0000, v5
	v_lshlrev_b32_e32 v192, 16, v38
	v_and_b32_e32 v193, 0xffff0000, v38
	v_lshlrev_b32_e32 v194, 16, v6
	v_and_b32_e32 v195, 0xffff0000, v6
	v_lshlrev_b32_e32 v196, 16, v39
	v_and_b32_e32 v197, 0xffff0000, v39
	v_lshlrev_b32_e32 v198, 16, v7
	v_and_b32_e32 v199, 0xffff0000, v7
	v_pk_add_f32 v[186:187], v[184:185], v[186:187] neg_lo:[0,1] neg_hi:[0,1]
	v_pk_add_f32 v[190:191], v[188:189], v[190:191] neg_lo:[0,1] neg_hi:[0,1]
	v_pk_add_f32 v[194:195], v[192:193], v[194:195] neg_lo:[0,1] neg_hi:[0,1]
	v_pk_add_f32 v[198:199], v[196:197], v[198:199] neg_lo:[0,1] neg_hi:[0,1]
	v_pk_add_f32 v[164:165], v[164:165], v[186:187]
	v_pk_add_f32 v[166:167], v[166:167], v[190:191]
	v_pk_add_f32 v[168:169], v[168:169], v[194:195]
	v_pk_add_f32 v[170:171], v[170:171], v[198:199]
	v_fma_f32 v186, s42, v164, -v184
	v_fma_f32 v187, s42, v165, -v185
	v_fma_f32 v190, s42, v166, -v188
	v_fma_f32 v191, s42, v167, -v189
	v_fma_f32 v194, s42, v168, -v192
	v_fma_f32 v195, s42, v169, -v193
	v_fma_f32 v198, s42, v170, -v196
	v_fma_f32 v199, s42, v171, -v197
	v_cvt_pk_bf16_f32 v172, v186, v187
	v_cvt_pk_bf16_f32 v173, v190, v191
	v_cvt_pk_bf16_f32 v174, v194, v195
	v_cvt_pk_bf16_f32 v175, v198, v199
	global_store_dwordx4 v3, v[172:175], s[10:11]
	v_add_u32_e32 v3, 0x2000, v3
	s_waitcnt vmcnt(31)
	s_cselect_b32 s42, 0x3f000000, s43
	v_lshlrev_b32_e32 v184, 16, v40
	v_and_b32_e32 v185, 0xffff0000, v40
	v_lshlrev_b32_e32 v186, 16, v8
	v_and_b32_e32 v187, 0xffff0000, v8
	v_lshlrev_b32_e32 v188, 16, v41
	v_and_b32_e32 v189, 0xffff0000, v41
	v_lshlrev_b32_e32 v190, 16, v9
	v_and_b32_e32 v191, 0xffff0000, v9
	v_lshlrev_b32_e32 v192, 16, v42
	v_and_b32_e32 v193, 0xffff0000, v42
	v_lshlrev_b32_e32 v194, 16, v10
	v_and_b32_e32 v195, 0xffff0000, v10
	v_lshlrev_b32_e32 v196, 16, v43
	v_and_b32_e32 v197, 0xffff0000, v43
	v_lshlrev_b32_e32 v198, 16, v11
	v_and_b32_e32 v199, 0xffff0000, v11
	v_pk_add_f32 v[186:187], v[184:185], v[186:187] neg_lo:[0,1] neg_hi:[0,1]
	v_pk_add_f32 v[190:191], v[188:189], v[190:191] neg_lo:[0,1] neg_hi:[0,1]
	v_pk_add_f32 v[194:195], v[192:193], v[194:195] neg_lo:[0,1] neg_hi:[0,1]
	v_pk_add_f32 v[198:199], v[196:197], v[198:199] neg_lo:[0,1] neg_hi:[0,1]
	v_pk_add_f32 v[164:165], v[164:165], v[186:187]
	v_pk_add_f32 v[166:167], v[166:167], v[190:191]
	v_pk_add_f32 v[168:169], v[168:169], v[194:195]
	v_pk_add_f32 v[170:171], v[170:171], v[198:199]
	v_fma_f32 v186, s42, v164, -v184
	v_fma_f32 v187, s42, v165, -v185
	v_fma_f32 v190, s42, v166, -v188
	v_fma_f32 v191, s42, v167, -v189
	v_fma_f32 v194, s42, v168, -v192
	v_fma_f32 v195, s42, v169, -v193
	v_fma_f32 v198, s42, v170, -v196
	v_fma_f32 v199, s42, v171, -v197
	v_cvt_pk_bf16_f32 v172, v186, v187
	v_cvt_pk_bf16_f32 v173, v190, v191
	v_cvt_pk_bf16_f32 v174, v194, v195
	v_cvt_pk_bf16_f32 v175, v198, v199
	global_store_dwordx4 v3, v[172:175], s[10:11]
	v_add_u32_e32 v3, 0x2000, v3
	s_waitcnt vmcnt(31)
; __device__ __forceinline__ unsigned cvt_pk_bf16(float lo, float hi) { unsigned r; asm volatile("v_cvt_pk_bf16_f32 %0, %1, %2" : "=v"(r) : "v"(lo), "v"(hi)); return r; }
; __device__ __forceinline__ float bf_lo(unsigned w) { return __uint_as_float(w << 16); }
; __device__ __forceinline__ float bf_hi(unsigned w) { return __uint_as_float(w & 0xffff0000u); }
; __device__ void phase_pool() {
;     ...
;             for (int k = 0; k < 8; ++k) { const int row = row0 + r0 + k, tl = tl0 + r0 + k; const u32x4 v = vv[k], o2 = ov[k];
;                 s[0] += bf_lo(v.x) - bf_lo(o2.x); s[1] += bf_hi(v.x) - bf_hi(o2.x); s[2] += bf_lo(v.y) - bf_lo(o2.y); s[3] += bf_hi(v.y) - bf_hi(o2.y);
;                 s[4] += bf_lo(v.z) - bf_lo(o2.z); s[5] += bf_hi(v.z) - bf_hi(o2.z); s[6] += bf_lo(v.w) - bf_lo(o2.w); s[7] += bf_hi(v.w) - bf_hi(o2.w);
;                 const float ic = 1.0f / (float)((tl + 1 < w) ? tl + 1 : w);
;                 u32x4 o;
;                 o.x = cvt_pk_bf16(s[0] * ic - bf_lo(v.x), s[1] * ic - bf_hi(v.x)); o.y = cvt_pk_bf16(s[2] * ic - bf_lo(v.y), s[3] * ic - bf_hi(v.y));
;                 o.z = cvt_pk_bf16(s[4] * ic - bf_lo(v.z), s[5] * ic - bf_hi(v.z)); o.w = cvt_pk_bf16(s[6] * ic - bf_lo(v.w), s[7] * ic - bf_hi(v.w));
;                 *(u32x4*)(pg + (size_t)row * DE + col) = o; }
	s_cselect_b32 s42, 0x3eaaaaab, s43
	v_lshlrev_b32_e32 v184, 16, v44
	v_and_b32_e32 v185, 0xffff0000, v44
	v_lshlrev_b32_e32 v186, 16, v12
	v_and_b32_e32 v187, 0xffff0000, v12
	v_lshlrev_b32_e32 v188, 16, v45
	v_and_b32_e32 v189, 0xffff0000, v45
	v_lshlrev_b32_e32 v190, 16, v13
	v_and_b32_e32 v191, 0xffff0000, v13
	v_lshlrev_b32_e32 v192, 16, v46
	v_and_b32_e32 v193, 0xffff0000, v46
	v_lshlrev_b32_e32 v194, 16, v14
	v_and_b32_e32 v195, 0xffff0000, v14
	v_lshlrev_b32_e32 v196, 16, v47
	v_and_b32_e32 v197, 0xffff0000, v47
	v_lshlrev_b32_e32 v198, 16, v15
	v_and_b32_e32 v199, 0xffff0000, v15
	v_pk_add_f32 v[186:187], v[184:185], v[186:187] neg_lo:[0,1] neg_hi:[0,1]
	v_pk_add_f32 v[190:191], v[188:189], v[190:191] neg_lo:[0,1] neg_hi:[0,1]
	v_pk_add_f32 v[194:195], v[192:193], v[194:195] neg_lo:[0,1] neg_hi:[0,1]
	v_pk_add_f32 v[198:199], v[196:197], v[198:199] neg_lo:[0,1] neg_hi:[0,1]
	v_pk_add_f32 v[164:165], v[164:165], v[186:187]
	v_pk_add_f32 v[166:167], v[166:167], v[190:191]
	v_pk_add_f32 v[168:169], v[168:169], v[194:195]
	v_pk_add_f32 v[170:171], v[170:171], v[198:199]
	v_fma_f32 v186, s42, v164, -v184
	v_fma_f32 v187, s42, v165, -v185
	v_fma_f32 v190, s42, v166, -v188
	v_fma_f32 v191, s42, v167, -v189
	v_fma_f32 v194, s42, v168, -v192
	v_fma_f32 v195, s42, v169, -v193
	v_fma_f32 v198, s42, v170, -v196
	v_fma_f32 v199, s42, v171, -v197
	v_cvt_pk_bf16_f32 v172, v186, v187
	v_cvt_pk_bf16_f32 v173, v190, v191
	v_cvt_pk_bf16_f32 v174, v194, v195
	v_cvt_pk_bf16_f32 v175, v198, v199
	global_store_dwordx4 v3, v[172:175], s[10:11]
	v_add_u32_e32 v3, 0x2000, v3
	s_waitcnt vmcnt(31)
	s_cselect_b32 s42, 0x3e800000, s43
	v_lshlrev_b32_e32 v184, 16, v48
	v_and_b32_e32 v185, 0xffff0000, v48
	v_lshlrev_b32_e32 v186, 16, v16
	v_and_b32_e32 v187, 0xffff0000, v16
	v_lshlrev_b32_e32 v188, 16, v49
	v_and_b32_e32 v189, 0xffff0000, v49
	v_lshlrev_b32_e32 v190, 16, v17
	v_and_b32_e32 v191, 0xffff0000, v17
	v_lshlrev_b32_e32 v192, 16, v50
	v_and_b32_e32 v193, 0xffff0000, v50
	v_lshlrev_b32_e32 v194, 16, v18
	v_and_b32_e32 v195, 0xffff0000, v18
	v_lshlrev_b32_e32 v196, 16, v51
	v_and_b32_e32 v197, 0xffff0000, v51
	v_lshlrev_b32_e32 v198, 16, v19
	v_and_b32_e32 v199, 0xffff0000, v19
	v_pk_add_f32 v[186:187], v[184:185], v[186:187] neg_lo:[0,1] neg_hi:[0,1]
	v_pk_add_f32 v[190:191], v[188:189], v[190:191] neg_lo:[0,1] neg_hi:[0,1]
	v_pk_add_f32 v[194:195], v[192:193], v[194:195] neg_lo:[0,1] neg_hi:[0,1]
	v_pk_add_f32 v[198:199], v[196:197], v[198:199] neg_lo:[0,1] neg_hi:[0,1]
	v_pk_add_f32 v[164:165], v[164:165], v[186:187]
	v_pk_add_f32 v[166:167], v[166:167], v[190:191]
	v_pk_add_f32 v[168:169], v[168:169], v[194:195]
	v_pk_add_f32 v[170:171], v[170:171], v[198:199]
	v_fma_f32 v186, s42, v164, -v184
	v_fma_f32 v187, s42, v165, -v185
	v_fma_f32 v190, s42, v166, -v188
	v_fma_f32 v191, s42, v167, -v189
	v_fma_f32 v194, s42, v168, -v192
	v_fma_f32 v195, s42, v169, -v193
	v_fma_f32 v198, s42, v170, -v196
	v_fma_f32 v199, s42, v171, -v197
	v_cvt_pk_bf16_f32 v172, v186, v187
	v_cvt_pk_bf16_f32 v173, v190, v191
	v_cvt_pk_bf16_f32 v174, v194, v195
	v_cvt_pk_bf16_f32 v175, v198, v199
	global_store_dwordx4 v3, v[172:175], s[10:11]
	v_add_u32_e32 v3, 0x2000, v3
	s_waitcnt vmcnt(31)
	s_cselect_b32 s42, 0x3e4ccccd, s43
	v_lshlrev_b32_e32 v184, 16, v52
	v_and_b32_e32 v185, 0xffff0000, v52
	v_lshlrev_b32_e32 v186, 16, v20
	v_and_b32_e32 v187, 0xffff0000, v20
	v_lshlrev_b32_e32 v188, 16, v53
	v_and_b32_e32 v189, 0xffff0000, v53
	v_lshlrev_b32_e32 v190, 16, v21
	v_and_b32_e32 v191, 0xffff0000, v21
	v_lshlrev_b32_e32 v192, 16, v54
	v_and_b32_e32 v193, 0xffff0000, v54
	v_lshlrev_b32_e32 v194, 16, v22
	v_and_b32_e32 v195, 0xffff0000, v22
	v_lshlrev_b32_e32 v196, 16, v55
	v_and_b32_e32 v197, 0xffff0000, v55
	v_lshlrev_b32_e32 v198, 16, v23
	v_and_b32_e32 v199, 0xffff0000, v23
	v_pk_add_f32 v[186:187], v[184:185], v[186:187] neg_lo:[0,1] neg_hi:[0,1]
	v_pk_add_f32 v[190:191], v[188:189], v[190:191] neg_lo:[0,1] neg_hi:[0,1]
	v_pk_add_f32 v[194:195], v[192:193], v[194:195] neg_lo:[0,1] neg_hi:[0,1]
	v_pk_add_f32 v[198:199], v[196:197], v[198:199] neg_lo:[0,1] neg_hi:[0,1]
	v_pk_add_f32 v[164:165], v[164:165], v[186:187]
	v_pk_add_f32 v[166:167], v[166:167], v[190:191]
	v_pk_add_f32 v[168:169], v[168:169], v[194:195]
	v_pk_add_f32 v[170:171], v[170:171], v[198:199]
	v_fma_f32 v186, s42, v164, -v184
	v_fma_f32 v187, s42, v165, -v185
	v_fma_f32 v190, s42, v166, -v188
	v_fma_f32 v191, s42, v167, -v189
	v_fma_f32 v194, s42, v168, -v192
	v_fma_f32 v195, s42, v169, -v193
	v_fma_f32 v198, s42, v170, -v196
	v_fma_f32 v199, s42, v171, -v197
	v_cvt_pk_bf16_f32 v172, v186, v187
	v_cvt_pk_bf16_f32 v173, v190, v191
	v_cvt_pk_bf16_f32 v174, v194, v195
	v_cvt_pk_bf16_f32 v175, v198, v199
	global_store_dwordx4 v3, v[172:175], s[10:11]
	v_add_u32_e32 v3, 0x2000, v3
	s_waitcnt vmcnt(31)
	s_cselect_b32 s42, 0x3e2aaaab, s43
	v_lshlrev_b32_e32 v184, 16, v56
	v_and_b32_e32 v185, 0xffff0000, v56
	v_lshlrev_b32_e32 v186, 16, v24
	v_and_b32_e32 v187, 0xffff0000, v24
	v_lshlrev_b32_e32 v188, 16, v57
	v_and_b32_e32 v189, 0xffff0000, v57
	v_lshlrev_b32_e32 v190, 16, v25
	v_and_b32_e32 v191, 0xffff0000, v25
	v_lshlrev_b32_e32 v192, 16, v58
	v_and_b32_e32 v193, 0xffff0000, v58
	v_lshlrev_b32_e32 v194, 16, v26
	v_and_b32_e32 v195, 0xffff0000, v26
	v_lshlrev_b32_e32 v196, 16, v59
	v_and_b32_e32 v197, 0xffff0000, v59
	v_lshlrev_b32_e32 v198, 16, v27
	v_and_b32_e32 v199, 0xffff0000, v27
	v_pk_add_f32 v[186:187], v[184:185], v[186:187] neg_lo:[0,1] neg_hi:[0,1]
	v_pk_add_f32 v[190:191], v[188:189], v[190:191] neg_lo:[0,1] neg_hi:[0,1]
	v_pk_add_f32 v[194:195], v[192:193], v[194:195] neg_lo:[0,1] neg_hi:[0,1]
	v_pk_add_f32 v[198:199], v[196:197], v[198:199] neg_lo:[0,1] neg_hi:[0,1]
	v_pk_add_f32 v[164:165], v[164:165], v[186:187]
	v_pk_add_f32 v[166:167], v[166:167], v[190:191]
	v_pk_add_f32 v[168:169], v[168:169], v[194:195]
	v_pk_add_f32 v[170:171], v[170:171], v[198:199]
	v_fma_f32 v186, s42, v164, -v184
	v_fma_f32 v187, s42, v165, -v185
	v_fma_f32 v190, s42, v166, -v188
	v_fma_f32 v191, s42, v167, -v189
	v_fma_f32 v194, s42, v168, -v192
	v_fma_f32 v195, s42, v169, -v193
	v_fma_f32 v198, s42, v170, -v196
	v_fma_f32 v199, s42, v171, -v197
	v_cvt_pk_bf16_f32 v172, v186, v187
	v_cvt_pk_bf16_f32 v173, v190, v191
	v_cvt_pk_bf16_f32 v174, v194, v195
	v_cvt_pk_bf16_f32 v175, v198, v199
	global_store_dwordx4 v3, v[172:175], s[10:11]
	v_add_u32_e32 v3, 0x2000, v3
	s_waitcnt vmcnt(31)
; __device__ __forceinline__ unsigned cvt_pk_bf16(float lo, float hi) { unsigned r; asm volatile("v_cvt_pk_bf16_f32 %0, %1, %2" : "=v"(r) : "v"(lo), "v"(hi)); return r; }
; __device__ __forceinline__ float bf_lo(unsigned w) { return __uint_as_float(w << 16); }
; __device__ __forceinline__ float bf_hi(unsigned w) { return __uint_as_float(w & 0xffff0000u); }
; __device__ void phase_pool() {
;     ...
;             for (int k = 0; k < 8; ++k) { const int row = row0 + r0 + k, tl = tl0 + r0 + k; const u32x4 v = vv[k], o2 = ov[k];
;                 s[0] += bf_lo(v.x) - bf_lo(o2.x); s[1] += bf_hi(v.x) - bf_hi(o2.x); s[2] += bf_lo(v.y) - bf_lo(o2.y); s[3] += bf_hi(v.y) - bf_hi(o2.y);
;                 s[4] += bf_lo(v.z) - bf_lo(o2.z); s[5] += bf_hi(v.z) - bf_hi(o2.z); s[6] += bf_lo(v.w) - bf_lo(o2.w); s[7] += bf_hi(v.w) - bf_hi(o2.w);
;                 const float ic = 1.0f / (float)((tl + 1 < w) ? tl + 1 : w);
;                 u32x4 o;
;                 o.x = cvt_pk_bf16(s[0] * ic - bf_lo(v.x), s[1] * ic - bf_hi(v.x)); o.y = cvt_pk_bf16(s[2] * ic - bf_lo(v.y), s[3] * ic - bf_hi(v.y));
;                 o.z = cvt_pk_bf16(s[4] * ic - bf_lo(v.z), s[5] * ic - bf_hi(v.z)); o.w = cvt_pk_bf16(s[6] * ic - bf_lo(v.w), s[7] * ic - bf_hi(v.w));
;                 *(u32x4*)(pg + (size_t)row * DE + col) = o; }
	s_cselect_b32 s42, 0x3e124925, s43
	v_lshlrev_b32_e32 v184, 16, v60
	v_and_b32_e32 v185, 0xffff0000, v60
	v_lshlrev_b32_e32 v186, 16, v28
	v_and_b32_e32 v187, 0xffff0000, v28
	v_lshlrev_b32_e32 v188, 16, v61
	v_and_b32_e32 v189, 0xffff0000, v61
	v_lshlrev_b32_e32 v190, 16, v29
	v_and_b32_e32 v191, 0xffff0000, v29
	v_lshlrev_b32_e32 v192, 16, v62
	v_and_b32_e32 v193, 0xffff0000, v62
	v_lshlrev_b32_e32 v194, 16, v30
	v_and_b32_e32 v195, 0xffff0000, v30
	v_lshlrev_b32_e32 v196, 16, v63
	v_and_b32_e32 v197, 0xffff0000, v63
	v_lshlrev_b32_e32 v198, 16, v31
	v_and_b32_e32 v199, 0xffff0000, v31
	v_pk_add_f32 v[186:187], v[184:185], v[186:187] neg_lo:[0,1] neg_hi:[0,1]
	v_pk_add_f32 v[190:191], v[188:189], v[190:191] neg_lo:[0,1] neg_hi:[0,1]
	v_pk_add_f32 v[194:195], v[192:193], v[194:195] neg_lo:[0,1] neg_hi:[0,1]
	v_pk_add_f32 v[198:199], v[196:197], v[198:199] neg_lo:[0,1] neg_hi:[0,1]
	v_pk_add_f32 v[164:165], v[164:165], v[186:187]
	v_pk_add_f32 v[166:167], v[166:167], v[190:191]
	v_pk_add_f32 v[168:169], v[168:169], v[194:195]
	v_pk_add_f32 v[170:171], v[170:171], v[198:199]
	v_fma_f32 v186, s42, v164, -v184
	v_fma_f32 v187, s42, v165, -v185
	v_fma_f32 v190, s42, v166, -v188
	v_fma_f32 v191, s42, v167, -v189
	v_fma_f32 v194, s42, v168, -v192
	v_fma_f32 v195, s42, v169, -v193
	v_fma_f32 v198, s42, v170, -v196
	v_fma_f32 v199, s42, v171, -v197
	v_cvt_pk_bf16_f32 v172, v186, v187
	v_cvt_pk_bf16_f32 v173, v190, v191
	v_cvt_pk_bf16_f32 v174, v194, v195
	v_cvt_pk_bf16_f32 v175, v198, v199
	global_store_dwordx4 v3, v[172:175], s[10:11]
	v_add_u32_e32 v3, 0x2000, v3
	s_waitcnt vmcnt(31)
	v_lshlrev_b32_e32 v184, 16, v64
	v_and_b32_e32 v185, 0xffff0000, v64
	v_lshlrev_b32_e32 v186, 16, v32
	v_and_b32_e32 v187, 0xffff0000, v32
	v_lshlrev_b32_e32 v188, 16, v65
	v_and_b32_e32 v189, 0xffff0000, v65
	v_lshlrev_b32_e32 v190, 16, v33
	v_and_b32_e32 v191, 0xffff0000, v33
	v_lshlrev_b32_e32 v192, 16, v66
	v_and_b32_e32 v193, 0xffff0000, v66
	v_lshlrev_b32_e32 v194, 16, v34
	v_and_b32_e32 v195, 0xffff0000, v34
	v_lshlrev_b32_e32 v196, 16, v67
	v_and_b32_e32 v197, 0xffff0000, v67
	v_lshlrev_b32_e32 v198, 16, v35
	v_and_b32_e32 v199, 0xffff0000, v35
	v_pk_add_f32 v[186:187], v[184:185], v[186:187] neg_lo:[0,1] neg_hi:[0,1]
	v_pk_add_f32 v[190:191], v[188:189], v[190:191] neg_lo:[0,1] neg_hi:[0,1]
	v_pk_add_f32 v[194:195], v[192:193], v[194:195] neg_lo:[0,1] neg_hi:[0,1]
	v_pk_add_f32 v[198:199], v[196:197], v[198:199] neg_lo:[0,1] neg_hi:[0,1]
	v_pk_add_f32 v[164:165], v[164:165], v[186:187]
	v_pk_add_f32 v[166:167], v[166:167], v[190:191]
	v_pk_add_f32 v[168:169], v[168:169], v[194:195]
	v_pk_add_f32 v[170:171], v[170:171], v[198:199]
	v_fma_f32 v186, s43, v164, -v184
	v_fma_f32 v187, s43, v165, -v185
	v_fma_f32 v190, s43, v166, -v188
	v_fma_f32 v191, s43, v167, -v189
	v_fma_f32 v194, s43, v168, -v192
	v_fma_f32 v195, s43, v169, -v193
	v_fma_f32 v198, s43, v170, -v196
	v_fma_f32 v199, s43, v171, -v197
	v_cvt_pk_bf16_f32 v172, v186, v187
	v_cvt_pk_bf16_f32 v173, v190, v191
	v_cvt_pk_bf16_f32 v174, v194, v195
	v_cvt_pk_bf16_f32 v175, v198, v199
	global_store_dwordx4 v3, v[172:175], s[10:11]
	v_add_u32_e32 v3, 0x2000, v3
	s_waitcnt vmcnt(31)
	v_lshlrev_b32_e32 v184, 16, v68
	v_and_b32_e32 v185, 0xffff0000, v68
	v_lshlrev_b32_e32 v186, 16, v36
	v_and_b32_e32 v187, 0xffff0000, v36
	v_lshlrev_b32_e32 v188, 16, v69
	v_and_b32_e32 v189, 0xffff0000, v69
	v_lshlrev_b32_e32 v190, 16, v37
	v_and_b32_e32 v191, 0xffff0000, v37
	v_lshlrev_b32_e32 v192, 16, v70
	v_and_b32_e32 v193, 0xffff0000, v70
	v_lshlrev_b32_e32 v194, 16, v38
	v_and_b32_e32 v195, 0xffff0000, v38
	v_lshlrev_b32_e32 v196, 16, v71
	v_and_b32_e32 v197, 0xffff0000, v71
	v_lshlrev_b32_e32 v198, 16, v39
	v_and_b32_e32 v199, 0xffff0000, v39
	v_pk_add_f32 v[186:187], v[184:185], v[186:187] neg_lo:[0,1] neg_hi:[0,1]
	v_pk_add_f32 v[190:191], v[188:189], v[190:191] neg_lo:[0,1] neg_hi:[0,1]
	v_pk_add_f32 v[194:195], v[192:193], v[194:195] neg_lo:[0,1] neg_hi:[0,1]
	v_pk_add_f32 v[198:199], v[196:197], v[198:199] neg_lo:[0,1] neg_hi:[0,1]
	v_pk_add_f32 v[164:165], v[164:165], v[186:187]
	v_pk_add_f32 v[166:167], v[166:167], v[190:191]
	v_pk_add_f32 v[168:169], v[168:169], v[194:195]
	v_pk_add_f32 v[170:171], v[170:171], v[198:199]
	v_fma_f32 v186, s43, v164, -v184
	v_fma_f32 v187, s43, v165, -v185
	v_fma_f32 v190, s43, v166, -v188
	v_fma_f32 v191, s43, v167, -v189
	v_fma_f32 v194, s43, v168, -v192
	v_fma_f32 v195, s43, v169, -v193
	v_fma_f32 v198, s43, v170, -v196
	v_fma_f32 v199, s43, v171, -v197
	v_cvt_pk_bf16_f32 v172, v186, v187
	v_cvt_pk_bf16_f32 v173, v190, v191
	v_cvt_pk_bf16_f32 v174, v194, v195
	v_cvt_pk_bf16_f32 v175, v198, v199
	global_store_dwordx4 v3, v[172:175], s[10:11]
	v_add_u32_e32 v3, 0x2000, v3
	s_waitcnt vmcnt(31)
	v_lshlrev_b32_e32 v184, 16, v72
	v_and_b32_e32 v185, 0xffff0000, v72
	v_lshlrev_b32_e32 v186, 16, v40
	v_and_b32_e32 v187, 0xffff0000, v40
	v_lshlrev_b32_e32 v188, 16, v73
	v_and_b32_e32 v189, 0xffff0000, v73
	v_lshlrev_b32_e32 v190, 16, v41
	v_and_b32_e32 v191, 0xffff0000, v41
	v_lshlrev_b32_e32 v192, 16, v74
	v_and_b32_e32 v193, 0xffff0000, v74
	v_lshlrev_b32_e32 v194, 16, v42
	v_and_b32_e32 v195, 0xffff0000, v42
	v_lshlrev_b32_e32 v196, 16, v75
	v_and_b32_e32 v197, 0xffff0000, v75
	v_lshlrev_b32_e32 v198, 16, v43
	v_and_b32_e32 v199, 0xffff0000, v43
	v_pk_add_f32 v[186:187], v[184:185], v[186:187] neg_lo:[0,1] neg_hi:[0,1]
	v_pk_add_f32 v[190:191], v[188:189], v[190:191] neg_lo:[0,1] neg_hi:[0,1]
	v_pk_add_f32 v[194:195], v[192:193], v[194:195] neg_lo:[0,1] neg_hi:[0,1]
	v_pk_add_f32 v[198:199], v[196:197], v[198:199] neg_lo:[0,1] neg_hi:[0,1]
	v_pk_add_f32 v[164:165], v[164:165], v[186:187]
	v_pk_add_f32 v[166:167], v[166:167], v[190:191]
	v_pk_add_f32 v[168:169], v[168:169], v[194:195]
	v_pk_add_f32 v[170:171], v[170:171], v[198:199]
	v_fma_f32 v186, s43, v164, -v184
	v_fma_f32 v187, s43, v165, -v185
	v_fma_f32 v190, s43, v166, -v188
	v_fma_f32 v191, s43, v167, -v189
	v_fma_f32 v194, s43, v168, -v192
	v_fma_f32 v195, s43, v169, -v193
	v_fma_f32 v198, s43, v170, -v196
	v_fma_f32 v199, s43, v171, -v197
	v_cvt_pk_bf16_f32 v172, v186, v187
	v_cvt_pk_bf16_f32 v173, v190, v191
	v_cvt_pk_bf16_f32 v174, v194, v195
	v_cvt_pk_bf16_f32 v175, v198, v199
	global_store_dwordx4 v3, v[172:175], s[10:11]
	v_add_u32_e32 v3, 0x2000, v3
	s_waitcnt vmcnt(31)
; __device__ __forceinline__ unsigned cvt_pk_bf16(float lo, float hi) { unsigned r; asm volatile("v_cvt_pk_bf16_f32 %0, %1, %2" : "=v"(r) : "v"(lo), "v"(hi)); return r; }
; __device__ __forceinline__ float bf_lo(unsigned w) { return __uint_as_float(w << 16); }
; __device__ __forceinline__ float bf_hi(unsigned w) { return __uint_as_float(w & 0xffff0000u); }
; __device__ void phase_pool() {
;     ...
;             for (int k = 0; k < 8; ++k) { const int row = row0 + r0 + k, tl = tl0 + r0 + k; const u32x4 v = vv[k], o2 = ov[k];
;                 s[0] += bf_lo(v.x) - bf_lo(o2.x); s[1] += bf_hi(v.x) - bf_hi(o2.x); s[2] += bf_lo(v.y) - bf_lo(o2.y); s[3] += bf_hi(v.y) - bf_hi(o2.y);
;                 s[4] += bf_lo(v.z) - bf_lo(o2.z); s[5] += bf_hi(v.z) - bf_hi(o2.z); s[6] += bf_lo(v.w) - bf_lo(o2.w); s[7] += bf_hi(v.w) - bf_hi(o2.w);
;                 const float ic = 1.0f / (float)((tl + 1 < w) ? tl + 1 : w);
;                 u32x4 o;
;                 o.x = cvt_pk_bf16(s[0] * ic - bf_lo(v.x), s[1] * ic - bf_hi(v.x)); o.y = cvt_pk_bf16(s[2] * ic - bf_lo(v.y), s[3] * ic - bf_hi(v.y));
;                 o.z = cvt_pk_bf16(s[4] * ic - bf_lo(v.z), s[5] * ic - bf_hi(v.z)); o.w = cvt_pk_bf16(s[6] * ic - bf_lo(v.w), s[7] * ic - bf_hi(v.w));
;                 *(u32x4*)(pg + (size_t)row * DE + col) = o; }
	v_lshlrev_b32_e32 v184, 16, v76
	v_and_b32_e32 v185, 0xffff0000, v76
	v_lshlrev_b32_e32 v186, 16, v44
	v_and_b32_e32 v187, 0xffff0000, v44
	v_lshlrev_b32_e32 v188, 16, v77
	v_and_b32_e32 v189, 0xffff0000, v77
	v_lshlrev_b32_e32 v190, 16, v45
	v_and_b32_e32 v191, 0xffff0000, v45
	v_lshlrev_b32_e32 v192, 16, v78
	v_and_b32_e32 v193, 0xffff0000, v78
	v_lshlrev_b32_e32 v194, 16, v46
	v_and_b32_e32 v195, 0xffff0000, v46
	v_lshlrev_b32_e32 v196, 16, v79
	v_and_b32_e32 v197, 0xffff0000, v79
	v_lshlrev_b32_e32 v198, 16, v47
	v_and_b32_e32 v199, 0xffff0000, v47
	v_pk_add_f32 v[186:187], v[184:185], v[186:187] neg_lo:[0,1] neg_hi:[0,1]
	v_pk_add_f32 v[190:191], v[188:189], v[190:191] neg_lo:[0,1] neg_hi:[0,1]
	v_pk_add_f32 v[194:195], v[192:193], v[194:195] neg_lo:[0,1] neg_hi:[0,1]
	v_pk_add_f32 v[198:199], v[196:197], v[198:199] neg_lo:[0,1] neg_hi:[0,1]
	v_pk_add_f32 v[164:165], v[164:165], v[186:187]
	v_pk_add_f32 v[166:167], v[166:167], v[190:191]
	v_pk_add_f32 v[168:169], v[168:169], v[194:195]
	v_pk_add_f32 v[170:171], v[170:171], v[198:199]
	v_fma_f32 v186, s43, v164, -v184
	v_fma_f32 v187, s43, v165, -v185
	v_fma_f32 v190, s43, v166, -v188
	v_fma_f32 v191, s43, v167, -v189
	v_fma_f32 v194, s43, v168, -v192
	v_fma_f32 v195, s43, v169, -v193
	v_fma_f32 v198, s43, v170, -v196
	v_fma_f32 v199, s43, v171, -v197
	v_cvt_pk_bf16_f32 v172, v186, v187
	v_cvt_pk_bf16_f32 v173, v190, v191
	v_cvt_pk_bf16_f32 v174, v194, v195
	v_cvt_pk_bf16_f32 v175, v198, v199
	global_store_dwordx4 v3, v[172:175], s[10:11]
	v_add_u32_e32 v3, 0x2000, v3
	s_waitcnt vmcnt(31)
	v_lshlrev_b32_e32 v184, 16, v80
	v_and_b32_e32 v185, 0xffff0000, v80
	v_lshlrev_b32_e32 v186, 16, v48
	v_and_b32_e32 v187, 0xffff0000, v48
	v_lshlrev_b32_e32 v188, 16, v81
	v_and_b32_e32 v189, 0xffff0000, v81
	v_lshlrev_b32_e32 v190, 16, v49
	v_and_b32_e32 v191, 0xffff0000, v49
	v_lshlrev_b32_e32 v192, 16, v82
	v_and_b32_e32 v193, 0xffff0000, v82
	v_lshlrev_b32_e32 v194, 16, v50
	v_and_b32_e32 v195, 0xffff0000, v50
	v_lshlrev_b32_e32 v196, 16, v83
	v_and_b32_e32 v197, 0xffff0000, v83
	v_lshlrev_b32_e32 v198, 16, v51
	v_and_b32_e32 v199, 0xffff0000, v51
	v_pk_add_f32 v[186:187], v[184:185], v[186:187] neg_lo:[0,1] neg_hi:[0,1]
	v_pk_add_f32 v[190:191], v[188:189], v[190:191] neg_lo:[0,1] neg_hi:[0,1]
	v_pk_add_f32 v[194:195], v[192:193], v[194:195] neg_lo:[0,1] neg_hi:[0,1]
	v_pk_add_f32 v[198:199], v[196:197], v[198:199] neg_lo:[0,1] neg_hi:[0,1]
	v_pk_add_f32 v[164:165], v[164:165], v[186:187]
	v_pk_add_f32 v[166:167], v[166:167], v[190:191]
	v_pk_add_f32 v[168:169], v[168:169], v[194:195]
	v_pk_add_f32 v[170:171], v[170:171], v[198:199]
	v_fma_f32 v186, s43, v164, -v184
	v_fma_f32 v187, s43, v165, -v185
	v_fma_f32 v190, s43, v166, -v188
	v_fma_f32 v191, s43, v167, -v189
	v_fma_f32 v194, s43, v168, -v192
	v_fma_f32 v195, s43, v169, -v193
	v_fma_f32 v198, s43, v170, -v196
	v_fma_f32 v199, s43, v171, -v197
	v_cvt_pk_bf16_f32 v172, v186, v187
	v_cvt_pk_bf16_f32 v173, v190, v191
	v_cvt_pk_bf16_f32 v174, v194, v195
	v_cvt_pk_bf16_f32 v175, v198, v199
	global_store_dwordx4 v3, v[172:175], s[10:11]
	v_add_u32_e32 v3, 0x2000, v3
	s_waitcnt vmcnt(31)
	v_lshlrev_b32_e32 v184, 16, v84
	v_and_b32_e32 v185, 0xffff0000, v84
	v_lshlrev_b32_e32 v186, 16, v52
	v_and_b32_e32 v187, 0xffff0000, v52
	v_lshlrev_b32_e32 v188, 16, v85
	v_and_b32_e32 v189, 0xffff0000, v85
	v_lshlrev_b32_e32 v190, 16, v53
	v_and_b32_e32 v191, 0xffff0000, v53
	v_lshlrev_b32_e32 v192, 16, v86
	v_and_b32_e32 v193, 0xffff0000, v86
	v_lshlrev_b32_e32 v194, 16, v54
	v_and_b32_e32 v195, 0xffff0000, v54
	v_lshlrev_b32_e32 v196, 16, v87
	v_and_b32_e32 v197, 0xffff0000, v87
	v_lshlrev_b32_e32 v198, 16, v55
	v_and_b32_e32 v199, 0xffff0000, v55
	v_pk_add_f32 v[186:187], v[184:185], v[186:187] neg_lo:[0,1] neg_hi:[0,1]
	v_pk_add_f32 v[190:191], v[188:189], v[190:191] neg_lo:[0,1] neg_hi:[0,1]
	v_pk_add_f32 v[194:195], v[192:193], v[194:195] neg_lo:[0,1] neg_hi:[0,1]
	v_pk_add_f32 v[198:199], v[196:197], v[198:199] neg_lo:[0,1] neg_hi:[0,1]
	v_pk_add_f32 v[164:165], v[164:165], v[186:187]
	v_pk_add_f32 v[166:167], v[166:167], v[190:191]
	v_pk_add_f32 v[168:169], v[168:169], v[194:195]
	v_pk_add_f32 v[170:171], v[170:171], v[198:199]
	v_fma_f32 v186, s43, v164, -v184
	v_fma_f32 v187, s43, v165, -v185
	v_fma_f32 v190, s43, v166, -v188
	v_fma_f32 v191, s43, v167, -v189
	v_fma_f32 v194, s43, v168, -v192
	v_fma_f32 v195, s43, v169, -v193
	v_fma_f32 v198, s43, v170, -v196
	v_fma_f32 v199, s43, v171, -v197
	v_cvt_pk_bf16_f32 v172, v186, v187
	v_cvt_pk_bf16_f32 v173, v190, v191
	v_cvt_pk_bf16_f32 v174, v194, v195
	v_cvt_pk_bf16_f32 v175, v198, v199
	global_store_dwordx4 v3, v[172:175], s[10:11]
	v_add_u32_e32 v3, 0x2000, v3
	s_waitcnt vmcnt(31)
	v_lshlrev_b32_e32 v184, 16, v88
	v_and_b32_e32 v185, 0xffff0000, v88
	v_lshlrev_b32_e32 v186, 16, v56
	v_and_b32_e32 v187, 0xffff0000, v56
	v_lshlrev_b32_e32 v188, 16, v89
	v_and_b32_e32 v189, 0xffff0000, v89
	v_lshlrev_b32_e32 v190, 16, v57
	v_and_b32_e32 v191, 0xffff0000, v57
	v_lshlrev_b32_e32 v192, 16, v90
	v_and_b32_e32 v193, 0xffff0000, v90
	v_lshlrev_b32_e32 v194, 16, v58
	v_and_b32_e32 v195, 0xffff0000, v58
	v_lshlrev_b32_e32 v196, 16, v91
	v_and_b32_e32 v197, 0xffff0000, v91
	v_lshlrev_b32_e32 v198, 16, v59
	v_and_b32_e32 v199, 0xffff0000, v59
	v_pk_add_f32 v[186:187], v[184:185], v[186:187] neg_lo:[0,1] neg_hi:[0,1]
	v_pk_add_f32 v[190:191], v[188:189], v[190:191] neg_lo:[0,1] neg_hi:[0,1]
	v_pk_add_f32 v[194:195], v[192:193], v[194:195] neg_lo:[0,1] neg_hi:[0,1]
	v_pk_add_f32 v[198:199], v[196:197], v[198:199] neg_lo:[0,1] neg_hi:[0,1]
	v_pk_add_f32 v[164:165], v[164:165], v[186:187]
	v_pk_add_f32 v[166:167], v[166:167], v[190:191]
	v_pk_add_f32 v[168:169], v[168:169], v[194:195]
	v_pk_add_f32 v[170:171], v[170:171], v[198:199]
	v_fma_f32 v186, s43, v164, -v184
	v_fma_f32 v187, s43, v165, -v185
	v_fma_f32 v190, s43, v166, -v188
	v_fma_f32 v191, s43, v167, -v189
	v_fma_f32 v194, s43, v168, -v192
	v_fma_f32 v195, s43, v169, -v193
	v_fma_f32 v198, s43, v170, -v196
	v_fma_f32 v199, s43, v171, -v197
	v_cvt_pk_bf16_f32 v172, v186, v187
	v_cvt_pk_bf16_f32 v173, v190, v191
	v_cvt_pk_bf16_f32 v174, v194, v195
	v_cvt_pk_bf16_f32 v175, v198, v199
	global_store_dwordx4 v3, v[172:175], s[10:11]
	v_add_u32_e32 v3, 0x2000, v3
	s_waitcnt vmcnt(31)
; __device__ __forceinline__ unsigned cvt_pk_bf16(float lo, float hi) { unsigned r; asm volatile("v_cvt_pk_bf16_f32 %0, %1, %2" : "=v"(r) : "v"(lo), "v"(hi)); return r; }
; __device__ __forceinline__ float bf_lo(unsigned w) { return __uint_as_float(w << 16); }
; __device__ __forceinline__ float bf_hi(unsigned w) { return __uint_as_float(w & 0xffff0000u); }
; __device__ void phase_pool() {
;     ...
;             for (int k = 0; k < 8; ++k) { const int row = row0 + r0 + k, tl = tl0 + r0 + k; const u32x4 v = vv[k], o2 = ov[k];
;                 s[0] += bf_lo(v.x) - bf_lo(o2.x); s[1] += bf_hi(v.x) - bf_hi(o2.x); s[2] += bf_lo(v.y) - bf_lo(o2.y); s[3] += bf_hi(v.y) - bf_hi(o2.y);
;                 s[4] += bf_lo(v.z) - bf_lo(o2.z); s[5] += bf_hi(v.z) - bf_hi(o2.z); s[6] += bf_lo(v.w) - bf_lo(o2.w); s[7] += bf_hi(v.w) - bf_hi(o2.w);
;                 const float ic = 1.0f / (float)((tl + 1 < w) ? tl + 1 : w);
;                 u32x4 o;
;                 o.x = cvt_pk_bf16(s[0] * ic - bf_lo(v.x), s[1] * ic - bf_hi(v.x)); o.y = cvt_pk_bf16(s[2] * ic - bf_lo(v.y), s[3] * ic - bf_hi(v.y));
;                 o.z = cvt_pk_bf16(s[4] * ic - bf_lo(v.z), s[5] * ic - bf_hi(v.z)); o.w = cvt_pk_bf16(s[6] * ic - bf_lo(v.w), s[7] * ic - bf_hi(v.w));
;                 *(u32x4*)(pg + (size_t)row * DE + col) = o; }
	v_lshlrev_b32_e32 v184, 16, v92
	v_and_b32_e32 v185, 0xffff0000, v92
	v_lshlrev_b32_e32 v186, 16, v60
	v_and_b32_e32 v187, 0xffff0000, v60
	v_lshlrev_b32_e32 v188, 16, v93
	v_and_b32_e32 v189, 0xffff0000, v93
	v_lshlrev_b32_e32 v190, 16, v61
	v_and_b32_e32 v191, 0xffff0000, v61
	v_lshlrev_b32_e32 v192, 16, v94
	v_and_b32_e32 v193, 0xffff0000, v94
	v_lshlrev_b32_e32 v194, 16, v62
	v_and_b32_e32 v195, 0xffff0000, v62
	v_lshlrev_b32_e32 v196, 16, v95
	v_and_b32_e32 v197, 0xffff0000, v95
	v_lshlrev_b32_e32 v198, 16, v63
	v_and_b32_e32 v199, 0xffff0000, v63
	v_pk_add_f32 v[186:187], v[184:185], v[186:187] neg_lo:[0,1] neg_hi:[0,1]
	v_pk_add_f32 v[190:191], v[188:189], v[190:191] neg_lo:[0,1] neg_hi:[0,1]
	v_pk_add_f32 v[194:195], v[192:193], v[194:195] neg_lo:[0,1] neg_hi:[0,1]
	v_pk_add_f32 v[198:199], v[196:197], v[198:199] neg_lo:[0,1] neg_hi:[0,1]
	v_pk_add_f32 v[164:165], v[164:165], v[186:187]
	v_pk_add_f32 v[166:167], v[166:167], v[190:191]
	v_pk_add_f32 v[168:169], v[168:169], v[194:195]
	v_pk_add_f32 v[170:171], v[170:171], v[198:199]
	v_fma_f32 v186, s43, v164, -v184
	v_fma_f32 v187, s43, v165, -v185
	v_fma_f32 v190, s43, v166, -v188
	v_fma_f32 v191, s43, v167, -v189
	v_fma_f32 v194, s43, v168, -v192
	v_fma_f32 v195, s43, v169, -v193
	v_fma_f32 v198, s43, v170, -v196
	v_fma_f32 v199, s43, v171, -v197
	v_cvt_pk_bf16_f32 v172, v186, v187
	v_cvt_pk_bf16_f32 v173, v190, v191
	v_cvt_pk_bf16_f32 v174, v194, v195
	v_cvt_pk_bf16_f32 v175, v198, v199
	global_store_dwordx4 v3, v[172:175], s[10:11]
	v_add_u32_e32 v3, 0x2000, v3
	s_waitcnt vmcnt(31)
	v_lshlrev_b32_e32 v184, 16, v96
	v_and_b32_e32 v185, 0xffff0000, v96
	v_lshlrev_b32_e32 v186, 16, v64
	v_and_b32_e32 v187, 0xffff0000, v64
	v_lshlrev_b32_e32 v188, 16, v97
	v_and_b32_e32 v189, 0xffff0000, v97
	v_lshlrev_b32_e32 v190, 16, v65
	v_and_b32_e32 v191, 0xffff0000, v65
	v_lshlrev_b32_e32 v192, 16, v98
	v_and_b32_e32 v193, 0xffff0000, v98
	v_lshlrev_b32_e32 v194, 16, v66
	v_and_b32_e32 v195, 0xffff0000, v66
	v_lshlrev_b32_e32 v196, 16, v99
	v_and_b32_e32 v197, 0xffff0000, v99
	v_lshlrev_b32_e32 v198, 16, v67
	v_and_b32_e32 v199, 0xffff0000, v67
	v_pk_add_f32 v[186:187], v[184:185], v[186:187] neg_lo:[0,1] neg_hi:[0,1]
	v_pk_add_f32 v[190:191], v[188:189], v[190:191] neg_lo:[0,1] neg_hi:[0,1]
	v_pk_add_f32 v[194:195], v[192:193], v[194:195] neg_lo:[0,1] neg_hi:[0,1]
	v_pk_add_f32 v[198:199], v[196:197], v[198:199] neg_lo:[0,1] neg_hi:[0,1]
	v_pk_add_f32 v[164:165], v[164:165], v[186:187]
	v_pk_add_f32 v[166:167], v[166:167], v[190:191]
	v_pk_add_f32 v[168:169], v[168:169], v[194:195]
	v_pk_add_f32 v[170:171], v[170:171], v[198:199]
	v_fma_f32 v186, s43, v164, -v184
	v_fma_f32 v187, s43, v165, -v185
	v_fma_f32 v190, s43, v166, -v188
	v_fma_f32 v191, s43, v167, -v189
	v_fma_f32 v194, s43, v168, -v192
	v_fma_f32 v195, s43, v169, -v193
	v_fma_f32 v198, s43, v170, -v196
	v_fma_f32 v199, s43, v171, -v197
	v_cvt_pk_bf16_f32 v172, v186, v187
	v_cvt_pk_bf16_f32 v173, v190, v191
	v_cvt_pk_bf16_f32 v174, v194, v195
	v_cvt_pk_bf16_f32 v175, v198, v199
	global_store_dwordx4 v3, v[172:175], s[10:11]
	v_add_u32_e32 v3, 0x2000, v3
	s_waitcnt vmcnt(31)
	v_lshlrev_b32_e32 v184, 16, v100
	v_and_b32_e32 v185, 0xffff0000, v100
	v_lshlrev_b32_e32 v186, 16, v68
	v_and_b32_e32 v187, 0xffff0000, v68
	v_lshlrev_b32_e32 v188, 16, v101
	v_and_b32_e32 v189, 0xffff0000, v101
	v_lshlrev_b32_e32 v190, 16, v69
	v_and_b32_e32 v191, 0xffff0000, v69
	v_lshlrev_b32_e32 v192, 16, v102
	v_and_b32_e32 v193, 0xffff0000, v102
	v_lshlrev_b32_e32 v194, 16, v70
	v_and_b32_e32 v195, 0xffff0000, v70
	v_lshlrev_b32_e32 v196, 16, v103
	v_and_b32_e32 v197, 0xffff0000, v103
	v_lshlrev_b32_e32 v198, 16, v71
	v_and_b32_e32 v199, 0xffff0000, v71
	v_pk_add_f32 v[186:187], v[184:185], v[186:187] neg_lo:[0,1] neg_hi:[0,1]
	v_pk_add_f32 v[190:191], v[188:189], v[190:191] neg_lo:[0,1] neg_hi:[0,1]
	v_pk_add_f32 v[194:195], v[192:193], v[194:195] neg_lo:[0,1] neg_hi:[0,1]
	v_pk_add_f32 v[198:199], v[196:197], v[198:199] neg_lo:[0,1] neg_hi:[0,1]
	v_pk_add_f32 v[164:165], v[164:165], v[186:187]
	v_pk_add_f32 v[166:167], v[166:167], v[190:191]
	v_pk_add_f32 v[168:169], v[168:169], v[194:195]
	v_pk_add_f32 v[170:171], v[170:171], v[198:199]
	v_fma_f32 v186, s43, v164, -v184
	v_fma_f32 v187, s43, v165, -v185
	v_fma_f32 v190, s43, v166, -v188
	v_fma_f32 v191, s43, v167, -v189
	v_fma_f32 v194, s43, v168, -v192
	v_fma_f32 v195, s43, v169, -v193
	v_fma_f32 v198, s43, v170, -v196
	v_fma_f32 v199, s43, v171, -v197
	v_cvt_pk_bf16_f32 v172, v186, v187
	v_cvt_pk_bf16_f32 v173, v190, v191
	v_cvt_pk_bf16_f32 v174, v194, v195
	v_cvt_pk_bf16_f32 v175, v198, v199
	global_store_dwordx4 v3, v[172:175], s[10:11]
	v_add_u32_e32 v3, 0x2000, v3
	s_waitcnt vmcnt(31)
	v_lshlrev_b32_e32 v184, 16, v104
	v_and_b32_e32 v185, 0xffff0000, v104
	v_lshlrev_b32_e32 v186, 16, v72
	v_and_b32_e32 v187, 0xffff0000, v72
	v_lshlrev_b32_e32 v188, 16, v105
	v_and_b32_e32 v189, 0xffff0000, v105
	v_lshlrev_b32_e32 v190, 16, v73
	v_and_b32_e32 v191, 0xffff0000, v73
	v_lshlrev_b32_e32 v192, 16, v106
	v_and_b32_e32 v193, 0xffff0000, v106
	v_lshlrev_b32_e32 v194, 16, v74
	v_and_b32_e32 v195, 0xffff0000, v74
	v_lshlrev_b32_e32 v196, 16, v107
	v_and_b32_e32 v197, 0xffff0000, v107
	v_lshlrev_b32_e32 v198, 16, v75
	v_and_b32_e32 v199, 0xffff0000, v75
	v_pk_add_f32 v[186:187], v[184:185], v[186:187] neg_lo:[0,1] neg_hi:[0,1]
	v_pk_add_f32 v[190:191], v[188:189], v[190:191] neg_lo:[0,1] neg_hi:[0,1]
	v_pk_add_f32 v[194:195], v[192:193], v[194:195] neg_lo:[0,1] neg_hi:[0,1]
	v_pk_add_f32 v[198:199], v[196:197], v[198:199] neg_lo:[0,1] neg_hi:[0,1]
	v_pk_add_f32 v[164:165], v[164:165], v[186:187]
	v_pk_add_f32 v[166:167], v[166:167], v[190:191]
	v_pk_add_f32 v[168:169], v[168:169], v[194:195]
	v_pk_add_f32 v[170:171], v[170:171], v[198:199]
	v_fma_f32 v186, s43, v164, -v184
	v_fma_f32 v187, s43, v165, -v185
	v_fma_f32 v190, s43, v166, -v188
	v_fma_f32 v191, s43, v167, -v189
	v_fma_f32 v194, s43, v168, -v192
	v_fma_f32 v195, s43, v169, -v193
	v_fma_f32 v198, s43, v170, -v196
	v_fma_f32 v199, s43, v171, -v197
	v_cvt_pk_bf16_f32 v172, v186, v187
	v_cvt_pk_bf16_f32 v173, v190, v191
	v_cvt_pk_bf16_f32 v174, v194, v195
	v_cvt_pk_bf16_f32 v175, v198, v199
	global_store_dwordx4 v3, v[172:175], s[10:11]
	v_add_u32_e32 v3, 0x2000, v3
	s_waitcnt vmcnt(31)
; __device__ __forceinline__ unsigned cvt_pk_bf16(float lo, float hi) { unsigned r; asm volatile("v_cvt_pk_bf16_f32 %0, %1, %2" : "=v"(r) : "v"(lo), "v"(hi)); return r; }
; __device__ __forceinline__ float bf_lo(unsigned w) { return __uint_as_float(w << 16); }
; __device__ __forceinline__ float bf_hi(unsigned w) { return __uint_as_float(w & 0xffff0000u); }
; __device__ void phase_pool() {
;     ...
;             for (int k = 0; k < 8; ++k) { const int row = row0 + r0 + k, tl = tl0 + r0 + k; const u32x4 v = vv[k], o2 = ov[k];
;                 s[0] += bf_lo(v.x) - bf_lo(o2.x); s[1] += bf_hi(v.x) - bf_hi(o2.x); s[2] += bf_lo(v.y) - bf_lo(o2.y); s[3] += bf_hi(v.y) - bf_hi(o2.y);
;                 s[4] += bf_lo(v.z) - bf_lo(o2.z); s[5] += bf_hi(v.z) - bf_hi(o2.z); s[6] += bf_lo(v.w) - bf_lo(o2.w); s[7] += bf_hi(v.w) - bf_hi(o2.w);
;                 const float ic = 1.0f / (float)((tl + 1 < w) ? tl + 1 : w);
;                 u32x4 o;
;                 o.x = cvt_pk_bf16(s[0] * ic - bf_lo(v.x), s[1] * ic - bf_hi(v.x)); o.y = cvt_pk_bf16(s[2] * ic - bf_lo(v.y), s[3] * ic - bf_hi(v.y));
;                 o.z = cvt_pk_bf16(s[4] * ic - bf_lo(v.z), s[5] * ic - bf_hi(v.z)); o.w = cvt_pk_bf16(s[6] * ic - bf_lo(v.w), s[7] * ic - bf_hi(v.w));
;                 *(u32x4*)(pg + (size_t)row * DE + col) = o; }
	v_lshlrev_b32_e32 v184, 16, v108
	v_and_b32_e32 v185, 0xffff0000, v108
	v_lshlrev_b32_e32 v186, 16, v76
	v_and_b32_e32 v187, 0xffff0000, v76
	v_lshlrev_b32_e32 v188, 16, v109
	v_and_b32_e32 v189, 0xffff0000, v109
	v_lshlrev_b32_e32 v190, 16, v77
	v_and_b32_e32 v191, 0xffff0000, v77
	v_lshlrev_b32_e32 v192, 16, v110
	v_and_b32_e32 v193, 0xffff0000, v110
	v_lshlrev_b32_e32 v194, 16, v78
	v_and_b32_e32 v195, 0xffff0000, v78
	v_lshlrev_b32_e32 v196, 16, v111
	v_and_b32_e32 v197, 0xffff0000, v111
	v_lshlrev_b32_e32 v198, 16, v79
	v_and_b32_e32 v199, 0xffff0000, v79
	v_pk_add_f32 v[186:187], v[184:185], v[186:187] neg_lo:[0,1] neg_hi:[0,1]
	v_pk_add_f32 v[190:191], v[188:189], v[190:191] neg_lo:[0,1] neg_hi:[0,1]
	v_pk_add_f32 v[194:195], v[192:193], v[194:195] neg_lo:[0,1] neg_hi:[0,1]
	v_pk_add_f32 v[198:199], v[196:197], v[198:199] neg_lo:[0,1] neg_hi:[0,1]
	v_pk_add_f32 v[164:165], v[164:165], v[186:187]
	v_pk_add_f32 v[166:167], v[166:167], v[190:191]
	v_pk_add_f32 v[168:169], v[168:169], v[194:195]
	v_pk_add_f32 v[170:171], v[170:171], v[198:199]
	v_fma_f32 v186, s43, v164, -v184
	v_fma_f32 v187, s43, v165, -v185
	v_fma_f32 v190, s43, v166, -v188
	v_fma_f32 v191, s43, v167, -v189
	v_fma_f32 v194, s43, v168, -v192
	v_fma_f32 v195, s43, v169, -v193
	v_fma_f32 v198, s43, v170, -v196
	v_fma_f32 v199, s43, v171, -v197
	v_cvt_pk_bf16_f32 v172, v186, v187
	v_cvt_pk_bf16_f32 v173, v190, v191
	v_cvt_pk_bf16_f32 v174, v194, v195
	v_cvt_pk_bf16_f32 v175, v198, v199
	global_store_dwordx4 v3, v[172:175], s[10:11]
	v_add_u32_e32 v3, 0x2000, v3
	s_waitcnt vmcnt(31)
	v_lshlrev_b32_e32 v184, 16, v112
	v_and_b32_e32 v185, 0xffff0000, v112
	v_lshlrev_b32_e32 v186, 16, v80
	v_and_b32_e32 v187, 0xffff0000, v80
	v_lshlrev_b32_e32 v188, 16, v113
	v_and_b32_e32 v189, 0xffff0000, v113
	v_lshlrev_b32_e32 v190, 16, v81
	v_and_b32_e32 v191, 0xffff0000, v81
	v_lshlrev_b32_e32 v192, 16, v114
	v_and_b32_e32 v193, 0xffff0000, v114
	v_lshlrev_b32_e32 v194, 16, v82
	v_and_b32_e32 v195, 0xffff0000, v82
	v_lshlrev_b32_e32 v196, 16, v115
	v_and_b32_e32 v197, 0xffff0000, v115
	v_lshlrev_b32_e32 v198, 16, v83
	v_and_b32_e32 v199, 0xffff0000, v83
	v_pk_add_f32 v[186:187], v[184:185], v[186:187] neg_lo:[0,1] neg_hi:[0,1]
	v_pk_add_f32 v[190:191], v[188:189], v[190:191] neg_lo:[0,1] neg_hi:[0,1]
	v_pk_add_f32 v[194:195], v[192:193], v[194:195] neg_lo:[0,1] neg_hi:[0,1]
	v_pk_add_f32 v[198:199], v[196:197], v[198:199] neg_lo:[0,1] neg_hi:[0,1]
	v_pk_add_f32 v[164:165], v[164:165], v[186:187]
	v_pk_add_f32 v[166:167], v[166:167], v[190:191]
	v_pk_add_f32 v[168:169], v[168:169], v[194:195]
	v_pk_add_f32 v[170:171], v[170:171], v[198:199]
	v_fma_f32 v186, s43, v164, -v184
	v_fma_f32 v187, s43, v165, -v185
	v_fma_f32 v190, s43, v166, -v188
	v_fma_f32 v191, s43, v167, -v189
	v_fma_f32 v194, s43, v168, -v192
	v_fma_f32 v195, s43, v169, -v193
	v_fma_f32 v198, s43, v170, -v196
	v_fma_f32 v199, s43, v171, -v197
	v_cvt_pk_bf16_f32 v172, v186, v187
	v_cvt_pk_bf16_f32 v173, v190, v191
	v_cvt_pk_bf16_f32 v174, v194, v195
	v_cvt_pk_bf16_f32 v175, v198, v199
	global_store_dwordx4 v3, v[172:175], s[10:11]
	v_add_u32_e32 v3, 0x2000, v3
	s_waitcnt vmcnt(31)
	v_lshlrev_b32_e32 v184, 16, v116
	v_and_b32_e32 v185, 0xffff0000, v116
	v_lshlrev_b32_e32 v186, 16, v84
	v_and_b32_e32 v187, 0xffff0000, v84
	v_lshlrev_b32_e32 v188, 16, v117
	v_and_b32_e32 v189, 0xffff0000, v117
	v_lshlrev_b32_e32 v190, 16, v85
	v_and_b32_e32 v191, 0xffff0000, v85
	v_lshlrev_b32_e32 v192, 16, v118
	v_and_b32_e32 v193, 0xffff0000, v118
	v_lshlrev_b32_e32 v194, 16, v86
	v_and_b32_e32 v195, 0xffff0000, v86
	v_lshlrev_b32_e32 v196, 16, v119
	v_and_b32_e32 v197, 0xffff0000, v119
	v_lshlrev_b32_e32 v198, 16, v87
	v_and_b32_e32 v199, 0xffff0000, v87
	v_pk_add_f32 v[186:187], v[184:185], v[186:187] neg_lo:[0,1] neg_hi:[0,1]
	v_pk_add_f32 v[190:191], v[188:189], v[190:191] neg_lo:[0,1] neg_hi:[0,1]
	v_pk_add_f32 v[194:195], v[192:193], v[194:195] neg_lo:[0,1] neg_hi:[0,1]
	v_pk_add_f32 v[198:199], v[196:197], v[198:199] neg_lo:[0,1] neg_hi:[0,1]
	v_pk_add_f32 v[164:165], v[164:165], v[186:187]
	v_pk_add_f32 v[166:167], v[166:167], v[190:191]
	v_pk_add_f32 v[168:169], v[168:169], v[194:195]
	v_pk_add_f32 v[170:171], v[170:171], v[198:199]
	v_fma_f32 v186, s43, v164, -v184
	v_fma_f32 v187, s43, v165, -v185
	v_fma_f32 v190, s43, v166, -v188
	v_fma_f32 v191, s43, v167, -v189
	v_fma_f32 v194, s43, v168, -v192
	v_fma_f32 v195, s43, v169, -v193
	v_fma_f32 v198, s43, v170, -v196
	v_fma_f32 v199, s43, v171, -v197
	v_cvt_pk_bf16_f32 v172, v186, v187
	v_cvt_pk_bf16_f32 v173, v190, v191
	v_cvt_pk_bf16_f32 v174, v194, v195
	v_cvt_pk_bf16_f32 v175, v198, v199
	global_store_dwordx4 v3, v[172:175], s[10:11]
	v_add_u32_e32 v3, 0x2000, v3
	s_waitcnt vmcnt(31)
	v_lshlrev_b32_e32 v184, 16, v120
	v_and_b32_e32 v185, 0xffff0000, v120
	v_lshlrev_b32_e32 v186, 16, v88
	v_and_b32_e32 v187, 0xffff0000, v88
	v_lshlrev_b32_e32 v188, 16, v121
	v_and_b32_e32 v189, 0xffff0000, v121
	v_lshlrev_b32_e32 v190, 16, v89
	v_and_b32_e32 v191, 0xffff0000, v89
	v_lshlrev_b32_e32 v192, 16, v122
	v_and_b32_e32 v193, 0xffff0000, v122
	v_lshlrev_b32_e32 v194, 16, v90
	v_and_b32_e32 v195, 0xffff0000, v90
	v_lshlrev_b32_e32 v196, 16, v123
	v_and_b32_e32 v197, 0xffff0000, v123
	v_lshlrev_b32_e32 v198, 16, v91
	v_and_b32_e32 v199, 0xffff0000, v91
	v_pk_add_f32 v[186:187], v[184:185], v[186:187] neg_lo:[0,1] neg_hi:[0,1]
	v_pk_add_f32 v[190:191], v[188:189], v[190:191] neg_lo:[0,1] neg_hi:[0,1]
	v_pk_add_f32 v[194:195], v[192:193], v[194:195] neg_lo:[0,1] neg_hi:[0,1]
	v_pk_add_f32 v[198:199], v[196:197], v[198:199] neg_lo:[0,1] neg_hi:[0,1]
	v_pk_add_f32 v[164:165], v[164:165], v[186:187]
	v_pk_add_f32 v[166:167], v[166:167], v[190:191]
	v_pk_add_f32 v[168:169], v[168:169], v[194:195]
	v_pk_add_f32 v[170:171], v[170:171], v[198:199]
	v_fma_f32 v186, s43, v164, -v184
	v_fma_f32 v187, s43, v165, -v185
	v_fma_f32 v190, s43, v166, -v188
	v_fma_f32 v191, s43, v167, -v189
	v_fma_f32 v194, s43, v168, -v192
	v_fma_f32 v195, s43, v169, -v193
	v_fma_f32 v198, s43, v170, -v196
	v_fma_f32 v199, s43, v171, -v197
	v_cvt_pk_bf16_f32 v172, v186, v187
	v_cvt_pk_bf16_f32 v173, v190, v191
	v_cvt_pk_bf16_f32 v174, v194, v195
	v_cvt_pk_bf16_f32 v175, v198, v199
	global_store_dwordx4 v3, v[172:175], s[10:11]
	v_add_u32_e32 v3, 0x2000, v3
	s_waitcnt vmcnt(31)
; __device__ __forceinline__ unsigned cvt_pk_bf16(float lo, float hi) { unsigned r; asm volatile("v_cvt_pk_bf16_f32 %0, %1, %2" : "=v"(r) : "v"(lo), "v"(hi)); return r; }
; __device__ __forceinline__ float bf_lo(unsigned w) { return __uint_as_float(w << 16); }
; __device__ __forceinline__ float bf_hi(unsigned w) { return __uint_as_float(w & 0xffff0000u); }
; __device__ void phase_pool() {
;     ...
;             for (int k = 0; k < 8; ++k) { const int row = row0 + r0 + k, tl = tl0 + r0 + k; const u32x4 v = vv[k], o2 = ov[k];
;                 s[0] += bf_lo(v.x) - bf_lo(o2.x); s[1] += bf_hi(v.x) - bf_hi(o2.x); s[2] += bf_lo(v.y) - bf_lo(o2.y); s[3] += bf_hi(v.y) - bf_hi(o2.y);
;                 s[4] += bf_lo(v.z) - bf_lo(o2.z); s[5] += bf_hi(v.z) - bf_hi(o2.z); s[6] += bf_lo(v.w) - bf_lo(o2.w); s[7] += bf_hi(v.w) - bf_hi(o2.w);
;                 const float ic = 1.0f / (float)((tl + 1 < w) ? tl + 1 : w);
;                 u32x4 o;
;                 o.x = cvt_pk_bf16(s[0] * ic - bf_lo(v.x), s[1] * ic - bf_hi(v.x)); o.y = cvt_pk_bf16(s[2] * ic - bf_lo(v.y), s[3] * ic - bf_hi(v.y));
;                 o.z = cvt_pk_bf16(s[4] * ic - bf_lo(v.z), s[5] * ic - bf_hi(v.z)); o.w = cvt_pk_bf16(s[6] * ic - bf_lo(v.w), s[7] * ic - bf_hi(v.w));
;                 *(u32x4*)(pg + (size_t)row * DE + col) = o; }
	v_lshlrev_b32_e32 v184, 16, v124
	v_and_b32_e32 v185, 0xffff0000, v124
	v_lshlrev_b32_e32 v186, 16, v92
	v_and_b32_e32 v187, 0xffff0000, v92
	v_lshlrev_b32_e32 v188, 16, v125
	v_and_b32_e32 v189, 0xffff0000, v125
	v_lshlrev_b32_e32 v190, 16, v93
	v_and_b32_e32 v191, 0xffff0000, v93
	v_lshlrev_b32_e32 v192, 16, v126
	v_and_b32_e32 v193, 0xffff0000, v126
	v_lshlrev_b32_e32 v194, 16, v94
	v_and_b32_e32 v195, 0xffff0000, v94
	v_lshlrev_b32_e32 v196, 16, v127
	v_and_b32_e32 v197, 0xffff0000, v127
	v_lshlrev_b32_e32 v198, 16, v95
	v_and_b32_e32 v199, 0xffff0000, v95
	v_pk_add_f32 v[186:187], v[184:185], v[186:187] neg_lo:[0,1] neg_hi:[0,1]
	v_pk_add_f32 v[190:191], v[188:189], v[190:191] neg_lo:[0,1] neg_hi:[0,1]
	v_pk_add_f32 v[194:195], v[192:193], v[194:195] neg_lo:[0,1] neg_hi:[0,1]
	v_pk_add_f32 v[198:199], v[196:197], v[198:199] neg_lo:[0,1] neg_hi:[0,1]
	v_pk_add_f32 v[164:165], v[164:165], v[186:187]
	v_pk_add_f32 v[166:167], v[166:167], v[190:191]
	v_pk_add_f32 v[168:169], v[168:169], v[194:195]
	v_pk_add_f32 v[170:171], v[170:171], v[198:199]
	v_fma_f32 v186, s43, v164, -v184
	v_fma_f32 v187, s43, v165, -v185
	v_fma_f32 v190, s43, v166, -v188
	v_fma_f32 v191, s43, v167, -v189
	v_fma_f32 v194, s43, v168, -v192
	v_fma_f32 v195, s43, v169, -v193
	v_fma_f32 v198, s43, v170, -v196
	v_fma_f32 v199, s43, v171, -v197
	v_cvt_pk_bf16_f32 v172, v186, v187
	v_cvt_pk_bf16_f32 v173, v190, v191
	v_cvt_pk_bf16_f32 v174, v194, v195
	v_cvt_pk_bf16_f32 v175, v198, v199
	global_store_dwordx4 v3, v[172:175], s[10:11]
	v_add_u32_e32 v3, 0x2000, v3
	s_waitcnt vmcnt(31)
	v_lshlrev_b32_e32 v184, 16, v128
	v_and_b32_e32 v185, 0xffff0000, v128
	v_lshlrev_b32_e32 v186, 16, v96
	v_and_b32_e32 v187, 0xffff0000, v96
	v_lshlrev_b32_e32 v188, 16, v129
	v_and_b32_e32 v189, 0xffff0000, v129
	v_lshlrev_b32_e32 v190, 16, v97
	v_and_b32_e32 v191, 0xffff0000, v97
	v_lshlrev_b32_e32 v192, 16, v130
	v_and_b32_e32 v193, 0xffff0000, v130
	v_lshlrev_b32_e32 v194, 16, v98
	v_and_b32_e32 v195, 0xffff0000, v98
	v_lshlrev_b32_e32 v196, 16, v131
	v_and_b32_e32 v197, 0xffff0000, v131
	v_lshlrev_b32_e32 v198, 16, v99
	v_and_b32_e32 v199, 0xffff0000, v99
	v_pk_add_f32 v[186:187], v[184:185], v[186:187] neg_lo:[0,1] neg_hi:[0,1]
	v_pk_add_f32 v[190:191], v[188:189], v[190:191] neg_lo:[0,1] neg_hi:[0,1]
	v_pk_add_f32 v[194:195], v[192:193], v[194:195] neg_lo:[0,1] neg_hi:[0,1]
	v_pk_add_f32 v[198:199], v[196:197], v[198:199] neg_lo:[0,1] neg_hi:[0,1]
	v_pk_add_f32 v[164:165], v[164:165], v[186:187]
	v_pk_add_f32 v[166:167], v[166:167], v[190:191]
	v_pk_add_f32 v[168:169], v[168:169], v[194:195]
	v_pk_add_f32 v[170:171], v[170:171], v[198:199]
	v_fma_f32 v186, s43, v164, -v184
	v_fma_f32 v187, s43, v165, -v185
	v_fma_f32 v190, s43, v166, -v188
	v_fma_f32 v191, s43, v167, -v189
	v_fma_f32 v194, s43, v168, -v192
	v_fma_f32 v195, s43, v169, -v193
	v_fma_f32 v198, s43, v170, -v196
	v_fma_f32 v199, s43, v171, -v197
	v_cvt_pk_bf16_f32 v172, v186, v187
	v_cvt_pk_bf16_f32 v173, v190, v191
	v_cvt_pk_bf16_f32 v174, v194, v195
	v_cvt_pk_bf16_f32 v175, v198, v199
	global_store_dwordx4 v3, v[172:175], s[10:11]
	v_add_u32_e32 v3, 0x2000, v3
	s_waitcnt vmcnt(31)
	v_lshlrev_b32_e32 v184, 16, v132
	v_and_b32_e32 v185, 0xffff0000, v132
	v_lshlrev_b32_e32 v186, 16, v100
	v_and_b32_e32 v187, 0xffff0000, v100
	v_lshlrev_b32_e32 v188, 16, v133
	v_and_b32_e32 v189, 0xffff0000, v133
	v_lshlrev_b32_e32 v190, 16, v101
	v_and_b32_e32 v191, 0xffff0000, v101
	v_lshlrev_b32_e32 v192, 16, v134
	v_and_b32_e32 v193, 0xffff0000, v134
	v_lshlrev_b32_e32 v194, 16, v102
	v_and_b32_e32 v195, 0xffff0000, v102
	v_lshlrev_b32_e32 v196, 16, v135
	v_and_b32_e32 v197, 0xffff0000, v135
	v_lshlrev_b32_e32 v198, 16, v103
	v_and_b32_e32 v199, 0xffff0000, v103
	v_pk_add_f32 v[186:187], v[184:185], v[186:187] neg_lo:[0,1] neg_hi:[0,1]
	v_pk_add_f32 v[190:191], v[188:189], v[190:191] neg_lo:[0,1] neg_hi:[0,1]
	v_pk_add_f32 v[194:195], v[192:193], v[194:195] neg_lo:[0,1] neg_hi:[0,1]
	v_pk_add_f32 v[198:199], v[196:197], v[198:199] neg_lo:[0,1] neg_hi:[0,1]
	v_pk_add_f32 v[164:165], v[164:165], v[186:187]
	v_pk_add_f32 v[166:167], v[166:167], v[190:191]
	v_pk_add_f32 v[168:169], v[168:169], v[194:195]
	v_pk_add_f32 v[170:171], v[170:171], v[198:199]
	v_fma_f32 v186, s43, v164, -v184
	v_fma_f32 v187, s43, v165, -v185
	v_fma_f32 v190, s43, v166, -v188
	v_fma_f32 v191, s43, v167, -v189
	v_fma_f32 v194, s43, v168, -v192
	v_fma_f32 v195, s43, v169, -v193
	v_fma_f32 v198, s43, v170, -v196
	v_fma_f32 v199, s43, v171, -v197
	v_cvt_pk_bf16_f32 v172, v186, v187
	v_cvt_pk_bf16_f32 v173, v190, v191
	v_cvt_pk_bf16_f32 v174, v194, v195
	v_cvt_pk_bf16_f32 v175, v198, v199
	global_store_dwordx4 v3, v[172:175], s[10:11]
	v_add_u32_e32 v3, 0x2000, v3
	s_waitcnt vmcnt(31)
	v_lshlrev_b32_e32 v184, 16, v136
	v_and_b32_e32 v185, 0xffff0000, v136
	v_lshlrev_b32_e32 v186, 16, v104
	v_and_b32_e32 v187, 0xffff0000, v104
	v_lshlrev_b32_e32 v188, 16, v137
	v_and_b32_e32 v189, 0xffff0000, v137
	v_lshlrev_b32_e32 v190, 16, v105
	v_and_b32_e32 v191, 0xffff0000, v105
	v_lshlrev_b32_e32 v192, 16, v138
	v_and_b32_e32 v193, 0xffff0000, v138
	v_lshlrev_b32_e32 v194, 16, v106
	v_and_b32_e32 v195, 0xffff0000, v106
	v_lshlrev_b32_e32 v196, 16, v139
	v_and_b32_e32 v197, 0xffff0000, v139
	v_lshlrev_b32_e32 v198, 16, v107
	v_and_b32_e32 v199, 0xffff0000, v107
	v_pk_add_f32 v[186:187], v[184:185], v[186:187] neg_lo:[0,1] neg_hi:[0,1]
	v_pk_add_f32 v[190:191], v[188:189], v[190:191] neg_lo:[0,1] neg_hi:[0,1]
	v_pk_add_f32 v[194:195], v[192:193], v[194:195] neg_lo:[0,1] neg_hi:[0,1]
	v_pk_add_f32 v[198:199], v[196:197], v[198:199] neg_lo:[0,1] neg_hi:[0,1]
	v_pk_add_f32 v[164:165], v[164:165], v[186:187]
	v_pk_add_f32 v[166:167], v[166:167], v[190:191]
	v_pk_add_f32 v[168:169], v[168:169], v[194:195]
	v_pk_add_f32 v[170:171], v[170:171], v[198:199]
	v_fma_f32 v186, s43, v164, -v184
	v_fma_f32 v187, s43, v165, -v185
	v_fma_f32 v190, s43, v166, -v188
	v_fma_f32 v191, s43, v167, -v189
	v_fma_f32 v194, s43, v168, -v192
	v_fma_f32 v195, s43, v169, -v193
	v_fma_f32 v198, s43, v170, -v196
	v_fma_f32 v199, s43, v171, -v197
	v_cvt_pk_bf16_f32 v172, v186, v187
	v_cvt_pk_bf16_f32 v173, v190, v191
	v_cvt_pk_bf16_f32 v174, v194, v195
	v_cvt_pk_bf16_f32 v175, v198, v199
	global_store_dwordx4 v3, v[172:175], s[10:11]
	v_add_u32_e32 v3, 0x2000, v3
	s_waitcnt vmcnt(31)
; __device__ __forceinline__ unsigned cvt_pk_bf16(float lo, float hi) { unsigned r; asm volatile("v_cvt_pk_bf16_f32 %0, %1, %2" : "=v"(r) : "v"(lo), "v"(hi)); return r; }
; __device__ __forceinline__ float bf_lo(unsigned w) { return __uint_as_float(w << 16); }
; __device__ __forceinline__ float bf_hi(unsigned w) { return __uint_as_float(w & 0xffff0000u); }
; __device__ void phase_pool() {
;     ...
;             for (int k = 0; k < 8; ++k) { const int row = row0 + r0 + k, tl = tl0 + r0 + k; const u32x4 v = vv[k], o2 = ov[k];
;                 s[0] += bf_lo(v.x) - bf_lo(o2.x); s[1] += bf_hi(v.x) - bf_hi(o2.x); s[2] += bf_lo(v.y) - bf_lo(o2.y); s[3] += bf_hi(v.y) - bf_hi(o2.y);
;                 s[4] += bf_lo(v.z) - bf_lo(o2.z); s[5] += bf_hi(v.z) - bf_hi(o2.z); s[6] += bf_lo(v.w) - bf_lo(o2.w); s[7] += bf_hi(v.w) - bf_hi(o2.w);
;                 const float ic = 1.0f / (float)((tl + 1 < w) ? tl + 1 : w);
;                 u32x4 o;
;                 o.x = cvt_pk_bf16(s[0] * ic - bf_lo(v.x), s[1] * ic - bf_hi(v.x)); o.y = cvt_pk_bf16(s[2] * ic - bf_lo(v.y), s[3] * ic - bf_hi(v.y));
;                 o.z = cvt_pk_bf16(s[4] * ic - bf_lo(v.z), s[5] * ic - bf_hi(v.z)); o.w = cvt_pk_bf16(s[6] * ic - bf_lo(v.w), s[7] * ic - bf_hi(v.w));
;                 *(u32x4*)(pg + (size_t)row * DE + col) = o; }
	v_lshlrev_b32_e32 v184, 16, v140
	v_and_b32_e32 v185, 0xffff0000, v140
	v_lshlrev_b32_e32 v186, 16, v108
	v_and_b32_e32 v187, 0xffff0000, v108
	v_lshlrev_b32_e32 v188, 16, v141
	v_and_b32_e32 v189, 0xffff0000, v141
	v_lshlrev_b32_e32 v190, 16, v109
	v_and_b32_e32 v191, 0xffff0000, v109
	v_lshlrev_b32_e32 v192, 16, v142
	v_and_b32_e32 v193, 0xffff0000, v142
	v_lshlrev_b32_e32 v194, 16, v110
	v_and_b32_e32 v195, 0xffff0000, v110
	v_lshlrev_b32_e32 v196, 16, v143
	v_and_b32_e32 v197, 0xffff0000, v143
	v_lshlrev_b32_e32 v198, 16, v111
	v_and_b32_e32 v199, 0xffff0000, v111
	v_pk_add_f32 v[186:187], v[184:185], v[186:187] neg_lo:[0,1] neg_hi:[0,1]
	v_pk_add_f32 v[190:191], v[188:189], v[190:191] neg_lo:[0,1] neg_hi:[0,1]
	v_pk_add_f32 v[194:195], v[192:193], v[194:195] neg_lo:[0,1] neg_hi:[0,1]
	v_pk_add_f32 v[198:199], v[196:197], v[198:199] neg_lo:[0,1] neg_hi:[0,1]
	v_pk_add_f32 v[164:165], v[164:165], v[186:187]
	v_pk_add_f32 v[166:167], v[166:167], v[190:191]
	v_pk_add_f32 v[168:169], v[168:169], v[194:195]
	v_pk_add_f32 v[170:171], v[170:171], v[198:199]
	v_fma_f32 v186, s43, v164, -v184
	v_fma_f32 v187, s43, v165, -v185
	v_fma_f32 v190, s43, v166, -v188
	v_fma_f32 v191, s43, v167, -v189
	v_fma_f32 v194, s43, v168, -v192
	v_fma_f32 v195, s43, v169, -v193
	v_fma_f32 v198, s43, v170, -v196
	v_fma_f32 v199, s43, v171, -v197
	v_cvt_pk_bf16_f32 v172, v186, v187
	v_cvt_pk_bf16_f32 v173, v190, v191
	v_cvt_pk_bf16_f32 v174, v194, v195
	v_cvt_pk_bf16_f32 v175, v198, v199
	global_store_dwordx4 v3, v[172:175], s[10:11]
	v_add_u32_e32 v3, 0x2000, v3
	s_waitcnt vmcnt(31)
	v_lshlrev_b32_e32 v184, 16, v144
	v_and_b32_e32 v185, 0xffff0000, v144
	v_lshlrev_b32_e32 v186, 16, v112
	v_and_b32_e32 v187, 0xffff0000, v112
	v_lshlrev_b32_e32 v188, 16, v145
	v_and_b32_e32 v189, 0xffff0000, v145
	v_lshlrev_b32_e32 v190, 16, v113
	v_and_b32_e32 v191, 0xffff0000, v113
	v_lshlrev_b32_e32 v192, 16, v146
	v_and_b32_e32 v193, 0xffff0000, v146
	v_lshlrev_b32_e32 v194, 16, v114
	v_and_b32_e32 v195, 0xffff0000, v114
	v_lshlrev_b32_e32 v196, 16, v147
	v_and_b32_e32 v197, 0xffff0000, v147
	v_lshlrev_b32_e32 v198, 16, v115
	v_and_b32_e32 v199, 0xffff0000, v115
	v_pk_add_f32 v[186:187], v[184:185], v[186:187] neg_lo:[0,1] neg_hi:[0,1]
	v_pk_add_f32 v[190:191], v[188:189], v[190:191] neg_lo:[0,1] neg_hi:[0,1]
	v_pk_add_f32 v[194:195], v[192:193], v[194:195] neg_lo:[0,1] neg_hi:[0,1]
	v_pk_add_f32 v[198:199], v[196:197], v[198:199] neg_lo:[0,1] neg_hi:[0,1]
	v_pk_add_f32 v[164:165], v[164:165], v[186:187]
	v_pk_add_f32 v[166:167], v[166:167], v[190:191]
	v_pk_add_f32 v[168:169], v[168:169], v[194:195]
	v_pk_add_f32 v[170:171], v[170:171], v[198:199]
	v_fma_f32 v186, s43, v164, -v184
	v_fma_f32 v187, s43, v165, -v185
	v_fma_f32 v190, s43, v166, -v188
	v_fma_f32 v191, s43, v167, -v189
	v_fma_f32 v194, s43, v168, -v192
	v_fma_f32 v195, s43, v169, -v193
	v_fma_f32 v198, s43, v170, -v196
	v_fma_f32 v199, s43, v171, -v197
	v_cvt_pk_bf16_f32 v172, v186, v187
	v_cvt_pk_bf16_f32 v173, v190, v191
	v_cvt_pk_bf16_f32 v174, v194, v195
	v_cvt_pk_bf16_f32 v175, v198, v199
	global_store_dwordx4 v3, v[172:175], s[10:11]
	v_add_u32_e32 v3, 0x2000, v3
	s_waitcnt vmcnt(31)
	v_lshlrev_b32_e32 v184, 16, v148
	v_and_b32_e32 v185, 0xffff0000, v148
	v_lshlrev_b32_e32 v186, 16, v116
	v_and_b32_e32 v187, 0xffff0000, v116
	v_lshlrev_b32_e32 v188, 16, v149
	v_and_b32_e32 v189, 0xffff0000, v149
	v_lshlrev_b32_e32 v190, 16, v117
	v_and_b32_e32 v191, 0xffff0000, v117
	v_lshlrev_b32_e32 v192, 16, v150
	v_and_b32_e32 v193, 0xffff0000, v150
	v_lshlrev_b32_e32 v194, 16, v118
	v_and_b32_e32 v195, 0xffff0000, v118
	v_lshlrev_b32_e32 v196, 16, v151
	v_and_b32_e32 v197, 0xffff0000, v151
	v_lshlrev_b32_e32 v198, 16, v119
	v_and_b32_e32 v199, 0xffff0000, v119
	v_pk_add_f32 v[186:187], v[184:185], v[186:187] neg_lo:[0,1] neg_hi:[0,1]
	v_pk_add_f32 v[190:191], v[188:189], v[190:191] neg_lo:[0,1] neg_hi:[0,1]
	v_pk_add_f32 v[194:195], v[192:193], v[194:195] neg_lo:[0,1] neg_hi:[0,1]
	v_pk_add_f32 v[198:199], v[196:197], v[198:199] neg_lo:[0,1] neg_hi:[0,1]
	v_pk_add_f32 v[164:165], v[164:165], v[186:187]
	v_pk_add_f32 v[166:167], v[166:167], v[190:191]
	v_pk_add_f32 v[168:169], v[168:169], v[194:195]
	v_pk_add_f32 v[170:171], v[170:171], v[198:199]
	v_fma_f32 v186, s43, v164, -v184
	v_fma_f32 v187, s43, v165, -v185
	v_fma_f32 v190, s43, v166, -v188
	v_fma_f32 v191, s43, v167, -v189
	v_fma_f32 v194, s43, v168, -v192
	v_fma_f32 v195, s43, v169, -v193
	v_fma_f32 v198, s43, v170, -v196
	v_fma_f32 v199, s43, v171, -v197
	v_cvt_pk_bf16_f32 v172, v186, v187
	v_cvt_pk_bf16_f32 v173, v190, v191
	v_cvt_pk_bf16_f32 v174, v194, v195
	v_cvt_pk_bf16_f32 v175, v198, v199
	global_store_dwordx4 v3, v[172:175], s[10:11]
	v_add_u32_e32 v3, 0x2000, v3
	s_waitcnt vmcnt(31)
	v_lshlrev_b32_e32 v184, 16, v152
	v_and_b32_e32 v185, 0xffff0000, v152
	v_lshlrev_b32_e32 v186, 16, v120
	v_and_b32_e32 v187, 0xffff0000, v120
	v_lshlrev_b32_e32 v188, 16, v153
	v_and_b32_e32 v189, 0xffff0000, v153
	v_lshlrev_b32_e32 v190, 16, v121
	v_and_b32_e32 v191, 0xffff0000, v121
	v_lshlrev_b32_e32 v192, 16, v154
	v_and_b32_e32 v193, 0xffff0000, v154
	v_lshlrev_b32_e32 v194, 16, v122
	v_and_b32_e32 v195, 0xffff0000, v122
	v_lshlrev_b32_e32 v196, 16, v155
	v_and_b32_e32 v197, 0xffff0000, v155
	v_lshlrev_b32_e32 v198, 16, v123
	v_and_b32_e32 v199, 0xffff0000, v123
	v_pk_add_f32 v[186:187], v[184:185], v[186:187] neg_lo:[0,1] neg_hi:[0,1]
	v_pk_add_f32 v[190:191], v[188:189], v[190:191] neg_lo:[0,1] neg_hi:[0,1]
	v_pk_add_f32 v[194:195], v[192:193], v[194:195] neg_lo:[0,1] neg_hi:[0,1]
	v_pk_add_f32 v[198:199], v[196:197], v[198:199] neg_lo:[0,1] neg_hi:[0,1]
	v_pk_add_f32 v[164:165], v[164:165], v[186:187]
	v_pk_add_f32 v[166:167], v[166:167], v[190:191]
	v_pk_add_f32 v[168:169], v[168:169], v[194:195]
	v_pk_add_f32 v[170:171], v[170:171], v[198:199]
	v_fma_f32 v186, s43, v164, -v184
	v_fma_f32 v187, s43, v165, -v185
	v_fma_f32 v190, s43, v166, -v188
	v_fma_f32 v191, s43, v167, -v189
	v_fma_f32 v194, s43, v168, -v192
	v_fma_f32 v195, s43, v169, -v193
	v_fma_f32 v198, s43, v170, -v196
	v_fma_f32 v199, s43, v171, -v197
	v_cvt_pk_bf16_f32 v172, v186, v187
	v_cvt_pk_bf16_f32 v173, v190, v191
	v_cvt_pk_bf16_f32 v174, v194, v195
	v_cvt_pk_bf16_f32 v175, v198, v199
	global_store_dwordx4 v3, v[172:175], s[10:11]
	v_add_u32_e32 v3, 0x2000, v3
	s_waitcnt vmcnt(31)
; __device__ __forceinline__ unsigned cvt_pk_bf16(float lo, float hi) { unsigned r; asm volatile("v_cvt_pk_bf16_f32 %0, %1, %2" : "=v"(r) : "v"(lo), "v"(hi)); return r; }
; __device__ __forceinline__ float bf_lo(unsigned w) { return __uint_as_float(w << 16); }
; __device__ __forceinline__ float bf_hi(unsigned w) { return __uint_as_float(w & 0xffff0000u); }
; __device__ void phase_pool() {
;     ...
;         const int nh = (tl0 < w) ? tl0 : w;
;         { u32x4 hv[16];
; #pragma unroll
;           for (int k = 1; k <= 16; ++k) hv[k - 1] = (k <= nh) ? *(const u32x4*)(uz + (size_t)(row0 - k) * DE2 + col) : (u32x4){0u, 0u, 0u, 0u};
;     ...
;             for (int k = 0; k < 8; ++k) { const int row = row0 + r0 + k, tl = tl0 + r0 + k; const u32x4 v = vv[k], o2 = ov[k];
;                 s[0] += bf_lo(v.x) - bf_lo(o2.x); s[1] += bf_hi(v.x) - bf_hi(o2.x); s[2] += bf_lo(v.y) - bf_lo(o2.y); s[3] += bf_hi(v.y) - bf_hi(o2.y);
;                 s[4] += bf_lo(v.z) - bf_lo(o2.z); s[5] += bf_hi(v.z) - bf_hi(o2.z); s[6] += bf_lo(v.w) - bf_lo(o2.w); s[7] += bf_hi(v.w) - bf_hi(o2.w);
;                 const float ic = 1.0f / (float)((tl + 1 < w) ? tl + 1 : w);
;                 u32x4 o;
;                 o.x = cvt_pk_bf16(s[0] * ic - bf_lo(v.x), s[1] * ic - bf_hi(v.x)); o.y = cvt_pk_bf16(s[2] * ic - bf_lo(v.y), s[3] * ic - bf_hi(v.y));
;                 o.z = cvt_pk_bf16(s[4] * ic - bf_lo(v.z), s[5] * ic - bf_hi(v.z)); o.w = cvt_pk_bf16(s[6] * ic - bf_lo(v.w), s[7] * ic - bf_hi(v.w));
;                 *(u32x4*)(pg + (size_t)row * DE + col) = o; }
	v_lshlrev_b32_e32 v184, 16, v156
	v_and_b32_e32 v185, 0xffff0000, v156
	v_lshlrev_b32_e32 v186, 16, v124
	v_and_b32_e32 v187, 0xffff0000, v124
	v_lshlrev_b32_e32 v188, 16, v157
	v_and_b32_e32 v189, 0xffff0000, v157
	v_lshlrev_b32_e32 v190, 16, v125
	v_and_b32_e32 v191, 0xffff0000, v125
	v_lshlrev_b32_e32 v192, 16, v158
	v_and_b32_e32 v193, 0xffff0000, v158
	v_lshlrev_b32_e32 v194, 16, v126
	v_and_b32_e32 v195, 0xffff0000, v126
	v_lshlrev_b32_e32 v196, 16, v159
	v_and_b32_e32 v197, 0xffff0000, v159
	v_lshlrev_b32_e32 v198, 16, v127
	v_and_b32_e32 v199, 0xffff0000, v127
	v_pk_add_f32 v[186:187], v[184:185], v[186:187] neg_lo:[0,1] neg_hi:[0,1]
	v_pk_add_f32 v[190:191], v[188:189], v[190:191] neg_lo:[0,1] neg_hi:[0,1]
	v_pk_add_f32 v[194:195], v[192:193], v[194:195] neg_lo:[0,1] neg_hi:[0,1]
	v_pk_add_f32 v[198:199], v[196:197], v[198:199] neg_lo:[0,1] neg_hi:[0,1]
	v_pk_add_f32 v[164:165], v[164:165], v[186:187]
	v_pk_add_f32 v[166:167], v[166:167], v[190:191]
	v_pk_add_f32 v[168:169], v[168:169], v[194:195]
	v_pk_add_f32 v[170:171], v[170:171], v[198:199]
	v_fma_f32 v186, s43, v164, -v184
	v_fma_f32 v187, s43, v165, -v185
	v_fma_f32 v190, s43, v166, -v188
	v_fma_f32 v191, s43, v167, -v189
	v_fma_f32 v194, s43, v168, -v192
	v_fma_f32 v195, s43, v169, -v193
	v_fma_f32 v198, s43, v170, -v196
	v_fma_f32 v199, s43, v171, -v197
	v_cvt_pk_bf16_f32 v172, v186, v187
	v_cvt_pk_bf16_f32 v173, v190, v191
	v_cvt_pk_bf16_f32 v174, v194, v195
	v_cvt_pk_bf16_f32 v175, v198, v199
	global_store_dwordx4 v3, v[172:175], s[10:11]
	v_add_u32_e32 v3, 0x2000, v3
	s_waitcnt vmcnt(31)
	v_lshlrev_b32_e32 v184, 16, v160
	v_and_b32_e32 v185, 0xffff0000, v160
	v_lshlrev_b32_e32 v186, 16, v128
	v_and_b32_e32 v187, 0xffff0000, v128
	v_lshlrev_b32_e32 v188, 16, v161
	v_and_b32_e32 v189, 0xffff0000, v161
	v_lshlrev_b32_e32 v190, 16, v129
	v_and_b32_e32 v191, 0xffff0000, v129
	v_lshlrev_b32_e32 v192, 16, v162
	v_and_b32_e32 v193, 0xffff0000, v162
	v_lshlrev_b32_e32 v194, 16, v130
	v_and_b32_e32 v195, 0xffff0000, v130
	v_lshlrev_b32_e32 v196, 16, v163
	v_and_b32_e32 v197, 0xffff0000, v163
	v_lshlrev_b32_e32 v198, 16, v131
	v_and_b32_e32 v199, 0xffff0000, v131
	v_pk_add_f32 v[186:187], v[184:185], v[186:187] neg_lo:[0,1] neg_hi:[0,1]
	v_pk_add_f32 v[190:191], v[188:189], v[190:191] neg_lo:[0,1] neg_hi:[0,1]
	v_pk_add_f32 v[194:195], v[192:193], v[194:195] neg_lo:[0,1] neg_hi:[0,1]
	v_pk_add_f32 v[198:199], v[196:197], v[198:199] neg_lo:[0,1] neg_hi:[0,1]
	v_pk_add_f32 v[164:165], v[164:165], v[186:187]
	v_pk_add_f32 v[166:167], v[166:167], v[190:191]
	v_pk_add_f32 v[168:169], v[168:169], v[194:195]
	v_pk_add_f32 v[170:171], v[170:171], v[198:199]
	v_fma_f32 v186, s43, v164, -v184
	v_fma_f32 v187, s43, v165, -v185
	v_fma_f32 v190, s43, v166, -v188
	v_fma_f32 v191, s43, v167, -v189
	v_fma_f32 v194, s43, v168, -v192
	v_fma_f32 v195, s43, v169, -v193
	v_fma_f32 v198, s43, v170, -v196
	v_fma_f32 v199, s43, v171, -v197
	v_cvt_pk_bf16_f32 v172, v186, v187
	v_cvt_pk_bf16_f32 v173, v190, v191
	v_cvt_pk_bf16_f32 v174, v194, v195
	v_cvt_pk_bf16_f32 v175, v198, v199
	global_store_dwordx4 v3, v[172:175], s[10:11]
	s_branch .LBB0_441
.Lpool_w16:
	s_cmp_eq_u32 s16, 0
	s_cbranch_scc1 .Lpool_w16_nohist
	s_sub_u32 s0, s15, 16
	s_lshl_b32 s0, s0, 14
	s_add_u32 s8, s4, s0
	s_addc_u32 s9, s5, 0
	global_load_dwordx4 v[4:7], v2, s[8:9]
	v_add_u32_e32 v2, 0x4000, v2
	global_load_dwordx4 v[8:11], v2, s[8:9]
	v_add_u32_e32 v2, 0x4000, v2
	global_load_dwordx4 v[12:15], v2, s[8:9]
	v_add_u32_e32 v2, 0x4000, v2
	global_load_dwordx4 v[16:19], v2, s[8:9]
	v_add_u32_e32 v2, 0x4000, v2
	global_load_dwordx4 v[20:23], v2, s[8:9]
	v_add_u32_e32 v2, 0x4000, v2
	global_load_dwordx4 v[24:27], v2, s[8:9]
	v_add_u32_e32 v2, 0x4000, v2
	global_load_dwordx4 v[28:31], v2, s[8:9]
	v_add_u32_e32 v2, 0x4000, v2
	global_load_dwordx4 v[32:35], v2, s[8:9]
	v_add_u32_e32 v2, 0x4000, v2
	global_load_dwordx4 v[36:39], v2, s[8:9]
	v_add_u32_e32 v2, 0x4000, v2
	global_load_dwordx4 v[40:43], v2, s[8:9]
	v_add_u32_e32 v2, 0x4000, v2
	global_load_dwordx4 v[44:47], v2, s[8:9]
	v_add_u32_e32 v2, 0x4000, v2
	global_load_dwordx4 v[48:51], v2, s[8:9]
	v_add_u32_e32 v2, 0x4000, v2
	global_load_dwordx4 v[52:55], v2, s[8:9]
	v_add_u32_e32 v2, 0x4000, v2
	global_load_dwordx4 v[56:59], v2, s[8:9]
	v_add_u32_e32 v2, 0x4000, v2
	global_load_dwordx4 v[60:63], v2, s[8:9]
	v_add_u32_e32 v2, 0x4000, v2
	global_load_dwordx4 v[64:67], v2, s[8:9]
	v_add_u32_e32 v2, 0x4000, v2
	s_branch .Lpool_w16_main
.Lpool_w16_nohist:
	v_mov_b32_e32 v4, 0
	v_mov_b32_e32 v5, 0
	v_mov_b32_e32 v6, 0
	v_mov_b32_e32 v7, 0
	v_mov_b32_e32 v8, 0
	v_mov_b32_e32 v9, 0
	v_mov_b32_e32 v10, 0
	v_mov_b32_e32 v11, 0
	v_mov_b32_e32 v12, 0
	v_mov_b32_e32 v13, 0
	v_mov_b32_e32 v14, 0
	v_mov_b32_e32 v15, 0
	v_mov_b32_e32 v16, 0
	v_mov_b32_e32 v17, 0
	v_mov_b32_e32 v18, 0
	v_mov_b32_e32 v19, 0
	v_mov_b32_e32 v20, 0
	v_mov_b32_e32 v21, 0
	v_mov_b32_e32 v22, 0
	v_mov_b32_e32 v23, 0
	v_mov_b32_e32 v24, 0
	v_mov_b32_e32 v25, 0
	v_mov_b32_e32 v26, 0
	v_mov_b32_e32 v27, 0
	v_mov_b32_e32 v28, 0
	v_mov_b32_e32 v29, 0
	v_mov_b32_e32 v30, 0
	v_mov_b32_e32 v31, 0
	v_mov_b32_e32 v32, 0
	v_mov_b32_e32 v33, 0
	v_mov_b32_e32 v34, 0
	v_mov_b32_e32 v35, 0
	v_mov_b32_e32 v36, 0
	v_mov_b32_e32 v37, 0
	v_mov_b32_e32 v38, 0
	v_mov_b32_e32 v39, 0
	v_mov_b32_e32 v40, 0
	v_mov_b32_e32 v41, 0
	v_mov_b32_e32 v42, 0
	v_mov_b32_e32 v43, 0
	v_mov_b32_e32 v44, 0
	v_mov_b32_e32 v45, 0
	v_mov_b32_e32 v46, 0
	v_mov_b32_e32 v47, 0
	v_mov_b32_e32 v48, 0
	v_mov_b32_e32 v49, 0
	v_mov_b32_e32 v50, 0
	v_mov_b32_e32 v51, 0
	v_mov_b32_e32 v52, 0
	v_mov_b32_e32 v53, 0
	v_mov_b32_e32 v54, 0
	v_mov_b32_e32 v55, 0
	v_mov_b32_e32 v56, 0
	v_mov_b32_e32 v57, 0
	v_mov_b32_e32 v58, 0
	v_mov_b32_e32 v59, 0
	v_mov_b32_e32 v60, 0
	v_mov_b32_e32 v61, 0
	v_mov_b32_e32 v62, 0
	v_mov_b32_e32 v63, 0
	v_mov_b32_e32 v64, 0
	v_mov_b32_e32 v65, 0
	v_mov_b32_e32 v66, 0
	v_mov_b32_e32 v67, 0
	s_lshl_b32 s0, s15, 14
	s_add_u32 s8, s4, s0
	s_addc_u32 s9, s5, 0
; __device__ __forceinline__ float bf_lo(unsigned w) { return __uint_as_float(w << 16); }
; __device__ __forceinline__ float bf_hi(unsigned w) { return __uint_as_float(w & 0xffff0000u); }
; __device__ void phase_pool() {
;     ...
;         const int nh = (tl0 < w) ? tl0 : w;
;         { u32x4 hv[16];
; #pragma unroll
;           for (int k = 1; k <= 16; ++k) hv[k - 1] = (k <= nh) ? *(const u32x4*)(uz + (size_t)(row0 - k) * DE2 + col) : (u32x4){0u, 0u, 0u, 0u};
; #pragma unroll
;           for (int k = 0; k < 16; ++k) { const u32x4 v = hv[k];
;             s[0] += bf_lo(v.x); s[1] += bf_hi(v.x); s[2] += bf_lo(v.y); s[3] += bf_hi(v.y); s[4] += bf_lo(v.z); s[5] += bf_hi(v.z); s[6] += bf_lo(v.w); s[7] += bf_hi(v.w); } }
; #pragma unroll 1
;         for (int r0 = 0; r0 < RB; r0 += 8) {
;             u32x4 vv[8], ov[8];
; #pragma unroll
;             for (int k = 0; k < 8; ++k) { const int row = row0 + r0 + k, tl = tl0 + r0 + k;
;                 vv[k] = *(const u32x4*)(uz + (size_t)row * DE2 + col);
;                 ov[k] = (tl >= w) ? *(const u32x4*)(uz + (size_t)(row - w) * DE2 + col) : (u32x4){0u, 0u, 0u, 0u}; }
.Lpool_w16_main:
	global_load_dwordx4 v[68:71], v2, s[8:9]
	v_add_u32_e32 v2, 0x4000, v2
	global_load_dwordx4 v[72:75], v2, s[8:9]
	v_add_u32_e32 v2, 0x4000, v2
	global_load_dwordx4 v[76:79], v2, s[8:9]
	v_add_u32_e32 v2, 0x4000, v2
	global_load_dwordx4 v[80:83], v2, s[8:9]
	v_add_u32_e32 v2, 0x4000, v2
	global_load_dwordx4 v[84:87], v2, s[8:9]
	v_add_u32_e32 v2, 0x4000, v2
	global_load_dwordx4 v[88:91], v2, s[8:9]
	v_add_u32_e32 v2, 0x4000, v2
	global_load_dwordx4 v[92:95], v2, s[8:9]
	v_add_u32_e32 v2, 0x4000, v2
	global_load_dwordx4 v[96:99], v2, s[8:9]
	v_add_u32_e32 v2, 0x4000, v2
	global_load_dwordx4 v[100:103], v2, s[8:9]
	v_add_u32_e32 v2, 0x4000, v2
	global_load_dwordx4 v[104:107], v2, s[8:9]
	v_add_u32_e32 v2, 0x4000, v2
	global_load_dwordx4 v[108:111], v2, s[8:9]
	v_add_u32_e32 v2, 0x4000, v2
	global_load_dwordx4 v[112:115], v2, s[8:9]
	v_add_u32_e32 v2, 0x4000, v2
	global_load_dwordx4 v[116:119], v2, s[8:9]
	v_add_u32_e32 v2, 0x4000, v2
	global_load_dwordx4 v[120:123], v2, s[8:9]
	v_add_u32_e32 v2, 0x4000, v2
	global_load_dwordx4 v[124:127], v2, s[8:9]
	v_add_u32_e32 v2, 0x4000, v2
	global_load_dwordx4 v[128:131], v2, s[8:9]
	v_add_u32_e32 v2, 0x4000, v2
	global_load_dwordx4 v[132:135], v2, s[8:9]
	v_add_u32_e32 v2, 0x4000, v2
	global_load_dwordx4 v[136:139], v2, s[8:9]
	v_add_u32_e32 v2, 0x4000, v2
	global_load_dwordx4 v[140:143], v2, s[8:9]
	v_add_u32_e32 v2, 0x4000, v2
	global_load_dwordx4 v[144:147], v2, s[8:9]
	v_add_u32_e32 v2, 0x4000, v2
	global_load_dwordx4 v[148:151], v2, s[8:9]
	v_add_u32_e32 v2, 0x4000, v2
	global_load_dwordx4 v[152:155], v2, s[8:9]
	v_add_u32_e32 v2, 0x4000, v2
	global_load_dwordx4 v[156:159], v2, s[8:9]
	v_add_u32_e32 v2, 0x4000, v2
	global_load_dwordx4 v[160:163], v2, s[8:9]
	v_add_u32_e32 v2, 0x4000, v2
	global_load_dwordx4 v[164:167], v2, s[8:9]
	v_add_u32_e32 v2, 0x4000, v2
	global_load_dwordx4 v[168:171], v2, s[8:9]
	v_add_u32_e32 v2, 0x4000, v2
	global_load_dwordx4 v[172:175], v2, s[8:9]
	v_add_u32_e32 v2, 0x4000, v2
	global_load_dwordx4 v[184:187], v2, s[8:9]
	v_add_u32_e32 v2, 0x4000, v2
	global_load_dwordx4 v[188:191], v2, s[8:9]
	v_add_u32_e32 v2, 0x4000, v2
	global_load_dwordx4 v[192:195], v2, s[8:9]
	v_add_u32_e32 v2, 0x4000, v2
	global_load_dwordx4 v[196:199], v2, s[8:9]
	v_add_u32_e32 v2, 0x4000, v2
	global_load_dwordx4 v[200:203], v2, s[8:9]
	v_mov_b32_e32 v204, 0
	v_mov_b32_e32 v205, 0
	v_mov_b32_e32 v206, 0
	v_mov_b32_e32 v207, 0
	v_mov_b32_e32 v208, 0
	v_mov_b32_e32 v209, 0
	v_mov_b32_e32 v210, 0
	v_mov_b32_e32 v211, 0
	s_mov_b32 s43, 0x3d800000
	s_cmp_eq_u32 s16, 0
	s_waitcnt vmcnt(32)
	v_lshlrev_b32_e32 v216, 16, v64
	v_and_b32_e32 v217, 0xffff0000, v64
	v_lshlrev_b32_e32 v220, 16, v65
	v_and_b32_e32 v221, 0xffff0000, v65
	v_lshlrev_b32_e32 v224, 16, v66
	v_and_b32_e32 v225, 0xffff0000, v66
	v_lshlrev_b32_e32 v228, 16, v67
	v_and_b32_e32 v229, 0xffff0000, v67
	v_pk_add_f32 v[204:205], v[204:205], v[216:217]
	v_pk_add_f32 v[206:207], v[206:207], v[220:221]
	v_pk_add_f32 v[208:209], v[208:209], v[224:225]
	v_pk_add_f32 v[210:211], v[210:211], v[228:229]
	v_lshlrev_b32_e32 v216, 16, v60
	v_and_b32_e32 v217, 0xffff0000, v60
	v_lshlrev_b32_e32 v220, 16, v61
	v_and_b32_e32 v221, 0xffff0000, v61
	v_lshlrev_b32_e32 v224, 16, v62
	v_and_b32_e32 v225, 0xffff0000, v62
	v_lshlrev_b32_e32 v228, 16, v63
	v_and_b32_e32 v229, 0xffff0000, v63
	v_pk_add_f32 v[204:205], v[204:205], v[216:217]
	v_pk_add_f32 v[206:207], v[206:207], v[220:221]
	v_pk_add_f32 v[208:209], v[208:209], v[224:225]
	v_pk_add_f32 v[210:211], v[210:211], v[228:229]
	v_lshlrev_b32_e32 v216, 16, v56
	v_and_b32_e32 v217, 0xffff0000, v56
	v_lshlrev_b32_e32 v220, 16, v57
	v_and_b32_e32 v221, 0xffff0000, v57
	v_lshlrev_b32_e32 v224, 16, v58
	v_and_b32_e32 v225, 0xffff0000, v58
	v_lshlrev_b32_e32 v228, 16, v59
	v_and_b32_e32 v229, 0xffff0000, v59
	v_pk_add_f32 v[204:205], v[204:205], v[216:217]
	v_pk_add_f32 v[206:207], v[206:207], v[220:221]
	v_pk_add_f32 v[208:209], v[208:209], v[224:225]
	v_pk_add_f32 v[210:211], v[210:211], v[228:229]
	v_lshlrev_b32_e32 v216, 16, v52
	v_and_b32_e32 v217, 0xffff0000, v52
	v_lshlrev_b32_e32 v220, 16, v53
	v_and_b32_e32 v221, 0xffff0000, v53
	v_lshlrev_b32_e32 v224, 16, v54
	v_and_b32_e32 v225, 0xffff0000, v54
	v_lshlrev_b32_e32 v228, 16, v55
	v_and_b32_e32 v229, 0xffff0000, v55
	v_pk_add_f32 v[204:205], v[204:205], v[216:217]
	v_pk_add_f32 v[206:207], v[206:207], v[220:221]
	v_pk_add_f32 v[208:209], v[208:209], v[224:225]
	v_pk_add_f32 v[210:211], v[210:211], v[228:229]
	v_lshlrev_b32_e32 v216, 16, v48
	v_and_b32_e32 v217, 0xffff0000, v48
	v_lshlrev_b32_e32 v220, 16, v49
	v_and_b32_e32 v221, 0xffff0000, v49
	v_lshlrev_b32_e32 v224, 16, v50
	v_and_b32_e32 v225, 0xffff0000, v50
	v_lshlrev_b32_e32 v228, 16, v51
	v_and_b32_e32 v229, 0xffff0000, v51
	v_pk_add_f32 v[204:205], v[204:205], v[216:217]
	v_pk_add_f32 v[206:207], v[206:207], v[220:221]
	v_pk_add_f32 v[208:209], v[208:209], v[224:225]
	v_pk_add_f32 v[210:211], v[210:211], v[228:229]
	v_lshlrev_b32_e32 v216, 16, v44
	v_and_b32_e32 v217, 0xffff0000, v44
	v_lshlrev_b32_e32 v220, 16, v45
	v_and_b32_e32 v221, 0xffff0000, v45
	v_lshlrev_b32_e32 v224, 16, v46
	v_and_b32_e32 v225, 0xffff0000, v46
	v_lshlrev_b32_e32 v228, 16, v47
	v_and_b32_e32 v229, 0xffff0000, v47
	v_pk_add_f32 v[204:205], v[204:205], v[216:217]
	v_pk_add_f32 v[206:207], v[206:207], v[220:221]
	v_pk_add_f32 v[208:209], v[208:209], v[224:225]
	v_pk_add_f32 v[210:211], v[210:211], v[228:229]
	v_lshlrev_b32_e32 v216, 16, v40
	v_and_b32_e32 v217, 0xffff0000, v40
	v_lshlrev_b32_e32 v220, 16, v41
	v_and_b32_e32 v221, 0xffff0000, v41
	v_lshlrev_b32_e32 v224, 16, v42
	v_and_b32_e32 v225, 0xffff0000, v42
; __device__ __forceinline__ unsigned cvt_pk_bf16(float lo, float hi) { unsigned r; asm volatile("v_cvt_pk_bf16_f32 %0, %1, %2" : "=v"(r) : "v"(lo), "v"(hi)); return r; }
; __device__ __forceinline__ float bf_lo(unsigned w) { return __uint_as_float(w << 16); }
; __device__ __forceinline__ float bf_hi(unsigned w) { return __uint_as_float(w & 0xffff0000u); }
; __device__ void phase_pool() {
;     ...
;           for (int k = 1; k <= 16; ++k) hv[k - 1] = (k <= nh) ? *(const u32x4*)(uz + (size_t)(row0 - k) * DE2 + col) : (u32x4){0u, 0u, 0u, 0u};
; #pragma unroll
;           for (int k = 0; k < 16; ++k) { const u32x4 v = hv[k];
;             s[0] += bf_lo(v.x); s[1] += bf_hi(v.x); s[2] += bf_lo(v.y); s[3] += bf_hi(v.y); s[4] += bf_lo(v.z); s[5] += bf_hi(v.z); s[6] += bf_lo(v.w); s[7] += bf_hi(v.w); } }
; #pragma unroll 1
;         for (int r0 = 0; r0 < RB; r0 += 8) {
;             u32x4 vv[8], ov[8];
; #pragma unroll
;             for (int k = 0; k < 8; ++k) { const int row = row0 + r0 + k, tl = tl0 + r0 + k;
;                 vv[k] = *(const u32x4*)(uz + (size_t)row * DE2 + col);
;                 ov[k] = (tl >= w) ? *(const u32x4*)(uz + (size_t)(row - w) * DE2 + col) : (u32x4){0u, 0u, 0u, 0u}; }
; #pragma unroll
;             for (int k = 0; k < 8; ++k) { const int row = row0 + r0 + k, tl = tl0 + r0 + k; const u32x4 v = vv[k], o2 = ov[k];
;                 s[0] += bf_lo(v.x) - bf_lo(o2.x); s[1] += bf_hi(v.x) - bf_hi(o2.x); s[2] += bf_lo(v.y) - bf_lo(o2.y); s[3] += bf_hi(v.y) - bf_hi(o2.y);
;                 s[4] += bf_lo(v.z) - bf_lo(o2.z); s[5] += bf_hi(v.z) - bf_hi(o2.z); s[6] += bf_lo(v.w) - bf_lo(o2.w); s[7] += bf_hi(v.w) - bf_hi(o2.w);
;                 const float ic = 1.0f / (float)((tl + 1 < w) ? tl + 1 : w);
;                 u32x4 o;
;                 o.x = cvt_pk_bf16(s[0] * ic - bf_lo(v.x), s[1] * ic - bf_hi(v.x)); o.y = cvt_pk_bf16(s[2] * ic - bf_lo(v.y), s[3] * ic - bf_hi(v.y));
;                 o.z = cvt_pk_bf16(s[4] * ic - bf_lo(v.z), s[5] * ic - bf_hi(v.z)); o.w = cvt_pk_bf16(s[6] * ic - bf_lo(v.w), s[7] * ic - bf_hi(v.w));
;                 *(u32x4*)(pg + (size_t)row * DE + col) = o; }
	v_lshlrev_b32_e32 v228, 16, v43
	v_and_b32_e32 v229, 0xffff0000, v43
	v_pk_add_f32 v[204:205], v[204:205], v[216:217]
	v_pk_add_f32 v[206:207], v[206:207], v[220:221]
	v_pk_add_f32 v[208:209], v[208:209], v[224:225]
	v_pk_add_f32 v[210:211], v[210:211], v[228:229]
	v_lshlrev_b32_e32 v216, 16, v36
	v_and_b32_e32 v217, 0xffff0000, v36
	v_lshlrev_b32_e32 v220, 16, v37
	v_and_b32_e32 v221, 0xffff0000, v37
	v_lshlrev_b32_e32 v224, 16, v38
	v_and_b32_e32 v225, 0xffff0000, v38
	v_lshlrev_b32_e32 v228, 16, v39
	v_and_b32_e32 v229, 0xffff0000, v39
	v_pk_add_f32 v[204:205], v[204:205], v[216:217]
	v_pk_add_f32 v[206:207], v[206:207], v[220:221]
	v_pk_add_f32 v[208:209], v[208:209], v[224:225]
	v_pk_add_f32 v[210:211], v[210:211], v[228:229]
	v_lshlrev_b32_e32 v216, 16, v32
	v_and_b32_e32 v217, 0xffff0000, v32
	v_lshlrev_b32_e32 v220, 16, v33
	v_and_b32_e32 v221, 0xffff0000, v33
	v_lshlrev_b32_e32 v224, 16, v34
	v_and_b32_e32 v225, 0xffff0000, v34
	v_lshlrev_b32_e32 v228, 16, v35
	v_and_b32_e32 v229, 0xffff0000, v35
	v_pk_add_f32 v[204:205], v[204:205], v[216:217]
	v_pk_add_f32 v[206:207], v[206:207], v[220:221]
	v_pk_add_f32 v[208:209], v[208:209], v[224:225]
	v_pk_add_f32 v[210:211], v[210:211], v[228:229]
	v_lshlrev_b32_e32 v216, 16, v28
	v_and_b32_e32 v217, 0xffff0000, v28
	v_lshlrev_b32_e32 v220, 16, v29
	v_and_b32_e32 v221, 0xffff0000, v29
	v_lshlrev_b32_e32 v224, 16, v30
	v_and_b32_e32 v225, 0xffff0000, v30
	v_lshlrev_b32_e32 v228, 16, v31
	v_and_b32_e32 v229, 0xffff0000, v31
	v_pk_add_f32 v[204:205], v[204:205], v[216:217]
	v_pk_add_f32 v[206:207], v[206:207], v[220:221]
	v_pk_add_f32 v[208:209], v[208:209], v[224:225]
	v_pk_add_f32 v[210:211], v[210:211], v[228:229]
	v_lshlrev_b32_e32 v216, 16, v24
	v_and_b32_e32 v217, 0xffff0000, v24
	v_lshlrev_b32_e32 v220, 16, v25
	v_and_b32_e32 v221, 0xffff0000, v25
	v_lshlrev_b32_e32 v224, 16, v26
	v_and_b32_e32 v225, 0xffff0000, v26
	v_lshlrev_b32_e32 v228, 16, v27
	v_and_b32_e32 v229, 0xffff0000, v27
	v_pk_add_f32 v[204:205], v[204:205], v[216:217]
	v_pk_add_f32 v[206:207], v[206:207], v[220:221]
	v_pk_add_f32 v[208:209], v[208:209], v[224:225]
	v_pk_add_f32 v[210:211], v[210:211], v[228:229]
	v_lshlrev_b32_e32 v216, 16, v20
	v_and_b32_e32 v217, 0xffff0000, v20
	v_lshlrev_b32_e32 v220, 16, v21
	v_and_b32_e32 v221, 0xffff0000, v21
	v_lshlrev_b32_e32 v224, 16, v22
	v_and_b32_e32 v225, 0xffff0000, v22
	v_lshlrev_b32_e32 v228, 16, v23
	v_and_b32_e32 v229, 0xffff0000, v23
	v_pk_add_f32 v[204:205], v[204:205], v[216:217]
	v_pk_add_f32 v[206:207], v[206:207], v[220:221]
	v_pk_add_f32 v[208:209], v[208:209], v[224:225]
	v_pk_add_f32 v[210:211], v[210:211], v[228:229]
	v_lshlrev_b32_e32 v216, 16, v16
	v_and_b32_e32 v217, 0xffff0000, v16
	v_lshlrev_b32_e32 v220, 16, v17
	v_and_b32_e32 v221, 0xffff0000, v17
	v_lshlrev_b32_e32 v224, 16, v18
	v_and_b32_e32 v225, 0xffff0000, v18
	v_lshlrev_b32_e32 v228, 16, v19
	v_and_b32_e32 v229, 0xffff0000, v19
	v_pk_add_f32 v[204:205], v[204:205], v[216:217]
	v_pk_add_f32 v[206:207], v[206:207], v[220:221]
	v_pk_add_f32 v[208:209], v[208:209], v[224:225]
	v_pk_add_f32 v[210:211], v[210:211], v[228:229]
	v_lshlrev_b32_e32 v216, 16, v12
	v_and_b32_e32 v217, 0xffff0000, v12
	v_lshlrev_b32_e32 v220, 16, v13
	v_and_b32_e32 v221, 0xffff0000, v13
	v_lshlrev_b32_e32 v224, 16, v14
	v_and_b32_e32 v225, 0xffff0000, v14
	v_lshlrev_b32_e32 v228, 16, v15
	v_and_b32_e32 v229, 0xffff0000, v15
	v_pk_add_f32 v[204:205], v[204:205], v[216:217]
	v_pk_add_f32 v[206:207], v[206:207], v[220:221]
	v_pk_add_f32 v[208:209], v[208:209], v[224:225]
	v_pk_add_f32 v[210:211], v[210:211], v[228:229]
	v_lshlrev_b32_e32 v216, 16, v8
	v_and_b32_e32 v217, 0xffff0000, v8
	v_lshlrev_b32_e32 v220, 16, v9
	v_and_b32_e32 v221, 0xffff0000, v9
	v_lshlrev_b32_e32 v224, 16, v10
	v_and_b32_e32 v225, 0xffff0000, v10
	v_lshlrev_b32_e32 v228, 16, v11
	v_and_b32_e32 v229, 0xffff0000, v11
	v_pk_add_f32 v[204:205], v[204:205], v[216:217]
	v_pk_add_f32 v[206:207], v[206:207], v[220:221]
	v_pk_add_f32 v[208:209], v[208:209], v[224:225]
	v_pk_add_f32 v[210:211], v[210:211], v[228:229]
	v_lshlrev_b32_e32 v216, 16, v4
	v_and_b32_e32 v217, 0xffff0000, v4
	v_lshlrev_b32_e32 v220, 16, v5
	v_and_b32_e32 v221, 0xffff0000, v5
	v_lshlrev_b32_e32 v224, 16, v6
	v_and_b32_e32 v225, 0xffff0000, v6
	v_lshlrev_b32_e32 v228, 16, v7
	v_and_b32_e32 v229, 0xffff0000, v7
	v_pk_add_f32 v[204:205], v[204:205], v[216:217]
	v_pk_add_f32 v[206:207], v[206:207], v[220:221]
	v_pk_add_f32 v[208:209], v[208:209], v[224:225]
	v_pk_add_f32 v[210:211], v[210:211], v[228:229]
	s_waitcnt vmcnt(31)
	s_cselect_b32 s42, 0x3f800000, s43
	v_lshlrev_b32_e32 v216, 16, v68
	v_and_b32_e32 v217, 0xffff0000, v68
	v_lshlrev_b32_e32 v218, 16, v4
	v_and_b32_e32 v219, 0xffff0000, v4
	v_lshlrev_b32_e32 v220, 16, v69
	v_and_b32_e32 v221, 0xffff0000, v69
	v_lshlrev_b32_e32 v222, 16, v5
	v_and_b32_e32 v223, 0xffff0000, v5
	v_lshlrev_b32_e32 v224, 16, v70
	v_and_b32_e32 v225, 0xffff0000, v70
	v_lshlrev_b32_e32 v226, 16, v6
	v_and_b32_e32 v227, 0xffff0000, v6
	v_lshlrev_b32_e32 v228, 16, v71
	v_and_b32_e32 v229, 0xffff0000, v71
	v_lshlrev_b32_e32 v230, 16, v7
	v_and_b32_e32 v231, 0xffff0000, v7
	v_pk_add_f32 v[218:219], v[216:217], v[218:219] neg_lo:[0,1] neg_hi:[0,1]
	v_pk_add_f32 v[222:223], v[220:221], v[222:223] neg_lo:[0,1] neg_hi:[0,1]
	v_pk_add_f32 v[226:227], v[224:225], v[226:227] neg_lo:[0,1] neg_hi:[0,1]
	v_pk_add_f32 v[230:231], v[228:229], v[230:231] neg_lo:[0,1] neg_hi:[0,1]
	v_pk_add_f32 v[204:205], v[204:205], v[218:219]
	v_pk_add_f32 v[206:207], v[206:207], v[222:223]
	v_pk_add_f32 v[208:209], v[208:209], v[226:227]
	v_pk_add_f32 v[210:211], v[210:211], v[230:231]
	v_fma_f32 v218, s42, v204, -v216
	v_fma_f32 v219, s42, v205, -v217
	v_fma_f32 v222, s42, v206, -v220
	v_fma_f32 v223, s42, v207, -v221
	v_fma_f32 v226, s42, v208, -v224
	v_fma_f32 v227, s42, v209, -v225
	v_fma_f32 v230, s42, v210, -v228
	v_fma_f32 v231, s42, v211, -v229
	v_cvt_pk_bf16_f32 v212, v218, v219
	v_cvt_pk_bf16_f32 v213, v222, v223
	v_cvt_pk_bf16_f32 v214, v226, v227
	v_cvt_pk_bf16_f32 v215, v230, v231
	global_store_dwordx4 v3, v[212:215], s[10:11]
	v_add_u32_e32 v3, 0x2000, v3
	s_waitcnt vmcnt(31)
; __device__ __forceinline__ unsigned cvt_pk_bf16(float lo, float hi) { unsigned r; asm volatile("v_cvt_pk_bf16_f32 %0, %1, %2" : "=v"(r) : "v"(lo), "v"(hi)); return r; }
; __device__ __forceinline__ float bf_lo(unsigned w) { return __uint_as_float(w << 16); }
; __device__ __forceinline__ float bf_hi(unsigned w) { return __uint_as_float(w & 0xffff0000u); }
; __device__ void phase_pool() {
;     ...
;             for (int k = 0; k < 8; ++k) { const int row = row0 + r0 + k, tl = tl0 + r0 + k; const u32x4 v = vv[k], o2 = ov[k];
;                 s[0] += bf_lo(v.x) - bf_lo(o2.x); s[1] += bf_hi(v.x) - bf_hi(o2.x); s[2] += bf_lo(v.y) - bf_lo(o2.y); s[3] += bf_hi(v.y) - bf_hi(o2.y);
;                 s[4] += bf_lo(v.z) - bf_lo(o2.z); s[5] += bf_hi(v.z) - bf_hi(o2.z); s[6] += bf_lo(v.w) - bf_lo(o2.w); s[7] += bf_hi(v.w) - bf_hi(o2.w);
;                 const float ic = 1.0f / (float)((tl + 1 < w) ? tl + 1 : w);
;                 u32x4 o;
;                 o.x = cvt_pk_bf16(s[0] * ic - bf_lo(v.x), s[1] * ic - bf_hi(v.x)); o.y = cvt_pk_bf16(s[2] * ic - bf_lo(v.y), s[3] * ic - bf_hi(v.y));
;                 o.z = cvt_pk_bf16(s[4] * ic - bf_lo(v.z), s[5] * ic - bf_hi(v.z)); o.w = cvt_pk_bf16(s[6] * ic - bf_lo(v.w), s[7] * ic - bf_hi(v.w));
;                 *(u32x4*)(pg + (size_t)row * DE + col) = o; }
	s_cselect_b32 s42, 0x3f000000, s43
	v_lshlrev_b32_e32 v216, 16, v72
	v_and_b32_e32 v217, 0xffff0000, v72
	v_lshlrev_b32_e32 v218, 16, v8
	v_and_b32_e32 v219, 0xffff0000, v8
	v_lshlrev_b32_e32 v220, 16, v73
	v_and_b32_e32 v221, 0xffff0000, v73
	v_lshlrev_b32_e32 v222, 16, v9
	v_and_b32_e32 v223, 0xffff0000, v9
	v_lshlrev_b32_e32 v224, 16, v74
	v_and_b32_e32 v225, 0xffff0000, v74
	v_lshlrev_b32_e32 v226, 16, v10
	v_and_b32_e32 v227, 0xffff0000, v10
	v_lshlrev_b32_e32 v228, 16, v75
	v_and_b32_e32 v229, 0xffff0000, v75
	v_lshlrev_b32_e32 v230, 16, v11
	v_and_b32_e32 v231, 0xffff0000, v11
	v_pk_add_f32 v[218:219], v[216:217], v[218:219] neg_lo:[0,1] neg_hi:[0,1]
	v_pk_add_f32 v[222:223], v[220:221], v[222:223] neg_lo:[0,1] neg_hi:[0,1]
	v_pk_add_f32 v[226:227], v[224:225], v[226:227] neg_lo:[0,1] neg_hi:[0,1]
	v_pk_add_f32 v[230:231], v[228:229], v[230:231] neg_lo:[0,1] neg_hi:[0,1]
	v_pk_add_f32 v[204:205], v[204:205], v[218:219]
	v_pk_add_f32 v[206:207], v[206:207], v[222:223]
	v_pk_add_f32 v[208:209], v[208:209], v[226:227]
	v_pk_add_f32 v[210:211], v[210:211], v[230:231]
	v_fma_f32 v218, s42, v204, -v216
	v_fma_f32 v219, s42, v205, -v217
	v_fma_f32 v222, s42, v206, -v220
	v_fma_f32 v223, s42, v207, -v221
	v_fma_f32 v226, s42, v208, -v224
	v_fma_f32 v227, s42, v209, -v225
	v_fma_f32 v230, s42, v210, -v228
	v_fma_f32 v231, s42, v211, -v229
	v_cvt_pk_bf16_f32 v212, v218, v219
	v_cvt_pk_bf16_f32 v213, v222, v223
	v_cvt_pk_bf16_f32 v214, v226, v227
	v_cvt_pk_bf16_f32 v215, v230, v231
	global_store_dwordx4 v3, v[212:215], s[10:11]
	v_add_u32_e32 v3, 0x2000, v3
	s_waitcnt vmcnt(31)
	s_cselect_b32 s42, 0x3eaaaaab, s43
	v_lshlrev_b32_e32 v216, 16, v76
	v_and_b32_e32 v217, 0xffff0000, v76
	v_lshlrev_b32_e32 v218, 16, v12
	v_and_b32_e32 v219, 0xffff0000, v12
	v_lshlrev_b32_e32 v220, 16, v77
	v_and_b32_e32 v221, 0xffff0000, v77
	v_lshlrev_b32_e32 v222, 16, v13
	v_and_b32_e32 v223, 0xffff0000, v13
	v_lshlrev_b32_e32 v224, 16, v78
	v_and_b32_e32 v225, 0xffff0000, v78
	v_lshlrev_b32_e32 v226, 16, v14
	v_and_b32_e32 v227, 0xffff0000, v14
	v_lshlrev_b32_e32 v228, 16, v79
	v_and_b32_e32 v229, 0xffff0000, v79
	v_lshlrev_b32_e32 v230, 16, v15
	v_and_b32_e32 v231, 0xffff0000, v15
	v_pk_add_f32 v[218:219], v[216:217], v[218:219] neg_lo:[0,1] neg_hi:[0,1]
	v_pk_add_f32 v[222:223], v[220:221], v[222:223] neg_lo:[0,1] neg_hi:[0,1]
	v_pk_add_f32 v[226:227], v[224:225], v[226:227] neg_lo:[0,1] neg_hi:[0,1]
	v_pk_add_f32 v[230:231], v[228:229], v[230:231] neg_lo:[0,1] neg_hi:[0,1]
	v_pk_add_f32 v[204:205], v[204:205], v[218:219]
	v_pk_add_f32 v[206:207], v[206:207], v[222:223]
	v_pk_add_f32 v[208:209], v[208:209], v[226:227]
	v_pk_add_f32 v[210:211], v[210:211], v[230:231]
	v_fma_f32 v218, s42, v204, -v216
	v_fma_f32 v219, s42, v205, -v217
	v_fma_f32 v222, s42, v206, -v220
	v_fma_f32 v223, s42, v207, -v221
	v_fma_f32 v226, s42, v208, -v224
	v_fma_f32 v227, s42, v209, -v225
	v_fma_f32 v230, s42, v210, -v228
	v_fma_f32 v231, s42, v211, -v229
	v_cvt_pk_bf16_f32 v212, v218, v219
	v_cvt_pk_bf16_f32 v213, v222, v223
	v_cvt_pk_bf16_f32 v214, v226, v227
	v_cvt_pk_bf16_f32 v215, v230, v231
	global_store_dwordx4 v3, v[212:215], s[10:11]
	v_add_u32_e32 v3, 0x2000, v3
	s_waitcnt vmcnt(31)
	s_cselect_b32 s42, 0x3e800000, s43
	v_lshlrev_b32_e32 v216, 16, v80
	v_and_b32_e32 v217, 0xffff0000, v80
	v_lshlrev_b32_e32 v218, 16, v16
	v_and_b32_e32 v219, 0xffff0000, v16
	v_lshlrev_b32_e32 v220, 16, v81
	v_and_b32_e32 v221, 0xffff0000, v81
	v_lshlrev_b32_e32 v222, 16, v17
	v_and_b32_e32 v223, 0xffff0000, v17
	v_lshlrev_b32_e32 v224, 16, v82
	v_and_b32_e32 v225, 0xffff0000, v82
	v_lshlrev_b32_e32 v226, 16, v18
	v_and_b32_e32 v227, 0xffff0000, v18
	v_lshlrev_b32_e32 v228, 16, v83
	v_and_b32_e32 v229, 0xffff0000, v83
	v_lshlrev_b32_e32 v230, 16, v19
	v_and_b32_e32 v231, 0xffff0000, v19
	v_pk_add_f32 v[218:219], v[216:217], v[218:219] neg_lo:[0,1] neg_hi:[0,1]
	v_pk_add_f32 v[222:223], v[220:221], v[222:223] neg_lo:[0,1] neg_hi:[0,1]
	v_pk_add_f32 v[226:227], v[224:225], v[226:227] neg_lo:[0,1] neg_hi:[0,1]
	v_pk_add_f32 v[230:231], v[228:229], v[230:231] neg_lo:[0,1] neg_hi:[0,1]
	v_pk_add_f32 v[204:205], v[204:205], v[218:219]
	v_pk_add_f32 v[206:207], v[206:207], v[222:223]
	v_pk_add_f32 v[208:209], v[208:209], v[226:227]
	v_pk_add_f32 v[210:211], v[210:211], v[230:231]
	v_fma_f32 v218, s42, v204, -v216
	v_fma_f32 v219, s42, v205, -v217
	v_fma_f32 v222, s42, v206, -v220
	v_fma_f32 v223, s42, v207, -v221
	v_fma_f32 v226, s42, v208, -v224
	v_fma_f32 v227, s42, v209, -v225
	v_fma_f32 v230, s42, v210, -v228
	v_fma_f32 v231, s42, v211, -v229
	v_cvt_pk_bf16_f32 v212, v218, v219
	v_cvt_pk_bf16_f32 v213, v222, v223
	v_cvt_pk_bf16_f32 v214, v226, v227
	v_cvt_pk_bf16_f32 v215, v230, v231
	global_store_dwordx4 v3, v[212:215], s[10:11]
	v_add_u32_e32 v3, 0x2000, v3
	s_waitcnt vmcnt(31)
	s_cselect_b32 s42, 0x3e4ccccd, s43
	v_lshlrev_b32_e32 v216, 16, v84
	v_and_b32_e32 v217, 0xffff0000, v84
	v_lshlrev_b32_e32 v218, 16, v20
	v_and_b32_e32 v219, 0xffff0000, v20
	v_lshlrev_b32_e32 v220, 16, v85
	v_and_b32_e32 v221, 0xffff0000, v85
	v_lshlrev_b32_e32 v222, 16, v21
	v_and_b32_e32 v223, 0xffff0000, v21
	v_lshlrev_b32_e32 v224, 16, v86
	v_and_b32_e32 v225, 0xffff0000, v86
	v_lshlrev_b32_e32 v226, 16, v22
	v_and_b32_e32 v227, 0xffff0000, v22
	v_lshlrev_b32_e32 v228, 16, v87
	v_and_b32_e32 v229, 0xffff0000, v87
	v_lshlrev_b32_e32 v230, 16, v23
	v_and_b32_e32 v231, 0xffff0000, v23
	v_pk_add_f32 v[218:219], v[216:217], v[218:219] neg_lo:[0,1] neg_hi:[0,1]
	v_pk_add_f32 v[222:223], v[220:221], v[222:223] neg_lo:[0,1] neg_hi:[0,1]
	v_pk_add_f32 v[226:227], v[224:225], v[226:227] neg_lo:[0,1] neg_hi:[0,1]
	v_pk_add_f32 v[230:231], v[228:229], v[230:231] neg_lo:[0,1] neg_hi:[0,1]
	v_pk_add_f32 v[204:205], v[204:205], v[218:219]
	v_pk_add_f32 v[206:207], v[206:207], v[222:223]
	v_pk_add_f32 v[208:209], v[208:209], v[226:227]
	v_pk_add_f32 v[210:211], v[210:211], v[230:231]
	v_fma_f32 v218, s42, v204, -v216
	v_fma_f32 v219, s42, v205, -v217
	v_fma_f32 v222, s42, v206, -v220
	v_fma_f32 v223, s42, v207, -v221
	v_fma_f32 v226, s42, v208, -v224
	v_fma_f32 v227, s42, v209, -v225
	v_fma_f32 v230, s42, v210, -v228
	v_fma_f32 v231, s42, v211, -v229
	v_cvt_pk_bf16_f32 v212, v218, v219
	v_cvt_pk_bf16_f32 v213, v222, v223
	v_cvt_pk_bf16_f32 v214, v226, v227
	v_cvt_pk_bf16_f32 v215, v230, v231
	global_store_dwordx4 v3, v[212:215], s[10:11]
	v_add_u32_e32 v3, 0x2000, v3
	s_waitcnt vmcnt(31)
; __device__ __forceinline__ unsigned cvt_pk_bf16(float lo, float hi) { unsigned r; asm volatile("v_cvt_pk_bf16_f32 %0, %1, %2" : "=v"(r) : "v"(lo), "v"(hi)); return r; }
; __device__ __forceinline__ float bf_lo(unsigned w) { return __uint_as_float(w << 16); }
; __device__ __forceinline__ float bf_hi(unsigned w) { return __uint_as_float(w & 0xffff0000u); }
; __device__ void phase_pool() {
;     ...
;             for (int k = 0; k < 8; ++k) { const int row = row0 + r0 + k, tl = tl0 + r0 + k; const u32x4 v = vv[k], o2 = ov[k];
;                 s[0] += bf_lo(v.x) - bf_lo(o2.x); s[1] += bf_hi(v.x) - bf_hi(o2.x); s[2] += bf_lo(v.y) - bf_lo(o2.y); s[3] += bf_hi(v.y) - bf_hi(o2.y);
;                 s[4] += bf_lo(v.z) - bf_lo(o2.z); s[5] += bf_hi(v.z) - bf_hi(o2.z); s[6] += bf_lo(v.w) - bf_lo(o2.w); s[7] += bf_hi(v.w) - bf_hi(o2.w);
;                 const float ic = 1.0f / (float)((tl + 1 < w) ? tl + 1 : w);
;                 u32x4 o;
;                 o.x = cvt_pk_bf16(s[0] * ic - bf_lo(v.x), s[1] * ic - bf_hi(v.x)); o.y = cvt_pk_bf16(s[2] * ic - bf_lo(v.y), s[3] * ic - bf_hi(v.y));
;                 o.z = cvt_pk_bf16(s[4] * ic - bf_lo(v.z), s[5] * ic - bf_hi(v.z)); o.w = cvt_pk_bf16(s[6] * ic - bf_lo(v.w), s[7] * ic - bf_hi(v.w));
;                 *(u32x4*)(pg + (size_t)row * DE + col) = o; }
	s_cselect_b32 s42, 0x3e2aaaab, s43
	v_lshlrev_b32_e32 v216, 16, v88
	v_and_b32_e32 v217, 0xffff0000, v88
	v_lshlrev_b32_e32 v218, 16, v24
	v_and_b32_e32 v219, 0xffff0000, v24
	v_lshlrev_b32_e32 v220, 16, v89
	v_and_b32_e32 v221, 0xffff0000, v89
	v_lshlrev_b32_e32 v222, 16, v25
	v_and_b32_e32 v223, 0xffff0000, v25
	v_lshlrev_b32_e32 v224, 16, v90
	v_and_b32_e32 v225, 0xffff0000, v90
	v_lshlrev_b32_e32 v226, 16, v26
	v_and_b32_e32 v227, 0xffff0000, v26
	v_lshlrev_b32_e32 v228, 16, v91
	v_and_b32_e32 v229, 0xffff0000, v91
	v_lshlrev_b32_e32 v230, 16, v27
	v_and_b32_e32 v231, 0xffff0000, v27
	v_pk_add_f32 v[218:219], v[216:217], v[218:219] neg_lo:[0,1] neg_hi:[0,1]
	v_pk_add_f32 v[222:223], v[220:221], v[222:223] neg_lo:[0,1] neg_hi:[0,1]
	v_pk_add_f32 v[226:227], v[224:225], v[226:227] neg_lo:[0,1] neg_hi:[0,1]
	v_pk_add_f32 v[230:231], v[228:229], v[230:231] neg_lo:[0,1] neg_hi:[0,1]
	v_pk_add_f32 v[204:205], v[204:205], v[218:219]
	v_pk_add_f32 v[206:207], v[206:207], v[222:223]
	v_pk_add_f32 v[208:209], v[208:209], v[226:227]
	v_pk_add_f32 v[210:211], v[210:211], v[230:231]
	v_fma_f32 v218, s42, v204, -v216
	v_fma_f32 v219, s42, v205, -v217
	v_fma_f32 v222, s42, v206, -v220
	v_fma_f32 v223, s42, v207, -v221
	v_fma_f32 v226, s42, v208, -v224
	v_fma_f32 v227, s42, v209, -v225
	v_fma_f32 v230, s42, v210, -v228
	v_fma_f32 v231, s42, v211, -v229
	v_cvt_pk_bf16_f32 v212, v218, v219
	v_cvt_pk_bf16_f32 v213, v222, v223
	v_cvt_pk_bf16_f32 v214, v226, v227
	v_cvt_pk_bf16_f32 v215, v230, v231
	global_store_dwordx4 v3, v[212:215], s[10:11]
	v_add_u32_e32 v3, 0x2000, v3
	s_waitcnt vmcnt(31)
	s_cselect_b32 s42, 0x3e124925, s43
	v_lshlrev_b32_e32 v216, 16, v92
	v_and_b32_e32 v217, 0xffff0000, v92
	v_lshlrev_b32_e32 v218, 16, v28
	v_and_b32_e32 v219, 0xffff0000, v28
	v_lshlrev_b32_e32 v220, 16, v93
	v_and_b32_e32 v221, 0xffff0000, v93
	v_lshlrev_b32_e32 v222, 16, v29
	v_and_b32_e32 v223, 0xffff0000, v29
	v_lshlrev_b32_e32 v224, 16, v94
	v_and_b32_e32 v225, 0xffff0000, v94
	v_lshlrev_b32_e32 v226, 16, v30
	v_and_b32_e32 v227, 0xffff0000, v30
	v_lshlrev_b32_e32 v228, 16, v95
	v_and_b32_e32 v229, 0xffff0000, v95
	v_lshlrev_b32_e32 v230, 16, v31
	v_and_b32_e32 v231, 0xffff0000, v31
	v_pk_add_f32 v[218:219], v[216:217], v[218:219] neg_lo:[0,1] neg_hi:[0,1]
	v_pk_add_f32 v[222:223], v[220:221], v[222:223] neg_lo:[0,1] neg_hi:[0,1]
	v_pk_add_f32 v[226:227], v[224:225], v[226:227] neg_lo:[0,1] neg_hi:[0,1]
	v_pk_add_f32 v[230:231], v[228:229], v[230:231] neg_lo:[0,1] neg_hi:[0,1]
	v_pk_add_f32 v[204:205], v[204:205], v[218:219]
	v_pk_add_f32 v[206:207], v[206:207], v[222:223]
	v_pk_add_f32 v[208:209], v[208:209], v[226:227]
	v_pk_add_f32 v[210:211], v[210:211], v[230:231]
	v_fma_f32 v218, s42, v204, -v216
	v_fma_f32 v219, s42, v205, -v217
	v_fma_f32 v222, s42, v206, -v220
	v_fma_f32 v223, s42, v207, -v221
	v_fma_f32 v226, s42, v208, -v224
	v_fma_f32 v227, s42, v209, -v225
	v_fma_f32 v230, s42, v210, -v228
	v_fma_f32 v231, s42, v211, -v229
	v_cvt_pk_bf16_f32 v212, v218, v219
	v_cvt_pk_bf16_f32 v213, v222, v223
	v_cvt_pk_bf16_f32 v214, v226, v227
	v_cvt_pk_bf16_f32 v215, v230, v231
	global_store_dwordx4 v3, v[212:215], s[10:11]
	v_add_u32_e32 v3, 0x2000, v3
	s_waitcnt vmcnt(31)
	s_cselect_b32 s42, 0x3e000000, s43
	v_lshlrev_b32_e32 v216, 16, v96
	v_and_b32_e32 v217, 0xffff0000, v96
	v_lshlrev_b32_e32 v218, 16, v32
	v_and_b32_e32 v219, 0xffff0000, v32
	v_lshlrev_b32_e32 v220, 16, v97
	v_and_b32_e32 v221, 0xffff0000, v97
	v_lshlrev_b32_e32 v222, 16, v33
	v_and_b32_e32 v223, 0xffff0000, v33
	v_lshlrev_b32_e32 v224, 16, v98
	v_and_b32_e32 v225, 0xffff0000, v98
	v_lshlrev_b32_e32 v226, 16, v34
	v_and_b32_e32 v227, 0xffff0000, v34
	v_lshlrev_b32_e32 v228, 16, v99
	v_and_b32_e32 v229, 0xffff0000, v99
	v_lshlrev_b32_e32 v230, 16, v35
	v_and_b32_e32 v231, 0xffff0000, v35
	v_pk_add_f32 v[218:219], v[216:217], v[218:219] neg_lo:[0,1] neg_hi:[0,1]
	v_pk_add_f32 v[222:223], v[220:221], v[222:223] neg_lo:[0,1] neg_hi:[0,1]
	v_pk_add_f32 v[226:227], v[224:225], v[226:227] neg_lo:[0,1] neg_hi:[0,1]
	v_pk_add_f32 v[230:231], v[228:229], v[230:231] neg_lo:[0,1] neg_hi:[0,1]
	v_pk_add_f32 v[204:205], v[204:205], v[218:219]
	v_pk_add_f32 v[206:207], v[206:207], v[222:223]
	v_pk_add_f32 v[208:209], v[208:209], v[226:227]
	v_pk_add_f32 v[210:211], v[210:211], v[230:231]
	v_fma_f32 v218, s42, v204, -v216
	v_fma_f32 v219, s42, v205, -v217
	v_fma_f32 v222, s42, v206, -v220
	v_fma_f32 v223, s42, v207, -v221
	v_fma_f32 v226, s42, v208, -v224
	v_fma_f32 v227, s42, v209, -v225
	v_fma_f32 v230, s42, v210, -v228
	v_fma_f32 v231, s42, v211, -v229
	v_cvt_pk_bf16_f32 v212, v218, v219
	v_cvt_pk_bf16_f32 v213, v222, v223
	v_cvt_pk_bf16_f32 v214, v226, v227
	v_cvt_pk_bf16_f32 v215, v230, v231
	global_store_dwordx4 v3, v[212:215], s[10:11]
	v_add_u32_e32 v3, 0x2000, v3
	s_waitcnt vmcnt(31)
	s_cselect_b32 s42, 0x3de38e39, s43
	v_lshlrev_b32_e32 v216, 16, v100
	v_and_b32_e32 v217, 0xffff0000, v100
	v_lshlrev_b32_e32 v218, 16, v36
	v_and_b32_e32 v219, 0xffff0000, v36
	v_lshlrev_b32_e32 v220, 16, v101
	v_and_b32_e32 v221, 0xffff0000, v101
	v_lshlrev_b32_e32 v222, 16, v37
	v_and_b32_e32 v223, 0xffff0000, v37
	v_lshlrev_b32_e32 v224, 16, v102
	v_and_b32_e32 v225, 0xffff0000, v102
	v_lshlrev_b32_e32 v226, 16, v38
	v_and_b32_e32 v227, 0xffff0000, v38
	v_lshlrev_b32_e32 v228, 16, v103
	v_and_b32_e32 v229, 0xffff0000, v103
	v_lshlrev_b32_e32 v230, 16, v39
	v_and_b32_e32 v231, 0xffff0000, v39
	v_pk_add_f32 v[218:219], v[216:217], v[218:219] neg_lo:[0,1] neg_hi:[0,1]
	v_pk_add_f32 v[222:223], v[220:221], v[222:223] neg_lo:[0,1] neg_hi:[0,1]
	v_pk_add_f32 v[226:227], v[224:225], v[226:227] neg_lo:[0,1] neg_hi:[0,1]
	v_pk_add_f32 v[230:231], v[228:229], v[230:231] neg_lo:[0,1] neg_hi:[0,1]
	v_pk_add_f32 v[204:205], v[204:205], v[218:219]
	v_pk_add_f32 v[206:207], v[206:207], v[222:223]
	v_pk_add_f32 v[208:209], v[208:209], v[226:227]
	v_pk_add_f32 v[210:211], v[210:211], v[230:231]
	v_fma_f32 v218, s42, v204, -v216
	v_fma_f32 v219, s42, v205, -v217
	v_fma_f32 v222, s42, v206, -v220
	v_fma_f32 v223, s42, v207, -v221
	v_fma_f32 v226, s42, v208, -v224
	v_fma_f32 v227, s42, v209, -v225
	v_fma_f32 v230, s42, v210, -v228
	v_fma_f32 v231, s42, v211, -v229
	v_cvt_pk_bf16_f32 v212, v218, v219
	v_cvt_pk_bf16_f32 v213, v222, v223
	v_cvt_pk_bf16_f32 v214, v226, v227
	v_cvt_pk_bf16_f32 v215, v230, v231
	global_store_dwordx4 v3, v[212:215], s[10:11]
	v_add_u32_e32 v3, 0x2000, v3
	s_waitcnt vmcnt(31)
; __device__ __forceinline__ unsigned cvt_pk_bf16(float lo, float hi) { unsigned r; asm volatile("v_cvt_pk_bf16_f32 %0, %1, %2" : "=v"(r) : "v"(lo), "v"(hi)); return r; }
; __device__ __forceinline__ float bf_lo(unsigned w) { return __uint_as_float(w << 16); }
; __device__ __forceinline__ float bf_hi(unsigned w) { return __uint_as_float(w & 0xffff0000u); }
; __device__ void phase_pool() {
;     ...
;             for (int k = 0; k < 8; ++k) { const int row = row0 + r0 + k, tl = tl0 + r0 + k; const u32x4 v = vv[k], o2 = ov[k];
;                 s[0] += bf_lo(v.x) - bf_lo(o2.x); s[1] += bf_hi(v.x) - bf_hi(o2.x); s[2] += bf_lo(v.y) - bf_lo(o2.y); s[3] += bf_hi(v.y) - bf_hi(o2.y);
;                 s[4] += bf_lo(v.z) - bf_lo(o2.z); s[5] += bf_hi(v.z) - bf_hi(o2.z); s[6] += bf_lo(v.w) - bf_lo(o2.w); s[7] += bf_hi(v.w) - bf_hi(o2.w);
;                 const float ic = 1.0f / (float)((tl + 1 < w) ? tl + 1 : w);
;                 u32x4 o;
;                 o.x = cvt_pk_bf16(s[0] * ic - bf_lo(v.x), s[1] * ic - bf_hi(v.x)); o.y = cvt_pk_bf16(s[2] * ic - bf_lo(v.y), s[3] * ic - bf_hi(v.y));
;                 o.z = cvt_pk_bf16(s[4] * ic - bf_lo(v.z), s[5] * ic - bf_hi(v.z)); o.w = cvt_pk_bf16(s[6] * ic - bf_lo(v.w), s[7] * ic - bf_hi(v.w));
;                 *(u32x4*)(pg + (size_t)row * DE + col) = o; }
	s_cselect_b32 s42, 0x3dcccccd, s43
	v_lshlrev_b32_e32 v216, 16, v104
	v_and_b32_e32 v217, 0xffff0000, v104
	v_lshlrev_b32_e32 v218, 16, v40
	v_and_b32_e32 v219, 0xffff0000, v40
	v_lshlrev_b32_e32 v220, 16, v105
	v_and_b32_e32 v221, 0xffff0000, v105
	v_lshlrev_b32_e32 v222, 16, v41
	v_and_b32_e32 v223, 0xffff0000, v41
	v_lshlrev_b32_e32 v224, 16, v106
	v_and_b32_e32 v225, 0xffff0000, v106
	v_lshlrev_b32_e32 v226, 16, v42
	v_and_b32_e32 v227, 0xffff0000, v42
	v_lshlrev_b32_e32 v228, 16, v107
	v_and_b32_e32 v229, 0xffff0000, v107
	v_lshlrev_b32_e32 v230, 16, v43
	v_and_b32_e32 v231, 0xffff0000, v43
	v_pk_add_f32 v[218:219], v[216:217], v[218:219] neg_lo:[0,1] neg_hi:[0,1]
	v_pk_add_f32 v[222:223], v[220:221], v[222:223] neg_lo:[0,1] neg_hi:[0,1]
	v_pk_add_f32 v[226:227], v[224:225], v[226:227] neg_lo:[0,1] neg_hi:[0,1]
	v_pk_add_f32 v[230:231], v[228:229], v[230:231] neg_lo:[0,1] neg_hi:[0,1]
	v_pk_add_f32 v[204:205], v[204:205], v[218:219]
	v_pk_add_f32 v[206:207], v[206:207], v[222:223]
	v_pk_add_f32 v[208:209], v[208:209], v[226:227]
	v_pk_add_f32 v[210:211], v[210:211], v[230:231]
	v_fma_f32 v218, s42, v204, -v216
	v_fma_f32 v219, s42, v205, -v217
	v_fma_f32 v222, s42, v206, -v220
	v_fma_f32 v223, s42, v207, -v221
	v_fma_f32 v226, s42, v208, -v224
	v_fma_f32 v227, s42, v209, -v225
	v_fma_f32 v230, s42, v210, -v228
	v_fma_f32 v231, s42, v211, -v229
	v_cvt_pk_bf16_f32 v212, v218, v219
	v_cvt_pk_bf16_f32 v213, v222, v223
	v_cvt_pk_bf16_f32 v214, v226, v227
	v_cvt_pk_bf16_f32 v215, v230, v231
	global_store_dwordx4 v3, v[212:215], s[10:11]
	v_add_u32_e32 v3, 0x2000, v3
	s_waitcnt vmcnt(31)
	s_cselect_b32 s42, 0x3dba2e8c, s43
	v_lshlrev_b32_e32 v216, 16, v108
	v_and_b32_e32 v217, 0xffff0000, v108
	v_lshlrev_b32_e32 v218, 16, v44
	v_and_b32_e32 v219, 0xffff0000, v44
	v_lshlrev_b32_e32 v220, 16, v109
	v_and_b32_e32 v221, 0xffff0000, v109
	v_lshlrev_b32_e32 v222, 16, v45
	v_and_b32_e32 v223, 0xffff0000, v45
	v_lshlrev_b32_e32 v224, 16, v110
	v_and_b32_e32 v225, 0xffff0000, v110
	v_lshlrev_b32_e32 v226, 16, v46
	v_and_b32_e32 v227, 0xffff0000, v46
	v_lshlrev_b32_e32 v228, 16, v111
	v_and_b32_e32 v229, 0xffff0000, v111
	v_lshlrev_b32_e32 v230, 16, v47
	v_and_b32_e32 v231, 0xffff0000, v47
	v_pk_add_f32 v[218:219], v[216:217], v[218:219] neg_lo:[0,1] neg_hi:[0,1]
	v_pk_add_f32 v[222:223], v[220:221], v[222:223] neg_lo:[0,1] neg_hi:[0,1]
	v_pk_add_f32 v[226:227], v[224:225], v[226:227] neg_lo:[0,1] neg_hi:[0,1]
	v_pk_add_f32 v[230:231], v[228:229], v[230:231] neg_lo:[0,1] neg_hi:[0,1]
	v_pk_add_f32 v[204:205], v[204:205], v[218:219]
	v_pk_add_f32 v[206:207], v[206:207], v[222:223]
	v_pk_add_f32 v[208:209], v[208:209], v[226:227]
	v_pk_add_f32 v[210:211], v[210:211], v[230:231]
	v_fma_f32 v218, s42, v204, -v216
	v_fma_f32 v219, s42, v205, -v217
	v_fma_f32 v222, s42, v206, -v220
	v_fma_f32 v223, s42, v207, -v221
	v_fma_f32 v226, s42, v208, -v224
	v_fma_f32 v227, s42, v209, -v225
	v_fma_f32 v230, s42, v210, -v228
	v_fma_f32 v231, s42, v211, -v229
	v_cvt_pk_bf16_f32 v212, v218, v219
	v_cvt_pk_bf16_f32 v213, v222, v223
	v_cvt_pk_bf16_f32 v214, v226, v227
	v_cvt_pk_bf16_f32 v215, v230, v231
	global_store_dwordx4 v3, v[212:215], s[10:11]
	v_add_u32_e32 v3, 0x2000, v3
	s_waitcnt vmcnt(31)
	s_cselect_b32 s42, 0x3daaaaab, s43
	v_lshlrev_b32_e32 v216, 16, v112
	v_and_b32_e32 v217, 0xffff0000, v112
	v_lshlrev_b32_e32 v218, 16, v48
	v_and_b32_e32 v219, 0xffff0000, v48
	v_lshlrev_b32_e32 v220, 16, v113
	v_and_b32_e32 v221, 0xffff0000, v113
	v_lshlrev_b32_e32 v222, 16, v49
	v_and_b32_e32 v223, 0xffff0000, v49
	v_lshlrev_b32_e32 v224, 16, v114
	v_and_b32_e32 v225, 0xffff0000, v114
	v_lshlrev_b32_e32 v226, 16, v50
	v_and_b32_e32 v227, 0xffff0000, v50
	v_lshlrev_b32_e32 v228, 16, v115
	v_and_b32_e32 v229, 0xffff0000, v115
	v_lshlrev_b32_e32 v230, 16, v51
	v_and_b32_e32 v231, 0xffff0000, v51
	v_pk_add_f32 v[218:219], v[216:217], v[218:219] neg_lo:[0,1] neg_hi:[0,1]
	v_pk_add_f32 v[222:223], v[220:221], v[222:223] neg_lo:[0,1] neg_hi:[0,1]
	v_pk_add_f32 v[226:227], v[224:225], v[226:227] neg_lo:[0,1] neg_hi:[0,1]
	v_pk_add_f32 v[230:231], v[228:229], v[230:231] neg_lo:[0,1] neg_hi:[0,1]
	v_pk_add_f32 v[204:205], v[204:205], v[218:219]
	v_pk_add_f32 v[206:207], v[206:207], v[222:223]
	v_pk_add_f32 v[208:209], v[208:209], v[226:227]
	v_pk_add_f32 v[210:211], v[210:211], v[230:231]
	v_fma_f32 v218, s42, v204, -v216
	v_fma_f32 v219, s42, v205, -v217
	v_fma_f32 v222, s42, v206, -v220
	v_fma_f32 v223, s42, v207, -v221
	v_fma_f32 v226, s42, v208, -v224
	v_fma_f32 v227, s42, v209, -v225
	v_fma_f32 v230, s42, v210, -v228
	v_fma_f32 v231, s42, v211, -v229
	v_cvt_pk_bf16_f32 v212, v218, v219
	v_cvt_pk_bf16_f32 v213, v222, v223
	v_cvt_pk_bf16_f32 v214, v226, v227
	v_cvt_pk_bf16_f32 v215, v230, v231
	global_store_dwordx4 v3, v[212:215], s[10:11]
	v_add_u32_e32 v3, 0x2000, v3
	s_waitcnt vmcnt(31)
; __device__ __forceinline__ unsigned cvt_pk_bf16(float lo, float hi) { unsigned r; asm volatile("v_cvt_pk_bf16_f32 %0, %1, %2" : "=v"(r) : "v"(lo), "v"(hi)); return r; }
; __device__ __forceinline__ float bf_lo(unsigned w) { return __uint_as_float(w << 16); }
; __device__ __forceinline__ float bf_hi(unsigned w) { return __uint_as_float(w & 0xffff0000u); }
; __device__ void phase_pool() {
;     ...
;             for (int k = 0; k < 8; ++k) { const int row = row0 + r0 + k, tl = tl0 + r0 + k; const u32x4 v = vv[k], o2 = ov[k];
;                 s[0] += bf_lo(v.x) - bf_lo(o2.x); s[1] += bf_hi(v.x) - bf_hi(o2.x); s[2] += bf_lo(v.y) - bf_lo(o2.y); s[3] += bf_hi(v.y) - bf_hi(o2.y);
;                 s[4] += bf_lo(v.z) - bf_lo(o2.z); s[5] += bf_hi(v.z) - bf_hi(o2.z); s[6] += bf_lo(v.w) - bf_lo(o2.w); s[7] += bf_hi(v.w) - bf_hi(o2.w);
;                 const float ic = 1.0f / (float)((tl + 1 < w) ? tl + 1 : w);
;                 u32x4 o;
;                 o.x = cvt_pk_bf16(s[0] * ic - bf_lo(v.x), s[1] * ic - bf_hi(v.x)); o.y = cvt_pk_bf16(s[2] * ic - bf_lo(v.y), s[3] * ic - bf_hi(v.y));
;                 o.z = cvt_pk_bf16(s[4] * ic - bf_lo(v.z), s[5] * ic - bf_hi(v.z)); o.w = cvt_pk_bf16(s[6] * ic - bf_lo(v.w), s[7] * ic - bf_hi(v.w));
;                 *(u32x4*)(pg + (size_t)row * DE + col) = o; }
	s_cselect_b32 s42, 0x3d9d89d9, s43
	v_lshlrev_b32_e32 v216, 16, v116
	v_and_b32_e32 v217, 0xffff0000, v116
	v_lshlrev_b32_e32 v218, 16, v52
	v_and_b32_e32 v219, 0xffff0000, v52
	v_lshlrev_b32_e32 v220, 16, v117
	v_and_b32_e32 v221, 0xffff0000, v117
	v_lshlrev_b32_e32 v222, 16, v53
	v_and_b32_e32 v223, 0xffff0000, v53
	v_lshlrev_b32_e32 v224, 16, v118
	v_and_b32_e32 v225, 0xffff0000, v118
	v_lshlrev_b32_e32 v226, 16, v54
	v_and_b32_e32 v227, 0xffff0000, v54
	v_lshlrev_b32_e32 v228, 16, v119
	v_and_b32_e32 v229, 0xffff0000, v119
	v_lshlrev_b32_e32 v230, 16, v55
	v_and_b32_e32 v231, 0xffff0000, v55
	v_pk_add_f32 v[218:219], v[216:217], v[218:219] neg_lo:[0,1] neg_hi:[0,1]
	v_pk_add_f32 v[222:223], v[220:221], v[222:223] neg_lo:[0,1] neg_hi:[0,1]
	v_pk_add_f32 v[226:227], v[224:225], v[226:227] neg_lo:[0,1] neg_hi:[0,1]
	v_pk_add_f32 v[230:231], v[228:229], v[230:231] neg_lo:[0,1] neg_hi:[0,1]
	v_pk_add_f32 v[204:205], v[204:205], v[218:219]
	v_pk_add_f32 v[206:207], v[206:207], v[222:223]
	v_pk_add_f32 v[208:209], v[208:209], v[226:227]
	v_pk_add_f32 v[210:211], v[210:211], v[230:231]
	v_fma_f32 v218, s42, v204, -v216
	v_fma_f32 v219, s42, v205, -v217
	v_fma_f32 v222, s42, v206, -v220
	v_fma_f32 v223, s42, v207, -v221
	v_fma_f32 v226, s42, v208, -v224
	v_fma_f32 v227, s42, v209, -v225
	v_fma_f32 v230, s42, v210, -v228
	v_fma_f32 v231, s42, v211, -v229
	v_cvt_pk_bf16_f32 v212, v218, v219
	v_cvt_pk_bf16_f32 v213, v222, v223
	v_cvt_pk_bf16_f32 v214, v226, v227
	v_cvt_pk_bf16_f32 v215, v230, v231
	global_store_dwordx4 v3, v[212:215], s[10:11]
	v_add_u32_e32 v3, 0x2000, v3
	s_waitcnt vmcnt(31)
	s_cselect_b32 s42, 0x3d924925, s43
	v_lshlrev_b32_e32 v216, 16, v120
	v_and_b32_e32 v217, 0xffff0000, v120
	v_lshlrev_b32_e32 v218, 16, v56
	v_and_b32_e32 v219, 0xffff0000, v56
	v_lshlrev_b32_e32 v220, 16, v121
	v_and_b32_e32 v221, 0xffff0000, v121
	v_lshlrev_b32_e32 v222, 16, v57
	v_and_b32_e32 v223, 0xffff0000, v57
	v_lshlrev_b32_e32 v224, 16, v122
	v_and_b32_e32 v225, 0xffff0000, v122
	v_lshlrev_b32_e32 v226, 16, v58
	v_and_b32_e32 v227, 0xffff0000, v58
	v_lshlrev_b32_e32 v228, 16, v123
	v_and_b32_e32 v229, 0xffff0000, v123
	v_lshlrev_b32_e32 v230, 16, v59
	v_and_b32_e32 v231, 0xffff0000, v59
	v_pk_add_f32 v[218:219], v[216:217], v[218:219] neg_lo:[0,1] neg_hi:[0,1]
	v_pk_add_f32 v[222:223], v[220:221], v[222:223] neg_lo:[0,1] neg_hi:[0,1]
	v_pk_add_f32 v[226:227], v[224:225], v[226:227] neg_lo:[0,1] neg_hi:[0,1]
	v_pk_add_f32 v[230:231], v[228:229], v[230:231] neg_lo:[0,1] neg_hi:[0,1]
	v_pk_add_f32 v[204:205], v[204:205], v[218:219]
	v_pk_add_f32 v[206:207], v[206:207], v[222:223]
	v_pk_add_f32 v[208:209], v[208:209], v[226:227]
	v_pk_add_f32 v[210:211], v[210:211], v[230:231]
	v_fma_f32 v218, s42, v204, -v216
	v_fma_f32 v219, s42, v205, -v217
	v_fma_f32 v222, s42, v206, -v220
	v_fma_f32 v223, s42, v207, -v221
	v_fma_f32 v226, s42, v208, -v224
	v_fma_f32 v227, s42, v209, -v225
	v_fma_f32 v230, s42, v210, -v228
	v_fma_f32 v231, s42, v211, -v229
	v_cvt_pk_bf16_f32 v212, v218, v219
	v_cvt_pk_bf16_f32 v213, v222, v223
	v_cvt_pk_bf16_f32 v214, v226, v227
	v_cvt_pk_bf16_f32 v215, v230, v231
	global_store_dwordx4 v3, v[212:215], s[10:11]
	v_add_u32_e32 v3, 0x2000, v3
	s_waitcnt vmcnt(31)
	s_cselect_b32 s42, 0x3d888889, s43
	v_lshlrev_b32_e32 v216, 16, v124
	v_and_b32_e32 v217, 0xffff0000, v124
	v_lshlrev_b32_e32 v218, 16, v60
	v_and_b32_e32 v219, 0xffff0000, v60
	v_lshlrev_b32_e32 v220, 16, v125
	v_and_b32_e32 v221, 0xffff0000, v125
	v_lshlrev_b32_e32 v222, 16, v61
	v_and_b32_e32 v223, 0xffff0000, v61
	v_lshlrev_b32_e32 v224, 16, v126
	v_and_b32_e32 v225, 0xffff0000, v126
	v_lshlrev_b32_e32 v226, 16, v62
	v_and_b32_e32 v227, 0xffff0000, v62
	v_lshlrev_b32_e32 v228, 16, v127
	v_and_b32_e32 v229, 0xffff0000, v127
	v_lshlrev_b32_e32 v230, 16, v63
	v_and_b32_e32 v231, 0xffff0000, v63
	v_pk_add_f32 v[218:219], v[216:217], v[218:219] neg_lo:[0,1] neg_hi:[0,1]
	v_pk_add_f32 v[222:223], v[220:221], v[222:223] neg_lo:[0,1] neg_hi:[0,1]
	v_pk_add_f32 v[226:227], v[224:225], v[226:227] neg_lo:[0,1] neg_hi:[0,1]
	v_pk_add_f32 v[230:231], v[228:229], v[230:231] neg_lo:[0,1] neg_hi:[0,1]
	v_pk_add_f32 v[204:205], v[204:205], v[218:219]
	v_pk_add_f32 v[206:207], v[206:207], v[222:223]
	v_pk_add_f32 v[208:209], v[208:209], v[226:227]
	v_pk_add_f32 v[210:211], v[210:211], v[230:231]
	v_fma_f32 v218, s42, v204, -v216
	v_fma_f32 v219, s42, v205, -v217
	v_fma_f32 v222, s42, v206, -v220
	v_fma_f32 v223, s42, v207, -v221
	v_fma_f32 v226, s42, v208, -v224
	v_fma_f32 v227, s42, v209, -v225
	v_fma_f32 v230, s42, v210, -v228
	v_fma_f32 v231, s42, v211, -v229
	v_cvt_pk_bf16_f32 v212, v218, v219
	v_cvt_pk_bf16_f32 v213, v222, v223
	v_cvt_pk_bf16_f32 v214, v226, v227
	v_cvt_pk_bf16_f32 v215, v230, v231
	global_store_dwordx4 v3, v[212:215], s[10:11]
	v_add_u32_e32 v3, 0x2000, v3
	s_waitcnt vmcnt(31)
	v_lshlrev_b32_e32 v216, 16, v128
	v_and_b32_e32 v217, 0xffff0000, v128
	v_lshlrev_b32_e32 v218, 16, v64
	v_and_b32_e32 v219, 0xffff0000, v64
	v_lshlrev_b32_e32 v220, 16, v129
	v_and_b32_e32 v221, 0xffff0000, v129
	v_lshlrev_b32_e32 v222, 16, v65
	v_and_b32_e32 v223, 0xffff0000, v65
	v_lshlrev_b32_e32 v224, 16, v130
	v_and_b32_e32 v225, 0xffff0000, v130
	v_lshlrev_b32_e32 v226, 16, v66
	v_and_b32_e32 v227, 0xffff0000, v66
	v_lshlrev_b32_e32 v228, 16, v131
	v_and_b32_e32 v229, 0xffff0000, v131
	v_lshlrev_b32_e32 v230, 16, v67
	v_and_b32_e32 v231, 0xffff0000, v67
	v_pk_add_f32 v[218:219], v[216:217], v[218:219] neg_lo:[0,1] neg_hi:[0,1]
	v_pk_add_f32 v[222:223], v[220:221], v[222:223] neg_lo:[0,1] neg_hi:[0,1]
	v_pk_add_f32 v[226:227], v[224:225], v[226:227] neg_lo:[0,1] neg_hi:[0,1]
	v_pk_add_f32 v[230:231], v[228:229], v[230:231] neg_lo:[0,1] neg_hi:[0,1]
	v_pk_add_f32 v[204:205], v[204:205], v[218:219]
	v_pk_add_f32 v[206:207], v[206:207], v[222:223]
	v_pk_add_f32 v[208:209], v[208:209], v[226:227]
	v_pk_add_f32 v[210:211], v[210:211], v[230:231]
	v_fma_f32 v218, s43, v204, -v216
	v_fma_f32 v219, s43, v205, -v217
	v_fma_f32 v222, s43, v206, -v220
	v_fma_f32 v223, s43, v207, -v221
	v_fma_f32 v226, s43, v208, -v224
	v_fma_f32 v227, s43, v209, -v225
	v_fma_f32 v230, s43, v210, -v228
	v_fma_f32 v231, s43, v211, -v229
	v_cvt_pk_bf16_f32 v212, v218, v219
	v_cvt_pk_bf16_f32 v213, v222, v223
	v_cvt_pk_bf16_f32 v214, v226, v227
	v_cvt_pk_bf16_f32 v215, v230, v231
	global_store_dwordx4 v3, v[212:215], s[10:11]
	v_add_u32_e32 v3, 0x2000, v3
	s_waitcnt vmcnt(31)
; __device__ __forceinline__ unsigned cvt_pk_bf16(float lo, float hi) { unsigned r; asm volatile("v_cvt_pk_bf16_f32 %0, %1, %2" : "=v"(r) : "v"(lo), "v"(hi)); return r; }
; __device__ __forceinline__ float bf_lo(unsigned w) { return __uint_as_float(w << 16); }
; __device__ __forceinline__ float bf_hi(unsigned w) { return __uint_as_float(w & 0xffff0000u); }
; __device__ void phase_pool() {
;     ...
;             for (int k = 0; k < 8; ++k) { const int row = row0 + r0 + k, tl = tl0 + r0 + k; const u32x4 v = vv[k], o2 = ov[k];
;                 s[0] += bf_lo(v.x) - bf_lo(o2.x); s[1] += bf_hi(v.x) - bf_hi(o2.x); s[2] += bf_lo(v.y) - bf_lo(o2.y); s[3] += bf_hi(v.y) - bf_hi(o2.y);
;                 s[4] += bf_lo(v.z) - bf_lo(o2.z); s[5] += bf_hi(v.z) - bf_hi(o2.z); s[6] += bf_lo(v.w) - bf_lo(o2.w); s[7] += bf_hi(v.w) - bf_hi(o2.w);
;                 const float ic = 1.0f / (float)((tl + 1 < w) ? tl + 1 : w);
;                 u32x4 o;
;                 o.x = cvt_pk_bf16(s[0] * ic - bf_lo(v.x), s[1] * ic - bf_hi(v.x)); o.y = cvt_pk_bf16(s[2] * ic - bf_lo(v.y), s[3] * ic - bf_hi(v.y));
;                 o.z = cvt_pk_bf16(s[4] * ic - bf_lo(v.z), s[5] * ic - bf_hi(v.z)); o.w = cvt_pk_bf16(s[6] * ic - bf_lo(v.w), s[7] * ic - bf_hi(v.w));
;                 *(u32x4*)(pg + (size_t)row * DE + col) = o; }
	v_lshlrev_b32_e32 v216, 16, v132
	v_and_b32_e32 v217, 0xffff0000, v132
	v_lshlrev_b32_e32 v218, 16, v68
	v_and_b32_e32 v219, 0xffff0000, v68
	v_lshlrev_b32_e32 v220, 16, v133
	v_and_b32_e32 v221, 0xffff0000, v133
	v_lshlrev_b32_e32 v222, 16, v69
	v_and_b32_e32 v223, 0xffff0000, v69
	v_lshlrev_b32_e32 v224, 16, v134
	v_and_b32_e32 v225, 0xffff0000, v134
	v_lshlrev_b32_e32 v226, 16, v70
	v_and_b32_e32 v227, 0xffff0000, v70
	v_lshlrev_b32_e32 v228, 16, v135
	v_and_b32_e32 v229, 0xffff0000, v135
	v_lshlrev_b32_e32 v230, 16, v71
	v_and_b32_e32 v231, 0xffff0000, v71
	v_pk_add_f32 v[218:219], v[216:217], v[218:219] neg_lo:[0,1] neg_hi:[0,1]
	v_pk_add_f32 v[222:223], v[220:221], v[222:223] neg_lo:[0,1] neg_hi:[0,1]
	v_pk_add_f32 v[226:227], v[224:225], v[226:227] neg_lo:[0,1] neg_hi:[0,1]
	v_pk_add_f32 v[230:231], v[228:229], v[230:231] neg_lo:[0,1] neg_hi:[0,1]
	v_pk_add_f32 v[204:205], v[204:205], v[218:219]
	v_pk_add_f32 v[206:207], v[206:207], v[222:223]
	v_pk_add_f32 v[208:209], v[208:209], v[226:227]
	v_pk_add_f32 v[210:211], v[210:211], v[230:231]
	v_fma_f32 v218, s43, v204, -v216
	v_fma_f32 v219, s43, v205, -v217
	v_fma_f32 v222, s43, v206, -v220
	v_fma_f32 v223, s43, v207, -v221
	v_fma_f32 v226, s43, v208, -v224
	v_fma_f32 v227, s43, v209, -v225
	v_fma_f32 v230, s43, v210, -v228
	v_fma_f32 v231, s43, v211, -v229
	v_cvt_pk_bf16_f32 v212, v218, v219
	v_cvt_pk_bf16_f32 v213, v222, v223
	v_cvt_pk_bf16_f32 v214, v226, v227
	v_cvt_pk_bf16_f32 v215, v230, v231
	global_store_dwordx4 v3, v[212:215], s[10:11]
	v_add_u32_e32 v3, 0x2000, v3
	s_waitcnt vmcnt(31)
	v_lshlrev_b32_e32 v216, 16, v136
	v_and_b32_e32 v217, 0xffff0000, v136
	v_lshlrev_b32_e32 v218, 16, v72
	v_and_b32_e32 v219, 0xffff0000, v72
	v_lshlrev_b32_e32 v220, 16, v137
	v_and_b32_e32 v221, 0xffff0000, v137
	v_lshlrev_b32_e32 v222, 16, v73
	v_and_b32_e32 v223, 0xffff0000, v73
	v_lshlrev_b32_e32 v224, 16, v138
	v_and_b32_e32 v225, 0xffff0000, v138
	v_lshlrev_b32_e32 v226, 16, v74
	v_and_b32_e32 v227, 0xffff0000, v74
	v_lshlrev_b32_e32 v228, 16, v139
	v_and_b32_e32 v229, 0xffff0000, v139
	v_lshlrev_b32_e32 v230, 16, v75
	v_and_b32_e32 v231, 0xffff0000, v75
	v_pk_add_f32 v[218:219], v[216:217], v[218:219] neg_lo:[0,1] neg_hi:[0,1]
	v_pk_add_f32 v[222:223], v[220:221], v[222:223] neg_lo:[0,1] neg_hi:[0,1]
	v_pk_add_f32 v[226:227], v[224:225], v[226:227] neg_lo:[0,1] neg_hi:[0,1]
	v_pk_add_f32 v[230:231], v[228:229], v[230:231] neg_lo:[0,1] neg_hi:[0,1]
	v_pk_add_f32 v[204:205], v[204:205], v[218:219]
	v_pk_add_f32 v[206:207], v[206:207], v[222:223]
	v_pk_add_f32 v[208:209], v[208:209], v[226:227]
	v_pk_add_f32 v[210:211], v[210:211], v[230:231]
	v_fma_f32 v218, s43, v204, -v216
	v_fma_f32 v219, s43, v205, -v217
	v_fma_f32 v222, s43, v206, -v220
	v_fma_f32 v223, s43, v207, -v221
	v_fma_f32 v226, s43, v208, -v224
	v_fma_f32 v227, s43, v209, -v225
	v_fma_f32 v230, s43, v210, -v228
	v_fma_f32 v231, s43, v211, -v229
	v_cvt_pk_bf16_f32 v212, v218, v219
	v_cvt_pk_bf16_f32 v213, v222, v223
	v_cvt_pk_bf16_f32 v214, v226, v227
	v_cvt_pk_bf16_f32 v215, v230, v231
	global_store_dwordx4 v3, v[212:215], s[10:11]
	v_add_u32_e32 v3, 0x2000, v3
	s_waitcnt vmcnt(31)
	v_lshlrev_b32_e32 v216, 16, v140
	v_and_b32_e32 v217, 0xffff0000, v140
	v_lshlrev_b32_e32 v218, 16, v76
	v_and_b32_e32 v219, 0xffff0000, v76
	v_lshlrev_b32_e32 v220, 16, v141
	v_and_b32_e32 v221, 0xffff0000, v141
	v_lshlrev_b32_e32 v222, 16, v77
	v_and_b32_e32 v223, 0xffff0000, v77
	v_lshlrev_b32_e32 v224, 16, v142
	v_and_b32_e32 v225, 0xffff0000, v142
	v_lshlrev_b32_e32 v226, 16, v78
	v_and_b32_e32 v227, 0xffff0000, v78
	v_lshlrev_b32_e32 v228, 16, v143
	v_and_b32_e32 v229, 0xffff0000, v143
	v_lshlrev_b32_e32 v230, 16, v79
	v_and_b32_e32 v231, 0xffff0000, v79
	v_pk_add_f32 v[218:219], v[216:217], v[218:219] neg_lo:[0,1] neg_hi:[0,1]
	v_pk_add_f32 v[222:223], v[220:221], v[222:223] neg_lo:[0,1] neg_hi:[0,1]
	v_pk_add_f32 v[226:227], v[224:225], v[226:227] neg_lo:[0,1] neg_hi:[0,1]
	v_pk_add_f32 v[230:231], v[228:229], v[230:231] neg_lo:[0,1] neg_hi:[0,1]
	v_pk_add_f32 v[204:205], v[204:205], v[218:219]
	v_pk_add_f32 v[206:207], v[206:207], v[222:223]
	v_pk_add_f32 v[208:209], v[208:209], v[226:227]
	v_pk_add_f32 v[210:211], v[210:211], v[230:231]
	v_fma_f32 v218, s43, v204, -v216
	v_fma_f32 v219, s43, v205, -v217
	v_fma_f32 v222, s43, v206, -v220
	v_fma_f32 v223, s43, v207, -v221
	v_fma_f32 v226, s43, v208, -v224
	v_fma_f32 v227, s43, v209, -v225
	v_fma_f32 v230, s43, v210, -v228
	v_fma_f32 v231, s43, v211, -v229
	v_cvt_pk_bf16_f32 v212, v218, v219
	v_cvt_pk_bf16_f32 v213, v222, v223
	v_cvt_pk_bf16_f32 v214, v226, v227
	v_cvt_pk_bf16_f32 v215, v230, v231
	global_store_dwordx4 v3, v[212:215], s[10:11]
	v_add_u32_e32 v3, 0x2000, v3
	s_waitcnt vmcnt(31)
	v_lshlrev_b32_e32 v216, 16, v144
	v_and_b32_e32 v217, 0xffff0000, v144
	v_lshlrev_b32_e32 v218, 16, v80
	v_and_b32_e32 v219, 0xffff0000, v80
	v_lshlrev_b32_e32 v220, 16, v145
	v_and_b32_e32 v221, 0xffff0000, v145
	v_lshlrev_b32_e32 v222, 16, v81
	v_and_b32_e32 v223, 0xffff0000, v81
	v_lshlrev_b32_e32 v224, 16, v146
	v_and_b32_e32 v225, 0xffff0000, v146
	v_lshlrev_b32_e32 v226, 16, v82
	v_and_b32_e32 v227, 0xffff0000, v82
	v_lshlrev_b32_e32 v228, 16, v147
	v_and_b32_e32 v229, 0xffff0000, v147
	v_lshlrev_b32_e32 v230, 16, v83
	v_and_b32_e32 v231, 0xffff0000, v83
	v_pk_add_f32 v[218:219], v[216:217], v[218:219] neg_lo:[0,1] neg_hi:[0,1]
	v_pk_add_f32 v[222:223], v[220:221], v[222:223] neg_lo:[0,1] neg_hi:[0,1]
	v_pk_add_f32 v[226:227], v[224:225], v[226:227] neg_lo:[0,1] neg_hi:[0,1]
	v_pk_add_f32 v[230:231], v[228:229], v[230:231] neg_lo:[0,1] neg_hi:[0,1]
	v_pk_add_f32 v[204:205], v[204:205], v[218:219]
	v_pk_add_f32 v[206:207], v[206:207], v[222:223]
	v_pk_add_f32 v[208:209], v[208:209], v[226:227]
	v_pk_add_f32 v[210:211], v[210:211], v[230:231]
	v_fma_f32 v218, s43, v204, -v216
	v_fma_f32 v219, s43, v205, -v217
	v_fma_f32 v222, s43, v206, -v220
	v_fma_f32 v223, s43, v207, -v221
	v_fma_f32 v226, s43, v208, -v224
	v_fma_f32 v227, s43, v209, -v225
	v_fma_f32 v230, s43, v210, -v228
	v_fma_f32 v231, s43, v211, -v229
	v_cvt_pk_bf16_f32 v212, v218, v219
	v_cvt_pk_bf16_f32 v213, v222, v223
	v_cvt_pk_bf16_f32 v214, v226, v227
	v_cvt_pk_bf16_f32 v215, v230, v231
	global_store_dwordx4 v3, v[212:215], s[10:11]
	v_add_u32_e32 v3, 0x2000, v3
	s_waitcnt vmcnt(31)
; __device__ __forceinline__ unsigned cvt_pk_bf16(float lo, float hi) { unsigned r; asm volatile("v_cvt_pk_bf16_f32 %0, %1, %2" : "=v"(r) : "v"(lo), "v"(hi)); return r; }
; __device__ __forceinline__ float bf_lo(unsigned w) { return __uint_as_float(w << 16); }
; __device__ __forceinline__ float bf_hi(unsigned w) { return __uint_as_float(w & 0xffff0000u); }
; __device__ void phase_pool() {
;     ...
;             for (int k = 0; k < 8; ++k) { const int row = row0 + r0 + k, tl = tl0 + r0 + k; const u32x4 v = vv[k], o2 = ov[k];
;                 s[0] += bf_lo(v.x) - bf_lo(o2.x); s[1] += bf_hi(v.x) - bf_hi(o2.x); s[2] += bf_lo(v.y) - bf_lo(o2.y); s[3] += bf_hi(v.y) - bf_hi(o2.y);
;                 s[4] += bf_lo(v.z) - bf_lo(o2.z); s[5] += bf_hi(v.z) - bf_hi(o2.z); s[6] += bf_lo(v.w) - bf_lo(o2.w); s[7] += bf_hi(v.w) - bf_hi(o2.w);
;                 const float ic = 1.0f / (float)((tl + 1 < w) ? tl + 1 : w);
;                 u32x4 o;
;                 o.x = cvt_pk_bf16(s[0] * ic - bf_lo(v.x), s[1] * ic - bf_hi(v.x)); o.y = cvt_pk_bf16(s[2] * ic - bf_lo(v.y), s[3] * ic - bf_hi(v.y));
;                 o.z = cvt_pk_bf16(s[4] * ic - bf_lo(v.z), s[5] * ic - bf_hi(v.z)); o.w = cvt_pk_bf16(s[6] * ic - bf_lo(v.w), s[7] * ic - bf_hi(v.w));
;                 *(u32x4*)(pg + (size_t)row * DE + col) = o; }
	v_lshlrev_b32_e32 v216, 16, v148
	v_and_b32_e32 v217, 0xffff0000, v148
	v_lshlrev_b32_e32 v218, 16, v84
	v_and_b32_e32 v219, 0xffff0000, v84
	v_lshlrev_b32_e32 v220, 16, v149
	v_and_b32_e32 v221, 0xffff0000, v149
	v_lshlrev_b32_e32 v222, 16, v85
	v_and_b32_e32 v223, 0xffff0000, v85
	v_lshlrev_b32_e32 v224, 16, v150
	v_and_b32_e32 v225, 0xffff0000, v150
	v_lshlrev_b32_e32 v226, 16, v86
	v_and_b32_e32 v227, 0xffff0000, v86
	v_lshlrev_b32_e32 v228, 16, v151
	v_and_b32_e32 v229, 0xffff0000, v151
	v_lshlrev_b32_e32 v230, 16, v87
	v_and_b32_e32 v231, 0xffff0000, v87
	v_pk_add_f32 v[218:219], v[216:217], v[218:219] neg_lo:[0,1] neg_hi:[0,1]
	v_pk_add_f32 v[222:223], v[220:221], v[222:223] neg_lo:[0,1] neg_hi:[0,1]
	v_pk_add_f32 v[226:227], v[224:225], v[226:227] neg_lo:[0,1] neg_hi:[0,1]
	v_pk_add_f32 v[230:231], v[228:229], v[230:231] neg_lo:[0,1] neg_hi:[0,1]
	v_pk_add_f32 v[204:205], v[204:205], v[218:219]
	v_pk_add_f32 v[206:207], v[206:207], v[222:223]
	v_pk_add_f32 v[208:209], v[208:209], v[226:227]
	v_pk_add_f32 v[210:211], v[210:211], v[230:231]
	v_fma_f32 v218, s43, v204, -v216
	v_fma_f32 v219, s43, v205, -v217
	v_fma_f32 v222, s43, v206, -v220
	v_fma_f32 v223, s43, v207, -v221
	v_fma_f32 v226, s43, v208, -v224
	v_fma_f32 v227, s43, v209, -v225
	v_fma_f32 v230, s43, v210, -v228
	v_fma_f32 v231, s43, v211, -v229
	v_cvt_pk_bf16_f32 v212, v218, v219
	v_cvt_pk_bf16_f32 v213, v222, v223
	v_cvt_pk_bf16_f32 v214, v226, v227
	v_cvt_pk_bf16_f32 v215, v230, v231
	global_store_dwordx4 v3, v[212:215], s[10:11]
	v_add_u32_e32 v3, 0x2000, v3
	s_waitcnt vmcnt(31)
	v_lshlrev_b32_e32 v216, 16, v152
	v_and_b32_e32 v217, 0xffff0000, v152
	v_lshlrev_b32_e32 v218, 16, v88
	v_and_b32_e32 v219, 0xffff0000, v88
	v_lshlrev_b32_e32 v220, 16, v153
	v_and_b32_e32 v221, 0xffff0000, v153
	v_lshlrev_b32_e32 v222, 16, v89
	v_and_b32_e32 v223, 0xffff0000, v89
	v_lshlrev_b32_e32 v224, 16, v154
	v_and_b32_e32 v225, 0xffff0000, v154
	v_lshlrev_b32_e32 v226, 16, v90
	v_and_b32_e32 v227, 0xffff0000, v90
	v_lshlrev_b32_e32 v228, 16, v155
	v_and_b32_e32 v229, 0xffff0000, v155
	v_lshlrev_b32_e32 v230, 16, v91
	v_and_b32_e32 v231, 0xffff0000, v91
	v_pk_add_f32 v[218:219], v[216:217], v[218:219] neg_lo:[0,1] neg_hi:[0,1]
	v_pk_add_f32 v[222:223], v[220:221], v[222:223] neg_lo:[0,1] neg_hi:[0,1]
	v_pk_add_f32 v[226:227], v[224:225], v[226:227] neg_lo:[0,1] neg_hi:[0,1]
	v_pk_add_f32 v[230:231], v[228:229], v[230:231] neg_lo:[0,1] neg_hi:[0,1]
	v_pk_add_f32 v[204:205], v[204:205], v[218:219]
	v_pk_add_f32 v[206:207], v[206:207], v[222:223]
	v_pk_add_f32 v[208:209], v[208:209], v[226:227]
	v_pk_add_f32 v[210:211], v[210:211], v[230:231]
	v_fma_f32 v218, s43, v204, -v216
	v_fma_f32 v219, s43, v205, -v217
	v_fma_f32 v222, s43, v206, -v220
	v_fma_f32 v223, s43, v207, -v221
	v_fma_f32 v226, s43, v208, -v224
	v_fma_f32 v227, s43, v209, -v225
	v_fma_f32 v230, s43, v210, -v228
	v_fma_f32 v231, s43, v211, -v229
	v_cvt_pk_bf16_f32 v212, v218, v219
	v_cvt_pk_bf16_f32 v213, v222, v223
	v_cvt_pk_bf16_f32 v214, v226, v227
	v_cvt_pk_bf16_f32 v215, v230, v231
	global_store_dwordx4 v3, v[212:215], s[10:11]
	v_add_u32_e32 v3, 0x2000, v3
	s_waitcnt vmcnt(31)
	v_lshlrev_b32_e32 v216, 16, v156
	v_and_b32_e32 v217, 0xffff0000, v156
	v_lshlrev_b32_e32 v218, 16, v92
	v_and_b32_e32 v219, 0xffff0000, v92
	v_lshlrev_b32_e32 v220, 16, v157
	v_and_b32_e32 v221, 0xffff0000, v157
	v_lshlrev_b32_e32 v222, 16, v93
	v_and_b32_e32 v223, 0xffff0000, v93
	v_lshlrev_b32_e32 v224, 16, v158
	v_and_b32_e32 v225, 0xffff0000, v158
	v_lshlrev_b32_e32 v226, 16, v94
	v_and_b32_e32 v227, 0xffff0000, v94
	v_lshlrev_b32_e32 v228, 16, v159
	v_and_b32_e32 v229, 0xffff0000, v159
	v_lshlrev_b32_e32 v230, 16, v95
	v_and_b32_e32 v231, 0xffff0000, v95
	v_pk_add_f32 v[218:219], v[216:217], v[218:219] neg_lo:[0,1] neg_hi:[0,1]
	v_pk_add_f32 v[222:223], v[220:221], v[222:223] neg_lo:[0,1] neg_hi:[0,1]
	v_pk_add_f32 v[226:227], v[224:225], v[226:227] neg_lo:[0,1] neg_hi:[0,1]
	v_pk_add_f32 v[230:231], v[228:229], v[230:231] neg_lo:[0,1] neg_hi:[0,1]
	v_pk_add_f32 v[204:205], v[204:205], v[218:219]
	v_pk_add_f32 v[206:207], v[206:207], v[222:223]
	v_pk_add_f32 v[208:209], v[208:209], v[226:227]
	v_pk_add_f32 v[210:211], v[210:211], v[230:231]
	v_fma_f32 v218, s43, v204, -v216
	v_fma_f32 v219, s43, v205, -v217
	v_fma_f32 v222, s43, v206, -v220
	v_fma_f32 v223, s43, v207, -v221
	v_fma_f32 v226, s43, v208, -v224
	v_fma_f32 v227, s43, v209, -v225
	v_fma_f32 v230, s43, v210, -v228
	v_fma_f32 v231, s43, v211, -v229
	v_cvt_pk_bf16_f32 v212, v218, v219
	v_cvt_pk_bf16_f32 v213, v222, v223
	v_cvt_pk_bf16_f32 v214, v226, v227
	v_cvt_pk_bf16_f32 v215, v230, v231
	global_store_dwordx4 v3, v[212:215], s[10:11]
	v_add_u32_e32 v3, 0x2000, v3
	s_waitcnt vmcnt(31)
	v_lshlrev_b32_e32 v216, 16, v160
	v_and_b32_e32 v217, 0xffff0000, v160
	v_lshlrev_b32_e32 v218, 16, v96
	v_and_b32_e32 v219, 0xffff0000, v96
	v_lshlrev_b32_e32 v220, 16, v161
	v_and_b32_e32 v221, 0xffff0000, v161
	v_lshlrev_b32_e32 v222, 16, v97
	v_and_b32_e32 v223, 0xffff0000, v97
	v_lshlrev_b32_e32 v224, 16, v162
	v_and_b32_e32 v225, 0xffff0000, v162
	v_lshlrev_b32_e32 v226, 16, v98
	v_and_b32_e32 v227, 0xffff0000, v98
	v_lshlrev_b32_e32 v228, 16, v163
	v_and_b32_e32 v229, 0xffff0000, v163
	v_lshlrev_b32_e32 v230, 16, v99
	v_and_b32_e32 v231, 0xffff0000, v99
	v_pk_add_f32 v[218:219], v[216:217], v[218:219] neg_lo:[0,1] neg_hi:[0,1]
	v_pk_add_f32 v[222:223], v[220:221], v[222:223] neg_lo:[0,1] neg_hi:[0,1]
	v_pk_add_f32 v[226:227], v[224:225], v[226:227] neg_lo:[0,1] neg_hi:[0,1]
	v_pk_add_f32 v[230:231], v[228:229], v[230:231] neg_lo:[0,1] neg_hi:[0,1]
	v_pk_add_f32 v[204:205], v[204:205], v[218:219]
	v_pk_add_f32 v[206:207], v[206:207], v[222:223]
	v_pk_add_f32 v[208:209], v[208:209], v[226:227]
	v_pk_add_f32 v[210:211], v[210:211], v[230:231]
	v_fma_f32 v218, s43, v204, -v216
	v_fma_f32 v219, s43, v205, -v217
	v_fma_f32 v222, s43, v206, -v220
	v_fma_f32 v223, s43, v207, -v221
	v_fma_f32 v226, s43, v208, -v224
	v_fma_f32 v227, s43, v209, -v225
	v_fma_f32 v230, s43, v210, -v228
	v_fma_f32 v231, s43, v211, -v229
	v_cvt_pk_bf16_f32 v212, v218, v219
	v_cvt_pk_bf16_f32 v213, v222, v223
	v_cvt_pk_bf16_f32 v214, v226, v227
	v_cvt_pk_bf16_f32 v215, v230, v231
	global_store_dwordx4 v3, v[212:215], s[10:11]
	v_add_u32_e32 v3, 0x2000, v3
	s_waitcnt vmcnt(31)
; __device__ __forceinline__ unsigned cvt_pk_bf16(float lo, float hi) { unsigned r; asm volatile("v_cvt_pk_bf16_f32 %0, %1, %2" : "=v"(r) : "v"(lo), "v"(hi)); return r; }
; __device__ __forceinline__ float bf_lo(unsigned w) { return __uint_as_float(w << 16); }
; __device__ __forceinline__ float bf_hi(unsigned w) { return __uint_as_float(w & 0xffff0000u); }
; __device__ void phase_pool() {
;     ...
;             for (int k = 0; k < 8; ++k) { const int row = row0 + r0 + k, tl = tl0 + r0 + k; const u32x4 v = vv[k], o2 = ov[k];
;                 s[0] += bf_lo(v.x) - bf_lo(o2.x); s[1] += bf_hi(v.x) - bf_hi(o2.x); s[2] += bf_lo(v.y) - bf_lo(o2.y); s[3] += bf_hi(v.y) - bf_hi(o2.y);
;                 s[4] += bf_lo(v.z) - bf_lo(o2.z); s[5] += bf_hi(v.z) - bf_hi(o2.z); s[6] += bf_lo(v.w) - bf_lo(o2.w); s[7] += bf_hi(v.w) - bf_hi(o2.w);
;                 const float ic = 1.0f / (float)((tl + 1 < w) ? tl + 1 : w);
;                 u32x4 o;
;                 o.x = cvt_pk_bf16(s[0] * ic - bf_lo(v.x), s[1] * ic - bf_hi(v.x)); o.y = cvt_pk_bf16(s[2] * ic - bf_lo(v.y), s[3] * ic - bf_hi(v.y));
;                 o.z = cvt_pk_bf16(s[4] * ic - bf_lo(v.z), s[5] * ic - bf_hi(v.z)); o.w = cvt_pk_bf16(s[6] * ic - bf_lo(v.w), s[7] * ic - bf_hi(v.w));
;                 *(u32x4*)(pg + (size_t)row * DE + col) = o; }
	v_lshlrev_b32_e32 v216, 16, v164
	v_and_b32_e32 v217, 0xffff0000, v164
	v_lshlrev_b32_e32 v218, 16, v100
	v_and_b32_e32 v219, 0xffff0000, v100
	v_lshlrev_b32_e32 v220, 16, v165
	v_and_b32_e32 v221, 0xffff0000, v165
	v_lshlrev_b32_e32 v222, 16, v101
	v_and_b32_e32 v223, 0xffff0000, v101
	v_lshlrev_b32_e32 v224, 16, v166
	v_and_b32_e32 v225, 0xffff0000, v166
	v_lshlrev_b32_e32 v226, 16, v102
	v_and_b32_e32 v227, 0xffff0000, v102
	v_lshlrev_b32_e32 v228, 16, v167
	v_and_b32_e32 v229, 0xffff0000, v167
	v_lshlrev_b32_e32 v230, 16, v103
	v_and_b32_e32 v231, 0xffff0000, v103
	v_pk_add_f32 v[218:219], v[216:217], v[218:219] neg_lo:[0,1] neg_hi:[0,1]
	v_pk_add_f32 v[222:223], v[220:221], v[222:223] neg_lo:[0,1] neg_hi:[0,1]
	v_pk_add_f32 v[226:227], v[224:225], v[226:227] neg_lo:[0,1] neg_hi:[0,1]
	v_pk_add_f32 v[230:231], v[228:229], v[230:231] neg_lo:[0,1] neg_hi:[0,1]
	v_pk_add_f32 v[204:205], v[204:205], v[218:219]
	v_pk_add_f32 v[206:207], v[206:207], v[222:223]
	v_pk_add_f32 v[208:209], v[208:209], v[226:227]
	v_pk_add_f32 v[210:211], v[210:211], v[230:231]
	v_fma_f32 v218, s43, v204, -v216
	v_fma_f32 v219, s43, v205, -v217
	v_fma_f32 v222, s43, v206, -v220
	v_fma_f32 v223, s43, v207, -v221
	v_fma_f32 v226, s43, v208, -v224
	v_fma_f32 v227, s43, v209, -v225
	v_fma_f32 v230, s43, v210, -v228
	v_fma_f32 v231, s43, v211, -v229
	v_cvt_pk_bf16_f32 v212, v218, v219
	v_cvt_pk_bf16_f32 v213, v222, v223
	v_cvt_pk_bf16_f32 v214, v226, v227
	v_cvt_pk_bf16_f32 v215, v230, v231
	global_store_dwordx4 v3, v[212:215], s[10:11]
	v_add_u32_e32 v3, 0x2000, v3
	s_waitcnt vmcnt(31)
	v_lshlrev_b32_e32 v216, 16, v168
	v_and_b32_e32 v217, 0xffff0000, v168
	v_lshlrev_b32_e32 v218, 16, v104
	v_and_b32_e32 v219, 0xffff0000, v104
	v_lshlrev_b32_e32 v220, 16, v169
	v_and_b32_e32 v221, 0xffff0000, v169
	v_lshlrev_b32_e32 v222, 16, v105
	v_and_b32_e32 v223, 0xffff0000, v105
	v_lshlrev_b32_e32 v224, 16, v170
	v_and_b32_e32 v225, 0xffff0000, v170
	v_lshlrev_b32_e32 v226, 16, v106
	v_and_b32_e32 v227, 0xffff0000, v106
	v_lshlrev_b32_e32 v228, 16, v171
	v_and_b32_e32 v229, 0xffff0000, v171
	v_lshlrev_b32_e32 v230, 16, v107
	v_and_b32_e32 v231, 0xffff0000, v107
	v_pk_add_f32 v[218:219], v[216:217], v[218:219] neg_lo:[0,1] neg_hi:[0,1]
	v_pk_add_f32 v[222:223], v[220:221], v[222:223] neg_lo:[0,1] neg_hi:[0,1]
	v_pk_add_f32 v[226:227], v[224:225], v[226:227] neg_lo:[0,1] neg_hi:[0,1]
	v_pk_add_f32 v[230:231], v[228:229], v[230:231] neg_lo:[0,1] neg_hi:[0,1]
	v_pk_add_f32 v[204:205], v[204:205], v[218:219]
	v_pk_add_f32 v[206:207], v[206:207], v[222:223]
	v_pk_add_f32 v[208:209], v[208:209], v[226:227]
	v_pk_add_f32 v[210:211], v[210:211], v[230:231]
	v_fma_f32 v218, s43, v204, -v216
	v_fma_f32 v219, s43, v205, -v217
	v_fma_f32 v222, s43, v206, -v220
	v_fma_f32 v223, s43, v207, -v221
	v_fma_f32 v226, s43, v208, -v224
	v_fma_f32 v227, s43, v209, -v225
	v_fma_f32 v230, s43, v210, -v228
	v_fma_f32 v231, s43, v211, -v229
	v_cvt_pk_bf16_f32 v212, v218, v219
	v_cvt_pk_bf16_f32 v213, v222, v223
	v_cvt_pk_bf16_f32 v214, v226, v227
	v_cvt_pk_bf16_f32 v215, v230, v231
	global_store_dwordx4 v3, v[212:215], s[10:11]
	v_add_u32_e32 v3, 0x2000, v3
	s_waitcnt vmcnt(31)
	v_lshlrev_b32_e32 v216, 16, v172
	v_and_b32_e32 v217, 0xffff0000, v172
	v_lshlrev_b32_e32 v218, 16, v108
	v_and_b32_e32 v219, 0xffff0000, v108
	v_lshlrev_b32_e32 v220, 16, v173
	v_and_b32_e32 v221, 0xffff0000, v173
	v_lshlrev_b32_e32 v222, 16, v109
	v_and_b32_e32 v223, 0xffff0000, v109
	v_lshlrev_b32_e32 v224, 16, v174
	v_and_b32_e32 v225, 0xffff0000, v174
	v_lshlrev_b32_e32 v226, 16, v110
	v_and_b32_e32 v227, 0xffff0000, v110
	v_lshlrev_b32_e32 v228, 16, v175
	v_and_b32_e32 v229, 0xffff0000, v175
	v_lshlrev_b32_e32 v230, 16, v111
	v_and_b32_e32 v231, 0xffff0000, v111
	v_pk_add_f32 v[218:219], v[216:217], v[218:219] neg_lo:[0,1] neg_hi:[0,1]
	v_pk_add_f32 v[222:223], v[220:221], v[222:223] neg_lo:[0,1] neg_hi:[0,1]
	v_pk_add_f32 v[226:227], v[224:225], v[226:227] neg_lo:[0,1] neg_hi:[0,1]
	v_pk_add_f32 v[230:231], v[228:229], v[230:231] neg_lo:[0,1] neg_hi:[0,1]
	v_pk_add_f32 v[204:205], v[204:205], v[218:219]
	v_pk_add_f32 v[206:207], v[206:207], v[222:223]
	v_pk_add_f32 v[208:209], v[208:209], v[226:227]
	v_pk_add_f32 v[210:211], v[210:211], v[230:231]
	v_fma_f32 v218, s43, v204, -v216
	v_fma_f32 v219, s43, v205, -v217
	v_fma_f32 v222, s43, v206, -v220
	v_fma_f32 v223, s43, v207, -v221
	v_fma_f32 v226, s43, v208, -v224
	v_fma_f32 v227, s43, v209, -v225
	v_fma_f32 v230, s43, v210, -v228
	v_fma_f32 v231, s43, v211, -v229
	v_cvt_pk_bf16_f32 v212, v218, v219
	v_cvt_pk_bf16_f32 v213, v222, v223
	v_cvt_pk_bf16_f32 v214, v226, v227
	v_cvt_pk_bf16_f32 v215, v230, v231
	global_store_dwordx4 v3, v[212:215], s[10:11]
	v_add_u32_e32 v3, 0x2000, v3
	s_waitcnt vmcnt(31)
	v_lshlrev_b32_e32 v216, 16, v184
	v_and_b32_e32 v217, 0xffff0000, v184
	v_lshlrev_b32_e32 v218, 16, v112
	v_and_b32_e32 v219, 0xffff0000, v112
	v_lshlrev_b32_e32 v220, 16, v185
	v_and_b32_e32 v221, 0xffff0000, v185
	v_lshlrev_b32_e32 v222, 16, v113
	v_and_b32_e32 v223, 0xffff0000, v113
	v_lshlrev_b32_e32 v224, 16, v186
	v_and_b32_e32 v225, 0xffff0000, v186
	v_lshlrev_b32_e32 v226, 16, v114
	v_and_b32_e32 v227, 0xffff0000, v114
	v_lshlrev_b32_e32 v228, 16, v187
	v_and_b32_e32 v229, 0xffff0000, v187
	v_lshlrev_b32_e32 v230, 16, v115
	v_and_b32_e32 v231, 0xffff0000, v115
	v_pk_add_f32 v[218:219], v[216:217], v[218:219] neg_lo:[0,1] neg_hi:[0,1]
	v_pk_add_f32 v[222:223], v[220:221], v[222:223] neg_lo:[0,1] neg_hi:[0,1]
	v_pk_add_f32 v[226:227], v[224:225], v[226:227] neg_lo:[0,1] neg_hi:[0,1]
	v_pk_add_f32 v[230:231], v[228:229], v[230:231] neg_lo:[0,1] neg_hi:[0,1]
	v_pk_add_f32 v[204:205], v[204:205], v[218:219]
	v_pk_add_f32 v[206:207], v[206:207], v[222:223]
	v_pk_add_f32 v[208:209], v[208:209], v[226:227]
	v_pk_add_f32 v[210:211], v[210:211], v[230:231]
	v_fma_f32 v218, s43, v204, -v216
	v_fma_f32 v219, s43, v205, -v217
	v_fma_f32 v222, s43, v206, -v220
	v_fma_f32 v223, s43, v207, -v221
	v_fma_f32 v226, s43, v208, -v224
	v_fma_f32 v227, s43, v209, -v225
	v_fma_f32 v230, s43, v210, -v228
	v_fma_f32 v231, s43, v211, -v229
	v_cvt_pk_bf16_f32 v212, v218, v219
	v_cvt_pk_bf16_f32 v213, v222, v223
	v_cvt_pk_bf16_f32 v214, v226, v227
	v_cvt_pk_bf16_f32 v215, v230, v231
	global_store_dwordx4 v3, v[212:215], s[10:11]
	v_add_u32_e32 v3, 0x2000, v3
	s_waitcnt vmcnt(31)
; __device__ __forceinline__ unsigned cvt_pk_bf16(float lo, float hi) { unsigned r; asm volatile("v_cvt_pk_bf16_f32 %0, %1, %2" : "=v"(r) : "v"(lo), "v"(hi)); return r; }
; __device__ __forceinline__ float bf_lo(unsigned w) { return __uint_as_float(w << 16); }
; __device__ __forceinline__ float bf_hi(unsigned w) { return __uint_as_float(w & 0xffff0000u); }
; __device__ void phase_pool() {
;     ...
;             for (int k = 0; k < 8; ++k) { const int row = row0 + r0 + k, tl = tl0 + r0 + k; const u32x4 v = vv[k], o2 = ov[k];
;                 s[0] += bf_lo(v.x) - bf_lo(o2.x); s[1] += bf_hi(v.x) - bf_hi(o2.x); s[2] += bf_lo(v.y) - bf_lo(o2.y); s[3] += bf_hi(v.y) - bf_hi(o2.y);
;                 s[4] += bf_lo(v.z) - bf_lo(o2.z); s[5] += bf_hi(v.z) - bf_hi(o2.z); s[6] += bf_lo(v.w) - bf_lo(o2.w); s[7] += bf_hi(v.w) - bf_hi(o2.w);
;                 const float ic = 1.0f / (float)((tl + 1 < w) ? tl + 1 : w);
;                 u32x4 o;
;                 o.x = cvt_pk_bf16(s[0] * ic - bf_lo(v.x), s[1] * ic - bf_hi(v.x)); o.y = cvt_pk_bf16(s[2] * ic - bf_lo(v.y), s[3] * ic - bf_hi(v.y));
;                 o.z = cvt_pk_bf16(s[4] * ic - bf_lo(v.z), s[5] * ic - bf_hi(v.z)); o.w = cvt_pk_bf16(s[6] * ic - bf_lo(v.w), s[7] * ic - bf_hi(v.w));
;                 *(u32x4*)(pg + (size_t)row * DE + col) = o; }
	v_lshlrev_b32_e32 v216, 16, v188
	v_and_b32_e32 v217, 0xffff0000, v188
	v_lshlrev_b32_e32 v218, 16, v116
	v_and_b32_e32 v219, 0xffff0000, v116
	v_lshlrev_b32_e32 v220, 16, v189
	v_and_b32_e32 v221, 0xffff0000, v189
	v_lshlrev_b32_e32 v222, 16, v117
	v_and_b32_e32 v223, 0xffff0000, v117
	v_lshlrev_b32_e32 v224, 16, v190
	v_and_b32_e32 v225, 0xffff0000, v190
	v_lshlrev_b32_e32 v226, 16, v118
	v_and_b32_e32 v227, 0xffff0000, v118
	v_lshlrev_b32_e32 v228, 16, v191
	v_and_b32_e32 v229, 0xffff0000, v191
	v_lshlrev_b32_e32 v230, 16, v119
	v_and_b32_e32 v231, 0xffff0000, v119
	v_pk_add_f32 v[218:219], v[216:217], v[218:219] neg_lo:[0,1] neg_hi:[0,1]
	v_pk_add_f32 v[222:223], v[220:221], v[222:223] neg_lo:[0,1] neg_hi:[0,1]
	v_pk_add_f32 v[226:227], v[224:225], v[226:227] neg_lo:[0,1] neg_hi:[0,1]
	v_pk_add_f32 v[230:231], v[228:229], v[230:231] neg_lo:[0,1] neg_hi:[0,1]
	v_pk_add_f32 v[204:205], v[204:205], v[218:219]
	v_pk_add_f32 v[206:207], v[206:207], v[222:223]
	v_pk_add_f32 v[208:209], v[208:209], v[226:227]
	v_pk_add_f32 v[210:211], v[210:211], v[230:231]
	v_fma_f32 v218, s43, v204, -v216
	v_fma_f32 v219, s43, v205, -v217
	v_fma_f32 v222, s43, v206, -v220
	v_fma_f32 v223, s43, v207, -v221
	v_fma_f32 v226, s43, v208, -v224
	v_fma_f32 v227, s43, v209, -v225
	v_fma_f32 v230, s43, v210, -v228
	v_fma_f32 v231, s43, v211, -v229
	v_cvt_pk_bf16_f32 v212, v218, v219
	v_cvt_pk_bf16_f32 v213, v222, v223
	v_cvt_pk_bf16_f32 v214, v226, v227
	v_cvt_pk_bf16_f32 v215, v230, v231
	global_store_dwordx4 v3, v[212:215], s[10:11]
	v_add_u32_e32 v3, 0x2000, v3
	s_waitcnt vmcnt(31)
	v_lshlrev_b32_e32 v216, 16, v192
	v_and_b32_e32 v217, 0xffff0000, v192
	v_lshlrev_b32_e32 v218, 16, v120
	v_and_b32_e32 v219, 0xffff0000, v120
	v_lshlrev_b32_e32 v220, 16, v193
	v_and_b32_e32 v221, 0xffff0000, v193
	v_lshlrev_b32_e32 v222, 16, v121
	v_and_b32_e32 v223, 0xffff0000, v121
	v_lshlrev_b32_e32 v224, 16, v194
	v_and_b32_e32 v225, 0xffff0000, v194
	v_lshlrev_b32_e32 v226, 16, v122
	v_and_b32_e32 v227, 0xffff0000, v122
	v_lshlrev_b32_e32 v228, 16, v195
	v_and_b32_e32 v229, 0xffff0000, v195
	v_lshlrev_b32_e32 v230, 16, v123
	v_and_b32_e32 v231, 0xffff0000, v123
	v_pk_add_f32 v[218:219], v[216:217], v[218:219] neg_lo:[0,1] neg_hi:[0,1]
	v_pk_add_f32 v[222:223], v[220:221], v[222:223] neg_lo:[0,1] neg_hi:[0,1]
	v_pk_add_f32 v[226:227], v[224:225], v[226:227] neg_lo:[0,1] neg_hi:[0,1]
	v_pk_add_f32 v[230:231], v[228:229], v[230:231] neg_lo:[0,1] neg_hi:[0,1]
	v_pk_add_f32 v[204:205], v[204:205], v[218:219]
	v_pk_add_f32 v[206:207], v[206:207], v[222:223]
	v_pk_add_f32 v[208:209], v[208:209], v[226:227]
	v_pk_add_f32 v[210:211], v[210:211], v[230:231]
	v_fma_f32 v218, s43, v204, -v216
	v_fma_f32 v219, s43, v205, -v217
	v_fma_f32 v222, s43, v206, -v220
	v_fma_f32 v223, s43, v207, -v221
	v_fma_f32 v226, s43, v208, -v224
	v_fma_f32 v227, s43, v209, -v225
	v_fma_f32 v230, s43, v210, -v228
	v_fma_f32 v231, s43, v211, -v229
	v_cvt_pk_bf16_f32 v212, v218, v219
	v_cvt_pk_bf16_f32 v213, v222, v223
	v_cvt_pk_bf16_f32 v214, v226, v227
	v_cvt_pk_bf16_f32 v215, v230, v231
	global_store_dwordx4 v3, v[212:215], s[10:11]
	v_add_u32_e32 v3, 0x2000, v3
	s_waitcnt vmcnt(31)
	v_lshlrev_b32_e32 v216, 16, v196
	v_and_b32_e32 v217, 0xffff0000, v196
	v_lshlrev_b32_e32 v218, 16, v124
	v_and_b32_e32 v219, 0xffff0000, v124
	v_lshlrev_b32_e32 v220, 16, v197
	v_and_b32_e32 v221, 0xffff0000, v197
	v_lshlrev_b32_e32 v222, 16, v125
	v_and_b32_e32 v223, 0xffff0000, v125
	v_lshlrev_b32_e32 v224, 16, v198
	v_and_b32_e32 v225, 0xffff0000, v198
	v_lshlrev_b32_e32 v226, 16, v126
	v_and_b32_e32 v227, 0xffff0000, v126
	v_lshlrev_b32_e32 v228, 16, v199
	v_and_b32_e32 v229, 0xffff0000, v199
	v_lshlrev_b32_e32 v230, 16, v127
	v_and_b32_e32 v231, 0xffff0000, v127
	v_pk_add_f32 v[218:219], v[216:217], v[218:219] neg_lo:[0,1] neg_hi:[0,1]
	v_pk_add_f32 v[222:223], v[220:221], v[222:223] neg_lo:[0,1] neg_hi:[0,1]
	v_pk_add_f32 v[226:227], v[224:225], v[226:227] neg_lo:[0,1] neg_hi:[0,1]
	v_pk_add_f32 v[230:231], v[228:229], v[230:231] neg_lo:[0,1] neg_hi:[0,1]
	v_pk_add_f32 v[204:205], v[204:205], v[218:219]
	v_pk_add_f32 v[206:207], v[206:207], v[222:223]
	v_pk_add_f32 v[208:209], v[208:209], v[226:227]
	v_pk_add_f32 v[210:211], v[210:211], v[230:231]
	v_fma_f32 v218, s43, v204, -v216
	v_fma_f32 v219, s43, v205, -v217
	v_fma_f32 v222, s43, v206, -v220
	v_fma_f32 v223, s43, v207, -v221
	v_fma_f32 v226, s43, v208, -v224
	v_fma_f32 v227, s43, v209, -v225
	v_fma_f32 v230, s43, v210, -v228
	v_fma_f32 v231, s43, v211, -v229
	v_cvt_pk_bf16_f32 v212, v218, v219
	v_cvt_pk_bf16_f32 v213, v222, v223
	v_cvt_pk_bf16_f32 v214, v226, v227
	v_cvt_pk_bf16_f32 v215, v230, v231
	global_store_dwordx4 v3, v[212:215], s[10:11]
	v_add_u32_e32 v3, 0x2000, v3
	s_waitcnt vmcnt(31)
	v_lshlrev_b32_e32 v216, 16, v200
	v_and_b32_e32 v217, 0xffff0000, v200
	v_lshlrev_b32_e32 v218, 16, v128
	v_and_b32_e32 v219, 0xffff0000, v128
	v_lshlrev_b32_e32 v220, 16, v201
	v_and_b32_e32 v221, 0xffff0000, v201
	v_lshlrev_b32_e32 v222, 16, v129
	v_and_b32_e32 v223, 0xffff0000, v129
	v_lshlrev_b32_e32 v224, 16, v202
	v_and_b32_e32 v225, 0xffff0000, v202
	v_lshlrev_b32_e32 v226, 16, v130
	v_and_b32_e32 v227, 0xffff0000, v130
	v_lshlrev_b32_e32 v228, 16, v203
	v_and_b32_e32 v229, 0xffff0000, v203
	v_lshlrev_b32_e32 v230, 16, v131
	v_and_b32_e32 v231, 0xffff0000, v131
	v_pk_add_f32 v[218:219], v[216:217], v[218:219] neg_lo:[0,1] neg_hi:[0,1]
	v_pk_add_f32 v[222:223], v[220:221], v[222:223] neg_lo:[0,1] neg_hi:[0,1]
	v_pk_add_f32 v[226:227], v[224:225], v[226:227] neg_lo:[0,1] neg_hi:[0,1]
	v_pk_add_f32 v[230:231], v[228:229], v[230:231] neg_lo:[0,1] neg_hi:[0,1]
	v_pk_add_f32 v[204:205], v[204:205], v[218:219]
	v_pk_add_f32 v[206:207], v[206:207], v[222:223]
	v_pk_add_f32 v[208:209], v[208:209], v[226:227]
	v_pk_add_f32 v[210:211], v[210:211], v[230:231]
	v_fma_f32 v218, s43, v204, -v216
	v_fma_f32 v219, s43, v205, -v217
	v_fma_f32 v222, s43, v206, -v220
	v_fma_f32 v223, s43, v207, -v221
	v_fma_f32 v226, s43, v208, -v224
	v_fma_f32 v227, s43, v209, -v225
	v_fma_f32 v230, s43, v210, -v228
	v_fma_f32 v231, s43, v211, -v229
	v_cvt_pk_bf16_f32 v212, v218, v219
	v_cvt_pk_bf16_f32 v213, v222, v223
	v_cvt_pk_bf16_f32 v214, v226, v227
	v_cvt_pk_bf16_f32 v215, v230, v231
	global_store_dwordx4 v3, v[212:215], s[10:11]
	s_branch .LBB0_441
.Lpool_generic:
	s_mov_b64 s[4:5], s[70:71]
	v_mov_b32_e32 v0, v232
	v_readlane_b32 s0, v253, 42
	s_nop 1
	v_add_u32_e32 v108, s0, v0
	s_mov_b32 s0, 0x20000
	v_cmp_gt_i32_e32 vcc, s0, v108
	s_and_saveexec_b64 s[0:1], vcc
	s_cbranch_execz .LBB0_440
	s_load_dwordx2 s[8:9], s[4:5], 0xa0
	s_mov_b64 s[14:15], 0
	s_waitcnt lgkmcnt(0)
	s_add_u32 s10, s8, 0x2200000
	s_addc_u32 s11, s9, 0
	s_branch .LBB0_292
